# v7 + nt (streaming) hint on all 16-byte global stores, to leave less dirty L2 data for the grid barrier's writeback
# baseline (speedup 1.0000x reference)
.LBB0_41:
	s_mov_b64 s[8:9], s[46:47]
	s_waitcnt vmcnt(15)
	v_lshlrev_b32_e32 v158, 16, v146
	v_and_b32_e32 v159, 0xffff0000, v146
	v_pk_fma_f32 v[124:125], v[124:125], 0.5, v[158:159] op_sel_hi:[1,0,1]
	v_lshlrev_b32_e32 v140, 16, v147
	v_and_b32_e32 v141, 0xffff0000, v147
	v_pk_fma_f32 v[126:127], v[126:127], 0.5, v[140:141] op_sel_hi:[1,0,1]
	v_lshlrev_b32_e32 v158, 16, v148
	v_and_b32_e32 v159, 0xffff0000, v148
	v_pk_fma_f32 v[120:121], v[120:121], 0.5, v[158:159] op_sel_hi:[1,0,1]
	v_lshlrev_b32_e32 v140, 16, v149
	v_and_b32_e32 v141, 0xffff0000, v149
	v_pk_fma_f32 v[122:123], v[122:123], 0.5, v[140:141] op_sel_hi:[1,0,1]
	global_store_dwordx4 v139, v[124:127], s[8:9] nt
	global_store_dwordx4 v139, v[120:123], s[8:9] offset:16 nt
	s_waitcnt vmcnt(16)
	v_lshlrev_b32_e32 v158, 16, v150
	v_and_b32_e32 v159, 0xffff0000, v150
	v_pk_fma_f32 v[116:117], v[116:117], 0.5, v[158:159] op_sel_hi:[1,0,1]
	v_lshlrev_b32_e32 v140, 16, v151
	v_and_b32_e32 v141, 0xffff0000, v151
	v_pk_fma_f32 v[118:119], v[118:119], 0.5, v[140:141] op_sel_hi:[1,0,1]
	v_lshlrev_b32_e32 v158, 16, v152
	v_and_b32_e32 v159, 0xffff0000, v152
	v_pk_fma_f32 v[112:113], v[112:113], 0.5, v[158:159] op_sel_hi:[1,0,1]
	v_lshlrev_b32_e32 v140, 16, v153
	v_and_b32_e32 v141, 0xffff0000, v153
	v_pk_fma_f32 v[114:115], v[114:115], 0.5, v[140:141] op_sel_hi:[1,0,1]
	global_store_dwordx4 v139, v[116:119], s[8:9] offset:512 nt
	global_store_dwordx4 v139, v[112:115], s[8:9] offset:528 nt
	s_add_u32 s8, s8, 0x10000
	s_addc_u32 s9, s9, 0
	s_waitcnt vmcnt(17)
	v_lshlrev_b32_e32 v158, 16, v154
	v_and_b32_e32 v159, 0xffff0000, v154
	v_pk_fma_f32 v[108:109], v[108:109], 0.5, v[158:159] op_sel_hi:[1,0,1]
	v_lshlrev_b32_e32 v140, 16, v155
	v_and_b32_e32 v141, 0xffff0000, v155
	v_pk_fma_f32 v[110:111], v[110:111], 0.5, v[140:141] op_sel_hi:[1,0,1]
	v_lshlrev_b32_e32 v158, 16, v156
	v_and_b32_e32 v159, 0xffff0000, v156
	v_pk_fma_f32 v[104:105], v[104:105], 0.5, v[158:159] op_sel_hi:[1,0,1]
	v_lshlrev_b32_e32 v140, 16, v157
	v_and_b32_e32 v141, 0xffff0000, v157
	v_pk_fma_f32 v[106:107], v[106:107], 0.5, v[140:141] op_sel_hi:[1,0,1]
	global_store_dwordx4 v139, v[108:111], s[8:9] nt
	global_store_dwordx4 v139, v[104:107], s[8:9] offset:16 nt
	s_waitcnt vmcnt(18)
	v_lshlrev_b32_e32 v158, 16, v162
	v_and_b32_e32 v159, 0xffff0000, v162
	v_pk_fma_f32 v[100:101], v[100:101], 0.5, v[158:159] op_sel_hi:[1,0,1]
	v_lshlrev_b32_e32 v140, 16, v163
	v_and_b32_e32 v141, 0xffff0000, v163
	v_pk_fma_f32 v[102:103], v[102:103], 0.5, v[140:141] op_sel_hi:[1,0,1]
	v_lshlrev_b32_e32 v158, 16, v164
	v_and_b32_e32 v159, 0xffff0000, v164
	v_pk_fma_f32 v[96:97], v[96:97], 0.5, v[158:159] op_sel_hi:[1,0,1]
	v_lshlrev_b32_e32 v140, 16, v165
	v_and_b32_e32 v141, 0xffff0000, v165
	v_pk_fma_f32 v[98:99], v[98:99], 0.5, v[140:141] op_sel_hi:[1,0,1]
	global_store_dwordx4 v139, v[100:103], s[8:9] offset:512 nt
	global_store_dwordx4 v139, v[96:99], s[8:9] offset:528 nt
	s_add_u32 s8, s8, 0x10000
	s_addc_u32 s9, s9, 0
	s_waitcnt vmcnt(19)
	v_lshlrev_b32_e32 v158, 16, v166
	v_and_b32_e32 v159, 0xffff0000, v166
	v_pk_fma_f32 v[92:93], v[92:93], 0.5, v[158:159] op_sel_hi:[1,0,1]
	v_lshlrev_b32_e32 v140, 16, v167
	v_and_b32_e32 v141, 0xffff0000, v167
	v_pk_fma_f32 v[94:95], v[94:95], 0.5, v[140:141] op_sel_hi:[1,0,1]
	v_lshlrev_b32_e32 v158, 16, v168
	v_and_b32_e32 v159, 0xffff0000, v168
	v_pk_fma_f32 v[88:89], v[88:89], 0.5, v[158:159] op_sel_hi:[1,0,1]
	v_lshlrev_b32_e32 v140, 16, v169
	v_and_b32_e32 v141, 0xffff0000, v169
	v_pk_fma_f32 v[90:91], v[90:91], 0.5, v[140:141] op_sel_hi:[1,0,1]
	global_store_dwordx4 v139, v[92:95], s[8:9] nt
	global_store_dwordx4 v139, v[88:91], s[8:9] offset:16 nt
	s_waitcnt vmcnt(20)
	v_lshlrev_b32_e32 v158, 16, v174
	v_and_b32_e32 v159, 0xffff0000, v174
	v_pk_fma_f32 v[84:85], v[84:85], 0.5, v[158:159] op_sel_hi:[1,0,1]
	v_lshlrev_b32_e32 v140, 16, v175
	v_and_b32_e32 v141, 0xffff0000, v175
	v_pk_fma_f32 v[86:87], v[86:87], 0.5, v[140:141] op_sel_hi:[1,0,1]
	v_lshlrev_b32_e32 v158, 16, v176
	v_and_b32_e32 v159, 0xffff0000, v176
	v_pk_fma_f32 v[80:81], v[80:81], 0.5, v[158:159] op_sel_hi:[1,0,1]
	v_lshlrev_b32_e32 v140, 16, v177
	v_and_b32_e32 v141, 0xffff0000, v177
	v_pk_fma_f32 v[82:83], v[82:83], 0.5, v[140:141] op_sel_hi:[1,0,1]
	global_store_dwordx4 v139, v[84:87], s[8:9] offset:512 nt
	global_store_dwordx4 v139, v[80:83], s[8:9] offset:528 nt
	s_add_u32 s8, s8, 0x10000
	s_addc_u32 s9, s9, 0
	s_waitcnt vmcnt(21)
	v_lshlrev_b32_e32 v158, 16, v178
	v_and_b32_e32 v159, 0xffff0000, v178
	v_pk_fma_f32 v[76:77], v[76:77], 0.5, v[158:159] op_sel_hi:[1,0,1]
	v_lshlrev_b32_e32 v140, 16, v179
	v_and_b32_e32 v141, 0xffff0000, v179
	v_pk_fma_f32 v[78:79], v[78:79], 0.5, v[140:141] op_sel_hi:[1,0,1]
	v_lshlrev_b32_e32 v158, 16, v180
	v_and_b32_e32 v159, 0xffff0000, v180
	v_pk_fma_f32 v[72:73], v[72:73], 0.5, v[158:159] op_sel_hi:[1,0,1]
	v_lshlrev_b32_e32 v140, 16, v181
	v_and_b32_e32 v141, 0xffff0000, v181
	v_pk_fma_f32 v[74:75], v[74:75], 0.5, v[140:141] op_sel_hi:[1,0,1]
	global_store_dwordx4 v139, v[76:79], s[8:9] nt
	global_store_dwordx4 v139, v[72:75], s[8:9] offset:16 nt
	s_waitcnt vmcnt(22)
	v_lshlrev_b32_e32 v158, 16, v182
	v_and_b32_e32 v159, 0xffff0000, v182
	v_pk_fma_f32 v[68:69], v[68:69], 0.5, v[158:159] op_sel_hi:[1,0,1]
	v_lshlrev_b32_e32 v140, 16, v183
	v_and_b32_e32 v141, 0xffff0000, v183
	v_pk_fma_f32 v[70:71], v[70:71], 0.5, v[140:141] op_sel_hi:[1,0,1]
	v_lshlrev_b32_e32 v158, 16, v184
	v_and_b32_e32 v159, 0xffff0000, v184
	v_pk_fma_f32 v[64:65], v[64:65], 0.5, v[158:159] op_sel_hi:[1,0,1]
	v_lshlrev_b32_e32 v140, 16, v185
	v_and_b32_e32 v141, 0xffff0000, v185
	v_pk_fma_f32 v[66:67], v[66:67], 0.5, v[140:141] op_sel_hi:[1,0,1]
	global_store_dwordx4 v139, v[68:71], s[8:9] offset:512 nt
	global_store_dwordx4 v139, v[64:67], s[8:9] offset:528 nt
	s_add_u32 s8, s8, 0x50000
	s_addc_u32 s9, s9, 0
	s_waitcnt vmcnt(23)
	v_lshlrev_b32_e32 v158, 16, v186
	v_and_b32_e32 v159, 0xffff0000, v186
	v_pk_fma_f32 v[60:61], v[60:61], 0.5, v[158:159] op_sel_hi:[1,0,1]
	v_lshlrev_b32_e32 v140, 16, v187
	v_and_b32_e32 v141, 0xffff0000, v187
	v_pk_fma_f32 v[62:63], v[62:63], 0.5, v[140:141] op_sel_hi:[1,0,1]
	v_lshlrev_b32_e32 v158, 16, v188
	v_and_b32_e32 v159, 0xffff0000, v188
	v_pk_fma_f32 v[56:57], v[56:57], 0.5, v[158:159] op_sel_hi:[1,0,1]
	v_lshlrev_b32_e32 v140, 16, v189
	v_and_b32_e32 v141, 0xffff0000, v189
	v_pk_fma_f32 v[58:59], v[58:59], 0.5, v[140:141] op_sel_hi:[1,0,1]
	global_store_dwordx4 v139, v[60:63], s[8:9] nt
	global_store_dwordx4 v139, v[56:59], s[8:9] offset:16 nt
	s_waitcnt vmcnt(24)
	v_lshlrev_b32_e32 v158, 16, v190
	v_and_b32_e32 v159, 0xffff0000, v190
	v_pk_fma_f32 v[52:53], v[52:53], 0.5, v[158:159] op_sel_hi:[1,0,1]
	v_lshlrev_b32_e32 v140, 16, v191
	v_and_b32_e32 v141, 0xffff0000, v191
	v_pk_fma_f32 v[54:55], v[54:55], 0.5, v[140:141] op_sel_hi:[1,0,1]
	v_lshlrev_b32_e32 v158, 16, v192
	v_and_b32_e32 v159, 0xffff0000, v192
	v_pk_fma_f32 v[48:49], v[48:49], 0.5, v[158:159] op_sel_hi:[1,0,1]
	v_lshlrev_b32_e32 v140, 16, v193
	v_and_b32_e32 v141, 0xffff0000, v193
	v_pk_fma_f32 v[50:51], v[50:51], 0.5, v[140:141] op_sel_hi:[1,0,1]
	global_store_dwordx4 v139, v[52:55], s[8:9] offset:512 nt
	global_store_dwordx4 v139, v[48:51], s[8:9] offset:528 nt
	s_add_u32 s8, s8, 0x10000
	s_addc_u32 s9, s9, 0
	s_waitcnt vmcnt(25)
	v_lshlrev_b32_e32 v158, 16, v194
	v_and_b32_e32 v159, 0xffff0000, v194
	v_pk_fma_f32 v[44:45], v[44:45], 0.5, v[158:159] op_sel_hi:[1,0,1]
	v_lshlrev_b32_e32 v140, 16, v195
	v_and_b32_e32 v141, 0xffff0000, v195
	v_pk_fma_f32 v[46:47], v[46:47], 0.5, v[140:141] op_sel_hi:[1,0,1]
	v_lshlrev_b32_e32 v158, 16, v196
	v_and_b32_e32 v159, 0xffff0000, v196
	v_pk_fma_f32 v[40:41], v[40:41], 0.5, v[158:159] op_sel_hi:[1,0,1]
	v_lshlrev_b32_e32 v140, 16, v197
	v_and_b32_e32 v141, 0xffff0000, v197
	v_pk_fma_f32 v[42:43], v[42:43], 0.5, v[140:141] op_sel_hi:[1,0,1]
	global_store_dwordx4 v139, v[44:47], s[8:9] nt
	global_store_dwordx4 v139, v[40:43], s[8:9] offset:16 nt
	s_waitcnt vmcnt(26)
	v_lshlrev_b32_e32 v158, 16, v198
	v_and_b32_e32 v159, 0xffff0000, v198
	v_pk_fma_f32 v[36:37], v[36:37], 0.5, v[158:159] op_sel_hi:[1,0,1]
	v_lshlrev_b32_e32 v140, 16, v199
	v_and_b32_e32 v141, 0xffff0000, v199
	v_pk_fma_f32 v[38:39], v[38:39], 0.5, v[140:141] op_sel_hi:[1,0,1]
	v_lshlrev_b32_e32 v158, 16, v200
	v_and_b32_e32 v159, 0xffff0000, v200
	v_pk_fma_f32 v[32:33], v[32:33], 0.5, v[158:159] op_sel_hi:[1,0,1]
	v_lshlrev_b32_e32 v140, 16, v201
	v_and_b32_e32 v141, 0xffff0000, v201
	v_pk_fma_f32 v[34:35], v[34:35], 0.5, v[140:141] op_sel_hi:[1,0,1]
	global_store_dwordx4 v139, v[36:39], s[8:9] offset:512 nt
	global_store_dwordx4 v139, v[32:35], s[8:9] offset:528 nt
	s_add_u32 s8, s8, 0x10000
	s_addc_u32 s9, s9, 0
	s_waitcnt vmcnt(27)
	v_lshlrev_b32_e32 v158, 16, v202
	v_and_b32_e32 v159, 0xffff0000, v202
	v_pk_fma_f32 v[28:29], v[28:29], 0.5, v[158:159] op_sel_hi:[1,0,1]
	v_lshlrev_b32_e32 v140, 16, v203
	v_and_b32_e32 v141, 0xffff0000, v203
	v_pk_fma_f32 v[30:31], v[30:31], 0.5, v[140:141] op_sel_hi:[1,0,1]
	v_lshlrev_b32_e32 v158, 16, v204
	v_and_b32_e32 v159, 0xffff0000, v204
	v_pk_fma_f32 v[24:25], v[24:25], 0.5, v[158:159] op_sel_hi:[1,0,1]
	v_lshlrev_b32_e32 v140, 16, v205
	v_and_b32_e32 v141, 0xffff0000, v205
	v_pk_fma_f32 v[26:27], v[26:27], 0.5, v[140:141] op_sel_hi:[1,0,1]
	global_store_dwordx4 v139, v[28:31], s[8:9] nt
	global_store_dwordx4 v139, v[24:27], s[8:9] offset:16 nt
	s_waitcnt vmcnt(28)
	v_lshlrev_b32_e32 v158, 16, v206
	v_and_b32_e32 v159, 0xffff0000, v206
	v_pk_fma_f32 v[20:21], v[20:21], 0.5, v[158:159] op_sel_hi:[1,0,1]
	v_lshlrev_b32_e32 v140, 16, v207
	v_and_b32_e32 v141, 0xffff0000, v207
	v_pk_fma_f32 v[22:23], v[22:23], 0.5, v[140:141] op_sel_hi:[1,0,1]
	v_lshlrev_b32_e32 v158, 16, v208
	v_and_b32_e32 v159, 0xffff0000, v208
	v_pk_fma_f32 v[16:17], v[16:17], 0.5, v[158:159] op_sel_hi:[1,0,1]
	v_lshlrev_b32_e32 v140, 16, v209
	v_and_b32_e32 v141, 0xffff0000, v209
	v_pk_fma_f32 v[18:19], v[18:19], 0.5, v[140:141] op_sel_hi:[1,0,1]
	global_store_dwordx4 v139, v[20:23], s[8:9] offset:512 nt
	global_store_dwordx4 v139, v[16:19], s[8:9] offset:528 nt
	s_add_u32 s8, s8, 0x10000
	s_addc_u32 s9, s9, 0
	s_waitcnt vmcnt(29)
	v_lshlrev_b32_e32 v158, 16, v210
	v_and_b32_e32 v159, 0xffff0000, v210
	v_pk_fma_f32 v[12:13], v[12:13], 0.5, v[158:159] op_sel_hi:[1,0,1]
	v_lshlrev_b32_e32 v140, 16, v211
	v_and_b32_e32 v141, 0xffff0000, v211
	v_pk_fma_f32 v[14:15], v[14:15], 0.5, v[140:141] op_sel_hi:[1,0,1]
	v_lshlrev_b32_e32 v158, 16, v212
	v_and_b32_e32 v159, 0xffff0000, v212
	v_pk_fma_f32 v[8:9], v[8:9], 0.5, v[158:159] op_sel_hi:[1,0,1]
	v_lshlrev_b32_e32 v140, 16, v213
	v_and_b32_e32 v141, 0xffff0000, v213
	v_pk_fma_f32 v[10:11], v[10:11], 0.5, v[140:141] op_sel_hi:[1,0,1]
	global_store_dwordx4 v139, v[12:15], s[8:9] nt
	global_store_dwordx4 v139, v[8:11], s[8:9] offset:16 nt
	s_waitcnt vmcnt(30)
	v_lshlrev_b32_e32 v158, 16, v214
	v_and_b32_e32 v159, 0xffff0000, v214
	v_pk_fma_f32 v[4:5], v[4:5], 0.5, v[158:159] op_sel_hi:[1,0,1]
	v_lshlrev_b32_e32 v140, 16, v215
	v_and_b32_e32 v141, 0xffff0000, v215
	v_pk_fma_f32 v[6:7], v[6:7], 0.5, v[140:141] op_sel_hi:[1,0,1]
	v_lshlrev_b32_e32 v158, 16, v216
	v_and_b32_e32 v159, 0xffff0000, v216
	v_pk_fma_f32 v[0:1], v[0:1], 0.5, v[158:159] op_sel_hi:[1,0,1]
	v_lshlrev_b32_e32 v140, 16, v217
	v_and_b32_e32 v141, 0xffff0000, v217
	v_pk_fma_f32 v[2:3], v[2:3], 0.5, v[140:141] op_sel_hi:[1,0,1]
	global_store_dwordx4 v139, v[4:7], s[8:9] offset:512 nt
	global_store_dwordx4 v139, v[0:3], s[8:9] offset:528 nt
	v_mov_b64_e32 v[172:173], v[244:245]
	s_mov_b64 s[8:9], -1
	s_and_b64 vcc, exec, s[38:39]
	s_cbranch_vccnz .LBB0_26
	s_andn2_b64 vcc, exec, s[2:3]
	s_cbranch_vccnz .LBB0_25
	s_barrier
	s_branch .LBB0_25

.LBB0_59:
	v_lshl_or_b32 v142, s9, 7, v148
	v_lshl_add_u32 v138, s8, 8, v146
	v_ashrrev_i32_e32 v143, 31, v142
	v_mov_b64_e32 v[140:141], s[2:3]
	v_ashrrev_i32_e32 v139, 31, v138
	v_mad_i64_i32 v[144:145], s[8:9], v138, s16, v[140:141]
	v_lshlrev_b64 v[142:143], 1, v[142:143]
	v_lshl_add_u64 v[150:151], v[144:145], 0, v[142:143]
	v_lshl_add_u64 v[144:145], v[138:139], 3, s[4:5]
	v_pk_mul_f32 v[120:121], v[124:125], v[120:121]
	v_pk_mul_f32 v[122:123], v[126:127], v[122:123]
	v_pk_mul_f32 v[112:113], v[116:117], v[112:113]
	v_pk_mul_f32 v[114:115], v[118:119], v[114:115]
	v_pk_mul_f32 v[104:105], v[108:109], v[104:105]
	v_pk_mul_f32 v[106:107], v[110:111], v[106:107]
	v_pk_mul_f32 v[96:97], v[100:101], v[96:97]
	v_pk_mul_f32 v[98:99], v[102:103], v[98:99]
	v_pk_mul_f32 v[88:89], v[92:93], v[88:89]
	v_pk_mul_f32 v[90:91], v[94:95], v[90:91]
	v_pk_mul_f32 v[80:81], v[84:85], v[80:81]
	v_pk_mul_f32 v[82:83], v[86:87], v[82:83]
	v_pk_mul_f32 v[72:73], v[76:77], v[72:73]
	v_pk_mul_f32 v[74:75], v[78:79], v[74:75]
	v_pk_mul_f32 v[70:71], v[66:67], v[70:71]
	v_pk_mul_f32 v[56:57], v[60:61], v[56:57]
	v_pk_mul_f32 v[58:59], v[62:63], v[58:59]
	v_pk_mul_f32 v[54:55], v[50:51], v[54:55]
	v_pk_mul_f32 v[40:41], v[44:45], v[40:41]
	v_pk_mul_f32 v[42:43], v[46:47], v[42:43]
	v_pk_mul_f32 v[38:39], v[34:35], v[38:39]
	v_pk_mul_f32 v[24:25], v[28:29], v[24:25]
	v_pk_mul_f32 v[26:27], v[30:31], v[26:27]
	v_pk_mul_f32 v[22:23], v[18:19], v[22:23]
	v_pk_mul_f32 v[8:9], v[12:13], v[8:9]
	v_pk_mul_f32 v[10:11], v[14:15], v[10:11]
	v_pk_mul_f32 v[6:7], v[2:3], v[6:7]
	s_andn2_b64 vcc, exec, s[38:39]
	v_mov_b64_e32 v[172:173], v[244:245]
	s_waitcnt vmcnt(0) lgkmcnt(0)
	v_mov_b64_e32 v[152:153], v[176:177]
	v_ffbh_u32_e32 v139, v153
	v_min_u32_e32 v139, 32, v139
	v_lshlrev_b64 v[152:153], v139, v[152:153]
	v_min_u32_e32 v152, 1, v152
	v_or_b32_e32 v152, v153, v152
	v_cvt_f32_u32_e32 v152, v152
	v_sub_u32_e32 v139, 32, v139
	v_ldexp_f32 v139, v152, v139
	v_mul_f32_e32 v139, 0x35800000, v139
	v_fmamk_f32 v139, v139, 0x3a800000, v219
	v_rsq_f32_e32 v139, v139
	s_nop 0
	v_mul_f32_e32 v152, 0xbfb8aa3b, v139
	v_pk_mul_f32 v[156:157], v[124:125], v[152:153] op_sel_hi:[1,0]
	v_mul_f32_e32 v154, v139, v139
	v_exp_f32_e32 v156, v156
	v_exp_f32_e32 v157, v157
	s_nop 0
	v_pk_add_f32 v[156:157], v[156:157], 1.0 op_sel_hi:[1,0]
	s_nop 0
	v_rcp_f32_e32 v156, v156
	v_rcp_f32_e32 v157, v157
	s_nop 0
	v_pk_mul_f32 v[124:125], v[154:155], v[156:157] op_sel_hi:[0,1]
	v_pk_mul_f32 v[120:121], v[120:121], v[124:125]
	v_pk_mul_f32 v[124:125], v[126:127], v[152:153] op_sel_hi:[1,0]
	s_nop 0
	v_exp_f32_e32 v124, v124
	v_exp_f32_e32 v125, v125
	s_nop 0
	v_pk_add_f32 v[124:125], v[124:125], 1.0 op_sel_hi:[1,0]
	s_nop 0
	v_rcp_f32_e32 v124, v124
	v_rcp_f32_e32 v125, v125
	s_nop 0
	v_pk_mul_f32 v[124:125], v[154:155], v[124:125] op_sel_hi:[0,1]
	v_pk_mul_f32 v[122:123], v[122:123], v[124:125]
	v_pk_mul_f32 v[124:125], v[116:117], v[152:153] op_sel_hi:[1,0]
	s_nop 0
	v_exp_f32_e32 v124, v124
	v_exp_f32_e32 v125, v125
	s_nop 0
	v_pk_add_f32 v[124:125], v[124:125], 1.0 op_sel_hi:[1,0]
	s_nop 0
	v_rcp_f32_e32 v124, v124
	v_rcp_f32_e32 v125, v125
	s_nop 0
	v_pk_mul_f32 v[116:117], v[154:155], v[124:125] op_sel_hi:[0,1]
	v_pk_mul_f32 v[116:117], v[112:113], v[116:117]
	v_pk_mul_f32 v[112:113], v[118:119], v[152:153] op_sel_hi:[1,0]
	s_nop 0
	v_exp_f32_e32 v112, v112
	v_exp_f32_e32 v113, v113
	s_nop 0
	v_pk_add_f32 v[112:113], v[112:113], 1.0 op_sel_hi:[1,0]
	s_nop 0
	v_rcp_f32_e32 v112, v112
	v_rcp_f32_e32 v113, v113
	s_nop 0
	v_pk_mul_f32 v[112:113], v[154:155], v[112:113] op_sel_hi:[0,1]
	v_pk_mul_f32 v[118:119], v[114:115], v[112:113]
	v_cvt_pk_bf16_f32 v112, v120, v121
	v_cvt_pk_bf16_f32 v113, v122, v123
	v_cvt_pk_bf16_f32 v114, v116, v117
	v_cvt_pk_bf16_f32 v115, v118, v119
	global_store_dwordx4 v[150:151], v[112:115], off nt
	s_nop 1
	v_or_b32_e32 v114, 16, v138
	v_ashrrev_i32_e32 v115, 31, v114
	v_mad_i64_i32 v[112:113], s[8:9], v114, s16, v[140:141]
	v_lshl_add_u64 v[114:115], v[114:115], 3, s[4:5]
	s_nop 1
	v_mov_b64_e32 v[114:115], v[178:179]
	v_lshl_add_u64 v[112:113], v[112:113], 0, v[142:143]
	v_ffbh_u32_e32 v116, v115
	v_min_u32_e32 v116, 32, v116
	v_lshlrev_b64 v[114:115], v116, v[114:115]
	v_min_u32_e32 v114, 1, v114
	v_or_b32_e32 v114, v115, v114
	v_cvt_f32_u32_e32 v114, v114
	v_sub_u32_e32 v115, 32, v116
	v_ldexp_f32 v114, v114, v115
	v_mul_f32_e32 v114, 0x35800000, v114
	v_fmamk_f32 v114, v114, 0x3a800000, v219
	v_rsq_f32_e32 v115, v114
	s_nop 0
	v_mul_f32_e32 v114, 0xbfb8aa3b, v115
	v_pk_mul_f32 v[118:119], v[108:109], v[114:115] op_sel_hi:[1,0]
	v_mul_f32_e32 v116, v115, v115
	v_exp_f32_e32 v118, v118
	v_exp_f32_e32 v119, v119
	s_nop 0
	v_pk_add_f32 v[118:119], v[118:119], 1.0 op_sel_hi:[1,0]
	s_nop 0
	v_rcp_f32_e32 v118, v118
	v_rcp_f32_e32 v119, v119
	s_nop 0
	v_pk_mul_f32 v[108:109], v[116:117], v[118:119] op_sel_hi:[0,1]
	v_pk_mul_f32 v[104:105], v[104:105], v[108:109]
	v_pk_mul_f32 v[108:109], v[110:111], v[114:115] op_sel_hi:[1,0]
	s_nop 0
	v_exp_f32_e32 v108, v108
	v_exp_f32_e32 v109, v109
	s_nop 0
	v_pk_add_f32 v[108:109], v[108:109], 1.0 op_sel_hi:[1,0]
	s_nop 0
	v_rcp_f32_e32 v108, v108
	v_rcp_f32_e32 v109, v109
	s_nop 0
	v_pk_mul_f32 v[108:109], v[116:117], v[108:109] op_sel_hi:[0,1]
	v_pk_mul_f32 v[106:107], v[106:107], v[108:109]
	v_pk_mul_f32 v[108:109], v[100:101], v[114:115] op_sel_hi:[1,0]
	s_nop 0
	v_exp_f32_e32 v108, v108
	v_exp_f32_e32 v109, v109
	s_nop 0
	v_pk_add_f32 v[108:109], v[108:109], 1.0 op_sel_hi:[1,0]
	s_nop 0
	v_rcp_f32_e32 v108, v108
	v_rcp_f32_e32 v109, v109
	s_nop 0
	v_pk_mul_f32 v[100:101], v[116:117], v[108:109] op_sel_hi:[0,1]
	v_pk_mul_f32 v[100:101], v[96:97], v[100:101]
	v_pk_mul_f32 v[96:97], v[102:103], v[114:115] op_sel_hi:[1,0]
	s_nop 0
	v_exp_f32_e32 v96, v96
	v_exp_f32_e32 v97, v97
	s_nop 0
	v_pk_add_f32 v[96:97], v[96:97], 1.0 op_sel_hi:[1,0]
	s_nop 0
	v_rcp_f32_e32 v96, v96
	v_rcp_f32_e32 v97, v97
	s_nop 0
	v_pk_mul_f32 v[96:97], v[116:117], v[96:97] op_sel_hi:[0,1]
	v_pk_mul_f32 v[102:103], v[98:99], v[96:97]
	v_cvt_pk_bf16_f32 v96, v104, v105
	v_cvt_pk_bf16_f32 v97, v106, v107
	v_cvt_pk_bf16_f32 v98, v100, v101
	v_cvt_pk_bf16_f32 v99, v102, v103
	global_store_dwordx4 v[112:113], v[96:99], off nt
	s_nop 1
	v_or_b32_e32 v98, 32, v138
	v_ashrrev_i32_e32 v99, 31, v98
	v_mad_i64_i32 v[96:97], s[8:9], v98, s16, v[140:141]
	v_lshl_add_u64 v[98:99], v[98:99], 3, s[4:5]
	s_nop 1
	v_mov_b64_e32 v[98:99], v[180:181]
	v_lshl_add_u64 v[96:97], v[96:97], 0, v[142:143]
	v_ffbh_u32_e32 v100, v99
	v_min_u32_e32 v100, 32, v100
	v_lshlrev_b64 v[98:99], v100, v[98:99]
	v_min_u32_e32 v98, 1, v98
	v_or_b32_e32 v98, v99, v98
	v_cvt_f32_u32_e32 v98, v98
	v_sub_u32_e32 v99, 32, v100
	v_ldexp_f32 v98, v98, v99
	v_mul_f32_e32 v98, 0x35800000, v98
	v_fmamk_f32 v98, v98, 0x3a800000, v219
	v_rsq_f32_e32 v99, v98
	s_nop 0
	v_mul_f32_e32 v98, 0xbfb8aa3b, v99
	v_pk_mul_f32 v[102:103], v[92:93], v[98:99] op_sel_hi:[1,0]
	v_mul_f32_e32 v100, v99, v99
	v_exp_f32_e32 v102, v102
	v_exp_f32_e32 v103, v103
	s_nop 0
	v_pk_add_f32 v[102:103], v[102:103], 1.0 op_sel_hi:[1,0]
	s_nop 0
	v_rcp_f32_e32 v102, v102
	v_rcp_f32_e32 v103, v103
	s_nop 0
	v_pk_mul_f32 v[92:93], v[100:101], v[102:103] op_sel_hi:[0,1]
	v_pk_mul_f32 v[88:89], v[88:89], v[92:93]
	v_pk_mul_f32 v[92:93], v[94:95], v[98:99] op_sel_hi:[1,0]
	s_nop 0
	v_exp_f32_e32 v92, v92
	v_exp_f32_e32 v93, v93
	s_nop 0
	v_pk_add_f32 v[92:93], v[92:93], 1.0 op_sel_hi:[1,0]
	s_nop 0
	v_rcp_f32_e32 v92, v92
	v_rcp_f32_e32 v93, v93
	s_nop 0
	v_pk_mul_f32 v[92:93], v[100:101], v[92:93] op_sel_hi:[0,1]
	v_pk_mul_f32 v[90:91], v[90:91], v[92:93]
	v_pk_mul_f32 v[92:93], v[84:85], v[98:99] op_sel_hi:[1,0]
	s_nop 0
	v_exp_f32_e32 v92, v92
	v_exp_f32_e32 v93, v93
	s_nop 0
	v_pk_add_f32 v[92:93], v[92:93], 1.0 op_sel_hi:[1,0]
	s_nop 0
	v_rcp_f32_e32 v92, v92
	v_rcp_f32_e32 v93, v93
	s_nop 0
	v_pk_mul_f32 v[84:85], v[100:101], v[92:93] op_sel_hi:[0,1]
	v_pk_mul_f32 v[84:85], v[80:81], v[84:85]
	v_pk_mul_f32 v[80:81], v[86:87], v[98:99] op_sel_hi:[1,0]
	s_nop 0
	v_exp_f32_e32 v80, v80
	v_exp_f32_e32 v81, v81
	s_nop 0
	v_pk_add_f32 v[80:81], v[80:81], 1.0 op_sel_hi:[1,0]
	s_nop 0
	v_rcp_f32_e32 v80, v80
	v_rcp_f32_e32 v81, v81
	s_nop 0
	v_pk_mul_f32 v[80:81], v[100:101], v[80:81] op_sel_hi:[0,1]
	v_pk_mul_f32 v[86:87], v[82:83], v[80:81]
	v_cvt_pk_bf16_f32 v80, v88, v89
	v_cvt_pk_bf16_f32 v81, v90, v91
	v_cvt_pk_bf16_f32 v82, v84, v85
	v_cvt_pk_bf16_f32 v83, v86, v87
	global_store_dwordx4 v[96:97], v[80:83], off nt
	s_nop 1
	v_or_b32_e32 v82, 48, v138
	v_ashrrev_i32_e32 v83, 31, v82
	v_mad_i64_i32 v[80:81], s[8:9], v82, s16, v[140:141]
	v_lshl_add_u64 v[82:83], v[82:83], 3, s[4:5]
	s_nop 1
	v_mov_b64_e32 v[82:83], v[182:183]
	v_lshl_add_u64 v[80:81], v[80:81], 0, v[142:143]
	v_ffbh_u32_e32 v84, v83
	v_min_u32_e32 v84, 32, v84
	v_lshlrev_b64 v[82:83], v84, v[82:83]
	v_min_u32_e32 v82, 1, v82
	v_or_b32_e32 v82, v83, v82
	v_cvt_f32_u32_e32 v82, v82
	v_sub_u32_e32 v83, 32, v84
	v_ldexp_f32 v82, v82, v83
	v_mul_f32_e32 v82, 0x35800000, v82
	v_fmamk_f32 v82, v82, 0x3a800000, v219
	v_rsq_f32_e32 v82, v82
	s_nop 0
	v_mul_f32_e32 v84, 0xbfb8aa3b, v82
	v_pk_mul_f32 v[86:87], v[76:77], v[84:85] op_sel_hi:[1,0]
	v_mul_f32_e32 v82, v82, v82
	v_exp_f32_e32 v86, v86
	v_exp_f32_e32 v87, v87
	s_nop 0
	v_pk_add_f32 v[86:87], v[86:87], 1.0 op_sel_hi:[1,0]
	s_nop 0
	v_rcp_f32_e32 v86, v86
	v_rcp_f32_e32 v87, v87
	s_nop 0
	v_pk_mul_f32 v[76:77], v[82:83], v[86:87] op_sel_hi:[0,1]
	v_pk_mul_f32 v[72:73], v[72:73], v[76:77]
	v_pk_mul_f32 v[76:77], v[78:79], v[84:85] op_sel_hi:[1,0]
	s_nop 0
	v_exp_f32_e32 v76, v76
	v_exp_f32_e32 v77, v77
	s_nop 0
	v_pk_add_f32 v[76:77], v[76:77], 1.0 op_sel_hi:[1,0]
	s_nop 0
	v_rcp_f32_e32 v76, v76
	v_rcp_f32_e32 v77, v77
	s_nop 0
	v_pk_mul_f32 v[76:77], v[82:83], v[76:77] op_sel_hi:[0,1]
	v_pk_mul_f32 v[74:75], v[74:75], v[76:77]
	v_pk_mul_f32 v[76:77], v[64:65], v[84:85] op_sel_hi:[1,0]
	v_pk_mul_f32 v[64:65], v[64:65], v[68:69]
	v_exp_f32_e32 v76, v76
	v_exp_f32_e32 v77, v77
	s_nop 0
	v_pk_add_f32 v[76:77], v[76:77], 1.0 op_sel_hi:[1,0]
	s_nop 0
	v_rcp_f32_e32 v76, v76
	v_rcp_f32_e32 v77, v77
	s_nop 0
	v_pk_mul_f32 v[68:69], v[82:83], v[76:77] op_sel_hi:[0,1]
	v_pk_mul_f32 v[68:69], v[64:65], v[68:69]
	v_pk_mul_f32 v[64:65], v[66:67], v[84:85] op_sel_hi:[1,0]
	v_cvt_pk_bf16_f32 v66, v68, v69
	v_exp_f32_e32 v64, v64
	v_exp_f32_e32 v65, v65
	s_nop 0
	v_pk_add_f32 v[64:65], v[64:65], 1.0 op_sel_hi:[1,0]
	s_nop 0
	v_rcp_f32_e32 v64, v64
	v_rcp_f32_e32 v65, v65
	s_nop 0
	v_pk_mul_f32 v[64:65], v[82:83], v[64:65] op_sel_hi:[0,1]
	v_pk_mul_f32 v[70:71], v[70:71], v[64:65]
	v_cvt_pk_bf16_f32 v64, v72, v73
	v_cvt_pk_bf16_f32 v65, v74, v75
	v_cvt_pk_bf16_f32 v67, v70, v71
	global_store_dwordx4 v[80:81], v[64:67], off nt
	s_nop 1
	v_mov_b64_e32 v[66:67], v[184:185]
	v_ffbh_u32_e32 v68, v67
	v_min_u32_e32 v68, 32, v68
	v_lshlrev_b64 v[66:67], v68, v[66:67]
	v_min_u32_e32 v66, 1, v66
	v_or_b32_e32 v66, v67, v66
	v_cvt_f32_u32_e32 v66, v66
	v_sub_u32_e32 v67, 32, v68
	v_add_u32_e32 v64, 0x80, v138
	v_mad_i64_i32 v[64:65], s[8:9], v64, s16, v[140:141]
	v_ldexp_f32 v66, v66, v67
	v_mul_f32_e32 v66, 0x35800000, v66
	v_fmamk_f32 v66, v66, 0x3a800000, v219
	v_rsq_f32_e32 v66, v66
	v_lshl_add_u64 v[64:65], v[64:65], 0, v[142:143]
	v_mul_f32_e32 v68, 0xbfb8aa3b, v66
	v_pk_mul_f32 v[70:71], v[60:61], v[68:69] op_sel_hi:[1,0]
	v_mul_f32_e32 v66, v66, v66
	v_exp_f32_e32 v70, v70
	v_exp_f32_e32 v71, v71
	s_nop 0
	v_pk_add_f32 v[70:71], v[70:71], 1.0 op_sel_hi:[1,0]
	s_nop 0
	v_rcp_f32_e32 v70, v70
	v_rcp_f32_e32 v71, v71
	s_nop 0
	v_pk_mul_f32 v[60:61], v[66:67], v[70:71] op_sel_hi:[0,1]
	v_pk_mul_f32 v[56:57], v[56:57], v[60:61]
	v_pk_mul_f32 v[60:61], v[62:63], v[68:69] op_sel_hi:[1,0]
	s_nop 0
	v_exp_f32_e32 v60, v60
	v_exp_f32_e32 v61, v61
	s_nop 0
	v_pk_add_f32 v[60:61], v[60:61], 1.0 op_sel_hi:[1,0]
	s_nop 0
	v_rcp_f32_e32 v60, v60
	v_rcp_f32_e32 v61, v61
	s_nop 0
	v_pk_mul_f32 v[60:61], v[66:67], v[60:61] op_sel_hi:[0,1]
	v_pk_mul_f32 v[58:59], v[58:59], v[60:61]
	v_pk_mul_f32 v[60:61], v[48:49], v[68:69] op_sel_hi:[1,0]
	v_pk_mul_f32 v[48:49], v[48:49], v[52:53]
	v_exp_f32_e32 v60, v60
	v_exp_f32_e32 v61, v61
	s_nop 0
	v_pk_add_f32 v[60:61], v[60:61], 1.0 op_sel_hi:[1,0]
	s_nop 0
	v_rcp_f32_e32 v60, v60
	v_rcp_f32_e32 v61, v61
	s_nop 0
	v_pk_mul_f32 v[52:53], v[66:67], v[60:61] op_sel_hi:[0,1]
	v_pk_mul_f32 v[52:53], v[48:49], v[52:53]
	v_pk_mul_f32 v[48:49], v[50:51], v[68:69] op_sel_hi:[1,0]
	v_cvt_pk_bf16_f32 v50, v52, v53
	v_exp_f32_e32 v48, v48
	v_exp_f32_e32 v49, v49
	s_nop 0
	v_pk_add_f32 v[48:49], v[48:49], 1.0 op_sel_hi:[1,0]
	s_nop 0
	v_rcp_f32_e32 v48, v48
	v_rcp_f32_e32 v49, v49
	s_nop 0
	v_pk_mul_f32 v[48:49], v[66:67], v[48:49] op_sel_hi:[0,1]
	v_pk_mul_f32 v[54:55], v[54:55], v[48:49]
	v_cvt_pk_bf16_f32 v48, v56, v57
	v_cvt_pk_bf16_f32 v49, v58, v59
	v_cvt_pk_bf16_f32 v51, v54, v55
	global_store_dwordx4 v[64:65], v[48:51], off nt
	s_nop 1
	v_mov_b64_e32 v[50:51], v[186:187]
	v_ffbh_u32_e32 v52, v51
	v_min_u32_e32 v52, 32, v52
	v_lshlrev_b64 v[50:51], v52, v[50:51]
	v_min_u32_e32 v50, 1, v50
	v_or_b32_e32 v50, v51, v50
	v_cvt_f32_u32_e32 v50, v50
	v_sub_u32_e32 v51, 32, v52
	v_add_u32_e32 v48, 0x90, v138
	v_mad_i64_i32 v[48:49], s[8:9], v48, s16, v[140:141]
	v_ldexp_f32 v50, v50, v51
	v_mul_f32_e32 v50, 0x35800000, v50
	v_fmamk_f32 v50, v50, 0x3a800000, v219
	v_rsq_f32_e32 v50, v50
	v_lshl_add_u64 v[48:49], v[48:49], 0, v[142:143]
	v_mul_f32_e32 v52, 0xbfb8aa3b, v50
	v_pk_mul_f32 v[54:55], v[44:45], v[52:53] op_sel_hi:[1,0]
	v_mul_f32_e32 v50, v50, v50
	v_exp_f32_e32 v54, v54
	v_exp_f32_e32 v55, v55
	s_nop 0
	v_pk_add_f32 v[54:55], v[54:55], 1.0 op_sel_hi:[1,0]
	s_nop 0
	v_rcp_f32_e32 v54, v54
	v_rcp_f32_e32 v55, v55
	s_nop 0
	v_pk_mul_f32 v[44:45], v[50:51], v[54:55] op_sel_hi:[0,1]
	v_pk_mul_f32 v[40:41], v[40:41], v[44:45]
	v_pk_mul_f32 v[44:45], v[46:47], v[52:53] op_sel_hi:[1,0]
	s_nop 0
	v_exp_f32_e32 v44, v44
	v_exp_f32_e32 v45, v45
	s_nop 0
	v_pk_add_f32 v[44:45], v[44:45], 1.0 op_sel_hi:[1,0]
	s_nop 0
	v_rcp_f32_e32 v44, v44
	v_rcp_f32_e32 v45, v45
	s_nop 0
	v_pk_mul_f32 v[44:45], v[50:51], v[44:45] op_sel_hi:[0,1]
	v_pk_mul_f32 v[42:43], v[42:43], v[44:45]
	v_pk_mul_f32 v[44:45], v[32:33], v[52:53] op_sel_hi:[1,0]
	v_pk_mul_f32 v[32:33], v[32:33], v[36:37]
	v_exp_f32_e32 v44, v44
	v_exp_f32_e32 v45, v45
	s_nop 0
	v_pk_add_f32 v[44:45], v[44:45], 1.0 op_sel_hi:[1,0]
	s_nop 0
	v_rcp_f32_e32 v44, v44
	v_rcp_f32_e32 v45, v45
	s_nop 0
	v_pk_mul_f32 v[36:37], v[50:51], v[44:45] op_sel_hi:[0,1]
	v_pk_mul_f32 v[36:37], v[32:33], v[36:37]
	v_pk_mul_f32 v[32:33], v[34:35], v[52:53] op_sel_hi:[1,0]
	v_cvt_pk_bf16_f32 v34, v36, v37
	v_exp_f32_e32 v32, v32
	v_exp_f32_e32 v33, v33
	s_nop 0
	v_pk_add_f32 v[32:33], v[32:33], 1.0 op_sel_hi:[1,0]
	s_nop 0
	v_rcp_f32_e32 v32, v32
	v_rcp_f32_e32 v33, v33
	s_nop 0
	v_pk_mul_f32 v[32:33], v[50:51], v[32:33] op_sel_hi:[0,1]
	v_pk_mul_f32 v[38:39], v[38:39], v[32:33]
	v_cvt_pk_bf16_f32 v32, v40, v41
	v_cvt_pk_bf16_f32 v33, v42, v43
	v_cvt_pk_bf16_f32 v35, v38, v39
	global_store_dwordx4 v[48:49], v[32:35], off nt
	s_nop 1
	v_mov_b64_e32 v[34:35], v[188:189]
	v_ffbh_u32_e32 v36, v35
	v_min_u32_e32 v36, 32, v36
	v_lshlrev_b64 v[34:35], v36, v[34:35]
	v_min_u32_e32 v34, 1, v34
	v_or_b32_e32 v34, v35, v34
	v_cvt_f32_u32_e32 v34, v34
	v_sub_u32_e32 v35, 32, v36
	v_add_u32_e32 v32, 0xa0, v138
	v_mad_i64_i32 v[32:33], s[8:9], v32, s16, v[140:141]
	v_ldexp_f32 v34, v34, v35
	v_mul_f32_e32 v34, 0x35800000, v34
	v_fmamk_f32 v34, v34, 0x3a800000, v219
	v_rsq_f32_e32 v34, v34
	v_lshl_add_u64 v[32:33], v[32:33], 0, v[142:143]
	v_mul_f32_e32 v36, 0xbfb8aa3b, v34
	v_pk_mul_f32 v[38:39], v[28:29], v[36:37] op_sel_hi:[1,0]
	v_mul_f32_e32 v34, v34, v34
	v_exp_f32_e32 v38, v38
	v_exp_f32_e32 v39, v39
	s_nop 0
	v_pk_add_f32 v[38:39], v[38:39], 1.0 op_sel_hi:[1,0]
	s_nop 0
	v_rcp_f32_e32 v38, v38
	v_rcp_f32_e32 v39, v39
	s_nop 0
	v_pk_mul_f32 v[28:29], v[34:35], v[38:39] op_sel_hi:[0,1]
	v_pk_mul_f32 v[24:25], v[24:25], v[28:29]
	v_pk_mul_f32 v[28:29], v[30:31], v[36:37] op_sel_hi:[1,0]
	s_nop 0
	v_exp_f32_e32 v28, v28
	v_exp_f32_e32 v29, v29
	s_nop 0
	v_pk_add_f32 v[28:29], v[28:29], 1.0 op_sel_hi:[1,0]
	s_nop 0
	v_rcp_f32_e32 v28, v28
	v_rcp_f32_e32 v29, v29
	s_nop 0
	v_pk_mul_f32 v[28:29], v[34:35], v[28:29] op_sel_hi:[0,1]
	v_pk_mul_f32 v[26:27], v[26:27], v[28:29]
	v_pk_mul_f32 v[28:29], v[16:17], v[36:37] op_sel_hi:[1,0]
	v_pk_mul_f32 v[16:17], v[16:17], v[20:21]
	v_exp_f32_e32 v28, v28
	v_exp_f32_e32 v29, v29
	s_nop 0
	v_pk_add_f32 v[28:29], v[28:29], 1.0 op_sel_hi:[1,0]
	s_nop 0
	v_rcp_f32_e32 v28, v28
	v_rcp_f32_e32 v29, v29
	s_nop 0
	v_pk_mul_f32 v[20:21], v[34:35], v[28:29] op_sel_hi:[0,1]
	v_pk_mul_f32 v[20:21], v[16:17], v[20:21]
	v_pk_mul_f32 v[16:17], v[18:19], v[36:37] op_sel_hi:[1,0]
	v_cvt_pk_bf16_f32 v18, v20, v21
	v_exp_f32_e32 v16, v16
	v_exp_f32_e32 v17, v17
	s_nop 0
	v_pk_add_f32 v[16:17], v[16:17], 1.0 op_sel_hi:[1,0]
	s_nop 0
	v_rcp_f32_e32 v16, v16
	v_rcp_f32_e32 v17, v17
	s_nop 0
	v_pk_mul_f32 v[16:17], v[34:35], v[16:17] op_sel_hi:[0,1]
	v_pk_mul_f32 v[22:23], v[22:23], v[16:17]
	v_cvt_pk_bf16_f32 v16, v24, v25
	v_cvt_pk_bf16_f32 v17, v26, v27
	v_cvt_pk_bf16_f32 v19, v22, v23
	global_store_dwordx4 v[32:33], v[16:19], off nt
	s_nop 1
	v_mov_b64_e32 v[18:19], v[190:191]
	v_ffbh_u32_e32 v20, v19
	v_min_u32_e32 v20, 32, v20
	v_lshlrev_b64 v[18:19], v20, v[18:19]
	v_min_u32_e32 v18, 1, v18
	v_or_b32_e32 v18, v19, v18
	v_cvt_f32_u32_e32 v18, v18
	v_sub_u32_e32 v19, 32, v20
	v_add_u32_e32 v16, 0xb0, v138
	v_mad_i64_i32 v[16:17], s[8:9], v16, s16, v[140:141]
	v_ldexp_f32 v18, v18, v19
	v_mul_f32_e32 v18, 0x35800000, v18
	v_fmamk_f32 v18, v18, 0x3a800000, v219
	v_rsq_f32_e32 v18, v18
	v_lshl_add_u64 v[16:17], v[16:17], 0, v[142:143]
	s_mov_b64 s[8:9], -1
	v_mul_f32_e32 v20, 0xbfb8aa3b, v18
	v_pk_mul_f32 v[22:23], v[12:13], v[20:21] op_sel_hi:[1,0]
	v_mul_f32_e32 v18, v18, v18
	v_exp_f32_e32 v22, v22
	v_exp_f32_e32 v23, v23
	s_nop 0
	v_pk_add_f32 v[22:23], v[22:23], 1.0 op_sel_hi:[1,0]
	s_nop 0
	v_rcp_f32_e32 v22, v22
	v_rcp_f32_e32 v23, v23
	s_nop 0
	v_pk_mul_f32 v[12:13], v[18:19], v[22:23] op_sel_hi:[0,1]
	v_pk_mul_f32 v[8:9], v[8:9], v[12:13]
	v_pk_mul_f32 v[12:13], v[14:15], v[20:21] op_sel_hi:[1,0]
	s_nop 0
	v_exp_f32_e32 v12, v12
	v_exp_f32_e32 v13, v13
	s_nop 0
	v_pk_add_f32 v[12:13], v[12:13], 1.0 op_sel_hi:[1,0]
	s_nop 0
	v_rcp_f32_e32 v12, v12
	v_rcp_f32_e32 v13, v13
	s_nop 0
	v_pk_mul_f32 v[12:13], v[18:19], v[12:13] op_sel_hi:[0,1]
	v_pk_mul_f32 v[10:11], v[10:11], v[12:13]
	v_pk_mul_f32 v[12:13], v[0:1], v[20:21] op_sel_hi:[1,0]
	v_pk_mul_f32 v[0:1], v[0:1], v[4:5]
	v_exp_f32_e32 v12, v12
	v_exp_f32_e32 v13, v13
	s_nop 0
	v_pk_add_f32 v[12:13], v[12:13], 1.0 op_sel_hi:[1,0]
	s_nop 0
	v_rcp_f32_e32 v12, v12
	v_rcp_f32_e32 v13, v13
	s_nop 0
	v_pk_mul_f32 v[4:5], v[18:19], v[12:13] op_sel_hi:[0,1]
	v_pk_mul_f32 v[4:5], v[0:1], v[4:5]
	v_pk_mul_f32 v[0:1], v[2:3], v[20:21] op_sel_hi:[1,0]
	v_cvt_pk_bf16_f32 v2, v4, v5
	v_exp_f32_e32 v0, v0
	v_exp_f32_e32 v1, v1
	s_nop 0
	v_pk_add_f32 v[0:1], v[0:1], 1.0 op_sel_hi:[1,0]
	s_nop 0
	v_rcp_f32_e32 v0, v0
	v_rcp_f32_e32 v1, v1
	s_nop 0
	v_pk_mul_f32 v[0:1], v[18:19], v[0:1] op_sel_hi:[0,1]
	v_pk_mul_f32 v[6:7], v[6:7], v[0:1]
	v_cvt_pk_bf16_f32 v0, v8, v9
	v_cvt_pk_bf16_f32 v1, v10, v11
	v_cvt_pk_bf16_f32 v3, v6, v7
	global_store_dwordx4 v[16:17], v[0:3], off nt
	s_cbranch_vccnz .LBB0_52
	s_andn2_b64 vcc, exec, s[0:1]
	s_cbranch_vccnz .LBB0_51
	s_barrier
	s_branch .LBB0_51

.LBB0_87:
	s_mov_b64 s[8:9], s[2:3]
	s_waitcnt vmcnt(15)
	v_lshlrev_b32_e32 v158, 16, v146
	v_and_b32_e32 v159, 0xffff0000, v146
	v_pk_add_f32 v[124:125], v[124:125], v[158:159]
	v_lshlrev_b32_e32 v140, 16, v147
	v_and_b32_e32 v141, 0xffff0000, v147
	v_pk_add_f32 v[126:127], v[126:127], v[140:141]
	v_lshlrev_b32_e32 v158, 16, v148
	v_and_b32_e32 v159, 0xffff0000, v148
	v_pk_add_f32 v[120:121], v[120:121], v[158:159]
	v_lshlrev_b32_e32 v140, 16, v149
	v_and_b32_e32 v141, 0xffff0000, v149
	v_pk_add_f32 v[122:123], v[122:123], v[140:141]
	v_cvt_pk_bf16_f32 v146, v124, v125
	v_cvt_pk_bf16_f32 v147, v126, v127
	v_cvt_pk_bf16_f32 v148, v120, v121
	v_cvt_pk_bf16_f32 v149, v122, v123
	global_store_dwordx4 v138, v[146:149], s[8:9] nt
	v_pk_mul_f32 v[124:125], v[124:125], v[124:125]
	v_pk_fma_f32 v[124:125], v[126:127], v[126:127], v[124:125]
	v_pk_fma_f32 v[124:125], v[120:121], v[120:121], v[124:125]
	v_pk_fma_f32 v[124:125], v[122:123], v[122:123], v[124:125]
	s_waitcnt vmcnt(15)
	v_lshlrev_b32_e32 v158, 16, v150
	v_and_b32_e32 v159, 0xffff0000, v150
	v_pk_add_f32 v[116:117], v[116:117], v[158:159]
	v_lshlrev_b32_e32 v140, 16, v151
	v_and_b32_e32 v141, 0xffff0000, v151
	v_pk_add_f32 v[118:119], v[118:119], v[140:141]
	v_lshlrev_b32_e32 v158, 16, v152
	v_and_b32_e32 v159, 0xffff0000, v152
	v_pk_add_f32 v[112:113], v[112:113], v[158:159]
	v_lshlrev_b32_e32 v140, 16, v153
	v_and_b32_e32 v141, 0xffff0000, v153
	v_pk_add_f32 v[114:115], v[114:115], v[140:141]
	v_cvt_pk_bf16_f32 v150, v116, v117
	v_cvt_pk_bf16_f32 v151, v118, v119
	v_cvt_pk_bf16_f32 v152, v112, v113
	v_cvt_pk_bf16_f32 v153, v114, v115
	global_store_dwordx4 v138, v[150:153], s[8:9] offset:256 nt
	v_pk_fma_f32 v[124:125], v[116:117], v[116:117], v[124:125]
	v_pk_fma_f32 v[124:125], v[118:119], v[118:119], v[124:125]
	v_pk_fma_f32 v[124:125], v[112:113], v[112:113], v[124:125]
	v_pk_fma_f32 v[124:125], v[114:115], v[114:115], v[124:125]
	v_add_f32_e32 v124, v124, v125
	s_add_u32 s8, s8, 0x8000
	s_addc_u32 s9, s9, 0
	s_waitcnt vmcnt(15)
	v_lshlrev_b32_e32 v158, 16, v154
	v_and_b32_e32 v159, 0xffff0000, v154
	v_pk_add_f32 v[108:109], v[108:109], v[158:159]
	v_lshlrev_b32_e32 v140, 16, v155
	v_and_b32_e32 v141, 0xffff0000, v155
	v_pk_add_f32 v[110:111], v[110:111], v[140:141]
	v_lshlrev_b32_e32 v158, 16, v156
	v_and_b32_e32 v159, 0xffff0000, v156
	v_pk_add_f32 v[104:105], v[104:105], v[158:159]
	v_lshlrev_b32_e32 v140, 16, v157
	v_and_b32_e32 v141, 0xffff0000, v157
	v_pk_add_f32 v[106:107], v[106:107], v[140:141]
	v_cvt_pk_bf16_f32 v154, v108, v109
	v_cvt_pk_bf16_f32 v155, v110, v111
	v_cvt_pk_bf16_f32 v156, v104, v105
	v_cvt_pk_bf16_f32 v157, v106, v107
	global_store_dwordx4 v138, v[154:157], s[8:9] nt
	v_pk_mul_f32 v[108:109], v[108:109], v[108:109]
	v_pk_fma_f32 v[108:109], v[110:111], v[110:111], v[108:109]
	v_pk_fma_f32 v[108:109], v[104:105], v[104:105], v[108:109]
	v_pk_fma_f32 v[108:109], v[106:107], v[106:107], v[108:109]
	s_waitcnt vmcnt(15)
	v_lshlrev_b32_e32 v158, 16, v162
	v_and_b32_e32 v159, 0xffff0000, v162
	v_pk_add_f32 v[100:101], v[100:101], v[158:159]
	v_lshlrev_b32_e32 v140, 16, v163
	v_and_b32_e32 v141, 0xffff0000, v163
	v_pk_add_f32 v[102:103], v[102:103], v[140:141]
	v_lshlrev_b32_e32 v158, 16, v164
	v_and_b32_e32 v159, 0xffff0000, v164
	v_pk_add_f32 v[96:97], v[96:97], v[158:159]
	v_lshlrev_b32_e32 v140, 16, v165
	v_and_b32_e32 v141, 0xffff0000, v165
	v_pk_add_f32 v[98:99], v[98:99], v[140:141]
	v_cvt_pk_bf16_f32 v162, v100, v101
	v_cvt_pk_bf16_f32 v163, v102, v103
	v_cvt_pk_bf16_f32 v164, v96, v97
	v_cvt_pk_bf16_f32 v165, v98, v99
	global_store_dwordx4 v138, v[162:165], s[8:9] offset:256 nt
	v_pk_fma_f32 v[108:109], v[100:101], v[100:101], v[108:109]
	v_pk_fma_f32 v[108:109], v[102:103], v[102:103], v[108:109]
	v_pk_fma_f32 v[108:109], v[96:97], v[96:97], v[108:109]
	v_pk_fma_f32 v[108:109], v[98:99], v[98:99], v[108:109]
	v_add_f32_e32 v108, v108, v109
	s_add_u32 s8, s8, 0x8000
	s_addc_u32 s9, s9, 0
	s_waitcnt vmcnt(15)
	v_lshlrev_b32_e32 v158, 16, v166
	v_and_b32_e32 v159, 0xffff0000, v166
	v_pk_add_f32 v[92:93], v[92:93], v[158:159]
	v_lshlrev_b32_e32 v140, 16, v167
	v_and_b32_e32 v141, 0xffff0000, v167
	v_pk_add_f32 v[94:95], v[94:95], v[140:141]
	v_lshlrev_b32_e32 v158, 16, v168
	v_and_b32_e32 v159, 0xffff0000, v168
	v_pk_add_f32 v[88:89], v[88:89], v[158:159]
	v_lshlrev_b32_e32 v140, 16, v169
	v_and_b32_e32 v141, 0xffff0000, v169
	v_pk_add_f32 v[90:91], v[90:91], v[140:141]
	v_cvt_pk_bf16_f32 v166, v92, v93
	v_cvt_pk_bf16_f32 v167, v94, v95
	v_cvt_pk_bf16_f32 v168, v88, v89
	v_cvt_pk_bf16_f32 v169, v90, v91
	global_store_dwordx4 v138, v[166:169], s[8:9] nt
	v_pk_mul_f32 v[92:93], v[92:93], v[92:93]
	v_pk_fma_f32 v[92:93], v[94:95], v[94:95], v[92:93]
	v_pk_fma_f32 v[92:93], v[88:89], v[88:89], v[92:93]
	v_pk_fma_f32 v[92:93], v[90:91], v[90:91], v[92:93]
	s_waitcnt vmcnt(15)
	v_lshlrev_b32_e32 v158, 16, v174
	v_and_b32_e32 v159, 0xffff0000, v174
	v_pk_add_f32 v[84:85], v[84:85], v[158:159]
	v_lshlrev_b32_e32 v140, 16, v175
	v_and_b32_e32 v141, 0xffff0000, v175
	v_pk_add_f32 v[86:87], v[86:87], v[140:141]
	v_lshlrev_b32_e32 v158, 16, v176
	v_and_b32_e32 v159, 0xffff0000, v176
	v_pk_add_f32 v[80:81], v[80:81], v[158:159]
	v_lshlrev_b32_e32 v140, 16, v177
	v_and_b32_e32 v141, 0xffff0000, v177
	v_pk_add_f32 v[82:83], v[82:83], v[140:141]
	v_cvt_pk_bf16_f32 v174, v84, v85
	v_cvt_pk_bf16_f32 v175, v86, v87
	v_cvt_pk_bf16_f32 v176, v80, v81
	v_cvt_pk_bf16_f32 v177, v82, v83
	global_store_dwordx4 v138, v[174:177], s[8:9] offset:256 nt
	v_pk_fma_f32 v[92:93], v[84:85], v[84:85], v[92:93]
	v_pk_fma_f32 v[92:93], v[86:87], v[86:87], v[92:93]
	v_pk_fma_f32 v[92:93], v[80:81], v[80:81], v[92:93]
	v_pk_fma_f32 v[92:93], v[82:83], v[82:83], v[92:93]
	v_add_f32_e32 v92, v92, v93
	s_add_u32 s8, s8, 0x8000
	s_addc_u32 s9, s9, 0
	s_waitcnt vmcnt(15)
	v_lshlrev_b32_e32 v158, 16, v178
	v_and_b32_e32 v159, 0xffff0000, v178
	v_pk_add_f32 v[76:77], v[76:77], v[158:159]
	v_lshlrev_b32_e32 v140, 16, v179
	v_and_b32_e32 v141, 0xffff0000, v179
	v_pk_add_f32 v[78:79], v[78:79], v[140:141]
	v_lshlrev_b32_e32 v158, 16, v180
	v_and_b32_e32 v159, 0xffff0000, v180
	v_pk_add_f32 v[72:73], v[72:73], v[158:159]
	v_lshlrev_b32_e32 v140, 16, v181
	v_and_b32_e32 v141, 0xffff0000, v181
	v_pk_add_f32 v[74:75], v[74:75], v[140:141]
	v_cvt_pk_bf16_f32 v178, v76, v77
	v_cvt_pk_bf16_f32 v179, v78, v79
	v_cvt_pk_bf16_f32 v180, v72, v73
	v_cvt_pk_bf16_f32 v181, v74, v75
	global_store_dwordx4 v138, v[178:181], s[8:9] nt
	v_pk_mul_f32 v[76:77], v[76:77], v[76:77]
	v_pk_fma_f32 v[76:77], v[78:79], v[78:79], v[76:77]
	v_pk_fma_f32 v[76:77], v[72:73], v[72:73], v[76:77]
	v_pk_fma_f32 v[76:77], v[74:75], v[74:75], v[76:77]
	s_waitcnt vmcnt(15)
	v_lshlrev_b32_e32 v158, 16, v182
	v_and_b32_e32 v159, 0xffff0000, v182
	v_pk_add_f32 v[68:69], v[68:69], v[158:159]
	v_lshlrev_b32_e32 v140, 16, v183
	v_and_b32_e32 v141, 0xffff0000, v183
	v_pk_add_f32 v[70:71], v[70:71], v[140:141]
	v_lshlrev_b32_e32 v158, 16, v184
	v_and_b32_e32 v159, 0xffff0000, v184
	v_pk_add_f32 v[64:65], v[64:65], v[158:159]
	v_lshlrev_b32_e32 v140, 16, v185
	v_and_b32_e32 v141, 0xffff0000, v185
	v_pk_add_f32 v[66:67], v[66:67], v[140:141]
	v_cvt_pk_bf16_f32 v182, v68, v69
	v_cvt_pk_bf16_f32 v183, v70, v71
	v_cvt_pk_bf16_f32 v184, v64, v65
	v_cvt_pk_bf16_f32 v185, v66, v67
	global_store_dwordx4 v138, v[182:185], s[8:9] offset:256 nt
	v_pk_fma_f32 v[76:77], v[68:69], v[68:69], v[76:77]
	v_pk_fma_f32 v[76:77], v[70:71], v[70:71], v[76:77]
	v_pk_fma_f32 v[76:77], v[64:65], v[64:65], v[76:77]
	v_pk_fma_f32 v[76:77], v[66:67], v[66:67], v[76:77]
	v_add_f32_e32 v76, v76, v77
	s_add_u32 s8, s8, 0x28000
	s_addc_u32 s9, s9, 0
	s_waitcnt vmcnt(15)
	v_lshlrev_b32_e32 v158, 16, v186
	v_and_b32_e32 v159, 0xffff0000, v186
	v_pk_add_f32 v[60:61], v[60:61], v[158:159]
	v_lshlrev_b32_e32 v140, 16, v187
	v_and_b32_e32 v141, 0xffff0000, v187
	v_pk_add_f32 v[62:63], v[62:63], v[140:141]
	v_lshlrev_b32_e32 v158, 16, v188
	v_and_b32_e32 v159, 0xffff0000, v188
	v_pk_add_f32 v[56:57], v[56:57], v[158:159]
	v_lshlrev_b32_e32 v140, 16, v189
	v_and_b32_e32 v141, 0xffff0000, v189
	v_pk_add_f32 v[58:59], v[58:59], v[140:141]
	v_cvt_pk_bf16_f32 v186, v60, v61
	v_cvt_pk_bf16_f32 v187, v62, v63
	v_cvt_pk_bf16_f32 v188, v56, v57
	v_cvt_pk_bf16_f32 v189, v58, v59
	global_store_dwordx4 v138, v[186:189], s[8:9] nt
	v_pk_mul_f32 v[60:61], v[60:61], v[60:61]
	v_pk_fma_f32 v[60:61], v[62:63], v[62:63], v[60:61]
	v_pk_fma_f32 v[60:61], v[56:57], v[56:57], v[60:61]
	v_pk_fma_f32 v[60:61], v[58:59], v[58:59], v[60:61]
	s_waitcnt vmcnt(15)
	v_lshlrev_b32_e32 v158, 16, v190
	v_and_b32_e32 v159, 0xffff0000, v190
	v_pk_add_f32 v[52:53], v[52:53], v[158:159]
	v_lshlrev_b32_e32 v140, 16, v191
	v_and_b32_e32 v141, 0xffff0000, v191
	v_pk_add_f32 v[54:55], v[54:55], v[140:141]
	v_lshlrev_b32_e32 v158, 16, v192
	v_and_b32_e32 v159, 0xffff0000, v192
	v_pk_add_f32 v[48:49], v[48:49], v[158:159]
	v_lshlrev_b32_e32 v140, 16, v193
	v_and_b32_e32 v141, 0xffff0000, v193
	v_pk_add_f32 v[50:51], v[50:51], v[140:141]
	v_cvt_pk_bf16_f32 v190, v52, v53
	v_cvt_pk_bf16_f32 v191, v54, v55
	v_cvt_pk_bf16_f32 v192, v48, v49
	v_cvt_pk_bf16_f32 v193, v50, v51
	global_store_dwordx4 v138, v[190:193], s[8:9] offset:256 nt
	v_pk_fma_f32 v[60:61], v[52:53], v[52:53], v[60:61]
	v_pk_fma_f32 v[60:61], v[54:55], v[54:55], v[60:61]
	v_pk_fma_f32 v[60:61], v[48:49], v[48:49], v[60:61]
	v_pk_fma_f32 v[60:61], v[50:51], v[50:51], v[60:61]
	v_add_f32_e32 v60, v60, v61
	s_add_u32 s8, s8, 0x8000
	s_addc_u32 s9, s9, 0
	s_waitcnt vmcnt(15)
	v_lshlrev_b32_e32 v158, 16, v194
	v_and_b32_e32 v159, 0xffff0000, v194
	v_pk_add_f32 v[44:45], v[44:45], v[158:159]
	v_lshlrev_b32_e32 v140, 16, v195
	v_and_b32_e32 v141, 0xffff0000, v195
	v_pk_add_f32 v[46:47], v[46:47], v[140:141]
	v_lshlrev_b32_e32 v158, 16, v196
	v_and_b32_e32 v159, 0xffff0000, v196
	v_pk_add_f32 v[40:41], v[40:41], v[158:159]
	v_lshlrev_b32_e32 v140, 16, v197
	v_and_b32_e32 v141, 0xffff0000, v197
	v_pk_add_f32 v[42:43], v[42:43], v[140:141]
	v_cvt_pk_bf16_f32 v194, v44, v45
	v_cvt_pk_bf16_f32 v195, v46, v47
	v_cvt_pk_bf16_f32 v196, v40, v41
	v_cvt_pk_bf16_f32 v197, v42, v43
	global_store_dwordx4 v138, v[194:197], s[8:9] nt
	v_pk_mul_f32 v[44:45], v[44:45], v[44:45]
	v_pk_fma_f32 v[44:45], v[46:47], v[46:47], v[44:45]
	v_pk_fma_f32 v[44:45], v[40:41], v[40:41], v[44:45]
	v_pk_fma_f32 v[44:45], v[42:43], v[42:43], v[44:45]
	s_waitcnt vmcnt(15)
	v_lshlrev_b32_e32 v158, 16, v198
	v_and_b32_e32 v159, 0xffff0000, v198
	v_pk_add_f32 v[36:37], v[36:37], v[158:159]
	v_lshlrev_b32_e32 v140, 16, v199
	v_and_b32_e32 v141, 0xffff0000, v199
	v_pk_add_f32 v[38:39], v[38:39], v[140:141]
	v_lshlrev_b32_e32 v158, 16, v200
	v_and_b32_e32 v159, 0xffff0000, v200
	v_pk_add_f32 v[32:33], v[32:33], v[158:159]
	v_lshlrev_b32_e32 v140, 16, v201
	v_and_b32_e32 v141, 0xffff0000, v201
	v_pk_add_f32 v[34:35], v[34:35], v[140:141]
	v_cvt_pk_bf16_f32 v198, v36, v37
	v_cvt_pk_bf16_f32 v199, v38, v39
	v_cvt_pk_bf16_f32 v200, v32, v33
	v_cvt_pk_bf16_f32 v201, v34, v35
	global_store_dwordx4 v138, v[198:201], s[8:9] offset:256 nt
	v_pk_fma_f32 v[44:45], v[36:37], v[36:37], v[44:45]
	v_pk_fma_f32 v[44:45], v[38:39], v[38:39], v[44:45]
	v_pk_fma_f32 v[44:45], v[32:33], v[32:33], v[44:45]
	v_pk_fma_f32 v[44:45], v[34:35], v[34:35], v[44:45]
	v_add_f32_e32 v44, v44, v45
	s_add_u32 s8, s8, 0x8000
	s_addc_u32 s9, s9, 0
	s_waitcnt vmcnt(15)
	v_lshlrev_b32_e32 v158, 16, v202
	v_and_b32_e32 v159, 0xffff0000, v202
	v_pk_add_f32 v[28:29], v[28:29], v[158:159]
	v_lshlrev_b32_e32 v140, 16, v203
	v_and_b32_e32 v141, 0xffff0000, v203
	v_pk_add_f32 v[30:31], v[30:31], v[140:141]
	v_lshlrev_b32_e32 v158, 16, v204
	v_and_b32_e32 v159, 0xffff0000, v204
	v_pk_add_f32 v[24:25], v[24:25], v[158:159]
	v_lshlrev_b32_e32 v140, 16, v205
	v_and_b32_e32 v141, 0xffff0000, v205
	v_pk_add_f32 v[26:27], v[26:27], v[140:141]
	v_cvt_pk_bf16_f32 v202, v28, v29
	v_cvt_pk_bf16_f32 v203, v30, v31
	v_cvt_pk_bf16_f32 v204, v24, v25
	v_cvt_pk_bf16_f32 v205, v26, v27
	global_store_dwordx4 v138, v[202:205], s[8:9] nt
	v_pk_mul_f32 v[28:29], v[28:29], v[28:29]
	v_pk_fma_f32 v[28:29], v[30:31], v[30:31], v[28:29]
	v_pk_fma_f32 v[28:29], v[24:25], v[24:25], v[28:29]
	v_pk_fma_f32 v[28:29], v[26:27], v[26:27], v[28:29]
	s_waitcnt vmcnt(15)
	v_lshlrev_b32_e32 v158, 16, v206
	v_and_b32_e32 v159, 0xffff0000, v206
	v_pk_add_f32 v[20:21], v[20:21], v[158:159]
	v_lshlrev_b32_e32 v140, 16, v207
	v_and_b32_e32 v141, 0xffff0000, v207
	v_pk_add_f32 v[22:23], v[22:23], v[140:141]
	v_lshlrev_b32_e32 v158, 16, v208
	v_and_b32_e32 v159, 0xffff0000, v208
	v_pk_add_f32 v[16:17], v[16:17], v[158:159]
	v_lshlrev_b32_e32 v140, 16, v209
	v_and_b32_e32 v141, 0xffff0000, v209
	v_pk_add_f32 v[18:19], v[18:19], v[140:141]
	v_cvt_pk_bf16_f32 v206, v20, v21
	v_cvt_pk_bf16_f32 v207, v22, v23
	v_cvt_pk_bf16_f32 v208, v16, v17
	v_cvt_pk_bf16_f32 v209, v18, v19
	global_store_dwordx4 v138, v[206:209], s[8:9] offset:256 nt
	v_pk_fma_f32 v[28:29], v[20:21], v[20:21], v[28:29]
	v_pk_fma_f32 v[28:29], v[22:23], v[22:23], v[28:29]
	v_pk_fma_f32 v[28:29], v[16:17], v[16:17], v[28:29]
	v_pk_fma_f32 v[28:29], v[18:19], v[18:19], v[28:29]
	v_add_f32_e32 v28, v28, v29
	s_add_u32 s8, s8, 0x8000
	s_addc_u32 s9, s9, 0
	s_waitcnt vmcnt(15)
	v_lshlrev_b32_e32 v158, 16, v210
	v_and_b32_e32 v159, 0xffff0000, v210
	v_pk_add_f32 v[12:13], v[12:13], v[158:159]
	v_lshlrev_b32_e32 v140, 16, v211
	v_and_b32_e32 v141, 0xffff0000, v211
	v_pk_add_f32 v[14:15], v[14:15], v[140:141]
	v_lshlrev_b32_e32 v158, 16, v212
	v_and_b32_e32 v159, 0xffff0000, v212
	v_pk_add_f32 v[8:9], v[8:9], v[158:159]
	v_lshlrev_b32_e32 v140, 16, v213
	v_and_b32_e32 v141, 0xffff0000, v213
	v_pk_add_f32 v[10:11], v[10:11], v[140:141]
	v_cvt_pk_bf16_f32 v210, v12, v13
	v_cvt_pk_bf16_f32 v211, v14, v15
	v_cvt_pk_bf16_f32 v212, v8, v9
	v_cvt_pk_bf16_f32 v213, v10, v11
	global_store_dwordx4 v138, v[210:213], s[8:9] nt
	v_pk_mul_f32 v[12:13], v[12:13], v[12:13]
	v_pk_fma_f32 v[12:13], v[14:15], v[14:15], v[12:13]
	v_pk_fma_f32 v[12:13], v[8:9], v[8:9], v[12:13]
	v_pk_fma_f32 v[12:13], v[10:11], v[10:11], v[12:13]
	s_waitcnt vmcnt(15)
	v_lshlrev_b32_e32 v158, 16, v214
	v_and_b32_e32 v159, 0xffff0000, v214
	v_pk_add_f32 v[4:5], v[4:5], v[158:159]
	v_lshlrev_b32_e32 v140, 16, v215
	v_and_b32_e32 v141, 0xffff0000, v215
	v_pk_add_f32 v[6:7], v[6:7], v[140:141]
	v_lshlrev_b32_e32 v158, 16, v216
	v_and_b32_e32 v159, 0xffff0000, v216
	v_pk_add_f32 v[0:1], v[0:1], v[158:159]
	v_lshlrev_b32_e32 v140, 16, v217
	v_and_b32_e32 v141, 0xffff0000, v217
	v_pk_add_f32 v[2:3], v[2:3], v[140:141]
	v_cvt_pk_bf16_f32 v214, v4, v5
	v_cvt_pk_bf16_f32 v215, v6, v7
	v_cvt_pk_bf16_f32 v216, v0, v1
	v_cvt_pk_bf16_f32 v217, v2, v3
	global_store_dwordx4 v138, v[214:217], s[8:9] offset:256 nt
	v_pk_fma_f32 v[12:13], v[4:5], v[4:5], v[12:13]
	v_pk_fma_f32 v[12:13], v[6:7], v[6:7], v[12:13]
	v_pk_fma_f32 v[12:13], v[0:1], v[0:1], v[12:13]
	v_pk_fma_f32 v[12:13], v[2:3], v[2:3], v[12:13]
	v_add_f32_e32 v12, v12, v13
	v_xor_b32_e32 v158, 16, v223
	v_xor_b32_e32 v159, 32, v223
	v_lshlrev_b32_e32 v158, 2, v158
	v_lshlrev_b32_e32 v159, 2, v159
	ds_bpermute_b32 v146, v158, v124
	ds_bpermute_b32 v148, v158, v108
	ds_bpermute_b32 v150, v158, v92
	ds_bpermute_b32 v152, v158, v76
	ds_bpermute_b32 v154, v158, v60
	ds_bpermute_b32 v156, v158, v44
	ds_bpermute_b32 v162, v158, v28
	ds_bpermute_b32 v164, v158, v12
	s_waitcnt lgkmcnt(7)
	v_add_f32_e32 v124, v124, v146
	s_waitcnt lgkmcnt(6)
	v_add_f32_e32 v108, v108, v148
	s_waitcnt lgkmcnt(5)
	v_add_f32_e32 v92, v92, v150
	s_waitcnt lgkmcnt(4)
	v_add_f32_e32 v76, v76, v152
	s_waitcnt lgkmcnt(3)
	v_add_f32_e32 v60, v60, v154
	s_waitcnt lgkmcnt(2)
	v_add_f32_e32 v44, v44, v156
	s_waitcnt lgkmcnt(1)
	v_add_f32_e32 v28, v28, v162
	s_waitcnt lgkmcnt(0)
	v_add_f32_e32 v12, v12, v164
	ds_bpermute_b32 v146, v159, v124
	ds_bpermute_b32 v148, v159, v108
	ds_bpermute_b32 v150, v159, v92
	ds_bpermute_b32 v152, v159, v76
	ds_bpermute_b32 v154, v159, v60
	ds_bpermute_b32 v156, v159, v44
	ds_bpermute_b32 v162, v159, v28
	ds_bpermute_b32 v164, v159, v12
	s_and_saveexec_b64 s[8:9], s[38:39]
	s_waitcnt lgkmcnt(7)
	v_add_f32_e32 v146, v124, v146
	v_fma_f32 v146, v146, s17, 0.5
	v_trunc_f32_e32 v146, v146
	v_mul_f32_e32 v147, 0x2f800000, v146
	v_floor_f32_e32 v147, v147
	v_fmac_f32_e32 v146, 0xcf800000, v147
	v_cvt_u32_f32_e32 v146, v146
	v_cvt_u32_f32_e32 v147, v147
	global_atomic_add_x2 v139, v[146:147], s[4:5]
	s_waitcnt lgkmcnt(6)
	v_add_f32_e32 v148, v108, v148
	v_fma_f32 v148, v148, s17, 0.5
	v_trunc_f32_e32 v148, v148
	v_mul_f32_e32 v149, 0x2f800000, v148
	v_floor_f32_e32 v149, v149
	v_fmac_f32_e32 v148, 0xcf800000, v149
	v_cvt_u32_f32_e32 v148, v148
	v_cvt_u32_f32_e32 v149, v149
	global_atomic_add_x2 v139, v[148:149], s[4:5] offset:128
	s_waitcnt lgkmcnt(5)
	v_add_f32_e32 v150, v92, v150
	v_fma_f32 v150, v150, s17, 0.5
	v_trunc_f32_e32 v150, v150
	v_mul_f32_e32 v151, 0x2f800000, v150
	v_floor_f32_e32 v151, v151
	v_fmac_f32_e32 v150, 0xcf800000, v151
	v_cvt_u32_f32_e32 v150, v150
	v_cvt_u32_f32_e32 v151, v151
	global_atomic_add_x2 v139, v[150:151], s[4:5] offset:256
	s_waitcnt lgkmcnt(4)
	v_add_f32_e32 v152, v76, v152
	v_fma_f32 v152, v152, s17, 0.5
	v_trunc_f32_e32 v152, v152
	v_mul_f32_e32 v153, 0x2f800000, v152
	v_floor_f32_e32 v153, v153
	v_fmac_f32_e32 v152, 0xcf800000, v153
	v_cvt_u32_f32_e32 v152, v152
	v_cvt_u32_f32_e32 v153, v153
	global_atomic_add_x2 v139, v[152:153], s[4:5] offset:384
	s_waitcnt lgkmcnt(3)
	v_add_f32_e32 v154, v60, v154
	v_fma_f32 v154, v154, s17, 0.5
	v_trunc_f32_e32 v154, v154
	v_mul_f32_e32 v155, 0x2f800000, v154
	v_floor_f32_e32 v155, v155
	v_fmac_f32_e32 v154, 0xcf800000, v155
	v_cvt_u32_f32_e32 v154, v154
	v_cvt_u32_f32_e32 v155, v155
	global_atomic_add_x2 v139, v[154:155], s[4:5] offset:1024
	s_waitcnt lgkmcnt(2)
	v_add_f32_e32 v156, v44, v156
	v_fma_f32 v156, v156, s17, 0.5
	v_trunc_f32_e32 v156, v156
	v_mul_f32_e32 v157, 0x2f800000, v156
	v_floor_f32_e32 v157, v157
	v_fmac_f32_e32 v156, 0xcf800000, v157
	v_cvt_u32_f32_e32 v156, v156
	v_cvt_u32_f32_e32 v157, v157
	global_atomic_add_x2 v139, v[156:157], s[4:5] offset:1152
	s_waitcnt lgkmcnt(1)
	v_add_f32_e32 v162, v28, v162
	v_fma_f32 v162, v162, s17, 0.5
	v_trunc_f32_e32 v162, v162
	v_mul_f32_e32 v163, 0x2f800000, v162
	v_floor_f32_e32 v163, v163
	v_fmac_f32_e32 v162, 0xcf800000, v163
	v_cvt_u32_f32_e32 v162, v162
	v_cvt_u32_f32_e32 v163, v163
	global_atomic_add_x2 v139, v[162:163], s[4:5] offset:1280
	s_waitcnt lgkmcnt(0)
	v_add_f32_e32 v164, v12, v164
	v_fma_f32 v164, v164, s17, 0.5
	v_trunc_f32_e32 v164, v164
	v_mul_f32_e32 v165, 0x2f800000, v164
	v_floor_f32_e32 v165, v165
	v_fmac_f32_e32 v164, 0xcf800000, v165
	v_cvt_u32_f32_e32 v164, v164
	v_cvt_u32_f32_e32 v165, v165
	global_atomic_add_x2 v139, v[164:165], s[4:5] offset:1408
	s_mov_b64 exec, s[8:9]
	v_mov_b64_e32 v[172:173], v[244:245]
	s_andn2_b64 vcc, exec, s[40:41]
	s_mov_b64 s[8:9], -1
	s_cbranch_vccnz .LBB0_76
	s_andn2_b64 vcc, exec, s[0:1]
	s_cbranch_vccnz .LBB0_75
	s_barrier
	s_branch .LBB0_75

.LBB0_111:
	s_or_b64 exec, exec, s[6:7]
	s_waitcnt lgkmcnt(0)
	v_lshlrev_b32_e32 v131, 2, v138
	s_waitcnt lgkmcnt(0)
	global_load_dword v133, v131, s[84:85]
	global_load_dword v132, v131, s[84:85] offset:128
	global_load_dword v130, v131, s[84:85] offset:256
	v_lshrrev_b32_e32 v134, 3, v129
	global_load_dword v131, v131, s[84:85] offset:384
	v_and_b32_e32 v148, 4, v134
	v_lshl_add_u32 v137, v148, 2, s91
	ds_read_b128 v[140:143], v137 offset:128
	ds_read_b128 v[144:147], v137
	v_xor_b32_e32 v136, 4, v139
	v_xor_b32_e32 v135, 8, v139
	v_xor_b32_e32 v134, 16, v139
	s_waitcnt lgkmcnt(1)
	v_rcp_f32_e32 v140, v140
	v_rcp_f32_e32 v141, v141
	s_waitcnt lgkmcnt(0)
	v_rcp_f32_e32 v144, v144
	v_rcp_f32_e32 v145, v145
	v_mul_f32_e32 v140, v237, v140
	v_mul_f32_e32 v141, v237, v141
	v_mul_f32_e32 v32, v32, v140
	v_mul_f32_e32 v0, v0, v140
	v_mul_f32_e32 v48, v48, v140
	v_mul_f32_e32 v16, v16, v140
	v_mul_f32_e32 v33, v33, v141
	v_fma_f32 v96, v96, v144, -v32
	v_fma_f32 v0, v64, v144, -v0
	v_fma_f32 v112, v112, v144, -v48
	v_fma_f32 v16, v80, v144, -v16
	v_fma_f32 v80, v97, v145, -v33
	v_mul_f32_e32 v32, v96, v96
	v_mul_f32_e32 v33, v0, v0
	v_fmac_f32_e32 v32, v112, v112
	v_fmac_f32_e32 v33, v16, v16
	v_add_f32_e32 v32, v32, v33
	ds_bpermute_b32 v33, v136, v32
	v_mul_f32_e32 v1, v1, v141
	v_mul_f32_e32 v49, v49, v141
	v_mul_f32_e32 v17, v17, v141
	v_fma_f32 v1, v65, v145, -v1
	s_waitcnt lgkmcnt(0)
	v_add_f32_e32 v32, v32, v33
	ds_bpermute_b32 v33, v135, v32
	v_fma_f32 v49, v113, v145, -v49
	v_fma_f32 v17, v81, v145, -v17
	v_mul_f32_e32 v48, v80, v80
	v_mul_f32_e32 v64, v1, v1
	v_fmac_f32_e32 v48, v49, v49
	v_fmac_f32_e32 v64, v17, v17
	v_add_f32_e32 v64, v48, v64
	ds_bpermute_b32 v65, v136, v64
	s_waitcnt lgkmcnt(1)
	v_add_f32_e32 v32, v32, v33
	ds_bpermute_b32 v33, v134, v32
	v_xor_b32_e32 v48, 32, v139
	v_lshlrev_b32_e32 v97, 1, v138
	s_waitcnt lgkmcnt(1)
	v_add_f32_e32 v64, v64, v65
	ds_bpermute_b32 v65, v135, v64
	s_waitcnt lgkmcnt(1)
	v_add_f32_e32 v32, v32, v33
	ds_bpermute_b32 v81, v48, v32
	v_xor_b32_e32 v33, 64, v139
	v_mul_u32_u24_e32 v113, 0x110, v148
	s_waitcnt lgkmcnt(1)
	v_add_f32_e32 v64, v64, v65
	ds_bpermute_b32 v65, v134, v64
	s_waitcnt lgkmcnt(1)
	v_add_f32_e32 v32, v32, v81
	ds_bpermute_b32 v81, v33, v32
	s_add_i32 s26, s26, 1
	s_cmp_eq_u32 s26, 4
	s_waitcnt lgkmcnt(1)
	v_add_f32_e32 v64, v64, v65
	ds_bpermute_b32 v65, v48, v64
	s_waitcnt lgkmcnt(1)
	v_add_f32_e32 v32, v32, v81
	v_fmamk_f32 v32, v32, 0x3c000000, v219
	v_rsq_f32_e32 v81, v32
	v_add3_u32 v32, s28, v97, v113
	s_waitcnt lgkmcnt(0)
	v_add_f32_e32 v64, v64, v65
	ds_bpermute_b32 v65, v33, v64
	v_mul_f32_e32 v81, 0x3f24fd5c, v81
	v_mul_f32_e32 v97, v112, v81
	v_mul_f32_e32 v16, v16, v81
	v_mul_f32_e32 v96, v96, v81
	v_mul_f32_e32 v0, v0, v81
	s_waitcnt vmcnt(3)
	v_mul_f32_e32 v97, v133, v97
	s_waitcnt vmcnt(2)
	v_mul_f32_e32 v96, v132, v96
	s_waitcnt vmcnt(1)
	v_mul_f32_e32 v16, v130, v16
	v_cvt_pk_bf16_f32 v97, v97, s0
	v_cvt_pk_bf16_f32 v16, v16, s0
	v_cvt_pk_bf16_f32 v96, v96, s0
	ds_write_b16 v32, v97
	ds_write_b16 v32, v96 offset:64
	ds_write_b16 v32, v16 offset:128
	s_waitcnt vmcnt(0)
	v_mul_f32_e32 v0, v131, v0
	s_waitcnt lgkmcnt(3)
	v_add_f32_e32 v16, v64, v65
	v_rcp_f32_e32 v64, v142
	v_cvt_pk_bf16_f32 v0, v0, s0
	ds_write_b16 v32, v0 offset:192
	v_rcp_f32_e32 v0, v146
	v_mul_f32_e32 v64, v237, v64
	v_mul_f32_e32 v34, v34, v64
	v_mul_f32_e32 v2, v2, v64
	v_mul_f32_e32 v50, v50, v64
	v_fma_f32 v81, v98, v0, -v34
	v_mul_f32_e32 v18, v18, v64
	v_fma_f32 v64, v66, v0, -v2
	v_fma_f32 v65, v114, v0, -v50
	v_fma_f32 v18, v82, v0, -v18
	v_mul_f32_e32 v0, v81, v81
	v_mul_f32_e32 v2, v64, v64
	v_fmac_f32_e32 v0, v65, v65
	v_fmac_f32_e32 v2, v18, v18
	v_add_f32_e32 v0, v0, v2
	ds_bpermute_b32 v2, v136, v0
	v_fmamk_f32 v16, v16, 0x3c000000, v219
	v_rsq_f32_e32 v16, v16
	s_waitcnt lgkmcnt(0)
	v_add_f32_e32 v0, v0, v2
	ds_bpermute_b32 v2, v135, v0
	v_mul_f32_e32 v16, 0x3f24fd5c, v16
	v_mul_f32_e32 v34, v49, v16
	v_mul_f32_e32 v34, v133, v34
	v_cvt_pk_bf16_f32 v34, v34, s0
	s_waitcnt lgkmcnt(0)
	v_add_f32_e32 v0, v0, v2
	ds_bpermute_b32 v2, v134, v0
	ds_write_b16 v32, v34 offset:272
	v_mul_f32_e32 v34, v80, v16
	v_mul_f32_e32 v17, v17, v16
	v_mul_f32_e32 v1, v1, v16
	s_waitcnt lgkmcnt(1)
	v_add_f32_e32 v0, v0, v2
	ds_bpermute_b32 v2, v48, v0
	v_rcp_f32_e32 v16, v143
	v_mul_f32_e32 v34, v132, v34
	v_cvt_pk_bf16_f32 v34, v34, s0
	ds_write_b16 v32, v34 offset:336
	s_waitcnt lgkmcnt(1)
	v_add_f32_e32 v0, v0, v2
	v_rcp_f32_e32 v2, v147
	v_mul_f32_e32 v16, v237, v16
	v_mul_f32_e32 v34, v51, v16
	v_mul_f32_e32 v3, v3, v16
	v_fma_f32 v50, v115, v2, -v34
	v_mul_f32_e32 v34, v35, v16
	v_fma_f32 v49, v99, v2, -v34
	v_mul_f32_e32 v19, v19, v16
	v_fma_f32 v34, v67, v2, -v3
	v_fma_f32 v35, v83, v2, -v19
	v_mul_f32_e32 v2, v49, v49
	v_mul_f32_e32 v3, v34, v34
	v_fmac_f32_e32 v2, v50, v50
	v_fmac_f32_e32 v3, v35, v35
	v_add_f32_e32 v2, v2, v3
	ds_bpermute_b32 v3, v136, v2
	v_mul_f32_e32 v17, v130, v17
	v_cvt_pk_bf16_f32 v17, v17, s0
	ds_write_b16 v32, v17 offset:400
	v_mul_f32_e32 v1, v131, v1
	ds_bpermute_b32 v17, v33, v0
	v_cvt_pk_bf16_f32 v1, v1, s0
	ds_write_b16 v32, v1 offset:464
	s_waitcnt lgkmcnt(3)
	v_add_f32_e32 v1, v2, v3
	ds_bpermute_b32 v2, v135, v1
	s_waitcnt lgkmcnt(2)
	v_add_f32_e32 v0, v0, v17
	v_fmamk_f32 v0, v0, 0x3c000000, v219
	v_rsq_f32_e32 v0, v0
	s_waitcnt lgkmcnt(0)
	v_add_f32_e32 v1, v1, v2
	ds_bpermute_b32 v2, v134, v1
	v_mul_f32_e32 v51, 0x3f24fd5c, v0
	v_mul_f32_e32 v0, v65, v51
	v_mul_f32_e32 v0, v133, v0
	v_cvt_pk_bf16_f32 v0, v0, s0
	s_waitcnt lgkmcnt(0)
	v_add_f32_e32 v1, v1, v2
	ds_write_b16 v32, v0 offset:544
	v_mul_f32_e32 v0, v81, v51
	ds_bpermute_b32 v2, v48, v1
	v_mul_f32_e32 v0, v132, v0
	v_cvt_pk_bf16_f32 v0, v0, s0
	ds_write_b16 v32, v0 offset:608
	v_mul_f32_e32 v0, v18, v51
	v_mul_f32_e32 v0, v130, v0
	v_cvt_pk_bf16_f32 v16, v0, s0
	s_waitcnt lgkmcnt(1)
	v_add_f32_e32 v65, v1, v2
	ds_read_b128 v[0:3], v137 offset:160
	ds_write_b16 v32, v16 offset:672
	ds_read_b128 v[16:19], v137 offset:32
	ds_bpermute_b32 v66, v33, v65
	v_mul_f32_e32 v51, v64, v51
	s_waitcnt lgkmcnt(3)
	v_rcp_f32_e32 v0, v0
	v_mul_f32_e32 v51, v131, v51
	s_waitcnt lgkmcnt(1)
	v_rcp_f32_e32 v16, v16
	s_waitcnt lgkmcnt(0)
	v_add_f32_e32 v64, v65, v66
	v_mul_f32_e32 v0, v237, v0
	v_mul_f32_e32 v52, v52, v0
	v_mul_f32_e32 v36, v36, v0
	v_mul_f32_e32 v20, v20, v0
	v_mul_f32_e32 v0, v4, v0
	v_fma_f32 v36, v100, v16, -v36
	v_fma_f32 v0, v68, v16, -v0
	v_fma_f32 v52, v116, v16, -v52
	v_fma_f32 v20, v84, v16, -v20
	v_mul_f32_e32 v4, v36, v36
	v_mul_f32_e32 v16, v0, v0
	v_fmac_f32_e32 v4, v52, v52
	v_fmac_f32_e32 v16, v20, v20
	v_add_f32_e32 v4, v4, v16
	ds_bpermute_b32 v16, v136, v4
	v_fmamk_f32 v64, v64, 0x3c000000, v219
	v_rsq_f32_e32 v64, v64
	v_cvt_pk_bf16_f32 v51, v51, s0
	v_rcp_f32_e32 v1, v1
	s_waitcnt lgkmcnt(0)
	v_add_f32_e32 v4, v4, v16
	ds_bpermute_b32 v16, v135, v4
	ds_write_b16 v32, v51 offset:736
	v_mul_f32_e32 v51, 0x3f24fd5c, v64
	v_mul_f32_e32 v34, v34, v51
	v_mul_f32_e32 v34, v131, v34
	s_waitcnt lgkmcnt(1)
	v_add_f32_e32 v4, v4, v16
	ds_bpermute_b32 v16, v134, v4
	v_cvt_pk_bf16_f32 v34, v34, s0
	v_mul_f32_e32 v1, v237, v1
	ds_write_b16 v32, v34 offset:1008
	v_mul_f32_e32 v34, v37, v1
	s_waitcnt lgkmcnt(1)
	v_add_f32_e32 v4, v4, v16
	ds_bpermute_b32 v16, v48, v4
	v_mul_f32_e32 v21, v21, v1
	v_mul_f32_e32 v35, v35, v51
	v_mul_f32_e32 v35, v130, v35
	v_cvt_pk_bf16_f32 v35, v35, s0
	s_waitcnt lgkmcnt(0)
	v_add_f32_e32 v4, v4, v16
	ds_bpermute_b32 v16, v33, v4
	ds_write_b16 v32, v35 offset:944
	v_rcp_f32_e32 v2, v2
	v_mul_f32_e32 v50, v50, v51
	v_mul_f32_e32 v49, v49, v51
	s_waitcnt lgkmcnt(1)
	v_add_f32_e32 v4, v4, v16
	v_rcp_f32_e32 v16, v17
	v_mul_f32_e32 v17, v53, v1
	v_mul_f32_e32 v1, v5, v1
	v_fmamk_f32 v4, v4, 0x3c000000, v219
	v_fma_f32 v34, v101, v16, -v34
	v_fma_f32 v1, v69, v16, -v1
	v_fma_f32 v17, v117, v16, -v17
	v_fma_f32 v21, v85, v16, -v21
	v_mul_f32_e32 v5, v34, v34
	v_mul_f32_e32 v16, v1, v1
	v_fmac_f32_e32 v5, v17, v17
	v_fmac_f32_e32 v16, v21, v21
	v_add_f32_e32 v5, v5, v16
	ds_bpermute_b32 v16, v136, v5
	v_rsq_f32_e32 v4, v4
	v_mul_f32_e32 v2, v237, v2
	v_mul_f32_e32 v22, v22, v2
	v_mul_f32_e32 v50, v133, v50
	s_waitcnt lgkmcnt(0)
	v_add_f32_e32 v5, v5, v16
	ds_bpermute_b32 v16, v135, v5
	v_mul_f32_e32 v4, 0x3f24fd5c, v4
	v_mul_f32_e32 v35, v52, v4
	v_mul_f32_e32 v35, v133, v35
	v_cvt_pk_bf16_f32 v35, v35, s0
	s_waitcnt lgkmcnt(0)
	v_add_f32_e32 v5, v5, v16
	ds_bpermute_b32 v16, v134, v5
	ds_write_b16 v32, v35 offset:2176
	v_mul_f32_e32 v35, v36, v4
	v_mul_f32_e32 v20, v20, v4
	v_mul_f32_e32 v0, v0, v4
	s_waitcnt lgkmcnt(1)
	v_add_f32_e32 v5, v5, v16
	ds_bpermute_b32 v16, v48, v5
	v_mul_f32_e32 v20, v130, v20
	v_cvt_pk_bf16_f32 v20, v20, s0
	ds_write_b16 v32, v20 offset:2304
	v_mul_f32_e32 v20, v38, v2
	s_waitcnt lgkmcnt(1)
	v_add_f32_e32 v4, v5, v16
	v_rcp_f32_e32 v5, v18
	v_mul_f32_e32 v18, v54, v2
	v_mul_f32_e32 v2, v6, v2
	ds_bpermute_b32 v16, v33, v4
	v_fma_f32 v20, v102, v5, -v20
	v_fma_f32 v2, v70, v5, -v2
	v_fma_f32 v18, v118, v5, -v18
	v_fma_f32 v22, v86, v5, -v22
	v_mul_f32_e32 v5, v20, v20
	v_mul_f32_e32 v6, v2, v2
	v_fmac_f32_e32 v5, v18, v18
	v_fmac_f32_e32 v6, v22, v22
	v_add_f32_e32 v5, v5, v6
	ds_bpermute_b32 v6, v136, v5
	s_waitcnt lgkmcnt(1)
	v_add_f32_e32 v4, v4, v16
	v_fmamk_f32 v4, v4, 0x3c000000, v219
	v_rsq_f32_e32 v4, v4
	v_mul_f32_e32 v0, v131, v0
	s_waitcnt lgkmcnt(0)
	v_add_f32_e32 v5, v5, v6
	ds_bpermute_b32 v6, v135, v5
	v_cvt_pk_bf16_f32 v0, v0, s0
	ds_write_b16 v32, v0 offset:2368
	v_mul_f32_e32 v0, 0x3f24fd5c, v4
	v_mul_f32_e32 v4, v17, v0
	s_waitcnt lgkmcnt(1)
	v_add_f32_e32 v5, v5, v6
	ds_bpermute_b32 v6, v134, v5
	v_mul_f32_e32 v4, v133, v4
	v_cvt_pk_bf16_f32 v4, v4, s0
	ds_write_b16 v32, v4 offset:2448
	v_mul_f32_e32 v4, v34, v0
	s_waitcnt lgkmcnt(1)
	v_add_f32_e32 v5, v5, v6
	ds_bpermute_b32 v6, v48, v5
	v_mul_f32_e32 v4, v132, v4
	v_cvt_pk_bf16_f32 v4, v4, s0
	ds_write_b16 v32, v4 offset:2512
	v_mul_f32_e32 v4, v21, v0
	s_waitcnt lgkmcnt(1)
	v_add_f32_e32 v5, v5, v6
	ds_bpermute_b32 v6, v33, v5
	v_mul_f32_e32 v0, v1, v0
	v_mul_f32_e32 v0, v131, v0
	v_cvt_pk_bf16_f32 v0, v0, s0
	ds_write_b16 v32, v0 offset:2640
	v_rcp_f32_e32 v0, v3
	s_waitcnt lgkmcnt(1)
	v_add_f32_e32 v1, v5, v6
	v_rcp_f32_e32 v3, v19
	v_fmamk_f32 v1, v1, 0x3c000000, v219
	v_rsq_f32_e32 v1, v1
	v_mul_f32_e32 v0, v237, v0
	v_mul_f32_e32 v5, v55, v0
	v_fma_f32 v16, v119, v3, -v5
	v_mul_f32_e32 v5, v39, v0
	v_mul_f32_e32 v4, v130, v4
	v_fma_f32 v17, v103, v3, -v5
	v_mul_f32_e32 v5, v23, v0
	v_mul_f32_e32 v0, v7, v0
	v_cvt_pk_bf16_f32 v4, v4, s0
	v_mul_f32_e32 v1, 0x3f24fd5c, v1
	v_fma_f32 v19, v71, v3, -v0
	ds_write_b16 v32, v4 offset:2576
	v_mul_f32_e32 v4, v18, v1
	v_fma_f32 v18, v87, v3, -v5
	v_mul_f32_e32 v0, v17, v17
	v_mul_f32_e32 v3, v19, v19
	v_fmac_f32_e32 v0, v16, v16
	v_fmac_f32_e32 v3, v18, v18
	v_add_f32_e32 v0, v0, v3
	ds_bpermute_b32 v3, v136, v0
	v_mul_f32_e32 v4, v133, v4
	v_cvt_pk_bf16_f32 v4, v4, s0
	ds_write_b16 v32, v4 offset:2720
	v_mul_f32_e32 v4, v20, v1
	s_waitcnt lgkmcnt(1)
	v_add_f32_e32 v0, v0, v3
	ds_bpermute_b32 v3, v135, v0
	v_mul_f32_e32 v4, v132, v4
	v_cvt_pk_bf16_f32 v4, v4, s0
	ds_write_b16 v32, v4 offset:2784
	v_mul_f32_e32 v4, v22, v1
	s_waitcnt lgkmcnt(1)
	v_add_f32_e32 v0, v0, v3
	ds_bpermute_b32 v3, v134, v0
	v_mul_f32_e32 v4, v130, v4
	v_mul_f32_e32 v20, v2, v1
	v_cvt_pk_bf16_f32 v4, v4, s0
	ds_write_b16 v32, v4 offset:2848
	s_waitcnt lgkmcnt(1)
	v_add_f32_e32 v21, v0, v3
	ds_read_b128 v[0:3], v137 offset:192
	ds_read_b128 v[4:7], v137 offset:64
	ds_bpermute_b32 v22, v48, v21
	v_mul_f32_e32 v20, v131, v20
	v_cvt_pk_bf16_f32 v20, v20, s0
	s_waitcnt lgkmcnt(2)
	v_rcp_f32_e32 v0, v0
	s_waitcnt lgkmcnt(1)
	v_rcp_f32_e32 v4, v4
	s_waitcnt lgkmcnt(0)
	v_add_f32_e32 v21, v21, v22
	ds_bpermute_b32 v22, v33, v21
	v_mul_f32_e32 v0, v237, v0
	v_mul_f32_e32 v23, v56, v0
	v_mul_f32_e32 v34, v40, v0
	v_mul_f32_e32 v24, v24, v0
	v_mul_f32_e32 v0, v8, v0
	v_fma_f32 v34, v104, v4, -v34
	v_fma_f32 v0, v72, v4, -v0
	v_fma_f32 v23, v120, v4, -v23
	v_fma_f32 v24, v88, v4, -v24
	v_mul_f32_e32 v4, v34, v34
	v_mul_f32_e32 v8, v0, v0
	v_fmac_f32_e32 v4, v23, v23
	v_fmac_f32_e32 v8, v24, v24
	v_add_f32_e32 v4, v4, v8
	ds_bpermute_b32 v8, v136, v4
	s_waitcnt lgkmcnt(1)
	v_add_f32_e32 v21, v21, v22
	v_fmamk_f32 v21, v21, 0x3c000000, v219
	v_rsq_f32_e32 v21, v21
	ds_write_b16 v32, v20 offset:2912
	s_waitcnt lgkmcnt(1)
	v_add_f32_e32 v4, v4, v8
	ds_bpermute_b32 v8, v135, v4
	v_mul_f32_e32 v20, 0x3f24fd5c, v21
	v_mul_f32_e32 v16, v16, v20
	v_mul_f32_e32 v16, v133, v16
	v_rcp_f32_e32 v1, v1
	s_waitcnt lgkmcnt(0)
	v_add_f32_e32 v4, v4, v8
	ds_bpermute_b32 v8, v134, v4
	v_cvt_pk_bf16_f32 v16, v16, s0
	ds_write_b16 v32, v16 offset:2992
	v_mul_f32_e32 v16, v17, v20
	v_rcp_f32_e32 v5, v5
	s_waitcnt lgkmcnt(1)
	v_add_f32_e32 v4, v4, v8
	ds_bpermute_b32 v8, v48, v4
	v_mul_f32_e32 v16, v132, v16
	v_cvt_pk_bf16_f32 v16, v16, s0
	v_mul_f32_e32 v1, v237, v1
	ds_write_b16 v32, v16 offset:3056
	s_waitcnt lgkmcnt(1)
	v_add_f32_e32 v4, v4, v8
	ds_bpermute_b32 v8, v33, v4
	v_mul_f32_e32 v16, v18, v20
	v_mul_f32_e32 v17, v41, v1
	v_mul_f32_e32 v18, v25, v1
	v_fma_f32 v17, v105, v5, -v17
	s_waitcnt lgkmcnt(0)
	v_add_f32_e32 v4, v4, v8
	v_mul_f32_e32 v8, v57, v1
	v_mul_f32_e32 v1, v9, v1
	v_fma_f32 v1, v73, v5, -v1
	v_fma_f32 v8, v121, v5, -v8
	v_fma_f32 v18, v89, v5, -v18
	v_mul_f32_e32 v5, v17, v17
	v_mul_f32_e32 v9, v1, v1
	v_fmac_f32_e32 v5, v8, v8
	v_fmac_f32_e32 v9, v18, v18
	v_add_f32_e32 v5, v5, v9
	ds_bpermute_b32 v9, v136, v5
	v_fmamk_f32 v4, v4, 0x3c000000, v219
	v_mul_f32_e32 v16, v130, v16
	v_rsq_f32_e32 v4, v4
	v_cvt_pk_bf16_f32 v16, v16, s0
	s_waitcnt lgkmcnt(0)
	v_add_f32_e32 v5, v5, v9
	ds_bpermute_b32 v9, v135, v5
	ds_write_b16 v32, v16 offset:3120
	v_mul_f32_e32 v16, v19, v20
	v_mul_f32_e32 v16, v131, v16
	v_cvt_pk_bf16_f32 v16, v16, s0
	s_waitcnt lgkmcnt(1)
	v_add_f32_e32 v5, v5, v9
	ds_bpermute_b32 v9, v134, v5
	v_mul_f32_e32 v4, 0x3f24fd5c, v4
	ds_write_b16 v32, v16 offset:3184
	v_mul_f32_e32 v16, v23, v4
	v_mul_f32_e32 v16, v133, v16
	s_waitcnt lgkmcnt(1)
	v_add_f32_e32 v5, v5, v9
	ds_bpermute_b32 v9, v48, v5
	v_cvt_pk_bf16_f32 v16, v16, s0
	ds_write_b16 v32, v16 offset:4352
	v_mul_f32_e32 v16, v34, v4
	v_mul_f32_e32 v16, v132, v16
	v_rcp_f32_e32 v2, v2
	v_cvt_pk_bf16_f32 v16, v16, s0
	ds_write_b16 v32, v16 offset:4416
	v_mul_f32_e32 v16, v24, v4
	v_mul_f32_e32 v0, v0, v4
	s_waitcnt lgkmcnt(2)
	v_add_f32_e32 v4, v5, v9
	v_rcp_f32_e32 v5, v6
	v_mul_f32_e32 v2, v237, v2
	v_mul_f32_e32 v9, v58, v2
	ds_bpermute_b32 v6, v33, v4
	v_fma_f32 v19, v122, v5, -v9
	v_mul_f32_e32 v9, v42, v2
	v_fma_f32 v20, v106, v5, -v9
	v_mul_f32_e32 v9, v26, v2
	v_mul_f32_e32 v2, v10, v2
	v_fma_f32 v2, v74, v5, -v2
	v_fma_f32 v21, v90, v5, -v9
	v_mul_f32_e32 v5, v20, v20
	v_mul_f32_e32 v9, v2, v2
	v_fmac_f32_e32 v5, v19, v19
	v_fmac_f32_e32 v9, v21, v21
	v_add_f32_e32 v5, v5, v9
	ds_bpermute_b32 v9, v136, v5
	s_waitcnt lgkmcnt(1)
	v_add_f32_e32 v4, v4, v6
	v_fmamk_f32 v4, v4, 0x3c000000, v219
	v_rsq_f32_e32 v4, v4
	v_mul_f32_e32 v0, v131, v0
	s_waitcnt lgkmcnt(0)
	v_add_f32_e32 v5, v5, v9
	ds_bpermute_b32 v6, v135, v5
	v_cvt_pk_bf16_f32 v0, v0, s0
	ds_write_b16 v32, v0 offset:4544
	v_mul_f32_e32 v0, 0x3f24fd5c, v4
	v_mul_f32_e32 v4, v8, v0
	s_waitcnt lgkmcnt(1)
	v_add_f32_e32 v5, v5, v6
	ds_bpermute_b32 v6, v134, v5
	v_mul_f32_e32 v4, v133, v4
	v_cvt_pk_bf16_f32 v4, v4, s0
	ds_write_b16 v32, v4 offset:4624
	v_mul_f32_e32 v4, v17, v0
	s_waitcnt lgkmcnt(1)
	v_add_f32_e32 v5, v5, v6
	ds_bpermute_b32 v6, v48, v5
	v_mul_f32_e32 v4, v132, v4
	v_cvt_pk_bf16_f32 v4, v4, s0
	ds_write_b16 v32, v4 offset:4688
	v_mul_f32_e32 v4, v18, v0
	s_waitcnt lgkmcnt(1)
	v_add_f32_e32 v5, v5, v6
	ds_bpermute_b32 v6, v33, v5
	v_mul_f32_e32 v4, v130, v4
	v_rcp_f32_e32 v3, v3
	v_cvt_pk_bf16_f32 v4, v4, s0
	ds_write_b16 v32, v4 offset:4752
	v_rcp_f32_e32 v4, v7
	v_mul_f32_e32 v16, v130, v16
	v_mul_f32_e32 v3, v237, v3
	v_cvt_pk_bf16_f32 v16, v16, s0
	v_mul_f32_e32 v0, v1, v0
	s_waitcnt lgkmcnt(1)
	v_add_f32_e32 v1, v5, v6
	v_mul_f32_e32 v5, v59, v3
	ds_write_b16 v32, v16 offset:4480
	v_fma_f32 v16, v123, v4, -v5
	v_mul_f32_e32 v5, v43, v3
	v_fma_f32 v10, v107, v4, -v5
	v_mul_f32_e32 v5, v27, v3
	v_mul_f32_e32 v3, v11, v3
	v_fma_f32 v8, v75, v4, -v3
	v_fma_f32 v9, v91, v4, -v5
	v_mul_f32_e32 v3, v10, v10
	v_mul_f32_e32 v4, v8, v8
	v_fmac_f32_e32 v3, v16, v16
	v_fmac_f32_e32 v4, v9, v9
	v_add_f32_e32 v3, v3, v4
	v_fmamk_f32 v1, v1, 0x3c000000, v219
	ds_bpermute_b32 v4, v136, v3
	v_rsq_f32_e32 v1, v1
	v_mul_f32_e32 v0, v131, v0
	v_cvt_pk_bf16_f32 v0, v0, s0
	ds_write_b16 v32, v0 offset:4816
	v_mul_f32_e32 v0, 0x3f24fd5c, v1
	s_waitcnt lgkmcnt(1)
	v_add_f32_e32 v1, v3, v4
	ds_bpermute_b32 v3, v135, v1
	v_mul_f32_e32 v4, v19, v0
	v_mul_f32_e32 v4, v133, v4
	v_cvt_pk_bf16_f32 v4, v4, s0
	ds_write_b16 v32, v4 offset:4896
	s_waitcnt lgkmcnt(1)
	v_add_f32_e32 v1, v1, v3
	ds_bpermute_b32 v3, v134, v1
	v_mul_f32_e32 v4, v20, v0
	v_mul_f32_e32 v4, v132, v4
	v_cvt_pk_bf16_f32 v4, v4, s0
	ds_write_b16 v32, v4 offset:4960
	s_waitcnt lgkmcnt(1)
	v_add_f32_e32 v1, v1, v3
	ds_bpermute_b32 v3, v48, v1
	v_mul_f32_e32 v4, v21, v0
	v_mul_f32_e32 v4, v130, v4
	v_cvt_pk_bf16_f32 v4, v4, s0
	ds_write_b16 v32, v4 offset:5024
	s_waitcnt lgkmcnt(1)
	v_add_f32_e32 v4, v1, v3
	ds_bpermute_b32 v5, v33, v4
	v_mul_f32_e32 v0, v2, v0
	v_mul_f32_e32 v0, v131, v0
	v_cvt_pk_bf16_f32 v11, v0, s0
	ds_read_b128 v[0:3], v137 offset:224
	s_waitcnt lgkmcnt(1)
	v_add_f32_e32 v17, v4, v5
	ds_read_b128 v[4:7], v137 offset:96
	v_fmamk_f32 v17, v17, 0x3c000000, v219
	v_rsq_f32_e32 v17, v17
	s_waitcnt lgkmcnt(1)
	v_rcp_f32_e32 v0, v0
	ds_write_b16 v32, v11 offset:5088
	s_waitcnt lgkmcnt(1)
	v_rcp_f32_e32 v4, v4
	v_mul_f32_e32 v11, 0x3f24fd5c, v17
	v_mul_f32_e32 v0, v237, v0
	v_mul_f32_e32 v17, v60, v0
	v_mul_f32_e32 v18, v44, v0
	v_mul_f32_e32 v19, v28, v0
	v_mul_f32_e32 v0, v12, v0
	v_fma_f32 v18, v108, v4, -v18
	v_fma_f32 v0, v76, v4, -v0
	v_fma_f32 v17, v124, v4, -v17
	v_fma_f32 v19, v92, v4, -v19
	v_mul_f32_e32 v4, v18, v18
	v_mul_f32_e32 v12, v0, v0
	v_fmac_f32_e32 v4, v17, v17
	v_fmac_f32_e32 v12, v19, v19
	v_add_f32_e32 v4, v4, v12
	ds_bpermute_b32 v12, v136, v4
	v_mul_f32_e32 v10, v10, v11
	v_mul_f32_e32 v10, v132, v10
	v_cvt_pk_bf16_f32 v10, v10, s0
	ds_write_b16 v32, v10 offset:5232
	s_waitcnt lgkmcnt(1)
	v_add_f32_e32 v4, v4, v12
	ds_bpermute_b32 v12, v135, v4
	v_rcp_f32_e32 v1, v1
	v_rcp_f32_e32 v5, v5
	v_mul_f32_e32 v16, v16, v11
	v_mul_f32_e32 v9, v9, v11
	s_waitcnt lgkmcnt(0)
	v_add_f32_e32 v4, v4, v12
	ds_bpermute_b32 v10, v134, v4
	v_mul_f32_e32 v1, v237, v1
	v_mul_f32_e32 v8, v8, v11
	v_mul_f32_e32 v11, v45, v1
	v_mul_f32_e32 v12, v29, v1
	s_waitcnt lgkmcnt(0)
	v_add_f32_e32 v4, v4, v10
	v_mul_f32_e32 v10, v61, v1
	v_mul_f32_e32 v1, v13, v1
	v_fma_f32 v11, v109, v5, -v11
	v_fma_f32 v1, v77, v5, -v1
	v_fma_f32 v10, v125, v5, -v10
	v_fma_f32 v12, v93, v5, -v12
	v_mul_f32_e32 v5, v11, v11
	v_mul_f32_e32 v13, v1, v1
	v_fmac_f32_e32 v5, v10, v10
	v_fmac_f32_e32 v13, v12, v12
	v_add_f32_e32 v5, v5, v13
	ds_bpermute_b32 v13, v136, v5
	v_mul_f32_e32 v9, v130, v9
	v_cvt_pk_bf16_f32 v9, v9, s0
	v_mul_f32_e32 v8, v131, v8
	ds_write_b16 v32, v9 offset:5296
	ds_bpermute_b32 v9, v48, v4
	v_cvt_pk_bf16_f32 v8, v8, s0
	s_waitcnt lgkmcnt(2)
	v_add_f32_e32 v5, v5, v13
	ds_write_b16 v32, v8 offset:5360
	ds_bpermute_b32 v8, v135, v5
	s_waitcnt lgkmcnt(2)
	v_add_f32_e32 v4, v4, v9
	ds_bpermute_b32 v9, v33, v4
	v_rcp_f32_e32 v2, v2
	v_mul_f32_e32 v49, v132, v49
	s_waitcnt lgkmcnt(1)
	v_add_f32_e32 v5, v5, v8
	ds_bpermute_b32 v8, v134, v5
	s_waitcnt lgkmcnt(1)
	v_add_f32_e32 v4, v4, v9
	v_fmamk_f32 v4, v4, 0x3c000000, v219
	v_rsq_f32_e32 v4, v4
	v_mul_f32_e32 v2, v237, v2
	s_waitcnt lgkmcnt(0)
	v_add_f32_e32 v5, v5, v8
	ds_bpermute_b32 v8, v48, v5
	v_mul_f32_e32 v4, 0x3f24fd5c, v4
	v_mul_f32_e32 v9, v17, v4
	v_mul_f32_e32 v9, v133, v9
	v_cvt_pk_bf16_f32 v9, v9, s0
	s_waitcnt lgkmcnt(0)
	v_add_f32_e32 v5, v5, v8
	ds_bpermute_b32 v8, v33, v5
	ds_write_b16 v32, v9 offset:6528
	v_mul_f32_e32 v9, v18, v4
	v_mul_f32_e32 v9, v132, v9
	v_cvt_pk_bf16_f32 v9, v9, s0
	ds_write_b16 v32, v9 offset:6592
	v_mul_f32_e32 v9, v19, v4
	v_mul_f32_e32 v0, v0, v4
	s_waitcnt lgkmcnt(2)
	v_add_f32_e32 v4, v5, v8
	v_rcp_f32_e32 v5, v6
	v_mul_f32_e32 v9, v130, v9
	v_cvt_pk_bf16_f32 v9, v9, s0
	ds_write_b16 v32, v9 offset:6656
	v_mul_f32_e32 v6, v62, v2
	v_mul_f32_e32 v8, v46, v2
	v_mul_f32_e32 v9, v30, v2
	v_mul_f32_e32 v2, v14, v2
	v_fma_f32 v8, v110, v5, -v8
	v_fma_f32 v2, v78, v5, -v2
	v_fma_f32 v6, v126, v5, -v6
	v_fma_f32 v9, v94, v5, -v9
	v_mul_f32_e32 v5, v8, v8
	v_mul_f32_e32 v13, v2, v2
	v_fmac_f32_e32 v5, v6, v6
	v_fmac_f32_e32 v13, v9, v9
	v_add_f32_e32 v5, v5, v13
	v_fmamk_f32 v4, v4, 0x3c000000, v219
	ds_bpermute_b32 v13, v136, v5
	v_rsq_f32_e32 v4, v4
	v_mul_f32_e32 v0, v131, v0
	v_cvt_pk_bf16_f32 v0, v0, s0
	ds_write_b16 v32, v0 offset:6720
	v_mul_f32_e32 v0, 0x3f24fd5c, v4
	s_waitcnt lgkmcnt(1)
	v_add_f32_e32 v5, v5, v13
	v_mul_f32_e32 v4, v10, v0
	ds_bpermute_b32 v10, v135, v5
	v_mul_f32_e32 v4, v133, v4
	v_cvt_pk_bf16_f32 v4, v4, s0
	ds_write_b16 v32, v4 offset:6800
	v_mul_f32_e32 v4, v11, v0
	s_waitcnt lgkmcnt(1)
	v_add_f32_e32 v5, v5, v10
	ds_bpermute_b32 v10, v134, v5
	v_mul_f32_e32 v4, v132, v4
	v_cvt_pk_bf16_f32 v4, v4, s0
	ds_write_b16 v32, v4 offset:6864
	v_mul_f32_e32 v4, v12, v0
	s_waitcnt lgkmcnt(1)
	v_add_f32_e32 v5, v5, v10
	v_mul_f32_e32 v4, v130, v4
	ds_bpermute_b32 v10, v48, v5
	v_mul_f32_e32 v0, v1, v0
	v_rcp_f32_e32 v1, v3
	v_cvt_pk_bf16_f32 v4, v4, s0
	ds_write_b16 v32, v4 offset:6928
	v_rcp_f32_e32 v4, v7
	v_mul_f32_e32 v1, v237, v1
	s_waitcnt lgkmcnt(1)
	v_add_f32_e32 v3, v5, v10
	v_mul_f32_e32 v7, v63, v1
	v_mul_f32_e32 v10, v47, v1
	v_mul_f32_e32 v11, v31, v1
	v_mul_f32_e32 v1, v15, v1
	v_fma_f32 v10, v111, v4, -v10
	v_fma_f32 v1, v79, v4, -v1
	v_fma_f32 v7, v127, v4, -v7
	v_fma_f32 v11, v95, v4, -v11
	v_mul_f32_e32 v4, v10, v10
	v_mul_f32_e32 v12, v1, v1
	v_fmac_f32_e32 v4, v7, v7
	v_fmac_f32_e32 v12, v11, v11
	v_add_f32_e32 v4, v4, v12
	ds_bpermute_b32 v12, v136, v4
	ds_bpermute_b32 v5, v33, v3
	v_mul_f32_e32 v0, v131, v0
	v_cvt_pk_bf16_f32 v0, v0, s0
	ds_write_b16 v32, v0 offset:6992
	s_waitcnt lgkmcnt(2)
	v_add_f32_e32 v4, v4, v12
	s_waitcnt lgkmcnt(1)
	v_add_f32_e32 v3, v3, v5
	ds_bpermute_b32 v5, v135, v4
	v_fmamk_f32 v3, v3, 0x3c000000, v219
	v_rsq_f32_e32 v3, v3
	v_mul_f32_e32 v35, v132, v35
	v_mul_f32_e32 v16, v133, v16
	s_waitcnt lgkmcnt(0)
	v_add_f32_e32 v4, v4, v5
	ds_bpermute_b32 v5, v134, v4
	v_mul_f32_e32 v0, 0x3f24fd5c, v3
	v_mul_f32_e32 v3, v6, v0
	v_mul_f32_e32 v3, v133, v3
	v_cvt_pk_bf16_f32 v3, v3, s0
	s_waitcnt lgkmcnt(0)
	v_add_f32_e32 v4, v4, v5
	ds_bpermute_b32 v5, v48, v4
	ds_write_b16 v32, v3 offset:7072
	v_mul_f32_e32 v3, v8, v0
	v_mul_f32_e32 v3, v132, v3
	v_cvt_pk_bf16_f32 v3, v3, s0
	s_waitcnt lgkmcnt(1)
	v_add_f32_e32 v4, v4, v5
	ds_bpermute_b32 v5, v33, v4
	ds_write_b16 v32, v3 offset:7136
	v_mul_f32_e32 v3, v9, v0
	v_mul_f32_e32 v0, v2, v0
	v_mul_f32_e32 v0, v131, v0
	s_waitcnt lgkmcnt(1)
	v_add_f32_e32 v2, v4, v5
	v_fmamk_f32 v2, v2, 0x3c000000, v219
	v_rsq_f32_e32 v2, v2
	v_cvt_pk_bf16_f32 v0, v0, s0
	ds_write_b16 v32, v0 offset:7264
	v_mul_f32_e32 v3, v130, v3
	v_mul_f32_e32 v0, 0x3f24fd5c, v2
	v_mul_f32_e32 v2, v7, v0
	v_mul_f32_e32 v2, v133, v2
	v_cvt_pk_bf16_f32 v2, v2, s0
	ds_write_b16 v32, v2 offset:7344
	v_mul_f32_e32 v2, v10, v0
	v_mul_f32_e32 v2, v132, v2
	v_cvt_pk_bf16_f32 v2, v2, s0
	ds_write_b16 v32, v2 offset:7408
	v_mul_f32_e32 v2, v11, v0
	v_mul_f32_e32 v0, v1, v0
	v_mul_f32_e32 v0, v131, v0
	v_mul_f32_e32 v2, v130, v2
	v_cvt_pk_bf16_f32 v0, v0, s0
	v_cvt_pk_bf16_f32 v50, v50, s0
	v_cvt_pk_bf16_f32 v49, v49, s0
	v_cvt_pk_bf16_f32 v35, v35, s0
	v_cvt_pk_bf16_f32 v16, v16, s0
	v_cvt_pk_bf16_f32 v3, v3, s0
	v_cvt_pk_bf16_f32 v2, v2, s0
	ds_write_b16 v32, v0 offset:7536
	v_lshlrev_b32_e32 v0, 4, v129
	v_lshrrev_b32_e32 v6, 4, v128
	ds_write_b16 v32, v50 offset:816
	ds_write_b16 v32, v49 offset:880
	ds_write_b16 v32, v35 offset:2240
	ds_write_b16 v32, v16 offset:5168
	ds_write_b16 v32, v3 offset:7200
	ds_write_b16 v32, v2 offset:7472
	v_and_b32_e32 v160, 0xf0, v0
	v_mul_u32_u24_e32 v0, 0x110, v6
	s_waitcnt lgkmcnt(0)
	v_add3_u32 v10, s28, v160, v0
	ds_read_b128 v[0:3], v10
	v_add_u32_e32 v6, s96, v6
	v_ashrrev_i32_e32 v7, 31, v6
	v_lshl_add_u64 v[4:5], s[4:5], 0, v[160:161]
	v_lshlrev_b64 v[8:9], 11, v[6:7]
	v_lshl_add_u64 v[8:9], v[4:5], 0, v[8:9]
	s_waitcnt lgkmcnt(0)
	flat_store_dwordx4 v[8:9], v[0:3] nt
	ds_read_b128 v[0:3], v10 offset:1088
	v_add_u32_e32 v8, 4, v6
	v_ashrrev_i32_e32 v9, 31, v8
	v_lshlrev_b64 v[8:9], 11, v[8:9]
	v_lshl_add_u64 v[8:9], v[4:5], 0, v[8:9]
	s_waitcnt lgkmcnt(0)
	flat_store_dwordx4 v[8:9], v[0:3] nt
	ds_read_b128 v[0:3], v10 offset:2176
	v_add_u32_e32 v8, 8, v6
	v_ashrrev_i32_e32 v9, 31, v8
	v_lshlrev_b64 v[8:9], 11, v[8:9]
	v_lshl_add_u64 v[8:9], v[4:5], 0, v[8:9]
	s_waitcnt lgkmcnt(0)
	flat_store_dwordx4 v[8:9], v[0:3] nt
	ds_read_b128 v[0:3], v10 offset:3264
	v_add_u32_e32 v8, 12, v6
	v_ashrrev_i32_e32 v9, 31, v8
	v_lshlrev_b64 v[8:9], 11, v[8:9]
	v_lshl_add_u64 v[8:9], v[4:5], 0, v[8:9]
	s_waitcnt lgkmcnt(0)
	flat_store_dwordx4 v[8:9], v[0:3] nt
	ds_read_b128 v[0:3], v10 offset:4352
	v_add_u32_e32 v8, 16, v6
	v_ashrrev_i32_e32 v9, 31, v8
	v_lshlrev_b64 v[8:9], 11, v[8:9]
	v_lshl_add_u64 v[8:9], v[4:5], 0, v[8:9]
	s_waitcnt lgkmcnt(0)
	flat_store_dwordx4 v[8:9], v[0:3] nt
	ds_read_b128 v[0:3], v10 offset:5440
	v_add_u32_e32 v8, 20, v6
	v_ashrrev_i32_e32 v9, 31, v8
	v_lshlrev_b64 v[8:9], 11, v[8:9]
	v_lshl_add_u64 v[8:9], v[4:5], 0, v[8:9]
	s_waitcnt lgkmcnt(0)
	flat_store_dwordx4 v[8:9], v[0:3] nt
	ds_read_b128 v[0:3], v10 offset:6528
	v_add_u32_e32 v8, 24, v6
	v_ashrrev_i32_e32 v9, 31, v8
	v_lshlrev_b64 v[8:9], 11, v[8:9]
	v_lshl_add_u64 v[8:9], v[4:5], 0, v[8:9]
	s_waitcnt lgkmcnt(0)
	flat_store_dwordx4 v[8:9], v[0:3] nt
	ds_read_b128 v[0:3], v10 offset:7616
	v_add_u32_e32 v6, 28, v6
	v_ashrrev_i32_e32 v7, 31, v6
	v_lshlrev_b64 v[6:7], 11, v[6:7]
	v_lshl_add_u64 v[4:5], v[4:5], 0, v[6:7]
	s_waitcnt lgkmcnt(0)
	flat_store_dwordx4 v[4:5], v[0:3] nt
	s_waitcnt lgkmcnt(0)
	s_cbranch_scc1 .LBB0_128

.LBB0_145:
	v_lshl_add_u64 v[130:131], v[188:189], 3, s[6:7]
	flat_load_dwordx2 v[128:129], v[130:131]
	v_lshl_add_u32 v160, s20, 8, v203
	s_mov_b64 s[8:9], 0x40000
	s_waitcnt vmcnt(0) lgkmcnt(0)
	v_ffbh_u32_e32 v132, v129
	v_min_u32_e32 v132, 32, v132
	v_lshlrev_b64 v[128:129], v132, v[128:129]
	v_min_u32_e32 v128, 1, v128
	v_or_b32_e32 v128, v129, v128
	v_cvt_f32_u32_e32 v128, v128
	v_sub_u32_e32 v129, 32, v132
	v_lshlrev_b64 v[132:133], 1, v[160:161]
	v_ldexp_f32 v128, v128, v129
	v_mul_f32_e32 v128, 0x35800000, v128
	v_fmamk_f32 v128, v128, 0x3a800000, v219
	v_rsq_f32_e32 v138, v128
	v_lshlrev_b64 v[128:129], 11, v[188:189]
	v_lshl_add_u64 v[128:129], s[2:3], 0, v[128:129]
	v_lshl_add_u64 v[128:129], v[128:129], 0, v[132:133]
	v_pk_mul_f32 v[134:135], v[124:125], v[138:139] op_sel_hi:[1,0]
	v_pk_mul_f32 v[136:137], v[126:127], v[138:139] op_sel_hi:[1,0]
	v_pk_mul_f32 v[140:141], v[120:121], v[138:139] op_sel_hi:[1,0]
	v_pk_mul_f32 v[142:143], v[122:123], v[138:139] op_sel_hi:[1,0]
	v_cvt_pk_bf16_f32 v134, v134, v135
	v_cvt_pk_bf16_f32 v135, v136, v137
	v_cvt_pk_bf16_f32 v136, v140, v141
	v_cvt_pk_bf16_f32 v137, v142, v143
	flat_store_dwordx4 v[128:129], v[134:137] nt
	v_pk_mul_f32 v[140:141], v[112:113], v[138:139] op_sel_hi:[1,0]
	s_nop 0
	v_pk_mul_f32 v[134:135], v[116:117], v[138:139] op_sel_hi:[1,0]
	v_pk_mul_f32 v[136:137], v[118:119], v[138:139] op_sel_hi:[1,0]
	v_pk_mul_f32 v[138:139], v[114:115], v[138:139] op_sel_hi:[1,0]
	v_cvt_pk_bf16_f32 v134, v134, v135
	v_cvt_pk_bf16_f32 v135, v136, v137
	v_cvt_pk_bf16_f32 v136, v140, v141
	v_cvt_pk_bf16_f32 v137, v138, v139
	flat_store_dwordx4 v[128:129], v[134:137] offset:256 nt
	s_nop 1
	v_lshl_add_u64 v[134:135], v[198:199], 3, s[6:7]
	flat_load_dwordx2 v[134:135], v[134:135]
	s_waitcnt vmcnt(0) lgkmcnt(0)
	v_ffbh_u32_e32 v136, v135
	v_min_u32_e32 v136, 32, v136
	v_lshlrev_b64 v[134:135], v136, v[134:135]
	v_min_u32_e32 v134, 1, v134
	v_or_b32_e32 v134, v135, v134
	v_cvt_f32_u32_e32 v134, v134
	v_sub_u32_e32 v135, 32, v136
	v_ldexp_f32 v134, v134, v135
	v_mul_f32_e32 v134, 0x35800000, v134
	v_fmamk_f32 v134, v134, 0x3a800000, v219
	v_rsq_f32_e32 v138, v134
	v_lshlrev_b64 v[134:135], 11, v[198:199]
	v_lshl_add_u64 v[134:135], s[2:3], 0, v[134:135]
	v_lshl_add_u64 v[146:147], v[134:135], 0, v[132:133]
	v_pk_mul_f32 v[136:137], v[108:109], v[138:139] op_sel_hi:[1,0]
	v_pk_mul_f32 v[140:141], v[110:111], v[138:139] op_sel_hi:[1,0]
	v_pk_mul_f32 v[142:143], v[104:105], v[138:139] op_sel_hi:[1,0]
	v_pk_mul_f32 v[144:145], v[106:107], v[138:139] op_sel_hi:[1,0]
	v_cvt_pk_bf16_f32 v134, v136, v137
	v_cvt_pk_bf16_f32 v135, v140, v141
	v_cvt_pk_bf16_f32 v136, v142, v143
	v_cvt_pk_bf16_f32 v137, v144, v145
	flat_store_dwordx4 v[146:147], v[134:137] nt
	v_pk_mul_f32 v[140:141], v[96:97], v[138:139] op_sel_hi:[1,0]
	s_nop 0
	v_pk_mul_f32 v[134:135], v[100:101], v[138:139] op_sel_hi:[1,0]
	v_pk_mul_f32 v[136:137], v[102:103], v[138:139] op_sel_hi:[1,0]
	v_pk_mul_f32 v[138:139], v[98:99], v[138:139] op_sel_hi:[1,0]
	v_cvt_pk_bf16_f32 v134, v134, v135
	v_cvt_pk_bf16_f32 v135, v136, v137
	v_cvt_pk_bf16_f32 v136, v140, v141
	v_cvt_pk_bf16_f32 v137, v138, v139
	flat_store_dwordx4 v[146:147], v[134:137] offset:256 nt
	s_nop 1
	v_lshl_add_u64 v[134:135], v[196:197], 3, s[6:7]
	flat_load_dwordx2 v[134:135], v[134:135]
	s_waitcnt vmcnt(0) lgkmcnt(0)
	v_ffbh_u32_e32 v136, v135
	v_min_u32_e32 v136, 32, v136
	v_lshlrev_b64 v[134:135], v136, v[134:135]
	v_min_u32_e32 v134, 1, v134
	v_or_b32_e32 v134, v135, v134
	v_cvt_f32_u32_e32 v134, v134
	v_sub_u32_e32 v135, 32, v136
	v_ldexp_f32 v134, v134, v135
	v_mul_f32_e32 v134, 0x35800000, v134
	v_fmamk_f32 v134, v134, 0x3a800000, v219
	v_rsq_f32_e32 v138, v134
	v_lshlrev_b64 v[134:135], 11, v[196:197]
	v_lshl_add_u64 v[134:135], s[2:3], 0, v[134:135]
	v_lshl_add_u64 v[146:147], v[134:135], 0, v[132:133]
	v_pk_mul_f32 v[136:137], v[92:93], v[138:139] op_sel_hi:[1,0]
	v_pk_mul_f32 v[140:141], v[94:95], v[138:139] op_sel_hi:[1,0]
	v_pk_mul_f32 v[142:143], v[88:89], v[138:139] op_sel_hi:[1,0]
	v_pk_mul_f32 v[144:145], v[90:91], v[138:139] op_sel_hi:[1,0]
	v_cvt_pk_bf16_f32 v134, v136, v137
	v_cvt_pk_bf16_f32 v135, v140, v141
	v_cvt_pk_bf16_f32 v136, v142, v143
	v_cvt_pk_bf16_f32 v137, v144, v145
	flat_store_dwordx4 v[146:147], v[134:137] nt
	v_pk_mul_f32 v[140:141], v[80:81], v[138:139] op_sel_hi:[1,0]
	s_nop 0
	v_pk_mul_f32 v[134:135], v[84:85], v[138:139] op_sel_hi:[1,0]
	v_pk_mul_f32 v[136:137], v[86:87], v[138:139] op_sel_hi:[1,0]
	v_pk_mul_f32 v[138:139], v[82:83], v[138:139] op_sel_hi:[1,0]
	v_cvt_pk_bf16_f32 v134, v134, v135
	v_cvt_pk_bf16_f32 v135, v136, v137
	v_cvt_pk_bf16_f32 v136, v140, v141
	v_cvt_pk_bf16_f32 v137, v138, v139
	flat_store_dwordx4 v[146:147], v[134:137] offset:256 nt
	s_nop 1
	v_lshl_add_u64 v[134:135], v[194:195], 3, s[6:7]
	flat_load_dwordx2 v[134:135], v[134:135]
	s_waitcnt vmcnt(0) lgkmcnt(0)
	v_ffbh_u32_e32 v136, v135
	v_min_u32_e32 v136, 32, v136
	v_lshlrev_b64 v[134:135], v136, v[134:135]
	v_min_u32_e32 v134, 1, v134
	v_or_b32_e32 v134, v135, v134
	v_cvt_f32_u32_e32 v134, v134
	v_sub_u32_e32 v135, 32, v136
	v_ldexp_f32 v134, v134, v135
	v_mul_f32_e32 v134, 0x35800000, v134
	v_fmamk_f32 v134, v134, 0x3a800000, v219
	v_rsq_f32_e32 v136, v134
	v_lshlrev_b64 v[134:135], 11, v[194:195]
	v_lshl_add_u64 v[134:135], s[2:3], 0, v[134:135]
	v_lshl_add_u64 v[146:147], v[134:135], 0, v[132:133]
	v_pk_mul_f32 v[138:139], v[76:77], v[136:137] op_sel_hi:[1,0]
	v_pk_mul_f32 v[140:141], v[78:79], v[136:137] op_sel_hi:[1,0]
	v_pk_mul_f32 v[142:143], v[72:73], v[136:137] op_sel_hi:[1,0]
	v_pk_mul_f32 v[144:145], v[74:75], v[136:137] op_sel_hi:[1,0]
	v_cvt_pk_bf16_f32 v132, v138, v139
	v_cvt_pk_bf16_f32 v133, v140, v141
	v_cvt_pk_bf16_f32 v134, v142, v143
	v_cvt_pk_bf16_f32 v135, v144, v145
	flat_store_dwordx4 v[146:147], v[132:135] nt
	v_pk_mul_f32 v[138:139], v[64:65], v[136:137] op_sel_hi:[1,0]
	v_lshl_add_u64 v[142:143], v[128:129], 0, s[8:9]
	v_pk_mul_f32 v[132:133], v[68:69], v[136:137] op_sel_hi:[1,0]
	v_pk_mul_f32 v[134:135], v[70:71], v[136:137] op_sel_hi:[1,0]
	v_pk_mul_f32 v[136:137], v[66:67], v[136:137] op_sel_hi:[1,0]
	v_cvt_pk_bf16_f32 v132, v132, v133
	v_cvt_pk_bf16_f32 v133, v134, v135
	v_cvt_pk_bf16_f32 v134, v138, v139
	v_cvt_pk_bf16_f32 v135, v136, v137
	flat_store_dwordx4 v[146:147], v[132:135] offset:256 nt
	flat_load_dwordx2 v[132:133], v[130:131] offset:1024
	s_mov_b32 s8, 0x40000
	s_waitcnt vmcnt(0) lgkmcnt(0)
	v_ffbh_u32_e32 v134, v133
	v_min_u32_e32 v134, 32, v134
	v_lshlrev_b64 v[132:133], v134, v[132:133]
	v_min_u32_e32 v132, 1, v132
	v_or_b32_e32 v132, v133, v132
	v_cvt_f32_u32_e32 v132, v132
	v_sub_u32_e32 v133, 32, v134
	v_ldexp_f32 v132, v132, v133
	v_mul_f32_e32 v132, 0x35800000, v132
	v_fmamk_f32 v132, v132, 0x3a800000, v219
	v_rsq_f32_e32 v136, v132
	s_nop 0
	v_pk_mul_f32 v[132:133], v[60:61], v[136:137] op_sel_hi:[1,0]
	v_pk_mul_f32 v[134:135], v[62:63], v[136:137] op_sel_hi:[1,0]
	v_pk_mul_f32 v[138:139], v[56:57], v[136:137] op_sel_hi:[1,0]
	v_pk_mul_f32 v[140:141], v[58:59], v[136:137] op_sel_hi:[1,0]
	v_cvt_pk_bf16_f32 v132, v132, v133
	v_cvt_pk_bf16_f32 v133, v134, v135
	v_cvt_pk_bf16_f32 v134, v138, v139
	v_add_co_u32_e32 v138, vcc, s8, v128
	v_cvt_pk_bf16_f32 v135, v140, v141
	s_nop 0
	v_addc_co_u32_e32 v139, vcc, 0, v129, vcc
	flat_store_dwordx4 v[138:139], v[132:135] nt
	v_pk_mul_f32 v[138:139], v[48:49], v[136:137] op_sel_hi:[1,0]
	s_mov_b64 s[8:9], 0x48000
	v_pk_mul_f32 v[132:133], v[52:53], v[136:137] op_sel_hi:[1,0]
	v_pk_mul_f32 v[134:135], v[54:55], v[136:137] op_sel_hi:[1,0]
	v_pk_mul_f32 v[136:137], v[50:51], v[136:137] op_sel_hi:[1,0]
	v_cvt_pk_bf16_f32 v132, v132, v133
	v_cvt_pk_bf16_f32 v133, v134, v135
	v_cvt_pk_bf16_f32 v134, v138, v139
	v_cvt_pk_bf16_f32 v135, v136, v137
	flat_store_dwordx4 v[142:143], v[132:135] offset:256 nt
	flat_load_dwordx2 v[132:133], v[130:131] offset:1152
	v_lshl_add_u64 v[142:143], v[128:129], 0, s[8:9]
	s_mov_b32 s8, 0x48000
	s_waitcnt vmcnt(0) lgkmcnt(0)
	v_ffbh_u32_e32 v134, v133
	v_min_u32_e32 v134, 32, v134
	v_lshlrev_b64 v[132:133], v134, v[132:133]
	v_min_u32_e32 v132, 1, v132
	v_or_b32_e32 v132, v133, v132
	v_cvt_f32_u32_e32 v132, v132
	v_sub_u32_e32 v133, 32, v134
	v_ldexp_f32 v132, v132, v133
	v_mul_f32_e32 v132, 0x35800000, v132
	v_fmamk_f32 v132, v132, 0x3a800000, v219
	v_rsq_f32_e32 v136, v132
	s_nop 0
	v_pk_mul_f32 v[132:133], v[44:45], v[136:137] op_sel_hi:[1,0]
	v_pk_mul_f32 v[134:135], v[46:47], v[136:137] op_sel_hi:[1,0]
	v_pk_mul_f32 v[138:139], v[40:41], v[136:137] op_sel_hi:[1,0]
	v_pk_mul_f32 v[140:141], v[42:43], v[136:137] op_sel_hi:[1,0]
	v_cvt_pk_bf16_f32 v132, v132, v133
	v_cvt_pk_bf16_f32 v133, v134, v135
	v_cvt_pk_bf16_f32 v134, v138, v139
	v_add_co_u32_e32 v138, vcc, s8, v128
	v_cvt_pk_bf16_f32 v135, v140, v141
	s_nop 0
	v_addc_co_u32_e32 v139, vcc, 0, v129, vcc
	flat_store_dwordx4 v[138:139], v[132:135] nt
	v_pk_mul_f32 v[138:139], v[32:33], v[136:137] op_sel_hi:[1,0]
	s_mov_b64 s[8:9], 0x50000
	v_pk_mul_f32 v[132:133], v[36:37], v[136:137] op_sel_hi:[1,0]
	v_pk_mul_f32 v[134:135], v[38:39], v[136:137] op_sel_hi:[1,0]
	v_pk_mul_f32 v[136:137], v[34:35], v[136:137] op_sel_hi:[1,0]
	v_cvt_pk_bf16_f32 v132, v132, v133
	v_cvt_pk_bf16_f32 v133, v134, v135
	v_cvt_pk_bf16_f32 v134, v138, v139
	v_cvt_pk_bf16_f32 v135, v136, v137
	flat_store_dwordx4 v[142:143], v[132:135] offset:256 nt
	flat_load_dwordx2 v[132:133], v[130:131] offset:1280
	v_lshl_add_u64 v[142:143], v[128:129], 0, s[8:9]
	s_mov_b32 s8, 0x50000
	s_waitcnt vmcnt(0) lgkmcnt(0)
	v_ffbh_u32_e32 v134, v133
	v_min_u32_e32 v134, 32, v134
	v_lshlrev_b64 v[132:133], v134, v[132:133]
	v_min_u32_e32 v132, 1, v132
	v_or_b32_e32 v132, v133, v132
	v_cvt_f32_u32_e32 v132, v132
	v_sub_u32_e32 v133, 32, v134
	v_ldexp_f32 v132, v132, v133
	v_mul_f32_e32 v132, 0x35800000, v132
	v_fmamk_f32 v132, v132, 0x3a800000, v219
	v_rsq_f32_e32 v136, v132
	s_nop 0
	v_pk_mul_f32 v[132:133], v[28:29], v[136:137] op_sel_hi:[1,0]
	v_pk_mul_f32 v[134:135], v[30:31], v[136:137] op_sel_hi:[1,0]
	v_pk_mul_f32 v[138:139], v[24:25], v[136:137] op_sel_hi:[1,0]
	v_pk_mul_f32 v[140:141], v[26:27], v[136:137] op_sel_hi:[1,0]
	v_cvt_pk_bf16_f32 v132, v132, v133
	v_cvt_pk_bf16_f32 v133, v134, v135
	v_cvt_pk_bf16_f32 v134, v138, v139
	v_add_co_u32_e32 v138, vcc, s8, v128
	v_cvt_pk_bf16_f32 v135, v140, v141
	s_nop 0
	v_addc_co_u32_e32 v139, vcc, 0, v129, vcc
	flat_store_dwordx4 v[138:139], v[132:135] nt
	v_pk_mul_f32 v[138:139], v[16:17], v[136:137] op_sel_hi:[1,0]
	s_mov_b64 s[8:9], 0x58000
	v_pk_mul_f32 v[132:133], v[20:21], v[136:137] op_sel_hi:[1,0]
	v_pk_mul_f32 v[134:135], v[22:23], v[136:137] op_sel_hi:[1,0]
	v_pk_mul_f32 v[136:137], v[18:19], v[136:137] op_sel_hi:[1,0]
	v_cvt_pk_bf16_f32 v132, v132, v133
	v_cvt_pk_bf16_f32 v133, v134, v135
	v_cvt_pk_bf16_f32 v134, v138, v139
	v_cvt_pk_bf16_f32 v135, v136, v137
	flat_store_dwordx4 v[142:143], v[132:135] offset:256 nt
	flat_load_dwordx2 v[130:131], v[130:131] offset:1408
	v_lshl_add_u64 v[140:141], v[128:129], 0, s[8:9]
	s_mov_b32 s8, 0x58000
	v_add_co_u32_e32 v128, vcc, s8, v128
	s_nop 1
	v_addc_co_u32_e32 v129, vcc, 0, v129, vcc
	s_waitcnt vmcnt(0) lgkmcnt(0)
	v_ffbh_u32_e32 v132, v131
	v_min_u32_e32 v132, 32, v132
	v_lshlrev_b64 v[130:131], v132, v[130:131]
	v_min_u32_e32 v130, 1, v130
	v_or_b32_e32 v130, v131, v130
	v_cvt_f32_u32_e32 v130, v130
	v_sub_u32_e32 v131, 32, v132
	v_ldexp_f32 v130, v130, v131
	v_mul_f32_e32 v130, 0x35800000, v130
	v_fmamk_f32 v130, v130, 0x3a800000, v219
	v_rsq_f32_e32 v134, v130
	s_nop 0
	v_pk_mul_f32 v[130:131], v[12:13], v[134:135] op_sel_hi:[1,0]
	v_pk_mul_f32 v[132:133], v[14:15], v[134:135] op_sel_hi:[1,0]
	v_pk_mul_f32 v[136:137], v[8:9], v[134:135] op_sel_hi:[1,0]
	v_pk_mul_f32 v[138:139], v[10:11], v[134:135] op_sel_hi:[1,0]
	v_cvt_pk_bf16_f32 v130, v130, v131
	v_cvt_pk_bf16_f32 v131, v132, v133
	v_cvt_pk_bf16_f32 v132, v136, v137
	v_cvt_pk_bf16_f32 v133, v138, v139
	flat_store_dwordx4 v[128:129], v[130:133] nt
	v_pk_mul_f32 v[128:129], v[4:5], v[134:135] op_sel_hi:[1,0]
	s_nop 0
	v_pk_mul_f32 v[130:131], v[6:7], v[134:135] op_sel_hi:[1,0]
	v_pk_mul_f32 v[132:133], v[0:1], v[134:135] op_sel_hi:[1,0]
	v_pk_mul_f32 v[134:135], v[2:3], v[134:135] op_sel_hi:[1,0]
	v_cvt_pk_bf16_f32 v128, v128, v129
	v_cvt_pk_bf16_f32 v129, v130, v131
	v_cvt_pk_bf16_f32 v130, v132, v133
	v_cvt_pk_bf16_f32 v131, v134, v135
	flat_store_dwordx4 v[140:141], v[128:131] offset:256 nt
	s_cbranch_execnz .LBB0_144
.LBB0_146:
	v_lshl_add_u64 v[192:193], v[188:189], 3, s[6:7]
	flat_load_dwordx2 v[144:145], v[192:193]
	s_lshl_b32 s8, s20, 2
	s_and_b32 s10, s8, 12
	s_cmp_lt_i32 s20, 4
	s_cselect_b64 vcc, -1, 0
	v_mov_b32_e32 v128, 0x3e38aa3b
	s_and_b64 s[8:9], vcc, exec
	s_movk_i32 s14, 0x4000
	s_mov_b32 s11, 0x9a00000
	v_cndmask_b32_e32 v200, 1.0, v128, vcc
	v_cmp_gt_i32_e32 vcc, s14, v188
	s_cselect_b32 s11, s11, 0xda00000
	v_lshlrev_b32_e32 v136, 2, v182
	s_cselect_b32 s8, s74, s76
	s_cselect_b32 s9, s75, s77
	v_cndmask_b32_e32 v132, v228, v229, vcc
	s_add_u32 s11, s94, s11
	global_load_dwordx4 v[152:155], v136, s[8:9]
	global_load_dwordx4 v[128:131], v136, s[8:9] offset:16
	v_and_b32_e32 v137, v132, v188
	global_load_dwordx4 v[132:135], v136, s[8:9] offset:144
	global_load_dwordx4 v[156:159], v136, s[8:9] offset:128
	s_addc_u32 s9, s95, 0
	s_or_b32 s8, s10, s91
	s_lshl_b32 s8, s8, 7
	s_add_u32 s8, s11, s8
	v_and_b32_e32 v147, 64, v223
	v_lshlrev_b32_e32 v160, 1, v182
	v_lshlrev_b32_e32 v207, 2, v201
	s_addc_u32 s9, s9, 0
	v_xor_b32_e32 v146, 16, v223
	v_add_u32_e32 v147, 64, v147
	v_lshl_add_u64 v[190:191], s[8:9], 0, v[160:161]
	v_lshl_or_b32 v160, v137, 8, v207
	v_xor_b32_e32 v150, 32, v223
	v_cmp_lt_i32_e32 vcc, v146, v147
	v_lshl_add_u64 v[148:149], s[4:5], 0, v[160:161]
	flat_load_dwordx4 v[140:143], v[148:149]
	flat_load_dwordx4 v[136:139], v[148:149] offset:16
	v_cndmask_b32_e32 v146, v223, v146, vcc
	v_cmp_lt_i32_e32 vcc, v150, v147
	v_lshlrev_b32_e32 v205, 2, v146
	s_movk_i32 s8, 0x3f80
	v_cndmask_b32_e32 v150, v223, v150, vcc
	v_lshlrev_b32_e32 v206, 2, v150
	v_cmp_gt_i32_e32 vcc, s14, v198
	s_waitcnt vmcnt(0) lgkmcnt(0)
	v_ffbh_u32_e32 v147, v145
	v_min_u32_e32 v151, 32, v147
	v_lshlrev_b64 v[144:145], v151, v[144:145]
	v_min_u32_e32 v144, 1, v144
	v_or_b32_e32 v144, v145, v144
	v_cvt_f32_u32_e32 v160, v144
	v_sub_u32_e32 v151, 32, v151
	flat_load_dwordx4 v[144:147], v[148:149] offset:32
	v_ldexp_f32 v151, v160, v151
	v_mul_f32_e32 v151, 0x35800000, v151
	v_fmamk_f32 v151, v151, 0x3a800000, v219
	v_rsq_f32_e32 v160, v151
	flat_load_dwordx4 v[148:151], v[148:149] offset:48
	v_pk_mul_f32 v[152:153], v[200:201], v[152:153] op_sel_hi:[0,1]
	v_pk_mul_f32 v[162:163], v[124:125], v[160:161] op_sel_hi:[1,0]
	v_pk_mul_f32 v[164:165], v[126:127], v[160:161] op_sel_hi:[1,0]
	v_pk_mul_f32 v[166:167], v[120:121], v[160:161] op_sel_hi:[1,0]
	v_pk_mul_f32 v[168:169], v[122:123], v[160:161] op_sel_hi:[1,0]
	v_pk_mul_f32 v[164:165], v[164:165], v[164:165]
	v_pk_mul_f32 v[162:163], v[162:163], v[162:163]
	v_pk_mul_f32 v[168:169], v[168:169], v[168:169]
	v_pk_mul_f32 v[166:167], v[166:167], v[166:167]
	v_pk_mul_f32 v[170:171], v[118:119], v[160:161] op_sel_hi:[1,0]
	v_pk_mul_f32 v[172:173], v[116:117], v[160:161] op_sel_hi:[1,0]
	v_pk_mov_b32 v[216:217], v[162:163], v[164:165] op_sel:[1,0]
	v_mov_b32_e32 v163, v165
	v_pk_mov_b32 v[164:165], v[166:167], v[168:169] op_sel:[1,0]
	v_mov_b32_e32 v167, v169
	v_mul_f32_e32 v212, v172, v172
	v_mul_f32_e32 v214, v170, v170
	v_pk_add_f32 v[162:163], v[216:217], v[162:163]
	v_pk_add_f32 v[164:165], v[164:165], v[166:167]
	v_pk_mul_f32 v[208:209], v[114:115], v[160:161] op_sel_hi:[1,0]
	v_pk_mul_f32 v[210:211], v[112:113], v[160:161] op_sel_hi:[1,0]
	v_pk_fma_f32 v[168:169], v[172:173], v[172:173], v[212:213] op_sel_hi:[1,1,0]
	v_pk_fma_f32 v[170:171], v[170:171], v[170:171], v[214:215] op_sel_hi:[1,1,0]
	v_pk_add_f32 v[162:163], v[162:163], v[162:163] op_sel_hi:[0,1]
	v_pk_add_f32 v[164:165], v[164:165], v[164:165] op_sel_hi:[0,1]
	v_mul_f32_e32 v168, v210, v210
	v_mul_f32_e32 v170, v211, v211
	v_mul_f32_e32 v162, v208, v208
	v_mul_f32_e32 v164, v209, v209
	v_pk_add_f32 v[166:167], v[168:169], v[170:171]
	v_pk_add_f32 v[162:163], v[162:163], v[164:165]
	v_pk_mul_f32 v[156:157], v[200:201], v[156:157] op_sel_hi:[0,1]
	v_pk_add_f32 v[162:163], v[166:167], v[162:163]
	v_pk_mul_f32 v[158:159], v[200:201], v[158:159] op_sel_hi:[0,1]
	v_add_f32_e32 v162, v162, v163
	ds_bpermute_b32 v163, v205, v162
	v_pk_mul_f32 v[154:155], v[200:201], v[154:155] op_sel_hi:[0,1]
	v_pk_mul_f32 v[132:133], v[200:201], v[132:133] op_sel_hi:[0,1]
	v_pk_mul_f32 v[128:129], v[200:201], v[128:129] op_sel_hi:[0,1]
	v_pk_mul_f32 v[130:131], v[200:201], v[130:131] op_sel_hi:[0,1]
	s_waitcnt lgkmcnt(0)
	v_add_f32_e32 v164, v162, v163
	ds_bpermute_b32 v165, v206, v164
	v_mov_b32_e32 v162, v140
	v_mov_b32_e32 v163, v142
	v_mov_b32_e32 v142, v141
	v_mov_b32_e32 v141, v138
	s_waitcnt lgkmcnt(0)
	v_add_f32_e32 v140, v164, v165
	v_fmamk_f32 v140, v140, 0x3c800000, v219
	v_rsq_f32_e32 v164, v140
	v_mov_b32_e32 v140, v136
	v_mov_b32_e32 v138, v137
	v_pk_mul_f32 v[134:135], v[200:201], v[134:135] op_sel_hi:[0,1]
	v_mul_f32_e32 v136, v160, v164
	v_pk_mul_f32 v[118:119], v[118:119], v[136:137] op_sel_hi:[1,0]
	v_pk_mul_f32 v[116:117], v[116:117], v[136:137] op_sel_hi:[1,0]
	v_pk_mul_f32 v[126:127], v[126:127], v[136:137] op_sel_hi:[1,0]
	v_pk_mul_f32 v[124:125], v[124:125], v[136:137] op_sel_hi:[1,0]
	v_pk_mul_f32 v[116:117], v[156:157], v[116:117]
	v_pk_mul_f32 v[118:119], v[158:159], v[118:119]
	v_pk_mul_f32 v[122:123], v[122:123], v[136:137] op_sel_hi:[1,0]
	v_pk_mul_f32 v[120:121], v[120:121], v[136:137] op_sel_hi:[1,0]
	v_pk_mul_f32 v[114:115], v[114:115], v[136:137] op_sel_hi:[1,0]
	v_pk_mul_f32 v[112:113], v[112:113], v[136:137] op_sel_hi:[1,0]
	v_pk_mul_f32 v[124:125], v[152:153], v[124:125]
	v_pk_mul_f32 v[126:127], v[154:155], v[126:127]
	v_pk_mul_f32 v[136:137], v[162:163], v[116:117]
	v_pk_mul_f32 v[116:117], v[142:143], v[116:117]
	v_pk_mul_f32 v[164:165], v[140:141], v[118:119]
	v_pk_mul_f32 v[118:119], v[138:139], v[118:119]
	v_pk_fma_f32 v[136:137], v[142:143], v[124:125], v[136:137]
	v_pk_fma_f32 v[116:117], v[162:163], v[124:125], v[116:117] neg_lo:[0,0,1] neg_hi:[0,0,1]
	v_pk_fma_f32 v[124:125], v[138:139], v[126:127], v[164:165]
	v_pk_fma_f32 v[118:119], v[140:141], v[126:127], v[118:119] neg_lo:[0,0,1] neg_hi:[0,0,1]
	v_pk_mul_f32 v[112:113], v[132:133], v[112:113]
	s_waitcnt vmcnt(0)
	v_mov_b32_e32 v126, v144
	v_mov_b32_e32 v127, v146
	v_mov_b32_e32 v146, v145
	v_pk_mul_f32 v[120:121], v[128:129], v[120:121]
	v_pk_mul_f32 v[138:139], v[126:127], v[112:113]
	v_pk_mul_f32 v[112:113], v[146:147], v[112:113]
	v_pk_fma_f32 v[138:139], v[146:147], v[120:121], v[138:139]
	v_pk_fma_f32 v[120:121], v[126:127], v[120:121], v[112:113] neg_lo:[0,0,1] neg_hi:[0,0,1]
	v_pk_mul_f32 v[112:113], v[130:131], v[122:123]
	v_pk_mul_f32 v[114:115], v[134:135], v[114:115]
	v_mov_b32_e32 v122, v148
	v_mov_b32_e32 v123, v150
	v_mov_b32_e32 v150, v149
	v_pk_mul_f32 v[126:127], v[122:123], v[114:115]
	v_pk_mul_f32 v[114:115], v[150:151], v[114:115]
	v_pk_fma_f32 v[126:127], v[150:151], v[112:113], v[126:127]
	v_pk_fma_f32 v[122:123], v[122:123], v[112:113], v[114:115] neg_lo:[0,0,1] neg_hi:[0,0,1]
	v_lshlrev_b64 v[112:113], 11, v[188:189]
	v_lshl_add_u64 v[140:141], v[190:191], 0, v[112:113]
	v_cvt_pk_bf16_f32 v112, v116, v117
	v_cvt_pk_bf16_f32 v113, v118, v119
	v_cvt_pk_bf16_f32 v114, v120, v121
	v_cvt_pk_bf16_f32 v115, v122, v123
	flat_store_dwordx4 v[140:141], v[112:115] nt
	v_mov_b64_e32 v[172:173], v[244:245]
	s_nop 0
	v_cvt_pk_bf16_f32 v112, v136, v137
	v_cvt_pk_bf16_f32 v113, v124, v125
	v_cvt_pk_bf16_f32 v114, v138, v139
	v_cvt_pk_bf16_f32 v115, v126, v127
	flat_store_dwordx4 v[140:141], v[112:115] offset:64 nt
	s_nop 1
	v_lshl_add_u64 v[112:113], v[198:199], 3, s[6:7]
	flat_load_dwordx2 v[112:113], v[112:113]
	v_cndmask_b32_e32 v114, v230, v231, vcc
	v_bitop3_b32 v114, v114, v188, 16 bitop3:0xe0
	v_lshl_or_b32 v160, v114, 8, v207
	v_lshl_add_u64 v[114:115], s[4:5], 0, v[160:161]
	flat_load_dwordx4 v[120:123], v[114:115]
	flat_load_dwordx4 v[116:119], v[114:115] offset:16
	flat_load_dwordx4 v[124:127], v[114:115] offset:32
	v_cmp_gt_i32_e32 vcc, s14, v196
	s_waitcnt vmcnt(0) lgkmcnt(0)
	v_ffbh_u32_e32 v136, v113
	v_min_u32_e32 v136, 32, v136
	v_lshlrev_b64 v[112:113], v136, v[112:113]
	v_min_u32_e32 v112, 1, v112
	v_or_b32_e32 v112, v113, v112
	v_cvt_f32_u32_e32 v112, v112
	v_sub_u32_e32 v113, 32, v136
	v_ldexp_f32 v112, v112, v113
	v_mul_f32_e32 v112, 0x35800000, v112
	v_fmamk_f32 v112, v112, 0x3a800000, v219
	v_rsq_f32_e32 v136, v112
	flat_load_dwordx4 v[112:115], v[114:115] offset:48
	v_pk_mul_f32 v[138:139], v[108:109], v[136:137] op_sel_hi:[1,0]
	v_pk_mul_f32 v[140:141], v[110:111], v[136:137] op_sel_hi:[1,0]
	v_pk_mul_f32 v[142:143], v[104:105], v[136:137] op_sel_hi:[1,0]
	v_pk_mul_f32 v[144:145], v[106:107], v[136:137] op_sel_hi:[1,0]
	v_pk_mul_f32 v[140:141], v[140:141], v[140:141]
	v_pk_mul_f32 v[138:139], v[138:139], v[138:139]
	v_pk_mul_f32 v[144:145], v[144:145], v[144:145]
	v_pk_mul_f32 v[142:143], v[142:143], v[142:143]
	v_pk_mul_f32 v[146:147], v[102:103], v[136:137] op_sel_hi:[1,0]
	v_pk_mul_f32 v[148:149], v[100:101], v[136:137] op_sel_hi:[1,0]
	v_pk_mov_b32 v[166:167], v[138:139], v[140:141] op_sel:[1,0]
	v_mov_b32_e32 v139, v141
	v_pk_mov_b32 v[140:141], v[142:143], v[144:145] op_sel:[1,0]
	v_mov_b32_e32 v143, v145
	v_mul_f32_e32 v160, v148, v148
	v_mul_f32_e32 v164, v146, v146
	v_pk_add_f32 v[138:139], v[166:167], v[138:139]
	v_pk_add_f32 v[140:141], v[140:141], v[142:143]
	v_pk_mul_f32 v[150:151], v[98:99], v[136:137] op_sel_hi:[1,0]
	v_pk_mul_f32 v[162:163], v[96:97], v[136:137] op_sel_hi:[1,0]
	v_pk_fma_f32 v[144:145], v[148:149], v[148:149], v[160:161] op_sel_hi:[1,1,0]
	v_pk_fma_f32 v[146:147], v[146:147], v[146:147], v[164:165] op_sel_hi:[1,1,0]
	v_pk_add_f32 v[138:139], v[138:139], v[138:139] op_sel_hi:[0,1]
	v_pk_add_f32 v[140:141], v[140:141], v[140:141] op_sel_hi:[0,1]
	v_mul_f32_e32 v144, v162, v162
	v_mul_f32_e32 v146, v163, v163
	v_mul_f32_e32 v138, v150, v150
	v_mul_f32_e32 v140, v151, v151
	v_pk_add_f32 v[142:143], v[144:145], v[146:147]
	v_pk_add_f32 v[138:139], v[138:139], v[140:141]
	s_nop 0
	v_pk_add_f32 v[138:139], v[142:143], v[138:139]
	s_nop 0
	v_add_f32_e32 v137, v138, v139
	ds_bpermute_b32 v140, v205, v137
	v_mov_b32_e32 v138, v120
	v_mov_b32_e32 v120, v116
	v_mov_b32_e32 v139, v122
	v_mov_b32_e32 v122, v121
	s_waitcnt lgkmcnt(0)
	v_add_f32_e32 v137, v137, v140
	ds_bpermute_b32 v140, v206, v137
	v_mov_b32_e32 v121, v118
	v_mov_b32_e32 v118, v117
	v_mov_b32_e32 v117, v126
	v_mov_b32_e32 v126, v125
	s_waitcnt lgkmcnt(0)
	v_add_f32_e32 v116, v137, v140
	v_fmamk_f32 v116, v116, 0x3c800000, v219
	v_rsq_f32_e32 v137, v116
	v_mov_b32_e32 v116, v124
	v_mul_f32_e32 v124, v136, v137
	v_pk_mul_f32 v[102:103], v[102:103], v[124:125] op_sel_hi:[1,0]
	v_pk_mul_f32 v[100:101], v[100:101], v[124:125] op_sel_hi:[1,0]
	v_pk_mul_f32 v[96:97], v[96:97], v[124:125] op_sel_hi:[1,0]
	v_pk_mul_f32 v[110:111], v[110:111], v[124:125] op_sel_hi:[1,0]
	v_pk_mul_f32 v[108:109], v[108:109], v[124:125] op_sel_hi:[1,0]
	v_pk_mul_f32 v[104:105], v[104:105], v[124:125] op_sel_hi:[1,0]
	v_pk_mul_f32 v[100:101], v[156:157], v[100:101]
	v_pk_mul_f32 v[102:103], v[158:159], v[102:103]
	v_pk_mul_f32 v[96:97], v[132:133], v[96:97]
	v_pk_mul_f32 v[106:107], v[106:107], v[124:125] op_sel_hi:[1,0]
	v_pk_mul_f32 v[98:99], v[98:99], v[124:125] op_sel_hi:[1,0]
	v_pk_mul_f32 v[108:109], v[152:153], v[108:109]
	v_pk_mul_f32 v[110:111], v[154:155], v[110:111]
	v_pk_mul_f32 v[104:105], v[128:129], v[104:105]
	v_pk_mul_f32 v[124:125], v[138:139], v[100:101]
	v_pk_mul_f32 v[100:101], v[122:123], v[100:101]
	v_pk_mul_f32 v[136:137], v[120:121], v[102:103]
	v_pk_mul_f32 v[102:103], v[118:119], v[102:103]
	v_pk_mul_f32 v[140:141], v[116:117], v[96:97]
	v_pk_mul_f32 v[96:97], v[126:127], v[96:97]
	v_pk_mul_f32 v[98:99], v[134:135], v[98:99]
	v_pk_fma_f32 v[122:123], v[122:123], v[108:109], v[124:125]
	v_pk_fma_f32 v[100:101], v[138:139], v[108:109], v[100:101] neg_lo:[0,0,1] neg_hi:[0,0,1]
	v_pk_fma_f32 v[108:109], v[118:119], v[110:111], v[136:137]
	v_pk_fma_f32 v[102:103], v[120:121], v[110:111], v[102:103] neg_lo:[0,0,1] neg_hi:[0,0,1]
	v_pk_fma_f32 v[110:111], v[126:127], v[104:105], v[140:141]
	v_pk_fma_f32 v[104:105], v[116:117], v[104:105], v[96:97] neg_lo:[0,0,1] neg_hi:[0,0,1]
	s_waitcnt vmcnt(0)
	v_mov_b32_e32 v96, v112
	v_mov_b32_e32 v97, v114
	v_mov_b32_e32 v114, v113
	v_pk_mul_f32 v[106:107], v[130:131], v[106:107]
	v_pk_mul_f32 v[116:117], v[96:97], v[98:99]
	v_pk_mul_f32 v[98:99], v[114:115], v[98:99]
	v_pk_fma_f32 v[112:113], v[114:115], v[106:107], v[116:117]
	v_pk_fma_f32 v[106:107], v[96:97], v[106:107], v[98:99] neg_lo:[0,0,1] neg_hi:[0,0,1]
	v_lshlrev_b64 v[96:97], 11, v[198:199]
	v_lshl_add_u64 v[114:115], v[190:191], 0, v[96:97]
	v_cvt_pk_bf16_f32 v96, v100, v101
	v_cvt_pk_bf16_f32 v97, v102, v103
	v_cvt_pk_bf16_f32 v98, v104, v105
	v_cvt_pk_bf16_f32 v99, v106, v107
	flat_store_dwordx4 v[114:115], v[96:99] nt
	s_nop 1
	v_cvt_pk_bf16_f32 v96, v122, v123
	v_cvt_pk_bf16_f32 v97, v108, v109
	v_cvt_pk_bf16_f32 v98, v110, v111
	v_cvt_pk_bf16_f32 v99, v112, v113
	flat_store_dwordx4 v[114:115], v[96:99] offset:64 nt
	s_nop 1
	v_lshl_add_u64 v[96:97], v[196:197], 3, s[6:7]
	flat_load_dwordx2 v[104:105], v[96:97]
	v_cndmask_b32_e32 v96, v222, v236, vcc
	v_bitop3_b32 v96, v96, v188, 32 bitop3:0xe0
	v_lshl_or_b32 v160, v96, 8, v207
	v_lshl_add_u64 v[110:111], s[4:5], 0, v[160:161]
	flat_load_dwordx4 v[100:103], v[110:111]
	flat_load_dwordx4 v[96:99], v[110:111] offset:16
	flat_load_dwordx4 v[106:109], v[110:111] offset:32
	s_nop 0
	flat_load_dwordx4 v[110:113], v[110:111] offset:48
	v_cmp_gt_i32_e32 vcc, s14, v194
	s_waitcnt vmcnt(0) lgkmcnt(0)
	v_ffbh_u32_e32 v114, v105
	v_min_u32_e32 v114, 32, v114
	v_lshlrev_b64 v[104:105], v114, v[104:105]
	v_min_u32_e32 v104, 1, v104
	v_or_b32_e32 v104, v105, v104
	v_cvt_f32_u32_e32 v104, v104
	v_sub_u32_e32 v105, 32, v114
	v_mov_b32_e32 v116, v100
	v_mov_b32_e32 v117, v102
	v_ldexp_f32 v104, v104, v105
	v_mul_f32_e32 v104, 0x35800000, v104
	v_fmamk_f32 v104, v104, 0x3a800000, v219
	v_rsq_f32_e32 v114, v104
	v_mov_b32_e32 v102, v101
	v_lshlrev_b64 v[104:105], 11, v[196:197]
	v_lshl_add_u64 v[104:105], v[190:191], 0, v[104:105]
	v_pk_mul_f32 v[118:119], v[92:93], v[114:115] op_sel_hi:[1,0]
	v_pk_mul_f32 v[120:121], v[94:95], v[114:115] op_sel_hi:[1,0]
	v_pk_mul_f32 v[122:123], v[88:89], v[114:115] op_sel_hi:[1,0]
	v_pk_mul_f32 v[124:125], v[90:91], v[114:115] op_sel_hi:[1,0]
	v_pk_mul_f32 v[120:121], v[120:121], v[120:121]
	v_pk_mul_f32 v[118:119], v[118:119], v[118:119]
	v_pk_mul_f32 v[124:125], v[124:125], v[124:125]
	v_pk_mul_f32 v[122:123], v[122:123], v[122:123]
	v_pk_mul_f32 v[126:127], v[86:87], v[114:115] op_sel_hi:[1,0]
	v_pk_mul_f32 v[136:137], v[84:85], v[114:115] op_sel_hi:[1,0]
	v_pk_mov_b32 v[144:145], v[118:119], v[120:121] op_sel:[1,0]
	v_mov_b32_e32 v119, v121
	v_pk_mov_b32 v[120:121], v[122:123], v[124:125] op_sel:[1,0]
	v_mov_b32_e32 v123, v125
	v_mul_f32_e32 v100, v136, v136
	v_mul_f32_e32 v142, v126, v126
	v_pk_add_f32 v[118:119], v[144:145], v[118:119]
	v_pk_add_f32 v[120:121], v[120:121], v[122:123]
	v_pk_mul_f32 v[138:139], v[82:83], v[114:115] op_sel_hi:[1,0]
	v_pk_mul_f32 v[140:141], v[80:81], v[114:115] op_sel_hi:[1,0]
	v_pk_fma_f32 v[124:125], v[136:137], v[136:137], v[100:101] op_sel_hi:[1,1,0]
	v_pk_fma_f32 v[126:127], v[126:127], v[126:127], v[142:143] op_sel_hi:[1,1,0]
	v_pk_add_f32 v[118:119], v[118:119], v[118:119] op_sel_hi:[0,1]
	v_pk_add_f32 v[120:121], v[120:121], v[120:121] op_sel_hi:[0,1]
	v_mul_f32_e32 v124, v140, v140
	v_mul_f32_e32 v126, v141, v141
	v_mul_f32_e32 v118, v138, v138
	v_mul_f32_e32 v120, v139, v139
	v_pk_add_f32 v[122:123], v[124:125], v[126:127]
	v_pk_add_f32 v[118:119], v[118:119], v[120:121]
	v_mov_b32_e32 v100, v96
	v_pk_add_f32 v[118:119], v[122:123], v[118:119]
	v_mov_b32_e32 v96, v106
	v_add_f32_e32 v115, v118, v119
	ds_bpermute_b32 v118, v205, v115
	v_mov_b32_e32 v101, v98
	v_mov_b32_e32 v98, v97
	v_mov_b32_e32 v97, v108
	v_mov_b32_e32 v108, v107
	s_waitcnt lgkmcnt(0)
	v_add_f32_e32 v115, v115, v118
	ds_bpermute_b32 v118, v206, v115
	v_mov_b32_e32 v107, v112
	v_mov_b32_e32 v112, v111
	s_waitcnt lgkmcnt(0)
	v_add_f32_e32 v106, v115, v118
	v_fmamk_f32 v106, v106, 0x3c800000, v219
	v_rsq_f32_e32 v115, v106
	v_mov_b32_e32 v106, v110
	v_mul_f32_e32 v110, v114, v115
	v_pk_mul_f32 v[86:87], v[86:87], v[110:111] op_sel_hi:[1,0]
	v_pk_mul_f32 v[84:85], v[84:85], v[110:111] op_sel_hi:[1,0]
	v_pk_mul_f32 v[82:83], v[82:83], v[110:111] op_sel_hi:[1,0]
	v_pk_mul_f32 v[80:81], v[80:81], v[110:111] op_sel_hi:[1,0]
	v_pk_mul_f32 v[94:95], v[94:95], v[110:111] op_sel_hi:[1,0]
	v_pk_mul_f32 v[92:93], v[92:93], v[110:111] op_sel_hi:[1,0]
	v_pk_mul_f32 v[90:91], v[90:91], v[110:111] op_sel_hi:[1,0]
	v_pk_mul_f32 v[88:89], v[88:89], v[110:111] op_sel_hi:[1,0]
	v_pk_mul_f32 v[84:85], v[156:157], v[84:85]
	v_pk_mul_f32 v[86:87], v[158:159], v[86:87]
	v_pk_mul_f32 v[80:81], v[132:133], v[80:81]
	v_pk_mul_f32 v[82:83], v[134:135], v[82:83]
	v_pk_mul_f32 v[92:93], v[152:153], v[92:93]
	v_pk_mul_f32 v[94:95], v[154:155], v[94:95]
	v_pk_mul_f32 v[110:111], v[128:129], v[88:89]
	v_pk_mul_f32 v[114:115], v[130:131], v[90:91]
	v_pk_mul_f32 v[88:89], v[116:117], v[84:85]
	v_pk_mul_f32 v[90:91], v[102:103], v[84:85]
	v_pk_mul_f32 v[118:119], v[100:101], v[86:87]
	v_pk_mul_f32 v[86:87], v[98:99], v[86:87]
	v_pk_mul_f32 v[122:123], v[108:109], v[80:81]
	v_pk_mul_f32 v[126:127], v[112:113], v[82:83]
	v_pk_mul_f32 v[120:121], v[96:97], v[80:81]
	v_pk_mul_f32 v[124:125], v[106:107], v[82:83]
	v_pk_fma_f32 v[84:85], v[102:103], v[92:93], v[88:89]
	v_pk_fma_f32 v[88:89], v[116:117], v[92:93], v[90:91] neg_lo:[0,0,1] neg_hi:[0,0,1]
	v_pk_fma_f32 v[80:81], v[98:99], v[94:95], v[118:119]
	v_pk_fma_f32 v[90:91], v[100:101], v[94:95], v[86:87] neg_lo:[0,0,1] neg_hi:[0,0,1]
	v_pk_fma_f32 v[92:93], v[96:97], v[110:111], v[122:123] neg_lo:[0,0,1] neg_hi:[0,0,1]
	v_pk_fma_f32 v[94:95], v[106:107], v[114:115], v[126:127] neg_lo:[0,0,1] neg_hi:[0,0,1]
	v_pk_fma_f32 v[82:83], v[108:109], v[110:111], v[120:121]
	v_pk_fma_f32 v[86:87], v[112:113], v[114:115], v[124:125]
	v_cvt_pk_bf16_f32 v88, v88, v89
	v_cvt_pk_bf16_f32 v89, v90, v91
	v_cvt_pk_bf16_f32 v90, v92, v93
	v_cvt_pk_bf16_f32 v91, v94, v95
	flat_store_dwordx4 v[104:105], v[88:91] nt
	s_nop 1
	v_cvt_pk_bf16_f32 v88, v84, v85
	v_cvt_pk_bf16_f32 v89, v80, v81
	v_cvt_pk_bf16_f32 v90, v82, v83
	v_cvt_pk_bf16_f32 v91, v86, v87
	flat_store_dwordx4 v[104:105], v[88:91] offset:64 nt
	v_lshl_add_u64 v[80:81], v[194:195], 3, s[6:7]
	flat_load_dwordx2 v[88:89], v[80:81]
	v_cndmask_b32_e32 v80, v232, v243, vcc
	v_bitop3_b32 v80, v80, v188, 48 bitop3:0xe0
	v_lshl_or_b32 v160, v80, 8, v207
	v_lshl_add_u64 v[94:95], s[4:5], 0, v[160:161]
	flat_load_dwordx4 v[84:87], v[94:95]
	flat_load_dwordx4 v[80:83], v[94:95] offset:16
	flat_load_dwordx4 v[90:93], v[94:95] offset:32
	s_nop 0
	flat_load_dwordx4 v[94:97], v[94:95] offset:48
	v_cmp_gt_i32_e32 vcc, s8, v188
	s_movk_i32 s8, 0x3f70
	s_waitcnt vmcnt(0) lgkmcnt(0)
	v_ffbh_u32_e32 v98, v89
	v_min_u32_e32 v98, 32, v98
	v_lshlrev_b64 v[88:89], v98, v[88:89]
	v_min_u32_e32 v88, 1, v88
	v_or_b32_e32 v88, v89, v88
	v_cvt_f32_u32_e32 v88, v88
	v_sub_u32_e32 v89, 32, v98
	v_mov_b32_e32 v100, v84
	v_mov_b32_e32 v101, v86
	v_ldexp_f32 v88, v88, v89
	v_mul_f32_e32 v88, 0x35800000, v88
	v_fmamk_f32 v88, v88, 0x3a800000, v219
	v_rsq_f32_e32 v98, v88
	v_mov_b32_e32 v86, v85
	v_lshlrev_b64 v[88:89], 11, v[194:195]
	v_lshl_add_u64 v[88:89], v[190:191], 0, v[88:89]
	v_pk_mul_f32 v[102:103], v[76:77], v[98:99] op_sel_hi:[1,0]
	v_pk_mul_f32 v[104:105], v[78:79], v[98:99] op_sel_hi:[1,0]
	v_pk_mul_f32 v[106:107], v[72:73], v[98:99] op_sel_hi:[1,0]
	v_pk_mul_f32 v[108:109], v[74:75], v[98:99] op_sel_hi:[1,0]
	v_pk_mul_f32 v[104:105], v[104:105], v[104:105]
	v_pk_mul_f32 v[102:103], v[102:103], v[102:103]
	v_pk_mul_f32 v[108:109], v[108:109], v[108:109]
	v_pk_mul_f32 v[106:107], v[106:107], v[106:107]
	v_pk_mul_f32 v[110:111], v[70:71], v[98:99] op_sel_hi:[1,0]
	v_pk_mul_f32 v[112:113], v[68:69], v[98:99] op_sel_hi:[1,0]
	v_pk_mov_b32 v[120:121], v[102:103], v[104:105] op_sel:[1,0]
	v_mov_b32_e32 v103, v105
	v_pk_mov_b32 v[104:105], v[106:107], v[108:109] op_sel:[1,0]
	v_mov_b32_e32 v107, v109
	v_mul_f32_e32 v84, v112, v112
	v_mul_f32_e32 v118, v110, v110
	v_pk_add_f32 v[102:103], v[120:121], v[102:103]
	v_pk_add_f32 v[104:105], v[104:105], v[106:107]
	v_pk_mul_f32 v[114:115], v[66:67], v[98:99] op_sel_hi:[1,0]
	v_pk_mul_f32 v[116:117], v[64:65], v[98:99] op_sel_hi:[1,0]
	v_pk_fma_f32 v[108:109], v[112:113], v[112:113], v[84:85] op_sel_hi:[1,1,0]
	v_pk_fma_f32 v[110:111], v[110:111], v[110:111], v[118:119] op_sel_hi:[1,1,0]
	v_pk_add_f32 v[102:103], v[102:103], v[102:103] op_sel_hi:[0,1]
	v_pk_add_f32 v[104:105], v[104:105], v[104:105] op_sel_hi:[0,1]
	v_mul_f32_e32 v108, v116, v116
	v_mul_f32_e32 v110, v117, v117
	v_mul_f32_e32 v102, v114, v114
	v_mul_f32_e32 v104, v115, v115
	v_pk_add_f32 v[106:107], v[108:109], v[110:111]
	v_pk_add_f32 v[102:103], v[102:103], v[104:105]
	v_mov_b32_e32 v84, v80
	v_pk_add_f32 v[102:103], v[106:107], v[102:103]
	v_mov_b32_e32 v80, v90
	v_add_f32_e32 v99, v102, v103
	ds_bpermute_b32 v102, v205, v99
	v_mov_b32_e32 v85, v82
	v_mov_b32_e32 v82, v81
	v_mov_b32_e32 v81, v92
	v_mov_b32_e32 v92, v91
	s_waitcnt lgkmcnt(0)
	v_add_f32_e32 v99, v99, v102
	ds_bpermute_b32 v102, v206, v99
	v_mov_b32_e32 v91, v96
	v_mov_b32_e32 v96, v95
	s_waitcnt lgkmcnt(0)
	v_add_f32_e32 v90, v99, v102
	v_fmamk_f32 v90, v90, 0x3c800000, v219
	v_rsq_f32_e32 v99, v90
	v_mov_b32_e32 v90, v94
	v_mul_f32_e32 v94, v98, v99
	v_pk_mul_f32 v[70:71], v[70:71], v[94:95] op_sel_hi:[1,0]
	v_pk_mul_f32 v[68:69], v[68:69], v[94:95] op_sel_hi:[1,0]
	v_pk_mul_f32 v[66:67], v[66:67], v[94:95] op_sel_hi:[1,0]
	v_pk_mul_f32 v[64:65], v[64:65], v[94:95] op_sel_hi:[1,0]
	v_pk_mul_f32 v[78:79], v[78:79], v[94:95] op_sel_hi:[1,0]
	v_pk_mul_f32 v[76:77], v[76:77], v[94:95] op_sel_hi:[1,0]
	v_pk_mul_f32 v[74:75], v[74:75], v[94:95] op_sel_hi:[1,0]
	v_pk_mul_f32 v[72:73], v[72:73], v[94:95] op_sel_hi:[1,0]
	v_pk_mul_f32 v[68:69], v[156:157], v[68:69]
	v_pk_mul_f32 v[70:71], v[158:159], v[70:71]
	v_pk_mul_f32 v[64:65], v[132:133], v[64:65]
	v_pk_mul_f32 v[66:67], v[134:135], v[66:67]
	v_pk_mul_f32 v[76:77], v[152:153], v[76:77]
	v_pk_mul_f32 v[78:79], v[154:155], v[78:79]
	v_pk_mul_f32 v[94:95], v[128:129], v[72:73]
	v_pk_mul_f32 v[98:99], v[130:131], v[74:75]
	v_pk_mul_f32 v[72:73], v[100:101], v[68:69]
	v_pk_mul_f32 v[68:69], v[86:87], v[68:69]
	v_pk_mul_f32 v[74:75], v[84:85], v[70:71]
	v_pk_mul_f32 v[70:71], v[82:83], v[70:71]
	v_pk_mul_f32 v[104:105], v[92:93], v[64:65]
	v_pk_mul_f32 v[108:109], v[96:97], v[66:67]
	v_pk_mul_f32 v[102:103], v[80:81], v[64:65]
	v_pk_mul_f32 v[106:107], v[90:91], v[66:67]
	v_pk_fma_f32 v[64:65], v[86:87], v[76:77], v[72:73]
	v_pk_fma_f32 v[72:73], v[100:101], v[76:77], v[68:69] neg_lo:[0,0,1] neg_hi:[0,0,1]
	v_pk_fma_f32 v[66:67], v[82:83], v[78:79], v[74:75]
	v_pk_fma_f32 v[74:75], v[84:85], v[78:79], v[70:71] neg_lo:[0,0,1] neg_hi:[0,0,1]
	v_pk_fma_f32 v[76:77], v[80:81], v[94:95], v[104:105] neg_lo:[0,0,1] neg_hi:[0,0,1]
	v_pk_fma_f32 v[78:79], v[90:91], v[98:99], v[108:109] neg_lo:[0,0,1] neg_hi:[0,0,1]
	v_pk_fma_f32 v[68:69], v[92:93], v[94:95], v[102:103]
	v_pk_fma_f32 v[70:71], v[96:97], v[98:99], v[106:107]
	v_cvt_pk_bf16_f32 v72, v72, v73
	v_cvt_pk_bf16_f32 v73, v74, v75
	v_cvt_pk_bf16_f32 v74, v76, v77
	v_cvt_pk_bf16_f32 v75, v78, v79
	v_cvt_pk_bf16_f32 v64, v64, v65
	v_cvt_pk_bf16_f32 v65, v66, v67
	v_cvt_pk_bf16_f32 v66, v68, v69
	v_cvt_pk_bf16_f32 v67, v70, v71
	flat_store_dwordx4 v[88:89], v[72:75] nt
	flat_store_dwordx4 v[88:89], v[64:67] offset:64 nt
	flat_load_dwordx2 v[74:75], v[192:193] offset:1024
	v_add_u32_e32 v72, 0x80, v188
	v_cndmask_b32_e32 v64, v228, v229, vcc
	v_and_b32_e32 v64, v64, v72
	v_lshl_or_b32 v160, v64, 8, v207
	v_lshl_add_u64 v[80:81], s[4:5], 0, v[160:161]
	flat_load_dwordx4 v[68:71], v[80:81]
	flat_load_dwordx4 v[64:67], v[80:81] offset:16
	flat_load_dwordx4 v[76:79], v[80:81] offset:32
	s_nop 0
	flat_load_dwordx4 v[80:83], v[80:81] offset:48
	v_cmp_gt_i32_e32 vcc, s8, v188
	s_movk_i32 s8, 0x3f60
	s_waitcnt vmcnt(0) lgkmcnt(0)
	v_ffbh_u32_e32 v73, v75
	v_min_u32_e32 v84, 32, v73
	v_lshlrev_b64 v[74:75], v84, v[74:75]
	v_min_u32_e32 v73, 1, v74
	v_or_b32_e32 v73, v75, v73
	v_cvt_f32_u32_e32 v74, v73
	v_sub_u32_e32 v75, 32, v84
	v_mov_b32_e32 v84, v68
	v_mov_b32_e32 v85, v70
	v_ldexp_f32 v74, v74, v75
	v_mul_f32_e32 v74, 0x35800000, v74
	v_fmamk_f32 v74, v74, 0x3a800000, v219
	v_rsq_f32_e32 v74, v74
	v_mov_b32_e32 v70, v69
	v_ashrrev_i32_e32 v73, 31, v72
	v_lshlrev_b64 v[72:73], 11, v[72:73]
	v_pk_mul_f32 v[86:87], v[60:61], v[74:75] op_sel_hi:[1,0]
	v_pk_mul_f32 v[88:89], v[62:63], v[74:75] op_sel_hi:[1,0]
	v_pk_mul_f32 v[90:91], v[56:57], v[74:75] op_sel_hi:[1,0]
	v_pk_mul_f32 v[92:93], v[58:59], v[74:75] op_sel_hi:[1,0]
	v_pk_mul_f32 v[88:89], v[88:89], v[88:89]
	v_pk_mul_f32 v[86:87], v[86:87], v[86:87]
	v_pk_mul_f32 v[92:93], v[92:93], v[92:93]
	v_pk_mul_f32 v[90:91], v[90:91], v[90:91]
	v_pk_mul_f32 v[94:95], v[54:55], v[74:75] op_sel_hi:[1,0]
	v_pk_mul_f32 v[96:97], v[52:53], v[74:75] op_sel_hi:[1,0]
	v_pk_mov_b32 v[104:105], v[86:87], v[88:89] op_sel:[1,0]
	v_mov_b32_e32 v87, v89
	v_pk_mov_b32 v[88:89], v[90:91], v[92:93] op_sel:[1,0]
	v_mov_b32_e32 v91, v93
	v_mul_f32_e32 v68, v96, v96
	v_mul_f32_e32 v102, v94, v94
	v_pk_add_f32 v[86:87], v[104:105], v[86:87]
	v_pk_add_f32 v[88:89], v[88:89], v[90:91]
	v_pk_mul_f32 v[98:99], v[50:51], v[74:75] op_sel_hi:[1,0]
	v_pk_mul_f32 v[100:101], v[48:49], v[74:75] op_sel_hi:[1,0]
	v_pk_fma_f32 v[92:93], v[96:97], v[96:97], v[68:69] op_sel_hi:[1,1,0]
	v_pk_fma_f32 v[94:95], v[94:95], v[94:95], v[102:103] op_sel_hi:[1,1,0]
	v_pk_add_f32 v[86:87], v[86:87], v[86:87] op_sel_hi:[0,1]
	v_pk_add_f32 v[88:89], v[88:89], v[88:89] op_sel_hi:[0,1]
	v_mul_f32_e32 v92, v100, v100
	v_mul_f32_e32 v94, v101, v101
	v_mul_f32_e32 v86, v98, v98
	v_mul_f32_e32 v88, v99, v99
	v_pk_add_f32 v[90:91], v[92:93], v[94:95]
	v_pk_add_f32 v[86:87], v[86:87], v[88:89]
	v_mov_b32_e32 v68, v64
	v_pk_add_f32 v[86:87], v[90:91], v[86:87]
	v_mov_b32_e32 v69, v66
	v_add_f32_e32 v75, v86, v87
	ds_bpermute_b32 v86, v205, v75
	v_mov_b32_e32 v66, v65
	v_mov_b32_e32 v65, v78
	v_mov_b32_e32 v78, v77
	v_mov_b32_e32 v77, v82
	s_waitcnt lgkmcnt(0)
	v_add_f32_e32 v75, v75, v86
	ds_bpermute_b32 v86, v206, v75
	v_mov_b32_e32 v82, v81
	v_mov_b32_e32 v64, v76
	v_mov_b32_e32 v76, v80
	v_lshl_add_u64 v[72:73], v[190:191], 0, v[72:73]
	s_waitcnt lgkmcnt(0)
	v_add_f32_e32 v75, v75, v86
	v_fmamk_f32 v75, v75, 0x3c800000, v219
	v_rsq_f32_e32 v75, v75
	s_nop 0
	v_mul_f32_e32 v74, v74, v75
	v_pk_mul_f32 v[54:55], v[54:55], v[74:75] op_sel_hi:[1,0]
	v_pk_mul_f32 v[52:53], v[52:53], v[74:75] op_sel_hi:[1,0]
	v_pk_mul_f32 v[50:51], v[50:51], v[74:75] op_sel_hi:[1,0]
	v_pk_mul_f32 v[48:49], v[48:49], v[74:75] op_sel_hi:[1,0]
	v_pk_mul_f32 v[62:63], v[62:63], v[74:75] op_sel_hi:[1,0]
	v_pk_mul_f32 v[60:61], v[60:61], v[74:75] op_sel_hi:[1,0]
	v_pk_mul_f32 v[58:59], v[58:59], v[74:75] op_sel_hi:[1,0]
	v_pk_mul_f32 v[56:57], v[56:57], v[74:75] op_sel_hi:[1,0]
	v_pk_mul_f32 v[52:53], v[156:157], v[52:53]
	v_pk_mul_f32 v[54:55], v[158:159], v[54:55]
	v_pk_mul_f32 v[48:49], v[132:133], v[48:49]
	v_pk_mul_f32 v[50:51], v[134:135], v[50:51]
	v_pk_mul_f32 v[60:61], v[152:153], v[60:61]
	v_pk_mul_f32 v[62:63], v[154:155], v[62:63]
	v_pk_mul_f32 v[74:75], v[128:129], v[56:57]
	v_pk_mul_f32 v[80:81], v[130:131], v[58:59]
	v_pk_mul_f32 v[56:57], v[84:85], v[52:53]
	v_pk_mul_f32 v[52:53], v[70:71], v[52:53]
	v_pk_mul_f32 v[58:59], v[68:69], v[54:55]
	v_pk_mul_f32 v[54:55], v[66:67], v[54:55]
	v_pk_mul_f32 v[88:89], v[78:79], v[48:49]
	v_pk_mul_f32 v[92:93], v[82:83], v[50:51]
	v_pk_mul_f32 v[86:87], v[64:65], v[48:49]
	v_pk_mul_f32 v[90:91], v[76:77], v[50:51]
	v_pk_fma_f32 v[48:49], v[70:71], v[60:61], v[56:57]
	v_pk_fma_f32 v[56:57], v[84:85], v[60:61], v[52:53] neg_lo:[0,0,1] neg_hi:[0,0,1]
	v_pk_fma_f32 v[50:51], v[66:67], v[62:63], v[58:59]
	v_pk_fma_f32 v[58:59], v[68:69], v[62:63], v[54:55] neg_lo:[0,0,1] neg_hi:[0,0,1]
	v_pk_fma_f32 v[60:61], v[64:65], v[74:75], v[88:89] neg_lo:[0,0,1] neg_hi:[0,0,1]
	v_pk_fma_f32 v[62:63], v[76:77], v[80:81], v[92:93] neg_lo:[0,0,1] neg_hi:[0,0,1]
	v_pk_fma_f32 v[52:53], v[78:79], v[74:75], v[86:87]
	v_pk_fma_f32 v[54:55], v[82:83], v[80:81], v[90:91]
	v_cvt_pk_bf16_f32 v56, v56, v57
	v_cvt_pk_bf16_f32 v57, v58, v59
	v_cvt_pk_bf16_f32 v58, v60, v61
	v_cvt_pk_bf16_f32 v59, v62, v63
	v_cvt_pk_bf16_f32 v48, v48, v49
	v_cvt_pk_bf16_f32 v49, v50, v51
	v_cvt_pk_bf16_f32 v50, v52, v53
	v_cvt_pk_bf16_f32 v51, v54, v55
	flat_store_dwordx4 v[72:73], v[56:59] nt
	flat_store_dwordx4 v[72:73], v[48:51] offset:64 nt
	flat_load_dwordx2 v[58:59], v[192:193] offset:1152
	v_add_u32_e32 v56, 0x90, v188
	v_cndmask_b32_e32 v48, v230, v231, vcc
	v_and_b32_e32 v48, v48, v56
	v_lshl_or_b32 v160, v48, 8, v207
	v_lshl_add_u64 v[64:65], s[4:5], 0, v[160:161]
	flat_load_dwordx4 v[52:55], v[64:65]
	flat_load_dwordx4 v[48:51], v[64:65] offset:16
	flat_load_dwordx4 v[60:63], v[64:65] offset:32
	s_nop 0
	flat_load_dwordx4 v[64:67], v[64:65] offset:48
	v_cmp_gt_i32_e32 vcc, s8, v188
	s_movk_i32 s8, 0x3f50
	s_waitcnt vmcnt(0) lgkmcnt(0)
	v_ffbh_u32_e32 v57, v59
	v_min_u32_e32 v68, 32, v57
	v_lshlrev_b64 v[58:59], v68, v[58:59]
	v_min_u32_e32 v57, 1, v58
	v_or_b32_e32 v57, v59, v57
	v_cvt_f32_u32_e32 v58, v57
	v_sub_u32_e32 v59, 32, v68
	v_mov_b32_e32 v68, v52
	v_mov_b32_e32 v69, v54
	v_ldexp_f32 v58, v58, v59
	v_mul_f32_e32 v58, 0x35800000, v58
	v_fmamk_f32 v58, v58, 0x3a800000, v219
	v_rsq_f32_e32 v58, v58
	v_mov_b32_e32 v54, v53
	v_ashrrev_i32_e32 v57, 31, v56
	v_lshlrev_b64 v[56:57], 11, v[56:57]
	v_pk_mul_f32 v[70:71], v[44:45], v[58:59] op_sel_hi:[1,0]
	v_pk_mul_f32 v[72:73], v[46:47], v[58:59] op_sel_hi:[1,0]
	v_pk_mul_f32 v[74:75], v[40:41], v[58:59] op_sel_hi:[1,0]
	v_pk_mul_f32 v[76:77], v[42:43], v[58:59] op_sel_hi:[1,0]
	v_pk_mul_f32 v[72:73], v[72:73], v[72:73]
	v_pk_mul_f32 v[70:71], v[70:71], v[70:71]
	v_pk_mul_f32 v[76:77], v[76:77], v[76:77]
	v_pk_mul_f32 v[74:75], v[74:75], v[74:75]
	v_pk_mul_f32 v[78:79], v[38:39], v[58:59] op_sel_hi:[1,0]
	v_pk_mul_f32 v[80:81], v[36:37], v[58:59] op_sel_hi:[1,0]
	v_pk_mov_b32 v[88:89], v[70:71], v[72:73] op_sel:[1,0]
	v_mov_b32_e32 v71, v73
	v_pk_mov_b32 v[72:73], v[74:75], v[76:77] op_sel:[1,0]
	v_mov_b32_e32 v75, v77
	v_mul_f32_e32 v52, v80, v80
	v_mul_f32_e32 v86, v78, v78
	v_pk_add_f32 v[70:71], v[88:89], v[70:71]
	v_pk_add_f32 v[72:73], v[72:73], v[74:75]
	v_pk_mul_f32 v[82:83], v[34:35], v[58:59] op_sel_hi:[1,0]
	v_pk_mul_f32 v[84:85], v[32:33], v[58:59] op_sel_hi:[1,0]
	v_pk_fma_f32 v[76:77], v[80:81], v[80:81], v[52:53] op_sel_hi:[1,1,0]
	v_pk_fma_f32 v[78:79], v[78:79], v[78:79], v[86:87] op_sel_hi:[1,1,0]
	v_pk_add_f32 v[70:71], v[70:71], v[70:71] op_sel_hi:[0,1]
	v_pk_add_f32 v[72:73], v[72:73], v[72:73] op_sel_hi:[0,1]
	v_mul_f32_e32 v76, v84, v84
	v_mul_f32_e32 v78, v85, v85
	v_mul_f32_e32 v70, v82, v82
	v_mul_f32_e32 v72, v83, v83
	v_pk_add_f32 v[74:75], v[76:77], v[78:79]
	v_pk_add_f32 v[70:71], v[70:71], v[72:73]
	v_mov_b32_e32 v52, v48
	v_pk_add_f32 v[70:71], v[74:75], v[70:71]
	v_mov_b32_e32 v53, v50
	v_add_f32_e32 v59, v70, v71
	ds_bpermute_b32 v70, v205, v59
	v_mov_b32_e32 v50, v49
	v_mov_b32_e32 v49, v62
	v_mov_b32_e32 v62, v61
	v_mov_b32_e32 v61, v66
	s_waitcnt lgkmcnt(0)
	v_add_f32_e32 v59, v59, v70
	ds_bpermute_b32 v70, v206, v59
	v_mov_b32_e32 v66, v65
	v_mov_b32_e32 v48, v60
	v_mov_b32_e32 v60, v64
	v_lshl_add_u64 v[56:57], v[190:191], 0, v[56:57]
	s_waitcnt lgkmcnt(0)
	v_add_f32_e32 v59, v59, v70
	v_fmamk_f32 v59, v59, 0x3c800000, v219
	v_rsq_f32_e32 v59, v59
	s_nop 0
	v_mul_f32_e32 v58, v58, v59
	v_pk_mul_f32 v[38:39], v[38:39], v[58:59] op_sel_hi:[1,0]
	v_pk_mul_f32 v[36:37], v[36:37], v[58:59] op_sel_hi:[1,0]
	v_pk_mul_f32 v[34:35], v[34:35], v[58:59] op_sel_hi:[1,0]
	v_pk_mul_f32 v[32:33], v[32:33], v[58:59] op_sel_hi:[1,0]
	v_pk_mul_f32 v[46:47], v[46:47], v[58:59] op_sel_hi:[1,0]
	v_pk_mul_f32 v[44:45], v[44:45], v[58:59] op_sel_hi:[1,0]
	v_pk_mul_f32 v[42:43], v[42:43], v[58:59] op_sel_hi:[1,0]
	v_pk_mul_f32 v[40:41], v[40:41], v[58:59] op_sel_hi:[1,0]
	v_pk_mul_f32 v[36:37], v[156:157], v[36:37]
	v_pk_mul_f32 v[38:39], v[158:159], v[38:39]
	v_pk_mul_f32 v[32:33], v[132:133], v[32:33]
	v_pk_mul_f32 v[34:35], v[134:135], v[34:35]
	v_pk_mul_f32 v[44:45], v[152:153], v[44:45]
	v_pk_mul_f32 v[46:47], v[154:155], v[46:47]
	v_pk_mul_f32 v[58:59], v[128:129], v[40:41]
	v_pk_mul_f32 v[64:65], v[130:131], v[42:43]
	v_pk_mul_f32 v[40:41], v[68:69], v[36:37]
	v_pk_mul_f32 v[36:37], v[54:55], v[36:37]
	v_pk_mul_f32 v[42:43], v[52:53], v[38:39]
	v_pk_mul_f32 v[38:39], v[50:51], v[38:39]
	v_pk_mul_f32 v[72:73], v[62:63], v[32:33]
	v_pk_mul_f32 v[76:77], v[66:67], v[34:35]
	v_pk_mul_f32 v[70:71], v[48:49], v[32:33]
	v_pk_mul_f32 v[74:75], v[60:61], v[34:35]
	v_pk_fma_f32 v[32:33], v[54:55], v[44:45], v[40:41]
	v_pk_fma_f32 v[40:41], v[68:69], v[44:45], v[36:37] neg_lo:[0,0,1] neg_hi:[0,0,1]
	v_pk_fma_f32 v[34:35], v[50:51], v[46:47], v[42:43]
	v_pk_fma_f32 v[42:43], v[52:53], v[46:47], v[38:39] neg_lo:[0,0,1] neg_hi:[0,0,1]
	v_pk_fma_f32 v[44:45], v[48:49], v[58:59], v[72:73] neg_lo:[0,0,1] neg_hi:[0,0,1]
	v_pk_fma_f32 v[46:47], v[60:61], v[64:65], v[76:77] neg_lo:[0,0,1] neg_hi:[0,0,1]
	v_pk_fma_f32 v[36:37], v[62:63], v[58:59], v[70:71]
	v_pk_fma_f32 v[38:39], v[66:67], v[64:65], v[74:75]
	v_cvt_pk_bf16_f32 v40, v40, v41
	v_cvt_pk_bf16_f32 v41, v42, v43
	v_cvt_pk_bf16_f32 v42, v44, v45
	v_cvt_pk_bf16_f32 v43, v46, v47
	v_cvt_pk_bf16_f32 v32, v32, v33
	v_cvt_pk_bf16_f32 v33, v34, v35
	v_cvt_pk_bf16_f32 v34, v36, v37
	v_cvt_pk_bf16_f32 v35, v38, v39
	flat_store_dwordx4 v[56:57], v[40:43] nt
	flat_store_dwordx4 v[56:57], v[32:35] offset:64 nt
	flat_load_dwordx2 v[42:43], v[192:193] offset:1280
	v_add_u32_e32 v40, 0xa0, v188
	v_cndmask_b32_e32 v32, v222, v236, vcc
	v_and_b32_e32 v32, v32, v40
	v_lshl_or_b32 v160, v32, 8, v207
	v_lshl_add_u64 v[48:49], s[4:5], 0, v[160:161]
	flat_load_dwordx4 v[36:39], v[48:49]
	flat_load_dwordx4 v[32:35], v[48:49] offset:16
	flat_load_dwordx4 v[44:47], v[48:49] offset:32
	s_nop 0
	flat_load_dwordx4 v[48:51], v[48:49] offset:48
	v_cmp_gt_i32_e32 vcc, s8, v188
	s_waitcnt vmcnt(0) lgkmcnt(0)
	v_ffbh_u32_e32 v41, v43
	v_min_u32_e32 v52, 32, v41
	v_lshlrev_b64 v[42:43], v52, v[42:43]
	v_min_u32_e32 v41, 1, v42
	v_or_b32_e32 v41, v43, v41
	v_cvt_f32_u32_e32 v42, v41
	v_sub_u32_e32 v43, 32, v52
	v_mov_b32_e32 v52, v36
	v_mov_b32_e32 v53, v38
	v_ldexp_f32 v42, v42, v43
	v_mul_f32_e32 v42, 0x35800000, v42
	v_fmamk_f32 v42, v42, 0x3a800000, v219
	v_rsq_f32_e32 v42, v42
	v_mov_b32_e32 v38, v37
	v_ashrrev_i32_e32 v41, 31, v40
	v_lshlrev_b64 v[40:41], 11, v[40:41]
	v_pk_mul_f32 v[54:55], v[28:29], v[42:43] op_sel_hi:[1,0]
	v_pk_mul_f32 v[56:57], v[30:31], v[42:43] op_sel_hi:[1,0]
	v_pk_mul_f32 v[58:59], v[24:25], v[42:43] op_sel_hi:[1,0]
	v_pk_mul_f32 v[60:61], v[26:27], v[42:43] op_sel_hi:[1,0]
	v_pk_mul_f32 v[56:57], v[56:57], v[56:57]
	v_pk_mul_f32 v[54:55], v[54:55], v[54:55]
	v_pk_mul_f32 v[60:61], v[60:61], v[60:61]
	v_pk_mul_f32 v[58:59], v[58:59], v[58:59]
	v_pk_mul_f32 v[62:63], v[22:23], v[42:43] op_sel_hi:[1,0]
	v_pk_mul_f32 v[64:65], v[20:21], v[42:43] op_sel_hi:[1,0]
	v_pk_mov_b32 v[72:73], v[54:55], v[56:57] op_sel:[1,0]
	v_mov_b32_e32 v55, v57
	v_pk_mov_b32 v[56:57], v[58:59], v[60:61] op_sel:[1,0]
	v_mov_b32_e32 v59, v61
	v_mul_f32_e32 v36, v64, v64
	v_mul_f32_e32 v70, v62, v62
	v_pk_add_f32 v[54:55], v[72:73], v[54:55]
	v_pk_add_f32 v[56:57], v[56:57], v[58:59]
	v_pk_mul_f32 v[66:67], v[18:19], v[42:43] op_sel_hi:[1,0]
	v_pk_mul_f32 v[68:69], v[16:17], v[42:43] op_sel_hi:[1,0]
	v_pk_fma_f32 v[60:61], v[64:65], v[64:65], v[36:37] op_sel_hi:[1,1,0]
	v_pk_fma_f32 v[62:63], v[62:63], v[62:63], v[70:71] op_sel_hi:[1,1,0]
	v_pk_add_f32 v[54:55], v[54:55], v[54:55] op_sel_hi:[0,1]
	v_pk_add_f32 v[56:57], v[56:57], v[56:57] op_sel_hi:[0,1]
	v_mul_f32_e32 v60, v68, v68
	v_mul_f32_e32 v62, v69, v69
	v_mul_f32_e32 v54, v66, v66
	v_mul_f32_e32 v56, v67, v67
	v_pk_add_f32 v[58:59], v[60:61], v[62:63]
	v_pk_add_f32 v[54:55], v[54:55], v[56:57]
	v_mov_b32_e32 v36, v32
	v_pk_add_f32 v[54:55], v[58:59], v[54:55]
	v_mov_b32_e32 v37, v34
	v_add_f32_e32 v43, v54, v55
	ds_bpermute_b32 v54, v205, v43
	v_mov_b32_e32 v34, v33
	v_mov_b32_e32 v33, v46
	v_mov_b32_e32 v46, v45
	v_mov_b32_e32 v45, v50
	s_waitcnt lgkmcnt(0)
	v_add_f32_e32 v43, v43, v54
	ds_bpermute_b32 v54, v206, v43
	v_mov_b32_e32 v50, v49
	v_mov_b32_e32 v32, v44
	v_mov_b32_e32 v44, v48
	v_lshl_add_u64 v[40:41], v[190:191], 0, v[40:41]
	s_waitcnt lgkmcnt(0)
	v_add_f32_e32 v43, v43, v54
	v_fmamk_f32 v43, v43, 0x3c800000, v219
	v_rsq_f32_e32 v43, v43
	s_nop 0
	v_mul_f32_e32 v42, v42, v43
	v_pk_mul_f32 v[22:23], v[22:23], v[42:43] op_sel_hi:[1,0]
	v_pk_mul_f32 v[20:21], v[20:21], v[42:43] op_sel_hi:[1,0]
	v_pk_mul_f32 v[18:19], v[18:19], v[42:43] op_sel_hi:[1,0]
	v_pk_mul_f32 v[16:17], v[16:17], v[42:43] op_sel_hi:[1,0]
	v_pk_mul_f32 v[30:31], v[30:31], v[42:43] op_sel_hi:[1,0]
	v_pk_mul_f32 v[28:29], v[28:29], v[42:43] op_sel_hi:[1,0]
	v_pk_mul_f32 v[26:27], v[26:27], v[42:43] op_sel_hi:[1,0]
	v_pk_mul_f32 v[24:25], v[24:25], v[42:43] op_sel_hi:[1,0]
	v_pk_mul_f32 v[20:21], v[156:157], v[20:21]
	v_pk_mul_f32 v[22:23], v[158:159], v[22:23]
	v_pk_mul_f32 v[16:17], v[132:133], v[16:17]
	v_pk_mul_f32 v[18:19], v[134:135], v[18:19]
	v_pk_mul_f32 v[28:29], v[152:153], v[28:29]
	v_pk_mul_f32 v[30:31], v[154:155], v[30:31]
	v_pk_mul_f32 v[42:43], v[128:129], v[24:25]
	v_pk_mul_f32 v[48:49], v[130:131], v[26:27]
	v_pk_mul_f32 v[24:25], v[52:53], v[20:21]
	v_pk_mul_f32 v[20:21], v[38:39], v[20:21]
	v_pk_mul_f32 v[26:27], v[36:37], v[22:23]
	v_pk_mul_f32 v[22:23], v[34:35], v[22:23]
	v_pk_mul_f32 v[56:57], v[46:47], v[16:17]
	v_pk_mul_f32 v[60:61], v[50:51], v[18:19]
	v_pk_mul_f32 v[54:55], v[32:33], v[16:17]
	v_pk_mul_f32 v[58:59], v[44:45], v[18:19]
	v_pk_fma_f32 v[16:17], v[38:39], v[28:29], v[24:25]
	v_pk_fma_f32 v[24:25], v[52:53], v[28:29], v[20:21] neg_lo:[0,0,1] neg_hi:[0,0,1]
	v_pk_fma_f32 v[18:19], v[34:35], v[30:31], v[26:27]
	v_pk_fma_f32 v[26:27], v[36:37], v[30:31], v[22:23] neg_lo:[0,0,1] neg_hi:[0,0,1]
	v_pk_fma_f32 v[28:29], v[32:33], v[42:43], v[56:57] neg_lo:[0,0,1] neg_hi:[0,0,1]
	v_pk_fma_f32 v[30:31], v[44:45], v[48:49], v[60:61] neg_lo:[0,0,1] neg_hi:[0,0,1]
	v_pk_fma_f32 v[20:21], v[46:47], v[42:43], v[54:55]
	v_pk_fma_f32 v[22:23], v[50:51], v[48:49], v[58:59]
	v_cvt_pk_bf16_f32 v24, v24, v25
	v_cvt_pk_bf16_f32 v25, v26, v27
	v_cvt_pk_bf16_f32 v26, v28, v29
	v_cvt_pk_bf16_f32 v27, v30, v31
	v_cvt_pk_bf16_f32 v16, v16, v17
	v_cvt_pk_bf16_f32 v17, v18, v19
	v_cvt_pk_bf16_f32 v18, v20, v21
	v_cvt_pk_bf16_f32 v19, v22, v23
	flat_store_dwordx4 v[40:41], v[24:27] nt
	flat_store_dwordx4 v[40:41], v[16:19] offset:64 nt
	flat_load_dwordx2 v[26:27], v[192:193] offset:1408
	v_add_u32_e32 v24, 0xb0, v188
	v_cndmask_b32_e32 v16, v232, v243, vcc
	v_and_b32_e32 v16, v16, v24
	v_lshl_or_b32 v160, v16, 8, v207
	v_lshl_add_u64 v[32:33], s[4:5], 0, v[160:161]
	flat_load_dwordx4 v[20:23], v[32:33]
	flat_load_dwordx4 v[16:19], v[32:33] offset:16
	flat_load_dwordx4 v[28:31], v[32:33] offset:32
	s_nop 0
	flat_load_dwordx4 v[32:35], v[32:33] offset:48
	s_waitcnt vmcnt(0) lgkmcnt(0)
	v_ffbh_u32_e32 v25, v27
	v_min_u32_e32 v36, 32, v25
	v_lshlrev_b64 v[26:27], v36, v[26:27]
	v_min_u32_e32 v25, 1, v26
	v_or_b32_e32 v25, v27, v25
	v_cvt_f32_u32_e32 v26, v25
	v_sub_u32_e32 v27, 32, v36
	v_mov_b32_e32 v36, v20
	v_mov_b32_e32 v37, v22
	v_ldexp_f32 v26, v26, v27
	v_mul_f32_e32 v26, 0x35800000, v26
	v_fmamk_f32 v26, v26, 0x3a800000, v219
	v_rsq_f32_e32 v26, v26
	v_mov_b32_e32 v22, v21
	v_ashrrev_i32_e32 v25, 31, v24
	v_lshlrev_b64 v[24:25], 11, v[24:25]
	v_pk_mul_f32 v[38:39], v[12:13], v[26:27] op_sel_hi:[1,0]
	v_pk_mul_f32 v[40:41], v[14:15], v[26:27] op_sel_hi:[1,0]
	v_pk_mul_f32 v[42:43], v[8:9], v[26:27] op_sel_hi:[1,0]
	v_pk_mul_f32 v[44:45], v[10:11], v[26:27] op_sel_hi:[1,0]
	v_pk_mul_f32 v[40:41], v[40:41], v[40:41]
	v_pk_mul_f32 v[38:39], v[38:39], v[38:39]
	v_pk_mul_f32 v[44:45], v[44:45], v[44:45]
	v_pk_mul_f32 v[42:43], v[42:43], v[42:43]
	v_pk_mul_f32 v[46:47], v[6:7], v[26:27] op_sel_hi:[1,0]
	v_pk_mul_f32 v[48:49], v[4:5], v[26:27] op_sel_hi:[1,0]
	v_pk_mov_b32 v[56:57], v[38:39], v[40:41] op_sel:[1,0]
	v_mov_b32_e32 v39, v41
	v_pk_mov_b32 v[40:41], v[42:43], v[44:45] op_sel:[1,0]
	v_mov_b32_e32 v43, v45
	v_mul_f32_e32 v20, v48, v48
	v_mul_f32_e32 v54, v46, v46
	v_pk_add_f32 v[38:39], v[56:57], v[38:39]
	v_pk_add_f32 v[40:41], v[40:41], v[42:43]
	v_pk_mul_f32 v[50:51], v[2:3], v[26:27] op_sel_hi:[1,0]
	v_pk_mul_f32 v[52:53], v[0:1], v[26:27] op_sel_hi:[1,0]
	v_pk_fma_f32 v[44:45], v[48:49], v[48:49], v[20:21] op_sel_hi:[1,1,0]
	v_pk_fma_f32 v[46:47], v[46:47], v[46:47], v[54:55] op_sel_hi:[1,1,0]
	v_pk_add_f32 v[38:39], v[38:39], v[38:39] op_sel_hi:[0,1]
	v_pk_add_f32 v[40:41], v[40:41], v[40:41] op_sel_hi:[0,1]
	v_mul_f32_e32 v44, v52, v52
	v_mul_f32_e32 v46, v53, v53
	v_mul_f32_e32 v38, v50, v50
	v_mul_f32_e32 v40, v51, v51
	v_pk_add_f32 v[42:43], v[44:45], v[46:47]
	v_pk_add_f32 v[38:39], v[38:39], v[40:41]
	v_mov_b32_e32 v20, v16
	v_pk_add_f32 v[38:39], v[42:43], v[38:39]
	v_mov_b32_e32 v21, v18
	v_add_f32_e32 v27, v38, v39
	ds_bpermute_b32 v38, v205, v27
	v_mov_b32_e32 v18, v17
	v_mov_b32_e32 v17, v30
	v_mov_b32_e32 v30, v29
	v_mov_b32_e32 v29, v34
	s_waitcnt lgkmcnt(0)
	v_add_f32_e32 v27, v27, v38
	ds_bpermute_b32 v38, v206, v27
	v_mov_b32_e32 v34, v33
	v_mov_b32_e32 v16, v28
	v_mov_b32_e32 v28, v32
	v_lshl_add_u64 v[24:25], v[190:191], 0, v[24:25]
	s_waitcnt lgkmcnt(0)
	v_add_f32_e32 v27, v27, v38
	v_fmamk_f32 v27, v27, 0x3c800000, v219
	v_rsq_f32_e32 v27, v27
	s_nop 0
	v_mul_f32_e32 v26, v26, v27
	v_pk_mul_f32 v[6:7], v[6:7], v[26:27] op_sel_hi:[1,0]
	v_pk_mul_f32 v[4:5], v[4:5], v[26:27] op_sel_hi:[1,0]
	v_pk_mul_f32 v[2:3], v[2:3], v[26:27] op_sel_hi:[1,0]
	v_pk_mul_f32 v[0:1], v[0:1], v[26:27] op_sel_hi:[1,0]
	v_pk_mul_f32 v[14:15], v[14:15], v[26:27] op_sel_hi:[1,0]
	v_pk_mul_f32 v[12:13], v[12:13], v[26:27] op_sel_hi:[1,0]
	v_pk_mul_f32 v[10:11], v[10:11], v[26:27] op_sel_hi:[1,0]
	v_pk_mul_f32 v[8:9], v[8:9], v[26:27] op_sel_hi:[1,0]
	v_pk_mul_f32 v[4:5], v[156:157], v[4:5]
	v_pk_mul_f32 v[6:7], v[158:159], v[6:7]
	v_pk_mul_f32 v[0:1], v[132:133], v[0:1]
	v_pk_mul_f32 v[2:3], v[134:135], v[2:3]
	v_pk_mul_f32 v[12:13], v[152:153], v[12:13]
	v_pk_mul_f32 v[14:15], v[154:155], v[14:15]
	v_pk_mul_f32 v[26:27], v[128:129], v[8:9]
	v_pk_mul_f32 v[32:33], v[130:131], v[10:11]
	v_pk_mul_f32 v[8:9], v[36:37], v[4:5]
	v_pk_mul_f32 v[4:5], v[22:23], v[4:5]
	v_pk_mul_f32 v[10:11], v[20:21], v[6:7]
	v_pk_mul_f32 v[6:7], v[18:19], v[6:7]
	v_pk_mul_f32 v[40:41], v[30:31], v[0:1]
	v_pk_mul_f32 v[44:45], v[34:35], v[2:3]
	v_pk_mul_f32 v[38:39], v[16:17], v[0:1]
	v_pk_mul_f32 v[42:43], v[28:29], v[2:3]
	v_pk_fma_f32 v[0:1], v[22:23], v[12:13], v[8:9]
	v_pk_fma_f32 v[8:9], v[36:37], v[12:13], v[4:5] neg_lo:[0,0,1] neg_hi:[0,0,1]
	v_pk_fma_f32 v[2:3], v[18:19], v[14:15], v[10:11]
	v_pk_fma_f32 v[10:11], v[20:21], v[14:15], v[6:7] neg_lo:[0,0,1] neg_hi:[0,0,1]
	v_pk_fma_f32 v[12:13], v[16:17], v[26:27], v[40:41] neg_lo:[0,0,1] neg_hi:[0,0,1]
	v_pk_fma_f32 v[14:15], v[28:29], v[32:33], v[44:45] neg_lo:[0,0,1] neg_hi:[0,0,1]
	v_pk_fma_f32 v[4:5], v[30:31], v[26:27], v[38:39]
	v_pk_fma_f32 v[6:7], v[34:35], v[32:33], v[42:43]
	v_cvt_pk_bf16_f32 v8, v8, v9
	v_cvt_pk_bf16_f32 v9, v10, v11
	v_cvt_pk_bf16_f32 v10, v12, v13
	v_cvt_pk_bf16_f32 v11, v14, v15
	v_cvt_pk_bf16_f32 v0, v0, v1
	v_cvt_pk_bf16_f32 v1, v2, v3
	v_cvt_pk_bf16_f32 v2, v4, v5
	v_cvt_pk_bf16_f32 v3, v6, v7
	flat_store_dwordx4 v[24:25], v[8:11] nt
	flat_store_dwordx4 v[24:25], v[0:3] offset:64 nt
	s_andn2_b64 vcc, exec, s[38:39]
	s_mov_b64 s[8:9], -1
	s_cbranch_vccnz .LBB0_135

.LBB0_181:
	s_mov_b64 s[8:9], s[4:5]
	s_waitcnt vmcnt(15)
	v_lshlrev_b32_e32 v158, 16, v146
	v_and_b32_e32 v159, 0xffff0000, v146
	v_pk_fma_f32 v[124:125], v[124:125], 0.5, v[158:159] op_sel_hi:[1,0,1]
	v_lshlrev_b32_e32 v140, 16, v147
	v_and_b32_e32 v141, 0xffff0000, v147
	v_pk_fma_f32 v[126:127], v[126:127], 0.5, v[140:141] op_sel_hi:[1,0,1]
	v_lshlrev_b32_e32 v158, 16, v148
	v_and_b32_e32 v159, 0xffff0000, v148
	v_pk_fma_f32 v[120:121], v[120:121], 0.5, v[158:159] op_sel_hi:[1,0,1]
	v_lshlrev_b32_e32 v140, 16, v149
	v_and_b32_e32 v141, 0xffff0000, v149
	v_pk_fma_f32 v[122:123], v[122:123], 0.5, v[140:141] op_sel_hi:[1,0,1]
	v_cvt_pk_bf16_f32 v146, v124, v125
	v_cvt_pk_bf16_f32 v147, v126, v127
	v_cvt_pk_bf16_f32 v148, v120, v121
	v_cvt_pk_bf16_f32 v149, v122, v123
	global_store_dwordx4 v138, v[146:149], s[8:9] nt
	v_pk_mul_f32 v[124:125], v[124:125], v[124:125]
	v_pk_fma_f32 v[124:125], v[126:127], v[126:127], v[124:125]
	v_pk_fma_f32 v[124:125], v[120:121], v[120:121], v[124:125]
	v_pk_fma_f32 v[124:125], v[122:123], v[122:123], v[124:125]
	s_waitcnt vmcnt(15)
	v_lshlrev_b32_e32 v158, 16, v150
	v_and_b32_e32 v159, 0xffff0000, v150
	v_pk_fma_f32 v[116:117], v[116:117], 0.5, v[158:159] op_sel_hi:[1,0,1]
	v_lshlrev_b32_e32 v140, 16, v151
	v_and_b32_e32 v141, 0xffff0000, v151
	v_pk_fma_f32 v[118:119], v[118:119], 0.5, v[140:141] op_sel_hi:[1,0,1]
	v_lshlrev_b32_e32 v158, 16, v152
	v_and_b32_e32 v159, 0xffff0000, v152
	v_pk_fma_f32 v[112:113], v[112:113], 0.5, v[158:159] op_sel_hi:[1,0,1]
	v_lshlrev_b32_e32 v140, 16, v153
	v_and_b32_e32 v141, 0xffff0000, v153
	v_pk_fma_f32 v[114:115], v[114:115], 0.5, v[140:141] op_sel_hi:[1,0,1]
	v_cvt_pk_bf16_f32 v150, v116, v117
	v_cvt_pk_bf16_f32 v151, v118, v119
	v_cvt_pk_bf16_f32 v152, v112, v113
	v_cvt_pk_bf16_f32 v153, v114, v115
	global_store_dwordx4 v138, v[150:153], s[8:9] offset:256 nt
	v_pk_fma_f32 v[124:125], v[116:117], v[116:117], v[124:125]
	v_pk_fma_f32 v[124:125], v[118:119], v[118:119], v[124:125]
	v_pk_fma_f32 v[124:125], v[112:113], v[112:113], v[124:125]
	v_pk_fma_f32 v[124:125], v[114:115], v[114:115], v[124:125]
	v_add_f32_e32 v124, v124, v125
	s_add_u32 s8, s8, 0x8000
	s_addc_u32 s9, s9, 0
	s_waitcnt vmcnt(15)
	v_lshlrev_b32_e32 v158, 16, v154
	v_and_b32_e32 v159, 0xffff0000, v154
	v_pk_fma_f32 v[108:109], v[108:109], 0.5, v[158:159] op_sel_hi:[1,0,1]
	v_lshlrev_b32_e32 v140, 16, v155
	v_and_b32_e32 v141, 0xffff0000, v155
	v_pk_fma_f32 v[110:111], v[110:111], 0.5, v[140:141] op_sel_hi:[1,0,1]
	v_lshlrev_b32_e32 v158, 16, v156
	v_and_b32_e32 v159, 0xffff0000, v156
	v_pk_fma_f32 v[104:105], v[104:105], 0.5, v[158:159] op_sel_hi:[1,0,1]
	v_lshlrev_b32_e32 v140, 16, v157
	v_and_b32_e32 v141, 0xffff0000, v157
	v_pk_fma_f32 v[106:107], v[106:107], 0.5, v[140:141] op_sel_hi:[1,0,1]
	v_cvt_pk_bf16_f32 v154, v108, v109
	v_cvt_pk_bf16_f32 v155, v110, v111
	v_cvt_pk_bf16_f32 v156, v104, v105
	v_cvt_pk_bf16_f32 v157, v106, v107
	global_store_dwordx4 v138, v[154:157], s[8:9] nt
	v_pk_mul_f32 v[108:109], v[108:109], v[108:109]
	v_pk_fma_f32 v[108:109], v[110:111], v[110:111], v[108:109]
	v_pk_fma_f32 v[108:109], v[104:105], v[104:105], v[108:109]
	v_pk_fma_f32 v[108:109], v[106:107], v[106:107], v[108:109]
	s_waitcnt vmcnt(15)
	v_lshlrev_b32_e32 v158, 16, v162
	v_and_b32_e32 v159, 0xffff0000, v162
	v_pk_fma_f32 v[100:101], v[100:101], 0.5, v[158:159] op_sel_hi:[1,0,1]
	v_lshlrev_b32_e32 v140, 16, v163
	v_and_b32_e32 v141, 0xffff0000, v163
	v_pk_fma_f32 v[102:103], v[102:103], 0.5, v[140:141] op_sel_hi:[1,0,1]
	v_lshlrev_b32_e32 v158, 16, v164
	v_and_b32_e32 v159, 0xffff0000, v164
	v_pk_fma_f32 v[96:97], v[96:97], 0.5, v[158:159] op_sel_hi:[1,0,1]
	v_lshlrev_b32_e32 v140, 16, v165
	v_and_b32_e32 v141, 0xffff0000, v165
	v_pk_fma_f32 v[98:99], v[98:99], 0.5, v[140:141] op_sel_hi:[1,0,1]
	v_cvt_pk_bf16_f32 v162, v100, v101
	v_cvt_pk_bf16_f32 v163, v102, v103
	v_cvt_pk_bf16_f32 v164, v96, v97
	v_cvt_pk_bf16_f32 v165, v98, v99
	global_store_dwordx4 v138, v[162:165], s[8:9] offset:256 nt
	v_pk_fma_f32 v[108:109], v[100:101], v[100:101], v[108:109]
	v_pk_fma_f32 v[108:109], v[102:103], v[102:103], v[108:109]
	v_pk_fma_f32 v[108:109], v[96:97], v[96:97], v[108:109]
	v_pk_fma_f32 v[108:109], v[98:99], v[98:99], v[108:109]
	v_add_f32_e32 v108, v108, v109
	s_add_u32 s8, s8, 0x8000
	s_addc_u32 s9, s9, 0
	s_waitcnt vmcnt(15)
	v_lshlrev_b32_e32 v158, 16, v166
	v_and_b32_e32 v159, 0xffff0000, v166
	v_pk_fma_f32 v[92:93], v[92:93], 0.5, v[158:159] op_sel_hi:[1,0,1]
	v_lshlrev_b32_e32 v140, 16, v167
	v_and_b32_e32 v141, 0xffff0000, v167
	v_pk_fma_f32 v[94:95], v[94:95], 0.5, v[140:141] op_sel_hi:[1,0,1]
	v_lshlrev_b32_e32 v158, 16, v168
	v_and_b32_e32 v159, 0xffff0000, v168
	v_pk_fma_f32 v[88:89], v[88:89], 0.5, v[158:159] op_sel_hi:[1,0,1]
	v_lshlrev_b32_e32 v140, 16, v169
	v_and_b32_e32 v141, 0xffff0000, v169
	v_pk_fma_f32 v[90:91], v[90:91], 0.5, v[140:141] op_sel_hi:[1,0,1]
	v_cvt_pk_bf16_f32 v166, v92, v93
	v_cvt_pk_bf16_f32 v167, v94, v95
	v_cvt_pk_bf16_f32 v168, v88, v89
	v_cvt_pk_bf16_f32 v169, v90, v91
	global_store_dwordx4 v138, v[166:169], s[8:9] nt
	v_pk_mul_f32 v[92:93], v[92:93], v[92:93]
	v_pk_fma_f32 v[92:93], v[94:95], v[94:95], v[92:93]
	v_pk_fma_f32 v[92:93], v[88:89], v[88:89], v[92:93]
	v_pk_fma_f32 v[92:93], v[90:91], v[90:91], v[92:93]
	s_waitcnt vmcnt(15)
	v_lshlrev_b32_e32 v158, 16, v174
	v_and_b32_e32 v159, 0xffff0000, v174
	v_pk_fma_f32 v[84:85], v[84:85], 0.5, v[158:159] op_sel_hi:[1,0,1]
	v_lshlrev_b32_e32 v140, 16, v175
	v_and_b32_e32 v141, 0xffff0000, v175
	v_pk_fma_f32 v[86:87], v[86:87], 0.5, v[140:141] op_sel_hi:[1,0,1]
	v_lshlrev_b32_e32 v158, 16, v176
	v_and_b32_e32 v159, 0xffff0000, v176
	v_pk_fma_f32 v[80:81], v[80:81], 0.5, v[158:159] op_sel_hi:[1,0,1]
	v_lshlrev_b32_e32 v140, 16, v177
	v_and_b32_e32 v141, 0xffff0000, v177
	v_pk_fma_f32 v[82:83], v[82:83], 0.5, v[140:141] op_sel_hi:[1,0,1]
	v_cvt_pk_bf16_f32 v174, v84, v85
	v_cvt_pk_bf16_f32 v175, v86, v87
	v_cvt_pk_bf16_f32 v176, v80, v81
	v_cvt_pk_bf16_f32 v177, v82, v83
	global_store_dwordx4 v138, v[174:177], s[8:9] offset:256 nt
	v_pk_fma_f32 v[92:93], v[84:85], v[84:85], v[92:93]
	v_pk_fma_f32 v[92:93], v[86:87], v[86:87], v[92:93]
	v_pk_fma_f32 v[92:93], v[80:81], v[80:81], v[92:93]
	v_pk_fma_f32 v[92:93], v[82:83], v[82:83], v[92:93]
	v_add_f32_e32 v92, v92, v93
	s_add_u32 s8, s8, 0x8000
	s_addc_u32 s9, s9, 0
	s_waitcnt vmcnt(15)
	v_lshlrev_b32_e32 v158, 16, v178
	v_and_b32_e32 v159, 0xffff0000, v178
	v_pk_fma_f32 v[76:77], v[76:77], 0.5, v[158:159] op_sel_hi:[1,0,1]
	v_lshlrev_b32_e32 v140, 16, v179
	v_and_b32_e32 v141, 0xffff0000, v179
	v_pk_fma_f32 v[78:79], v[78:79], 0.5, v[140:141] op_sel_hi:[1,0,1]
	v_lshlrev_b32_e32 v158, 16, v180
	v_and_b32_e32 v159, 0xffff0000, v180
	v_pk_fma_f32 v[72:73], v[72:73], 0.5, v[158:159] op_sel_hi:[1,0,1]
	v_lshlrev_b32_e32 v140, 16, v181
	v_and_b32_e32 v141, 0xffff0000, v181
	v_pk_fma_f32 v[74:75], v[74:75], 0.5, v[140:141] op_sel_hi:[1,0,1]
	v_cvt_pk_bf16_f32 v178, v76, v77
	v_cvt_pk_bf16_f32 v179, v78, v79
	v_cvt_pk_bf16_f32 v180, v72, v73
	v_cvt_pk_bf16_f32 v181, v74, v75
	global_store_dwordx4 v138, v[178:181], s[8:9] nt
	v_pk_mul_f32 v[76:77], v[76:77], v[76:77]
	v_pk_fma_f32 v[76:77], v[78:79], v[78:79], v[76:77]
	v_pk_fma_f32 v[76:77], v[72:73], v[72:73], v[76:77]
	v_pk_fma_f32 v[76:77], v[74:75], v[74:75], v[76:77]
	s_waitcnt vmcnt(15)
	v_lshlrev_b32_e32 v158, 16, v182
	v_and_b32_e32 v159, 0xffff0000, v182
	v_pk_fma_f32 v[68:69], v[68:69], 0.5, v[158:159] op_sel_hi:[1,0,1]
	v_lshlrev_b32_e32 v140, 16, v183
	v_and_b32_e32 v141, 0xffff0000, v183
	v_pk_fma_f32 v[70:71], v[70:71], 0.5, v[140:141] op_sel_hi:[1,0,1]
	v_lshlrev_b32_e32 v158, 16, v184
	v_and_b32_e32 v159, 0xffff0000, v184
	v_pk_fma_f32 v[64:65], v[64:65], 0.5, v[158:159] op_sel_hi:[1,0,1]
	v_lshlrev_b32_e32 v140, 16, v185
	v_and_b32_e32 v141, 0xffff0000, v185
	v_pk_fma_f32 v[66:67], v[66:67], 0.5, v[140:141] op_sel_hi:[1,0,1]
	v_cvt_pk_bf16_f32 v182, v68, v69
	v_cvt_pk_bf16_f32 v183, v70, v71
	v_cvt_pk_bf16_f32 v184, v64, v65
	v_cvt_pk_bf16_f32 v185, v66, v67
	global_store_dwordx4 v138, v[182:185], s[8:9] offset:256 nt
	v_pk_fma_f32 v[76:77], v[68:69], v[68:69], v[76:77]
	v_pk_fma_f32 v[76:77], v[70:71], v[70:71], v[76:77]
	v_pk_fma_f32 v[76:77], v[64:65], v[64:65], v[76:77]
	v_pk_fma_f32 v[76:77], v[66:67], v[66:67], v[76:77]
	v_add_f32_e32 v76, v76, v77
	s_add_u32 s8, s8, 0x28000
	s_addc_u32 s9, s9, 0
	s_waitcnt vmcnt(15)
	v_lshlrev_b32_e32 v158, 16, v186
	v_and_b32_e32 v159, 0xffff0000, v186
	v_pk_fma_f32 v[60:61], v[60:61], 0.5, v[158:159] op_sel_hi:[1,0,1]
	v_lshlrev_b32_e32 v140, 16, v187
	v_and_b32_e32 v141, 0xffff0000, v187
	v_pk_fma_f32 v[62:63], v[62:63], 0.5, v[140:141] op_sel_hi:[1,0,1]
	v_lshlrev_b32_e32 v158, 16, v188
	v_and_b32_e32 v159, 0xffff0000, v188
	v_pk_fma_f32 v[56:57], v[56:57], 0.5, v[158:159] op_sel_hi:[1,0,1]
	v_lshlrev_b32_e32 v140, 16, v189
	v_and_b32_e32 v141, 0xffff0000, v189
	v_pk_fma_f32 v[58:59], v[58:59], 0.5, v[140:141] op_sel_hi:[1,0,1]
	v_cvt_pk_bf16_f32 v186, v60, v61
	v_cvt_pk_bf16_f32 v187, v62, v63
	v_cvt_pk_bf16_f32 v188, v56, v57
	v_cvt_pk_bf16_f32 v189, v58, v59
	global_store_dwordx4 v138, v[186:189], s[8:9] nt
	v_pk_mul_f32 v[60:61], v[60:61], v[60:61]
	v_pk_fma_f32 v[60:61], v[62:63], v[62:63], v[60:61]
	v_pk_fma_f32 v[60:61], v[56:57], v[56:57], v[60:61]
	v_pk_fma_f32 v[60:61], v[58:59], v[58:59], v[60:61]
	s_waitcnt vmcnt(15)
	v_lshlrev_b32_e32 v158, 16, v190
	v_and_b32_e32 v159, 0xffff0000, v190
	v_pk_fma_f32 v[52:53], v[52:53], 0.5, v[158:159] op_sel_hi:[1,0,1]
	v_lshlrev_b32_e32 v140, 16, v191
	v_and_b32_e32 v141, 0xffff0000, v191
	v_pk_fma_f32 v[54:55], v[54:55], 0.5, v[140:141] op_sel_hi:[1,0,1]
	v_lshlrev_b32_e32 v158, 16, v192
	v_and_b32_e32 v159, 0xffff0000, v192
	v_pk_fma_f32 v[48:49], v[48:49], 0.5, v[158:159] op_sel_hi:[1,0,1]
	v_lshlrev_b32_e32 v140, 16, v193
	v_and_b32_e32 v141, 0xffff0000, v193
	v_pk_fma_f32 v[50:51], v[50:51], 0.5, v[140:141] op_sel_hi:[1,0,1]
	v_cvt_pk_bf16_f32 v190, v52, v53
	v_cvt_pk_bf16_f32 v191, v54, v55
	v_cvt_pk_bf16_f32 v192, v48, v49
	v_cvt_pk_bf16_f32 v193, v50, v51
	global_store_dwordx4 v138, v[190:193], s[8:9] offset:256 nt
	v_pk_fma_f32 v[60:61], v[52:53], v[52:53], v[60:61]
	v_pk_fma_f32 v[60:61], v[54:55], v[54:55], v[60:61]
	v_pk_fma_f32 v[60:61], v[48:49], v[48:49], v[60:61]
	v_pk_fma_f32 v[60:61], v[50:51], v[50:51], v[60:61]
	v_add_f32_e32 v60, v60, v61
	s_add_u32 s8, s8, 0x8000
	s_addc_u32 s9, s9, 0
	s_waitcnt vmcnt(15)
	v_lshlrev_b32_e32 v158, 16, v194
	v_and_b32_e32 v159, 0xffff0000, v194
	v_pk_fma_f32 v[44:45], v[44:45], 0.5, v[158:159] op_sel_hi:[1,0,1]
	v_lshlrev_b32_e32 v140, 16, v195
	v_and_b32_e32 v141, 0xffff0000, v195
	v_pk_fma_f32 v[46:47], v[46:47], 0.5, v[140:141] op_sel_hi:[1,0,1]
	v_lshlrev_b32_e32 v158, 16, v196
	v_and_b32_e32 v159, 0xffff0000, v196
	v_pk_fma_f32 v[40:41], v[40:41], 0.5, v[158:159] op_sel_hi:[1,0,1]
	v_lshlrev_b32_e32 v140, 16, v197
	v_and_b32_e32 v141, 0xffff0000, v197
	v_pk_fma_f32 v[42:43], v[42:43], 0.5, v[140:141] op_sel_hi:[1,0,1]
	v_cvt_pk_bf16_f32 v194, v44, v45
	v_cvt_pk_bf16_f32 v195, v46, v47
	v_cvt_pk_bf16_f32 v196, v40, v41
	v_cvt_pk_bf16_f32 v197, v42, v43
	global_store_dwordx4 v138, v[194:197], s[8:9] nt
	v_pk_mul_f32 v[44:45], v[44:45], v[44:45]
	v_pk_fma_f32 v[44:45], v[46:47], v[46:47], v[44:45]
	v_pk_fma_f32 v[44:45], v[40:41], v[40:41], v[44:45]
	v_pk_fma_f32 v[44:45], v[42:43], v[42:43], v[44:45]
	s_waitcnt vmcnt(15)
	v_lshlrev_b32_e32 v158, 16, v198
	v_and_b32_e32 v159, 0xffff0000, v198
	v_pk_fma_f32 v[36:37], v[36:37], 0.5, v[158:159] op_sel_hi:[1,0,1]
	v_lshlrev_b32_e32 v140, 16, v199
	v_and_b32_e32 v141, 0xffff0000, v199
	v_pk_fma_f32 v[38:39], v[38:39], 0.5, v[140:141] op_sel_hi:[1,0,1]
	v_lshlrev_b32_e32 v158, 16, v200
	v_and_b32_e32 v159, 0xffff0000, v200
	v_pk_fma_f32 v[32:33], v[32:33], 0.5, v[158:159] op_sel_hi:[1,0,1]
	v_lshlrev_b32_e32 v140, 16, v201
	v_and_b32_e32 v141, 0xffff0000, v201
	v_pk_fma_f32 v[34:35], v[34:35], 0.5, v[140:141] op_sel_hi:[1,0,1]
	v_cvt_pk_bf16_f32 v198, v36, v37
	v_cvt_pk_bf16_f32 v199, v38, v39
	v_cvt_pk_bf16_f32 v200, v32, v33
	v_cvt_pk_bf16_f32 v201, v34, v35
	global_store_dwordx4 v138, v[198:201], s[8:9] offset:256 nt
	v_pk_fma_f32 v[44:45], v[36:37], v[36:37], v[44:45]
	v_pk_fma_f32 v[44:45], v[38:39], v[38:39], v[44:45]
	v_pk_fma_f32 v[44:45], v[32:33], v[32:33], v[44:45]
	v_pk_fma_f32 v[44:45], v[34:35], v[34:35], v[44:45]
	v_add_f32_e32 v44, v44, v45
	s_add_u32 s8, s8, 0x8000
	s_addc_u32 s9, s9, 0
	s_waitcnt vmcnt(15)
	v_lshlrev_b32_e32 v158, 16, v202
	v_and_b32_e32 v159, 0xffff0000, v202
	v_pk_fma_f32 v[28:29], v[28:29], 0.5, v[158:159] op_sel_hi:[1,0,1]
	v_lshlrev_b32_e32 v140, 16, v203
	v_and_b32_e32 v141, 0xffff0000, v203
	v_pk_fma_f32 v[30:31], v[30:31], 0.5, v[140:141] op_sel_hi:[1,0,1]
	v_lshlrev_b32_e32 v158, 16, v204
	v_and_b32_e32 v159, 0xffff0000, v204
	v_pk_fma_f32 v[24:25], v[24:25], 0.5, v[158:159] op_sel_hi:[1,0,1]
	v_lshlrev_b32_e32 v140, 16, v205
	v_and_b32_e32 v141, 0xffff0000, v205
	v_pk_fma_f32 v[26:27], v[26:27], 0.5, v[140:141] op_sel_hi:[1,0,1]
	v_cvt_pk_bf16_f32 v202, v28, v29
	v_cvt_pk_bf16_f32 v203, v30, v31
	v_cvt_pk_bf16_f32 v204, v24, v25
	v_cvt_pk_bf16_f32 v205, v26, v27
	global_store_dwordx4 v138, v[202:205], s[8:9] nt
	v_pk_mul_f32 v[28:29], v[28:29], v[28:29]
	v_pk_fma_f32 v[28:29], v[30:31], v[30:31], v[28:29]
	v_pk_fma_f32 v[28:29], v[24:25], v[24:25], v[28:29]
	v_pk_fma_f32 v[28:29], v[26:27], v[26:27], v[28:29]
	s_waitcnt vmcnt(15)
	v_lshlrev_b32_e32 v158, 16, v206
	v_and_b32_e32 v159, 0xffff0000, v206
	v_pk_fma_f32 v[20:21], v[20:21], 0.5, v[158:159] op_sel_hi:[1,0,1]
	v_lshlrev_b32_e32 v140, 16, v207
	v_and_b32_e32 v141, 0xffff0000, v207
	v_pk_fma_f32 v[22:23], v[22:23], 0.5, v[140:141] op_sel_hi:[1,0,1]
	v_lshlrev_b32_e32 v158, 16, v208
	v_and_b32_e32 v159, 0xffff0000, v208
	v_pk_fma_f32 v[16:17], v[16:17], 0.5, v[158:159] op_sel_hi:[1,0,1]
	v_lshlrev_b32_e32 v140, 16, v209
	v_and_b32_e32 v141, 0xffff0000, v209
	v_pk_fma_f32 v[18:19], v[18:19], 0.5, v[140:141] op_sel_hi:[1,0,1]
	v_cvt_pk_bf16_f32 v206, v20, v21
	v_cvt_pk_bf16_f32 v207, v22, v23
	v_cvt_pk_bf16_f32 v208, v16, v17
	v_cvt_pk_bf16_f32 v209, v18, v19
	global_store_dwordx4 v138, v[206:209], s[8:9] offset:256 nt
	v_pk_fma_f32 v[28:29], v[20:21], v[20:21], v[28:29]
	v_pk_fma_f32 v[28:29], v[22:23], v[22:23], v[28:29]
	v_pk_fma_f32 v[28:29], v[16:17], v[16:17], v[28:29]
	v_pk_fma_f32 v[28:29], v[18:19], v[18:19], v[28:29]
	v_add_f32_e32 v28, v28, v29
	s_add_u32 s8, s8, 0x8000
	s_addc_u32 s9, s9, 0
	s_waitcnt vmcnt(15)
	v_lshlrev_b32_e32 v158, 16, v210
	v_and_b32_e32 v159, 0xffff0000, v210
	v_pk_fma_f32 v[12:13], v[12:13], 0.5, v[158:159] op_sel_hi:[1,0,1]
	v_lshlrev_b32_e32 v140, 16, v211
	v_and_b32_e32 v141, 0xffff0000, v211
	v_pk_fma_f32 v[14:15], v[14:15], 0.5, v[140:141] op_sel_hi:[1,0,1]
	v_lshlrev_b32_e32 v158, 16, v212
	v_and_b32_e32 v159, 0xffff0000, v212
	v_pk_fma_f32 v[8:9], v[8:9], 0.5, v[158:159] op_sel_hi:[1,0,1]
	v_lshlrev_b32_e32 v140, 16, v213
	v_and_b32_e32 v141, 0xffff0000, v213
	v_pk_fma_f32 v[10:11], v[10:11], 0.5, v[140:141] op_sel_hi:[1,0,1]
	v_cvt_pk_bf16_f32 v210, v12, v13
	v_cvt_pk_bf16_f32 v211, v14, v15
	v_cvt_pk_bf16_f32 v212, v8, v9
	v_cvt_pk_bf16_f32 v213, v10, v11
	global_store_dwordx4 v138, v[210:213], s[8:9] nt
	v_pk_mul_f32 v[12:13], v[12:13], v[12:13]
	v_pk_fma_f32 v[12:13], v[14:15], v[14:15], v[12:13]
	v_pk_fma_f32 v[12:13], v[8:9], v[8:9], v[12:13]
	v_pk_fma_f32 v[12:13], v[10:11], v[10:11], v[12:13]
	s_waitcnt vmcnt(15)
	v_lshlrev_b32_e32 v158, 16, v214
	v_and_b32_e32 v159, 0xffff0000, v214
	v_pk_fma_f32 v[4:5], v[4:5], 0.5, v[158:159] op_sel_hi:[1,0,1]
	v_lshlrev_b32_e32 v140, 16, v215
	v_and_b32_e32 v141, 0xffff0000, v215
	v_pk_fma_f32 v[6:7], v[6:7], 0.5, v[140:141] op_sel_hi:[1,0,1]
	v_lshlrev_b32_e32 v158, 16, v216
	v_and_b32_e32 v159, 0xffff0000, v216
	v_pk_fma_f32 v[0:1], v[0:1], 0.5, v[158:159] op_sel_hi:[1,0,1]
	v_lshlrev_b32_e32 v140, 16, v217
	v_and_b32_e32 v141, 0xffff0000, v217
	v_pk_fma_f32 v[2:3], v[2:3], 0.5, v[140:141] op_sel_hi:[1,0,1]
	v_cvt_pk_bf16_f32 v214, v4, v5
	v_cvt_pk_bf16_f32 v215, v6, v7
	v_cvt_pk_bf16_f32 v216, v0, v1
	v_cvt_pk_bf16_f32 v217, v2, v3
	global_store_dwordx4 v138, v[214:217], s[8:9] offset:256 nt
	v_pk_fma_f32 v[12:13], v[4:5], v[4:5], v[12:13]
	v_pk_fma_f32 v[12:13], v[6:7], v[6:7], v[12:13]
	v_pk_fma_f32 v[12:13], v[0:1], v[0:1], v[12:13]
	v_pk_fma_f32 v[12:13], v[2:3], v[2:3], v[12:13]
	v_add_f32_e32 v12, v12, v13
	v_xor_b32_e32 v158, 16, v223
	v_xor_b32_e32 v159, 32, v223
	v_lshlrev_b32_e32 v158, 2, v158
	v_lshlrev_b32_e32 v159, 2, v159
	ds_bpermute_b32 v146, v158, v124
	ds_bpermute_b32 v148, v158, v108
	ds_bpermute_b32 v150, v158, v92
	ds_bpermute_b32 v152, v158, v76
	ds_bpermute_b32 v154, v158, v60
	ds_bpermute_b32 v156, v158, v44
	ds_bpermute_b32 v162, v158, v28
	ds_bpermute_b32 v164, v158, v12
	s_waitcnt lgkmcnt(7)
	v_add_f32_e32 v124, v124, v146
	s_waitcnt lgkmcnt(6)
	v_add_f32_e32 v108, v108, v148
	s_waitcnt lgkmcnt(5)
	v_add_f32_e32 v92, v92, v150
	s_waitcnt lgkmcnt(4)
	v_add_f32_e32 v76, v76, v152
	s_waitcnt lgkmcnt(3)
	v_add_f32_e32 v60, v60, v154
	s_waitcnt lgkmcnt(2)
	v_add_f32_e32 v44, v44, v156
	s_waitcnt lgkmcnt(1)
	v_add_f32_e32 v28, v28, v162
	s_waitcnt lgkmcnt(0)
	v_add_f32_e32 v12, v12, v164
	ds_bpermute_b32 v146, v159, v124
	ds_bpermute_b32 v148, v159, v108
	ds_bpermute_b32 v150, v159, v92
	ds_bpermute_b32 v152, v159, v76
	ds_bpermute_b32 v154, v159, v60
	ds_bpermute_b32 v156, v159, v44
	ds_bpermute_b32 v162, v159, v28
	ds_bpermute_b32 v164, v159, v12
	s_and_saveexec_b64 s[8:9], s[38:39]
	s_waitcnt lgkmcnt(7)
	v_add_f32_e32 v146, v124, v146
	v_fma_f32 v146, v146, s17, 0.5
	v_trunc_f32_e32 v146, v146
	v_mul_f32_e32 v147, 0x2f800000, v146
	v_floor_f32_e32 v147, v147
	v_fmac_f32_e32 v146, 0xcf800000, v147
	v_cvt_u32_f32_e32 v146, v146
	v_cvt_u32_f32_e32 v147, v147
	global_atomic_add_x2 v139, v[146:147], s[6:7]
	s_waitcnt lgkmcnt(6)
	v_add_f32_e32 v148, v108, v148
	v_fma_f32 v148, v148, s17, 0.5
	v_trunc_f32_e32 v148, v148
	v_mul_f32_e32 v149, 0x2f800000, v148
	v_floor_f32_e32 v149, v149
	v_fmac_f32_e32 v148, 0xcf800000, v149
	v_cvt_u32_f32_e32 v148, v148
	v_cvt_u32_f32_e32 v149, v149
	global_atomic_add_x2 v139, v[148:149], s[6:7] offset:128
	s_waitcnt lgkmcnt(5)
	v_add_f32_e32 v150, v92, v150
	v_fma_f32 v150, v150, s17, 0.5
	v_trunc_f32_e32 v150, v150
	v_mul_f32_e32 v151, 0x2f800000, v150
	v_floor_f32_e32 v151, v151
	v_fmac_f32_e32 v150, 0xcf800000, v151
	v_cvt_u32_f32_e32 v150, v150
	v_cvt_u32_f32_e32 v151, v151
	global_atomic_add_x2 v139, v[150:151], s[6:7] offset:256
	s_waitcnt lgkmcnt(4)
	v_add_f32_e32 v152, v76, v152
	v_fma_f32 v152, v152, s17, 0.5
	v_trunc_f32_e32 v152, v152
	v_mul_f32_e32 v153, 0x2f800000, v152
	v_floor_f32_e32 v153, v153
	v_fmac_f32_e32 v152, 0xcf800000, v153
	v_cvt_u32_f32_e32 v152, v152
	v_cvt_u32_f32_e32 v153, v153
	global_atomic_add_x2 v139, v[152:153], s[6:7] offset:384
	s_waitcnt lgkmcnt(3)
	v_add_f32_e32 v154, v60, v154
	v_fma_f32 v154, v154, s17, 0.5
	v_trunc_f32_e32 v154, v154
	v_mul_f32_e32 v155, 0x2f800000, v154
	v_floor_f32_e32 v155, v155
	v_fmac_f32_e32 v154, 0xcf800000, v155
	v_cvt_u32_f32_e32 v154, v154
	v_cvt_u32_f32_e32 v155, v155
	global_atomic_add_x2 v139, v[154:155], s[6:7] offset:1024
	s_waitcnt lgkmcnt(2)
	v_add_f32_e32 v156, v44, v156
	v_fma_f32 v156, v156, s17, 0.5
	v_trunc_f32_e32 v156, v156
	v_mul_f32_e32 v157, 0x2f800000, v156
	v_floor_f32_e32 v157, v157
	v_fmac_f32_e32 v156, 0xcf800000, v157
	v_cvt_u32_f32_e32 v156, v156
	v_cvt_u32_f32_e32 v157, v157
	global_atomic_add_x2 v139, v[156:157], s[6:7] offset:1152
	s_waitcnt lgkmcnt(1)
	v_add_f32_e32 v162, v28, v162
	v_fma_f32 v162, v162, s17, 0.5
	v_trunc_f32_e32 v162, v162
	v_mul_f32_e32 v163, 0x2f800000, v162
	v_floor_f32_e32 v163, v163
	v_fmac_f32_e32 v162, 0xcf800000, v163
	v_cvt_u32_f32_e32 v162, v162
	v_cvt_u32_f32_e32 v163, v163
	global_atomic_add_x2 v139, v[162:163], s[6:7] offset:1280
	s_waitcnt lgkmcnt(0)
	v_add_f32_e32 v164, v12, v164
	v_fma_f32 v164, v164, s17, 0.5
	v_trunc_f32_e32 v164, v164
	v_mul_f32_e32 v165, 0x2f800000, v164
	v_floor_f32_e32 v165, v165
	v_fmac_f32_e32 v164, 0xcf800000, v165
	v_cvt_u32_f32_e32 v164, v164
	v_cvt_u32_f32_e32 v165, v165
	global_atomic_add_x2 v139, v[164:165], s[6:7] offset:1408
	s_mov_b64 exec, s[8:9]
	v_mov_b64_e32 v[172:173], v[244:245]
	s_and_b64 vcc, exec, s[40:41]
	s_mov_b64 s[8:9], -1
	s_cbranch_vccnz .LBB0_166
	s_andn2_b64 vcc, exec, s[2:3]
	s_cbranch_vccnz .LBB0_165
	s_barrier
	s_branch .LBB0_165

.LBB0_215:
	v_lshl_or_b32 v142, s9, 7, v148
	v_lshl_add_u32 v138, s8, 8, v146
	v_ashrrev_i32_e32 v143, 31, v142
	v_mov_b64_e32 v[140:141], s[2:3]
	v_ashrrev_i32_e32 v139, 31, v138
	v_mad_i64_i32 v[144:145], s[8:9], v138, s16, v[140:141]
	v_lshlrev_b64 v[142:143], 1, v[142:143]
	v_lshl_add_u64 v[150:151], v[144:145], 0, v[142:143]
	v_lshl_add_u64 v[144:145], v[138:139], 3, s[4:5]
	v_pk_mul_f32 v[120:121], v[124:125], v[120:121]
	v_pk_mul_f32 v[122:123], v[126:127], v[122:123]
	v_pk_mul_f32 v[112:113], v[116:117], v[112:113]
	v_pk_mul_f32 v[114:115], v[118:119], v[114:115]
	v_pk_mul_f32 v[104:105], v[108:109], v[104:105]
	v_pk_mul_f32 v[106:107], v[110:111], v[106:107]
	v_pk_mul_f32 v[96:97], v[100:101], v[96:97]
	v_pk_mul_f32 v[98:99], v[102:103], v[98:99]
	v_pk_mul_f32 v[88:89], v[92:93], v[88:89]
	v_pk_mul_f32 v[90:91], v[94:95], v[90:91]
	v_pk_mul_f32 v[80:81], v[84:85], v[80:81]
	v_pk_mul_f32 v[82:83], v[86:87], v[82:83]
	v_pk_mul_f32 v[72:73], v[76:77], v[72:73]
	v_pk_mul_f32 v[74:75], v[78:79], v[74:75]
	v_pk_mul_f32 v[70:71], v[66:67], v[70:71]
	v_pk_mul_f32 v[56:57], v[60:61], v[56:57]
	v_pk_mul_f32 v[58:59], v[62:63], v[58:59]
	v_pk_mul_f32 v[54:55], v[50:51], v[54:55]
	v_pk_mul_f32 v[40:41], v[44:45], v[40:41]
	v_pk_mul_f32 v[42:43], v[46:47], v[42:43]
	v_pk_mul_f32 v[38:39], v[34:35], v[38:39]
	v_pk_mul_f32 v[24:25], v[28:29], v[24:25]
	v_pk_mul_f32 v[26:27], v[30:31], v[26:27]
	v_pk_mul_f32 v[22:23], v[18:19], v[22:23]
	v_pk_mul_f32 v[8:9], v[12:13], v[8:9]
	v_pk_mul_f32 v[10:11], v[14:15], v[10:11]
	v_pk_mul_f32 v[6:7], v[2:3], v[6:7]
	s_andn2_b64 vcc, exec, s[38:39]
	s_waitcnt vmcnt(0) lgkmcnt(0)
	v_mov_b64_e32 v[152:153], v[176:177]
	v_ffbh_u32_e32 v139, v153
	v_min_u32_e32 v139, 32, v139
	v_lshlrev_b64 v[152:153], v139, v[152:153]
	v_min_u32_e32 v152, 1, v152
	v_or_b32_e32 v152, v153, v152
	v_cvt_f32_u32_e32 v152, v152
	v_sub_u32_e32 v139, 32, v139
	v_ldexp_f32 v139, v152, v139
	v_mul_f32_e32 v139, 0x35800000, v139
	v_fmamk_f32 v139, v139, 0x3a800000, v219
	v_rsq_f32_e32 v139, v139
	s_nop 0
	v_mul_f32_e32 v152, 0xbfb8aa3b, v139
	v_pk_mul_f32 v[156:157], v[124:125], v[152:153] op_sel_hi:[1,0]
	v_mul_f32_e32 v154, v139, v139
	v_exp_f32_e32 v156, v156
	v_exp_f32_e32 v157, v157
	s_nop 0
	v_pk_add_f32 v[156:157], v[156:157], 1.0 op_sel_hi:[1,0]
	s_nop 0
	v_rcp_f32_e32 v156, v156
	v_rcp_f32_e32 v157, v157
	s_nop 0
	v_pk_mul_f32 v[124:125], v[154:155], v[156:157] op_sel_hi:[0,1]
	v_pk_mul_f32 v[120:121], v[120:121], v[124:125]
	v_pk_mul_f32 v[124:125], v[126:127], v[152:153] op_sel_hi:[1,0]
	s_nop 0
	v_exp_f32_e32 v124, v124
	v_exp_f32_e32 v125, v125
	s_nop 0
	v_pk_add_f32 v[124:125], v[124:125], 1.0 op_sel_hi:[1,0]
	s_nop 0
	v_rcp_f32_e32 v124, v124
	v_rcp_f32_e32 v125, v125
	s_nop 0
	v_pk_mul_f32 v[124:125], v[154:155], v[124:125] op_sel_hi:[0,1]
	v_pk_mul_f32 v[122:123], v[122:123], v[124:125]
	v_pk_mul_f32 v[124:125], v[116:117], v[152:153] op_sel_hi:[1,0]
	s_nop 0
	v_exp_f32_e32 v124, v124
	v_exp_f32_e32 v125, v125
	s_nop 0
	v_pk_add_f32 v[124:125], v[124:125], 1.0 op_sel_hi:[1,0]
	s_nop 0
	v_rcp_f32_e32 v124, v124
	v_rcp_f32_e32 v125, v125
	s_nop 0
	v_pk_mul_f32 v[116:117], v[154:155], v[124:125] op_sel_hi:[0,1]
	v_pk_mul_f32 v[116:117], v[112:113], v[116:117]
	v_pk_mul_f32 v[112:113], v[118:119], v[152:153] op_sel_hi:[1,0]
	s_nop 0
	v_exp_f32_e32 v112, v112
	v_exp_f32_e32 v113, v113
	s_nop 0
	v_pk_add_f32 v[112:113], v[112:113], 1.0 op_sel_hi:[1,0]
	s_nop 0
	v_rcp_f32_e32 v112, v112
	v_rcp_f32_e32 v113, v113
	s_nop 0
	v_pk_mul_f32 v[112:113], v[154:155], v[112:113] op_sel_hi:[0,1]
	v_pk_mul_f32 v[118:119], v[114:115], v[112:113]
	v_cvt_pk_bf16_f32 v112, v120, v121
	v_cvt_pk_bf16_f32 v113, v122, v123
	v_cvt_pk_bf16_f32 v114, v116, v117
	v_cvt_pk_bf16_f32 v115, v118, v119
	global_store_dwordx4 v[150:151], v[112:115], off nt
	s_nop 1
	v_or_b32_e32 v114, 16, v138
	v_ashrrev_i32_e32 v115, 31, v114
	v_mad_i64_i32 v[112:113], s[8:9], v114, s16, v[140:141]
	v_lshl_add_u64 v[114:115], v[114:115], 3, s[4:5]
	s_nop 1
	v_mov_b64_e32 v[114:115], v[178:179]
	v_lshl_add_u64 v[112:113], v[112:113], 0, v[142:143]
	v_ffbh_u32_e32 v116, v115
	v_min_u32_e32 v116, 32, v116
	v_lshlrev_b64 v[114:115], v116, v[114:115]
	v_min_u32_e32 v114, 1, v114
	v_or_b32_e32 v114, v115, v114
	v_cvt_f32_u32_e32 v114, v114
	v_sub_u32_e32 v115, 32, v116
	v_ldexp_f32 v114, v114, v115
	v_mul_f32_e32 v114, 0x35800000, v114
	v_fmamk_f32 v114, v114, 0x3a800000, v219
	v_rsq_f32_e32 v115, v114
	s_nop 0
	v_mul_f32_e32 v114, 0xbfb8aa3b, v115
	v_pk_mul_f32 v[118:119], v[108:109], v[114:115] op_sel_hi:[1,0]
	v_mul_f32_e32 v116, v115, v115
	v_exp_f32_e32 v118, v118
	v_exp_f32_e32 v119, v119
	s_nop 0
	v_pk_add_f32 v[118:119], v[118:119], 1.0 op_sel_hi:[1,0]
	s_nop 0
	v_rcp_f32_e32 v118, v118
	v_rcp_f32_e32 v119, v119
	s_nop 0
	v_pk_mul_f32 v[108:109], v[116:117], v[118:119] op_sel_hi:[0,1]
	v_pk_mul_f32 v[104:105], v[104:105], v[108:109]
	v_pk_mul_f32 v[108:109], v[110:111], v[114:115] op_sel_hi:[1,0]
	s_nop 0
	v_exp_f32_e32 v108, v108
	v_exp_f32_e32 v109, v109
	s_nop 0
	v_pk_add_f32 v[108:109], v[108:109], 1.0 op_sel_hi:[1,0]
	s_nop 0
	v_rcp_f32_e32 v108, v108
	v_rcp_f32_e32 v109, v109
	s_nop 0
	v_pk_mul_f32 v[108:109], v[116:117], v[108:109] op_sel_hi:[0,1]
	v_pk_mul_f32 v[106:107], v[106:107], v[108:109]
	v_pk_mul_f32 v[108:109], v[100:101], v[114:115] op_sel_hi:[1,0]
	s_nop 0
	v_exp_f32_e32 v108, v108
	v_exp_f32_e32 v109, v109
	s_nop 0
	v_pk_add_f32 v[108:109], v[108:109], 1.0 op_sel_hi:[1,0]
	s_nop 0
	v_rcp_f32_e32 v108, v108
	v_rcp_f32_e32 v109, v109
	s_nop 0
	v_pk_mul_f32 v[100:101], v[116:117], v[108:109] op_sel_hi:[0,1]
	v_pk_mul_f32 v[100:101], v[96:97], v[100:101]
	v_pk_mul_f32 v[96:97], v[102:103], v[114:115] op_sel_hi:[1,0]
	s_nop 0
	v_exp_f32_e32 v96, v96
	v_exp_f32_e32 v97, v97
	s_nop 0
	v_pk_add_f32 v[96:97], v[96:97], 1.0 op_sel_hi:[1,0]
	s_nop 0
	v_rcp_f32_e32 v96, v96
	v_rcp_f32_e32 v97, v97
	s_nop 0
	v_pk_mul_f32 v[96:97], v[116:117], v[96:97] op_sel_hi:[0,1]
	v_pk_mul_f32 v[102:103], v[98:99], v[96:97]
	v_cvt_pk_bf16_f32 v96, v104, v105
	v_cvt_pk_bf16_f32 v97, v106, v107
	v_cvt_pk_bf16_f32 v98, v100, v101
	v_cvt_pk_bf16_f32 v99, v102, v103
	global_store_dwordx4 v[112:113], v[96:99], off nt
	s_nop 1
	v_or_b32_e32 v98, 32, v138
	v_ashrrev_i32_e32 v99, 31, v98
	v_mad_i64_i32 v[96:97], s[8:9], v98, s16, v[140:141]
	v_lshl_add_u64 v[98:99], v[98:99], 3, s[4:5]
	s_nop 1
	v_mov_b64_e32 v[98:99], v[180:181]
	v_lshl_add_u64 v[96:97], v[96:97], 0, v[142:143]
	v_ffbh_u32_e32 v100, v99
	v_min_u32_e32 v100, 32, v100
	v_lshlrev_b64 v[98:99], v100, v[98:99]
	v_min_u32_e32 v98, 1, v98
	v_or_b32_e32 v98, v99, v98
	v_cvt_f32_u32_e32 v98, v98
	v_sub_u32_e32 v99, 32, v100
	v_ldexp_f32 v98, v98, v99
	v_mul_f32_e32 v98, 0x35800000, v98
	v_fmamk_f32 v98, v98, 0x3a800000, v219
	v_rsq_f32_e32 v99, v98
	s_nop 0
	v_mul_f32_e32 v98, 0xbfb8aa3b, v99
	v_pk_mul_f32 v[102:103], v[92:93], v[98:99] op_sel_hi:[1,0]
	v_mul_f32_e32 v100, v99, v99
	v_exp_f32_e32 v102, v102
	v_exp_f32_e32 v103, v103
	s_nop 0
	v_pk_add_f32 v[102:103], v[102:103], 1.0 op_sel_hi:[1,0]
	s_nop 0
	v_rcp_f32_e32 v102, v102
	v_rcp_f32_e32 v103, v103
	s_nop 0
	v_pk_mul_f32 v[92:93], v[100:101], v[102:103] op_sel_hi:[0,1]
	v_pk_mul_f32 v[88:89], v[88:89], v[92:93]
	v_pk_mul_f32 v[92:93], v[94:95], v[98:99] op_sel_hi:[1,0]
	s_nop 0
	v_exp_f32_e32 v92, v92
	v_exp_f32_e32 v93, v93
	s_nop 0
	v_pk_add_f32 v[92:93], v[92:93], 1.0 op_sel_hi:[1,0]
	s_nop 0
	v_rcp_f32_e32 v92, v92
	v_rcp_f32_e32 v93, v93
	s_nop 0
	v_pk_mul_f32 v[92:93], v[100:101], v[92:93] op_sel_hi:[0,1]
	v_pk_mul_f32 v[90:91], v[90:91], v[92:93]
	v_pk_mul_f32 v[92:93], v[84:85], v[98:99] op_sel_hi:[1,0]
	s_nop 0
	v_exp_f32_e32 v92, v92
	v_exp_f32_e32 v93, v93
	s_nop 0
	v_pk_add_f32 v[92:93], v[92:93], 1.0 op_sel_hi:[1,0]
	s_nop 0
	v_rcp_f32_e32 v92, v92
	v_rcp_f32_e32 v93, v93
	s_nop 0
	v_pk_mul_f32 v[84:85], v[100:101], v[92:93] op_sel_hi:[0,1]
	v_pk_mul_f32 v[84:85], v[80:81], v[84:85]
	v_pk_mul_f32 v[80:81], v[86:87], v[98:99] op_sel_hi:[1,0]
	s_nop 0
	v_exp_f32_e32 v80, v80
	v_exp_f32_e32 v81, v81
	s_nop 0
	v_pk_add_f32 v[80:81], v[80:81], 1.0 op_sel_hi:[1,0]
	s_nop 0
	v_rcp_f32_e32 v80, v80
	v_rcp_f32_e32 v81, v81
	s_nop 0
	v_pk_mul_f32 v[80:81], v[100:101], v[80:81] op_sel_hi:[0,1]
	v_pk_mul_f32 v[86:87], v[82:83], v[80:81]
	v_cvt_pk_bf16_f32 v80, v88, v89
	v_cvt_pk_bf16_f32 v81, v90, v91
	v_cvt_pk_bf16_f32 v82, v84, v85
	v_cvt_pk_bf16_f32 v83, v86, v87
	global_store_dwordx4 v[96:97], v[80:83], off nt
	s_nop 1
	v_or_b32_e32 v82, 48, v138
	v_ashrrev_i32_e32 v83, 31, v82
	v_mad_i64_i32 v[80:81], s[8:9], v82, s16, v[140:141]
	v_lshl_add_u64 v[82:83], v[82:83], 3, s[4:5]
	s_nop 1
	v_mov_b64_e32 v[82:83], v[182:183]
	v_lshl_add_u64 v[80:81], v[80:81], 0, v[142:143]
	v_ffbh_u32_e32 v84, v83
	v_min_u32_e32 v84, 32, v84
	v_lshlrev_b64 v[82:83], v84, v[82:83]
	v_min_u32_e32 v82, 1, v82
	v_or_b32_e32 v82, v83, v82
	v_cvt_f32_u32_e32 v82, v82
	v_sub_u32_e32 v83, 32, v84
	v_ldexp_f32 v82, v82, v83
	v_mul_f32_e32 v82, 0x35800000, v82
	v_fmamk_f32 v82, v82, 0x3a800000, v219
	v_rsq_f32_e32 v82, v82
	s_nop 0
	v_mul_f32_e32 v84, 0xbfb8aa3b, v82
	v_pk_mul_f32 v[86:87], v[76:77], v[84:85] op_sel_hi:[1,0]
	v_mul_f32_e32 v82, v82, v82
	v_exp_f32_e32 v86, v86
	v_exp_f32_e32 v87, v87
	s_nop 0
	v_pk_add_f32 v[86:87], v[86:87], 1.0 op_sel_hi:[1,0]
	s_nop 0
	v_rcp_f32_e32 v86, v86
	v_rcp_f32_e32 v87, v87
	s_nop 0
	v_pk_mul_f32 v[76:77], v[82:83], v[86:87] op_sel_hi:[0,1]
	v_pk_mul_f32 v[72:73], v[72:73], v[76:77]
	v_pk_mul_f32 v[76:77], v[78:79], v[84:85] op_sel_hi:[1,0]
	s_nop 0
	v_exp_f32_e32 v76, v76
	v_exp_f32_e32 v77, v77
	s_nop 0
	v_pk_add_f32 v[76:77], v[76:77], 1.0 op_sel_hi:[1,0]
	s_nop 0
	v_rcp_f32_e32 v76, v76
	v_rcp_f32_e32 v77, v77
	s_nop 0
	v_pk_mul_f32 v[76:77], v[82:83], v[76:77] op_sel_hi:[0,1]
	v_pk_mul_f32 v[74:75], v[74:75], v[76:77]
	v_pk_mul_f32 v[76:77], v[64:65], v[84:85] op_sel_hi:[1,0]
	v_pk_mul_f32 v[64:65], v[64:65], v[68:69]
	v_exp_f32_e32 v76, v76
	v_exp_f32_e32 v77, v77
	s_nop 0
	v_pk_add_f32 v[76:77], v[76:77], 1.0 op_sel_hi:[1,0]
	s_nop 0
	v_rcp_f32_e32 v76, v76
	v_rcp_f32_e32 v77, v77
	s_nop 0
	v_pk_mul_f32 v[68:69], v[82:83], v[76:77] op_sel_hi:[0,1]
	v_pk_mul_f32 v[68:69], v[64:65], v[68:69]
	v_pk_mul_f32 v[64:65], v[66:67], v[84:85] op_sel_hi:[1,0]
	v_cvt_pk_bf16_f32 v66, v68, v69
	v_exp_f32_e32 v64, v64
	v_exp_f32_e32 v65, v65
	s_nop 0
	v_pk_add_f32 v[64:65], v[64:65], 1.0 op_sel_hi:[1,0]
	s_nop 0
	v_rcp_f32_e32 v64, v64
	v_rcp_f32_e32 v65, v65
	s_nop 0
	v_pk_mul_f32 v[64:65], v[82:83], v[64:65] op_sel_hi:[0,1]
	v_pk_mul_f32 v[70:71], v[70:71], v[64:65]
	v_cvt_pk_bf16_f32 v64, v72, v73
	v_cvt_pk_bf16_f32 v65, v74, v75
	v_cvt_pk_bf16_f32 v67, v70, v71
	global_store_dwordx4 v[80:81], v[64:67], off nt
	s_nop 1
	v_mov_b64_e32 v[66:67], v[184:185]
	v_ffbh_u32_e32 v68, v67
	v_min_u32_e32 v68, 32, v68
	v_lshlrev_b64 v[66:67], v68, v[66:67]
	v_min_u32_e32 v66, 1, v66
	v_or_b32_e32 v66, v67, v66
	v_cvt_f32_u32_e32 v66, v66
	v_sub_u32_e32 v67, 32, v68
	v_add_u32_e32 v64, 0x80, v138
	v_mad_i64_i32 v[64:65], s[8:9], v64, s16, v[140:141]
	v_ldexp_f32 v66, v66, v67
	v_mul_f32_e32 v66, 0x35800000, v66
	v_fmamk_f32 v66, v66, 0x3a800000, v219
	v_rsq_f32_e32 v66, v66
	v_lshl_add_u64 v[64:65], v[64:65], 0, v[142:143]
	v_mul_f32_e32 v68, 0xbfb8aa3b, v66
	v_pk_mul_f32 v[70:71], v[60:61], v[68:69] op_sel_hi:[1,0]
	v_mul_f32_e32 v66, v66, v66
	v_exp_f32_e32 v70, v70
	v_exp_f32_e32 v71, v71
	s_nop 0
	v_pk_add_f32 v[70:71], v[70:71], 1.0 op_sel_hi:[1,0]
	s_nop 0
	v_rcp_f32_e32 v70, v70
	v_rcp_f32_e32 v71, v71
	s_nop 0
	v_pk_mul_f32 v[60:61], v[66:67], v[70:71] op_sel_hi:[0,1]
	v_pk_mul_f32 v[56:57], v[56:57], v[60:61]
	v_pk_mul_f32 v[60:61], v[62:63], v[68:69] op_sel_hi:[1,0]
	s_nop 0
	v_exp_f32_e32 v60, v60
	v_exp_f32_e32 v61, v61
	s_nop 0
	v_pk_add_f32 v[60:61], v[60:61], 1.0 op_sel_hi:[1,0]
	s_nop 0
	v_rcp_f32_e32 v60, v60
	v_rcp_f32_e32 v61, v61
	s_nop 0
	v_pk_mul_f32 v[60:61], v[66:67], v[60:61] op_sel_hi:[0,1]
	v_pk_mul_f32 v[58:59], v[58:59], v[60:61]
	v_pk_mul_f32 v[60:61], v[48:49], v[68:69] op_sel_hi:[1,0]
	v_pk_mul_f32 v[48:49], v[48:49], v[52:53]
	v_exp_f32_e32 v60, v60
	v_exp_f32_e32 v61, v61
	s_nop 0
	v_pk_add_f32 v[60:61], v[60:61], 1.0 op_sel_hi:[1,0]
	s_nop 0
	v_rcp_f32_e32 v60, v60
	v_rcp_f32_e32 v61, v61
	s_nop 0
	v_pk_mul_f32 v[52:53], v[66:67], v[60:61] op_sel_hi:[0,1]
	v_pk_mul_f32 v[52:53], v[48:49], v[52:53]
	v_pk_mul_f32 v[48:49], v[50:51], v[68:69] op_sel_hi:[1,0]
	v_cvt_pk_bf16_f32 v50, v52, v53
	v_exp_f32_e32 v48, v48
	v_exp_f32_e32 v49, v49
	s_nop 0
	v_pk_add_f32 v[48:49], v[48:49], 1.0 op_sel_hi:[1,0]
	s_nop 0
	v_rcp_f32_e32 v48, v48
	v_rcp_f32_e32 v49, v49
	s_nop 0
	v_pk_mul_f32 v[48:49], v[66:67], v[48:49] op_sel_hi:[0,1]
	v_pk_mul_f32 v[54:55], v[54:55], v[48:49]
	v_cvt_pk_bf16_f32 v48, v56, v57
	v_cvt_pk_bf16_f32 v49, v58, v59
	v_cvt_pk_bf16_f32 v51, v54, v55
	global_store_dwordx4 v[64:65], v[48:51], off nt
	s_nop 1
	v_mov_b64_e32 v[50:51], v[186:187]
	v_ffbh_u32_e32 v52, v51
	v_min_u32_e32 v52, 32, v52
	v_lshlrev_b64 v[50:51], v52, v[50:51]
	v_min_u32_e32 v50, 1, v50
	v_or_b32_e32 v50, v51, v50
	v_cvt_f32_u32_e32 v50, v50
	v_sub_u32_e32 v51, 32, v52
	v_add_u32_e32 v48, 0x90, v138
	v_mad_i64_i32 v[48:49], s[8:9], v48, s16, v[140:141]
	v_ldexp_f32 v50, v50, v51
	v_mul_f32_e32 v50, 0x35800000, v50
	v_fmamk_f32 v50, v50, 0x3a800000, v219
	v_rsq_f32_e32 v50, v50
	v_lshl_add_u64 v[48:49], v[48:49], 0, v[142:143]
	v_mul_f32_e32 v52, 0xbfb8aa3b, v50
	v_pk_mul_f32 v[54:55], v[44:45], v[52:53] op_sel_hi:[1,0]
	v_mul_f32_e32 v50, v50, v50
	v_exp_f32_e32 v54, v54
	v_exp_f32_e32 v55, v55
	s_nop 0
	v_pk_add_f32 v[54:55], v[54:55], 1.0 op_sel_hi:[1,0]
	s_nop 0
	v_rcp_f32_e32 v54, v54
	v_rcp_f32_e32 v55, v55
	s_nop 0
	v_pk_mul_f32 v[44:45], v[50:51], v[54:55] op_sel_hi:[0,1]
	v_pk_mul_f32 v[40:41], v[40:41], v[44:45]
	v_pk_mul_f32 v[44:45], v[46:47], v[52:53] op_sel_hi:[1,0]
	s_nop 0
	v_exp_f32_e32 v44, v44
	v_exp_f32_e32 v45, v45
	s_nop 0
	v_pk_add_f32 v[44:45], v[44:45], 1.0 op_sel_hi:[1,0]
	s_nop 0
	v_rcp_f32_e32 v44, v44
	v_rcp_f32_e32 v45, v45
	s_nop 0
	v_pk_mul_f32 v[44:45], v[50:51], v[44:45] op_sel_hi:[0,1]
	v_pk_mul_f32 v[42:43], v[42:43], v[44:45]
	v_pk_mul_f32 v[44:45], v[32:33], v[52:53] op_sel_hi:[1,0]
	v_pk_mul_f32 v[32:33], v[32:33], v[36:37]
	v_exp_f32_e32 v44, v44
	v_exp_f32_e32 v45, v45
	s_nop 0
	v_pk_add_f32 v[44:45], v[44:45], 1.0 op_sel_hi:[1,0]
	s_nop 0
	v_rcp_f32_e32 v44, v44
	v_rcp_f32_e32 v45, v45
	s_nop 0
	v_pk_mul_f32 v[36:37], v[50:51], v[44:45] op_sel_hi:[0,1]
	v_pk_mul_f32 v[36:37], v[32:33], v[36:37]
	v_pk_mul_f32 v[32:33], v[34:35], v[52:53] op_sel_hi:[1,0]
	v_cvt_pk_bf16_f32 v34, v36, v37
	v_exp_f32_e32 v32, v32
	v_exp_f32_e32 v33, v33
	s_nop 0
	v_pk_add_f32 v[32:33], v[32:33], 1.0 op_sel_hi:[1,0]
	s_nop 0
	v_rcp_f32_e32 v32, v32
	v_rcp_f32_e32 v33, v33
	s_nop 0
	v_pk_mul_f32 v[32:33], v[50:51], v[32:33] op_sel_hi:[0,1]
	v_pk_mul_f32 v[38:39], v[38:39], v[32:33]
	v_cvt_pk_bf16_f32 v32, v40, v41
	v_cvt_pk_bf16_f32 v33, v42, v43
	v_cvt_pk_bf16_f32 v35, v38, v39
	global_store_dwordx4 v[48:49], v[32:35], off nt
	s_nop 1
	v_mov_b64_e32 v[34:35], v[188:189]
	v_ffbh_u32_e32 v36, v35
	v_min_u32_e32 v36, 32, v36
	v_lshlrev_b64 v[34:35], v36, v[34:35]
	v_min_u32_e32 v34, 1, v34
	v_or_b32_e32 v34, v35, v34
	v_cvt_f32_u32_e32 v34, v34
	v_sub_u32_e32 v35, 32, v36
	v_add_u32_e32 v32, 0xa0, v138
	v_mad_i64_i32 v[32:33], s[8:9], v32, s16, v[140:141]
	v_ldexp_f32 v34, v34, v35
	v_mul_f32_e32 v34, 0x35800000, v34
	v_fmamk_f32 v34, v34, 0x3a800000, v219
	v_rsq_f32_e32 v34, v34
	v_lshl_add_u64 v[32:33], v[32:33], 0, v[142:143]
	v_mul_f32_e32 v36, 0xbfb8aa3b, v34
	v_pk_mul_f32 v[38:39], v[28:29], v[36:37] op_sel_hi:[1,0]
	v_mul_f32_e32 v34, v34, v34
	v_exp_f32_e32 v38, v38
	v_exp_f32_e32 v39, v39
	s_nop 0
	v_pk_add_f32 v[38:39], v[38:39], 1.0 op_sel_hi:[1,0]
	s_nop 0
	v_rcp_f32_e32 v38, v38
	v_rcp_f32_e32 v39, v39
	s_nop 0
	v_pk_mul_f32 v[28:29], v[34:35], v[38:39] op_sel_hi:[0,1]
	v_pk_mul_f32 v[24:25], v[24:25], v[28:29]
	v_pk_mul_f32 v[28:29], v[30:31], v[36:37] op_sel_hi:[1,0]
	s_nop 0
	v_exp_f32_e32 v28, v28
	v_exp_f32_e32 v29, v29
	s_nop 0
	v_pk_add_f32 v[28:29], v[28:29], 1.0 op_sel_hi:[1,0]
	s_nop 0
	v_rcp_f32_e32 v28, v28
	v_rcp_f32_e32 v29, v29
	s_nop 0
	v_pk_mul_f32 v[28:29], v[34:35], v[28:29] op_sel_hi:[0,1]
	v_pk_mul_f32 v[26:27], v[26:27], v[28:29]
	v_pk_mul_f32 v[28:29], v[16:17], v[36:37] op_sel_hi:[1,0]
	v_pk_mul_f32 v[16:17], v[16:17], v[20:21]
	v_exp_f32_e32 v28, v28
	v_exp_f32_e32 v29, v29
	s_nop 0
	v_pk_add_f32 v[28:29], v[28:29], 1.0 op_sel_hi:[1,0]
	s_nop 0
	v_rcp_f32_e32 v28, v28
	v_rcp_f32_e32 v29, v29
	s_nop 0
	v_pk_mul_f32 v[20:21], v[34:35], v[28:29] op_sel_hi:[0,1]
	v_pk_mul_f32 v[20:21], v[16:17], v[20:21]
	v_pk_mul_f32 v[16:17], v[18:19], v[36:37] op_sel_hi:[1,0]
	v_cvt_pk_bf16_f32 v18, v20, v21
	v_exp_f32_e32 v16, v16
	v_exp_f32_e32 v17, v17
	s_nop 0
	v_pk_add_f32 v[16:17], v[16:17], 1.0 op_sel_hi:[1,0]
	s_nop 0
	v_rcp_f32_e32 v16, v16
	v_rcp_f32_e32 v17, v17
	s_nop 0
	v_pk_mul_f32 v[16:17], v[34:35], v[16:17] op_sel_hi:[0,1]
	v_pk_mul_f32 v[22:23], v[22:23], v[16:17]
	v_cvt_pk_bf16_f32 v16, v24, v25
	v_cvt_pk_bf16_f32 v17, v26, v27
	v_cvt_pk_bf16_f32 v19, v22, v23
	global_store_dwordx4 v[32:33], v[16:19], off nt
	s_nop 1
	v_mov_b64_e32 v[18:19], v[190:191]
	v_ffbh_u32_e32 v20, v19
	v_min_u32_e32 v20, 32, v20
	v_lshlrev_b64 v[18:19], v20, v[18:19]
	v_min_u32_e32 v18, 1, v18
	v_or_b32_e32 v18, v19, v18
	v_cvt_f32_u32_e32 v18, v18
	v_sub_u32_e32 v19, 32, v20
	v_add_u32_e32 v16, 0xb0, v138
	v_mad_i64_i32 v[16:17], s[8:9], v16, s16, v[140:141]
	v_ldexp_f32 v18, v18, v19
	v_mul_f32_e32 v18, 0x35800000, v18
	v_fmamk_f32 v18, v18, 0x3a800000, v219
	v_rsq_f32_e32 v18, v18
	v_lshl_add_u64 v[16:17], v[16:17], 0, v[142:143]
	s_mov_b64 s[8:9], -1
	v_mul_f32_e32 v20, 0xbfb8aa3b, v18
	v_pk_mul_f32 v[22:23], v[12:13], v[20:21] op_sel_hi:[1,0]
	v_mul_f32_e32 v18, v18, v18
	v_exp_f32_e32 v22, v22
	v_exp_f32_e32 v23, v23
	s_nop 0
	v_pk_add_f32 v[22:23], v[22:23], 1.0 op_sel_hi:[1,0]
	s_nop 0
	v_rcp_f32_e32 v22, v22
	v_rcp_f32_e32 v23, v23
	s_nop 0
	v_pk_mul_f32 v[12:13], v[18:19], v[22:23] op_sel_hi:[0,1]
	v_pk_mul_f32 v[8:9], v[8:9], v[12:13]
	v_pk_mul_f32 v[12:13], v[14:15], v[20:21] op_sel_hi:[1,0]
	s_nop 0
	v_exp_f32_e32 v12, v12
	v_exp_f32_e32 v13, v13
	s_nop 0
	v_pk_add_f32 v[12:13], v[12:13], 1.0 op_sel_hi:[1,0]
	s_nop 0
	v_rcp_f32_e32 v12, v12
	v_rcp_f32_e32 v13, v13
	s_nop 0
	v_pk_mul_f32 v[12:13], v[18:19], v[12:13] op_sel_hi:[0,1]
	v_pk_mul_f32 v[10:11], v[10:11], v[12:13]
	v_pk_mul_f32 v[12:13], v[0:1], v[20:21] op_sel_hi:[1,0]
	v_pk_mul_f32 v[0:1], v[0:1], v[4:5]
	v_exp_f32_e32 v12, v12
	v_exp_f32_e32 v13, v13
	s_nop 0
	v_pk_add_f32 v[12:13], v[12:13], 1.0 op_sel_hi:[1,0]
	s_nop 0
	v_rcp_f32_e32 v12, v12
	v_rcp_f32_e32 v13, v13
	s_nop 0
	v_pk_mul_f32 v[4:5], v[18:19], v[12:13] op_sel_hi:[0,1]
	v_pk_mul_f32 v[4:5], v[0:1], v[4:5]
	v_pk_mul_f32 v[0:1], v[2:3], v[20:21] op_sel_hi:[1,0]
	v_cvt_pk_bf16_f32 v2, v4, v5
	v_exp_f32_e32 v0, v0
	v_exp_f32_e32 v1, v1
	s_nop 0
	v_pk_add_f32 v[0:1], v[0:1], 1.0 op_sel_hi:[1,0]
	s_nop 0
	v_rcp_f32_e32 v0, v0
	v_rcp_f32_e32 v1, v1
	s_nop 0
	v_pk_mul_f32 v[0:1], v[18:19], v[0:1] op_sel_hi:[0,1]
	v_pk_mul_f32 v[6:7], v[6:7], v[0:1]
	v_cvt_pk_bf16_f32 v0, v8, v9
	v_cvt_pk_bf16_f32 v1, v10, v11
	v_cvt_pk_bf16_f32 v3, v6, v7
	global_store_dwordx4 v[16:17], v[0:3], off nt
	s_cbranch_vccnz .LBB0_208
	s_andn2_b64 vcc, exec, s[0:1]
	s_cbranch_vccnz .LBB0_207
	s_barrier
	s_branch .LBB0_207

.LBB0_313:
	s_mov_b64 s[12:13], s[2:3]
	s_waitcnt vmcnt(15)
	v_lshlrev_b32_e32 v158, 16, v146
	v_and_b32_e32 v159, 0xffff0000, v146
	v_pk_add_f32 v[124:125], v[124:125], v[158:159]
	v_lshlrev_b32_e32 v140, 16, v147
	v_and_b32_e32 v141, 0xffff0000, v147
	v_pk_add_f32 v[126:127], v[126:127], v[140:141]
	v_lshlrev_b32_e32 v158, 16, v148
	v_and_b32_e32 v159, 0xffff0000, v148
	v_pk_add_f32 v[120:121], v[120:121], v[158:159]
	v_lshlrev_b32_e32 v140, 16, v149
	v_and_b32_e32 v141, 0xffff0000, v149
	v_pk_add_f32 v[122:123], v[122:123], v[140:141]
	v_cvt_pk_bf16_f32 v146, v124, v125
	v_cvt_pk_bf16_f32 v147, v126, v127
	v_cvt_pk_bf16_f32 v148, v120, v121
	v_cvt_pk_bf16_f32 v149, v122, v123
	global_store_dwordx4 v138, v[146:149], s[12:13] nt
	v_pk_mul_f32 v[124:125], v[124:125], v[124:125]
	v_pk_fma_f32 v[124:125], v[126:127], v[126:127], v[124:125]
	v_pk_fma_f32 v[124:125], v[120:121], v[120:121], v[124:125]
	v_pk_fma_f32 v[124:125], v[122:123], v[122:123], v[124:125]
	s_waitcnt vmcnt(15)
	v_lshlrev_b32_e32 v158, 16, v150
	v_and_b32_e32 v159, 0xffff0000, v150
	v_pk_add_f32 v[116:117], v[116:117], v[158:159]
	v_lshlrev_b32_e32 v140, 16, v151
	v_and_b32_e32 v141, 0xffff0000, v151
	v_pk_add_f32 v[118:119], v[118:119], v[140:141]
	v_lshlrev_b32_e32 v158, 16, v152
	v_and_b32_e32 v159, 0xffff0000, v152
	v_pk_add_f32 v[112:113], v[112:113], v[158:159]
	v_lshlrev_b32_e32 v140, 16, v153
	v_and_b32_e32 v141, 0xffff0000, v153
	v_pk_add_f32 v[114:115], v[114:115], v[140:141]
	v_cvt_pk_bf16_f32 v150, v116, v117
	v_cvt_pk_bf16_f32 v151, v118, v119
	v_cvt_pk_bf16_f32 v152, v112, v113
	v_cvt_pk_bf16_f32 v153, v114, v115
	global_store_dwordx4 v138, v[150:153], s[12:13] offset:256 nt
	v_pk_fma_f32 v[124:125], v[116:117], v[116:117], v[124:125]
	v_pk_fma_f32 v[124:125], v[118:119], v[118:119], v[124:125]
	v_pk_fma_f32 v[124:125], v[112:113], v[112:113], v[124:125]
	v_pk_fma_f32 v[124:125], v[114:115], v[114:115], v[124:125]
	v_add_f32_e32 v124, v124, v125
	s_add_u32 s12, s12, 0x8000
	s_addc_u32 s13, s13, 0
	s_waitcnt vmcnt(15)
	v_lshlrev_b32_e32 v158, 16, v154
	v_and_b32_e32 v159, 0xffff0000, v154
	v_pk_add_f32 v[108:109], v[108:109], v[158:159]
	v_lshlrev_b32_e32 v140, 16, v155
	v_and_b32_e32 v141, 0xffff0000, v155
	v_pk_add_f32 v[110:111], v[110:111], v[140:141]
	v_lshlrev_b32_e32 v158, 16, v156
	v_and_b32_e32 v159, 0xffff0000, v156
	v_pk_add_f32 v[104:105], v[104:105], v[158:159]
	v_lshlrev_b32_e32 v140, 16, v157
	v_and_b32_e32 v141, 0xffff0000, v157
	v_pk_add_f32 v[106:107], v[106:107], v[140:141]
	v_cvt_pk_bf16_f32 v154, v108, v109
	v_cvt_pk_bf16_f32 v155, v110, v111
	v_cvt_pk_bf16_f32 v156, v104, v105
	v_cvt_pk_bf16_f32 v157, v106, v107
	global_store_dwordx4 v138, v[154:157], s[12:13] nt
	v_pk_mul_f32 v[108:109], v[108:109], v[108:109]
	v_pk_fma_f32 v[108:109], v[110:111], v[110:111], v[108:109]
	v_pk_fma_f32 v[108:109], v[104:105], v[104:105], v[108:109]
	v_pk_fma_f32 v[108:109], v[106:107], v[106:107], v[108:109]
	s_waitcnt vmcnt(15)
	v_lshlrev_b32_e32 v158, 16, v162
	v_and_b32_e32 v159, 0xffff0000, v162
	v_pk_add_f32 v[100:101], v[100:101], v[158:159]
	v_lshlrev_b32_e32 v140, 16, v163
	v_and_b32_e32 v141, 0xffff0000, v163
	v_pk_add_f32 v[102:103], v[102:103], v[140:141]
	v_lshlrev_b32_e32 v158, 16, v164
	v_and_b32_e32 v159, 0xffff0000, v164
	v_pk_add_f32 v[96:97], v[96:97], v[158:159]
	v_lshlrev_b32_e32 v140, 16, v165
	v_and_b32_e32 v141, 0xffff0000, v165
	v_pk_add_f32 v[98:99], v[98:99], v[140:141]
	v_cvt_pk_bf16_f32 v162, v100, v101
	v_cvt_pk_bf16_f32 v163, v102, v103
	v_cvt_pk_bf16_f32 v164, v96, v97
	v_cvt_pk_bf16_f32 v165, v98, v99
	global_store_dwordx4 v138, v[162:165], s[12:13] offset:256 nt
	v_pk_fma_f32 v[108:109], v[100:101], v[100:101], v[108:109]
	v_pk_fma_f32 v[108:109], v[102:103], v[102:103], v[108:109]
	v_pk_fma_f32 v[108:109], v[96:97], v[96:97], v[108:109]
	v_pk_fma_f32 v[108:109], v[98:99], v[98:99], v[108:109]
	v_add_f32_e32 v108, v108, v109
	s_add_u32 s12, s12, 0x8000
	s_addc_u32 s13, s13, 0
	s_waitcnt vmcnt(15)
	v_lshlrev_b32_e32 v158, 16, v166
	v_and_b32_e32 v159, 0xffff0000, v166
	v_pk_add_f32 v[92:93], v[92:93], v[158:159]
	v_lshlrev_b32_e32 v140, 16, v167
	v_and_b32_e32 v141, 0xffff0000, v167
	v_pk_add_f32 v[94:95], v[94:95], v[140:141]
	v_lshlrev_b32_e32 v158, 16, v168
	v_and_b32_e32 v159, 0xffff0000, v168
	v_pk_add_f32 v[88:89], v[88:89], v[158:159]
	v_lshlrev_b32_e32 v140, 16, v169
	v_and_b32_e32 v141, 0xffff0000, v169
	v_pk_add_f32 v[90:91], v[90:91], v[140:141]
	v_cvt_pk_bf16_f32 v166, v92, v93
	v_cvt_pk_bf16_f32 v167, v94, v95
	v_cvt_pk_bf16_f32 v168, v88, v89
	v_cvt_pk_bf16_f32 v169, v90, v91
	global_store_dwordx4 v138, v[166:169], s[12:13] nt
	v_pk_mul_f32 v[92:93], v[92:93], v[92:93]
	v_pk_fma_f32 v[92:93], v[94:95], v[94:95], v[92:93]
	v_pk_fma_f32 v[92:93], v[88:89], v[88:89], v[92:93]
	v_pk_fma_f32 v[92:93], v[90:91], v[90:91], v[92:93]
	s_waitcnt vmcnt(15)
	v_lshlrev_b32_e32 v158, 16, v174
	v_and_b32_e32 v159, 0xffff0000, v174
	v_pk_add_f32 v[84:85], v[84:85], v[158:159]
	v_lshlrev_b32_e32 v140, 16, v175
	v_and_b32_e32 v141, 0xffff0000, v175
	v_pk_add_f32 v[86:87], v[86:87], v[140:141]
	v_lshlrev_b32_e32 v158, 16, v176
	v_and_b32_e32 v159, 0xffff0000, v176
	v_pk_add_f32 v[80:81], v[80:81], v[158:159]
	v_lshlrev_b32_e32 v140, 16, v177
	v_and_b32_e32 v141, 0xffff0000, v177
	v_pk_add_f32 v[82:83], v[82:83], v[140:141]
	v_cvt_pk_bf16_f32 v174, v84, v85
	v_cvt_pk_bf16_f32 v175, v86, v87
	v_cvt_pk_bf16_f32 v176, v80, v81
	v_cvt_pk_bf16_f32 v177, v82, v83
	global_store_dwordx4 v138, v[174:177], s[12:13] offset:256 nt
	v_pk_fma_f32 v[92:93], v[84:85], v[84:85], v[92:93]
	v_pk_fma_f32 v[92:93], v[86:87], v[86:87], v[92:93]
	v_pk_fma_f32 v[92:93], v[80:81], v[80:81], v[92:93]
	v_pk_fma_f32 v[92:93], v[82:83], v[82:83], v[92:93]
	v_add_f32_e32 v92, v92, v93
	s_add_u32 s12, s12, 0x8000
	s_addc_u32 s13, s13, 0
	s_waitcnt vmcnt(15)
	v_lshlrev_b32_e32 v158, 16, v178
	v_and_b32_e32 v159, 0xffff0000, v178
	v_pk_add_f32 v[76:77], v[76:77], v[158:159]
	v_lshlrev_b32_e32 v140, 16, v179
	v_and_b32_e32 v141, 0xffff0000, v179
	v_pk_add_f32 v[78:79], v[78:79], v[140:141]
	v_lshlrev_b32_e32 v158, 16, v180
	v_and_b32_e32 v159, 0xffff0000, v180
	v_pk_add_f32 v[72:73], v[72:73], v[158:159]
	v_lshlrev_b32_e32 v140, 16, v181
	v_and_b32_e32 v141, 0xffff0000, v181
	v_pk_add_f32 v[74:75], v[74:75], v[140:141]
	v_cvt_pk_bf16_f32 v178, v76, v77
	v_cvt_pk_bf16_f32 v179, v78, v79
	v_cvt_pk_bf16_f32 v180, v72, v73
	v_cvt_pk_bf16_f32 v181, v74, v75
	global_store_dwordx4 v138, v[178:181], s[12:13] nt
	v_pk_mul_f32 v[76:77], v[76:77], v[76:77]
	v_pk_fma_f32 v[76:77], v[78:79], v[78:79], v[76:77]
	v_pk_fma_f32 v[76:77], v[72:73], v[72:73], v[76:77]
	v_pk_fma_f32 v[76:77], v[74:75], v[74:75], v[76:77]
	s_waitcnt vmcnt(15)
	v_lshlrev_b32_e32 v158, 16, v182
	v_and_b32_e32 v159, 0xffff0000, v182
	v_pk_add_f32 v[68:69], v[68:69], v[158:159]
	v_lshlrev_b32_e32 v140, 16, v183
	v_and_b32_e32 v141, 0xffff0000, v183
	v_pk_add_f32 v[70:71], v[70:71], v[140:141]
	v_lshlrev_b32_e32 v158, 16, v184
	v_and_b32_e32 v159, 0xffff0000, v184
	v_pk_add_f32 v[64:65], v[64:65], v[158:159]
	v_lshlrev_b32_e32 v140, 16, v185
	v_and_b32_e32 v141, 0xffff0000, v185
	v_pk_add_f32 v[66:67], v[66:67], v[140:141]
	v_cvt_pk_bf16_f32 v182, v68, v69
	v_cvt_pk_bf16_f32 v183, v70, v71
	v_cvt_pk_bf16_f32 v184, v64, v65
	v_cvt_pk_bf16_f32 v185, v66, v67
	global_store_dwordx4 v138, v[182:185], s[12:13] offset:256 nt
	v_pk_fma_f32 v[76:77], v[68:69], v[68:69], v[76:77]
	v_pk_fma_f32 v[76:77], v[70:71], v[70:71], v[76:77]
	v_pk_fma_f32 v[76:77], v[64:65], v[64:65], v[76:77]
	v_pk_fma_f32 v[76:77], v[66:67], v[66:67], v[76:77]
	v_add_f32_e32 v76, v76, v77
	s_add_u32 s12, s12, 0x28000
	s_addc_u32 s13, s13, 0
	s_waitcnt vmcnt(15)
	v_lshlrev_b32_e32 v158, 16, v186
	v_and_b32_e32 v159, 0xffff0000, v186
	v_pk_add_f32 v[60:61], v[60:61], v[158:159]
	v_lshlrev_b32_e32 v140, 16, v187
	v_and_b32_e32 v141, 0xffff0000, v187
	v_pk_add_f32 v[62:63], v[62:63], v[140:141]
	v_lshlrev_b32_e32 v158, 16, v188
	v_and_b32_e32 v159, 0xffff0000, v188
	v_pk_add_f32 v[56:57], v[56:57], v[158:159]
	v_lshlrev_b32_e32 v140, 16, v189
	v_and_b32_e32 v141, 0xffff0000, v189
	v_pk_add_f32 v[58:59], v[58:59], v[140:141]
	v_cvt_pk_bf16_f32 v186, v60, v61
	v_cvt_pk_bf16_f32 v187, v62, v63
	v_cvt_pk_bf16_f32 v188, v56, v57
	v_cvt_pk_bf16_f32 v189, v58, v59
	global_store_dwordx4 v138, v[186:189], s[12:13] nt
	v_pk_mul_f32 v[60:61], v[60:61], v[60:61]
	v_pk_fma_f32 v[60:61], v[62:63], v[62:63], v[60:61]
	v_pk_fma_f32 v[60:61], v[56:57], v[56:57], v[60:61]
	v_pk_fma_f32 v[60:61], v[58:59], v[58:59], v[60:61]
	s_waitcnt vmcnt(15)
	v_lshlrev_b32_e32 v158, 16, v190
	v_and_b32_e32 v159, 0xffff0000, v190
	v_pk_add_f32 v[52:53], v[52:53], v[158:159]
	v_lshlrev_b32_e32 v140, 16, v191
	v_and_b32_e32 v141, 0xffff0000, v191
	v_pk_add_f32 v[54:55], v[54:55], v[140:141]
	v_lshlrev_b32_e32 v158, 16, v192
	v_and_b32_e32 v159, 0xffff0000, v192
	v_pk_add_f32 v[48:49], v[48:49], v[158:159]
	v_lshlrev_b32_e32 v140, 16, v193
	v_and_b32_e32 v141, 0xffff0000, v193
	v_pk_add_f32 v[50:51], v[50:51], v[140:141]
	v_cvt_pk_bf16_f32 v190, v52, v53
	v_cvt_pk_bf16_f32 v191, v54, v55
	v_cvt_pk_bf16_f32 v192, v48, v49
	v_cvt_pk_bf16_f32 v193, v50, v51
	global_store_dwordx4 v138, v[190:193], s[12:13] offset:256 nt
	v_pk_fma_f32 v[60:61], v[52:53], v[52:53], v[60:61]
	v_pk_fma_f32 v[60:61], v[54:55], v[54:55], v[60:61]
	v_pk_fma_f32 v[60:61], v[48:49], v[48:49], v[60:61]
	v_pk_fma_f32 v[60:61], v[50:51], v[50:51], v[60:61]
	v_add_f32_e32 v60, v60, v61
	s_add_u32 s12, s12, 0x8000
	s_addc_u32 s13, s13, 0
	s_waitcnt vmcnt(15)
	v_lshlrev_b32_e32 v158, 16, v194
	v_and_b32_e32 v159, 0xffff0000, v194
	v_pk_add_f32 v[44:45], v[44:45], v[158:159]
	v_lshlrev_b32_e32 v140, 16, v195
	v_and_b32_e32 v141, 0xffff0000, v195
	v_pk_add_f32 v[46:47], v[46:47], v[140:141]
	v_lshlrev_b32_e32 v158, 16, v196
	v_and_b32_e32 v159, 0xffff0000, v196
	v_pk_add_f32 v[40:41], v[40:41], v[158:159]
	v_lshlrev_b32_e32 v140, 16, v197
	v_and_b32_e32 v141, 0xffff0000, v197
	v_pk_add_f32 v[42:43], v[42:43], v[140:141]
	v_cvt_pk_bf16_f32 v194, v44, v45
	v_cvt_pk_bf16_f32 v195, v46, v47
	v_cvt_pk_bf16_f32 v196, v40, v41
	v_cvt_pk_bf16_f32 v197, v42, v43
	global_store_dwordx4 v138, v[194:197], s[12:13] nt
	v_pk_mul_f32 v[44:45], v[44:45], v[44:45]
	v_pk_fma_f32 v[44:45], v[46:47], v[46:47], v[44:45]
	v_pk_fma_f32 v[44:45], v[40:41], v[40:41], v[44:45]
	v_pk_fma_f32 v[44:45], v[42:43], v[42:43], v[44:45]
	s_waitcnt vmcnt(15)
	v_lshlrev_b32_e32 v158, 16, v198
	v_and_b32_e32 v159, 0xffff0000, v198
	v_pk_add_f32 v[36:37], v[36:37], v[158:159]
	v_lshlrev_b32_e32 v140, 16, v199
	v_and_b32_e32 v141, 0xffff0000, v199
	v_pk_add_f32 v[38:39], v[38:39], v[140:141]
	v_lshlrev_b32_e32 v158, 16, v200
	v_and_b32_e32 v159, 0xffff0000, v200
	v_pk_add_f32 v[32:33], v[32:33], v[158:159]
	v_lshlrev_b32_e32 v140, 16, v201
	v_and_b32_e32 v141, 0xffff0000, v201
	v_pk_add_f32 v[34:35], v[34:35], v[140:141]
	v_cvt_pk_bf16_f32 v198, v36, v37
	v_cvt_pk_bf16_f32 v199, v38, v39
	v_cvt_pk_bf16_f32 v200, v32, v33
	v_cvt_pk_bf16_f32 v201, v34, v35
	global_store_dwordx4 v138, v[198:201], s[12:13] offset:256 nt
	v_pk_fma_f32 v[44:45], v[36:37], v[36:37], v[44:45]
	v_pk_fma_f32 v[44:45], v[38:39], v[38:39], v[44:45]
	v_pk_fma_f32 v[44:45], v[32:33], v[32:33], v[44:45]
	v_pk_fma_f32 v[44:45], v[34:35], v[34:35], v[44:45]
	v_add_f32_e32 v44, v44, v45
	s_add_u32 s12, s12, 0x8000
	s_addc_u32 s13, s13, 0
	s_waitcnt vmcnt(15)
	v_lshlrev_b32_e32 v158, 16, v202
	v_and_b32_e32 v159, 0xffff0000, v202
	v_pk_add_f32 v[28:29], v[28:29], v[158:159]
	v_lshlrev_b32_e32 v140, 16, v203
	v_and_b32_e32 v141, 0xffff0000, v203
	v_pk_add_f32 v[30:31], v[30:31], v[140:141]
	v_lshlrev_b32_e32 v158, 16, v204
	v_and_b32_e32 v159, 0xffff0000, v204
	v_pk_add_f32 v[24:25], v[24:25], v[158:159]
	v_lshlrev_b32_e32 v140, 16, v205
	v_and_b32_e32 v141, 0xffff0000, v205
	v_pk_add_f32 v[26:27], v[26:27], v[140:141]
	v_cvt_pk_bf16_f32 v202, v28, v29
	v_cvt_pk_bf16_f32 v203, v30, v31
	v_cvt_pk_bf16_f32 v204, v24, v25
	v_cvt_pk_bf16_f32 v205, v26, v27
	global_store_dwordx4 v138, v[202:205], s[12:13] nt
	v_pk_mul_f32 v[28:29], v[28:29], v[28:29]
	v_pk_fma_f32 v[28:29], v[30:31], v[30:31], v[28:29]
	v_pk_fma_f32 v[28:29], v[24:25], v[24:25], v[28:29]
	v_pk_fma_f32 v[28:29], v[26:27], v[26:27], v[28:29]
	s_waitcnt vmcnt(15)
	v_lshlrev_b32_e32 v158, 16, v206
	v_and_b32_e32 v159, 0xffff0000, v206
	v_pk_add_f32 v[20:21], v[20:21], v[158:159]
	v_lshlrev_b32_e32 v140, 16, v207
	v_and_b32_e32 v141, 0xffff0000, v207
	v_pk_add_f32 v[22:23], v[22:23], v[140:141]
	v_lshlrev_b32_e32 v158, 16, v208
	v_and_b32_e32 v159, 0xffff0000, v208
	v_pk_add_f32 v[16:17], v[16:17], v[158:159]
	v_lshlrev_b32_e32 v140, 16, v209
	v_and_b32_e32 v141, 0xffff0000, v209
	v_pk_add_f32 v[18:19], v[18:19], v[140:141]
	v_cvt_pk_bf16_f32 v206, v20, v21
	v_cvt_pk_bf16_f32 v207, v22, v23
	v_cvt_pk_bf16_f32 v208, v16, v17
	v_cvt_pk_bf16_f32 v209, v18, v19
	global_store_dwordx4 v138, v[206:209], s[12:13] offset:256 nt
	v_pk_fma_f32 v[28:29], v[20:21], v[20:21], v[28:29]
	v_pk_fma_f32 v[28:29], v[22:23], v[22:23], v[28:29]
	v_pk_fma_f32 v[28:29], v[16:17], v[16:17], v[28:29]
	v_pk_fma_f32 v[28:29], v[18:19], v[18:19], v[28:29]
	v_add_f32_e32 v28, v28, v29
	s_add_u32 s12, s12, 0x8000
	s_addc_u32 s13, s13, 0
	s_waitcnt vmcnt(15)
	v_lshlrev_b32_e32 v158, 16, v210
	v_and_b32_e32 v159, 0xffff0000, v210
	v_pk_add_f32 v[12:13], v[12:13], v[158:159]
	v_lshlrev_b32_e32 v140, 16, v211
	v_and_b32_e32 v141, 0xffff0000, v211
	v_pk_add_f32 v[14:15], v[14:15], v[140:141]
	v_lshlrev_b32_e32 v158, 16, v212
	v_and_b32_e32 v159, 0xffff0000, v212
	v_pk_add_f32 v[8:9], v[8:9], v[158:159]
	v_lshlrev_b32_e32 v140, 16, v213
	v_and_b32_e32 v141, 0xffff0000, v213
	v_pk_add_f32 v[10:11], v[10:11], v[140:141]
	v_cvt_pk_bf16_f32 v210, v12, v13
	v_cvt_pk_bf16_f32 v211, v14, v15
	v_cvt_pk_bf16_f32 v212, v8, v9
	v_cvt_pk_bf16_f32 v213, v10, v11
	global_store_dwordx4 v138, v[210:213], s[12:13] nt
	v_pk_mul_f32 v[12:13], v[12:13], v[12:13]
	v_pk_fma_f32 v[12:13], v[14:15], v[14:15], v[12:13]
	v_pk_fma_f32 v[12:13], v[8:9], v[8:9], v[12:13]
	v_pk_fma_f32 v[12:13], v[10:11], v[10:11], v[12:13]
	s_waitcnt vmcnt(15)
	v_lshlrev_b32_e32 v158, 16, v214
	v_and_b32_e32 v159, 0xffff0000, v214
	v_pk_add_f32 v[4:5], v[4:5], v[158:159]
	v_lshlrev_b32_e32 v140, 16, v215
	v_and_b32_e32 v141, 0xffff0000, v215
	v_pk_add_f32 v[6:7], v[6:7], v[140:141]
	v_lshlrev_b32_e32 v158, 16, v216
	v_and_b32_e32 v159, 0xffff0000, v216
	v_pk_add_f32 v[0:1], v[0:1], v[158:159]
	v_lshlrev_b32_e32 v140, 16, v217
	v_and_b32_e32 v141, 0xffff0000, v217
	v_pk_add_f32 v[2:3], v[2:3], v[140:141]
	v_cvt_pk_bf16_f32 v214, v4, v5
	v_cvt_pk_bf16_f32 v215, v6, v7
	v_cvt_pk_bf16_f32 v216, v0, v1
	v_cvt_pk_bf16_f32 v217, v2, v3
	global_store_dwordx4 v138, v[214:217], s[12:13] offset:256 nt
	v_pk_fma_f32 v[12:13], v[4:5], v[4:5], v[12:13]
	v_pk_fma_f32 v[12:13], v[6:7], v[6:7], v[12:13]
	v_pk_fma_f32 v[12:13], v[0:1], v[0:1], v[12:13]
	v_pk_fma_f32 v[12:13], v[2:3], v[2:3], v[12:13]
	v_add_f32_e32 v12, v12, v13
	v_xor_b32_e32 v158, 16, v223
	v_xor_b32_e32 v159, 32, v223
	v_lshlrev_b32_e32 v158, 2, v158
	v_lshlrev_b32_e32 v159, 2, v159
	ds_bpermute_b32 v146, v158, v124
	ds_bpermute_b32 v148, v158, v108
	ds_bpermute_b32 v150, v158, v92
	ds_bpermute_b32 v152, v158, v76
	ds_bpermute_b32 v154, v158, v60
	ds_bpermute_b32 v156, v158, v44
	ds_bpermute_b32 v162, v158, v28
	ds_bpermute_b32 v164, v158, v12
	s_waitcnt lgkmcnt(7)
	v_add_f32_e32 v124, v124, v146
	s_waitcnt lgkmcnt(6)
	v_add_f32_e32 v108, v108, v148
	s_waitcnt lgkmcnt(5)
	v_add_f32_e32 v92, v92, v150
	s_waitcnt lgkmcnt(4)
	v_add_f32_e32 v76, v76, v152
	s_waitcnt lgkmcnt(3)
	v_add_f32_e32 v60, v60, v154
	s_waitcnt lgkmcnt(2)
	v_add_f32_e32 v44, v44, v156
	s_waitcnt lgkmcnt(1)
	v_add_f32_e32 v28, v28, v162
	s_waitcnt lgkmcnt(0)
	v_add_f32_e32 v12, v12, v164
	ds_bpermute_b32 v146, v159, v124
	ds_bpermute_b32 v148, v159, v108
	ds_bpermute_b32 v150, v159, v92
	ds_bpermute_b32 v152, v159, v76
	ds_bpermute_b32 v154, v159, v60
	ds_bpermute_b32 v156, v159, v44
	ds_bpermute_b32 v162, v159, v28
	ds_bpermute_b32 v164, v159, v12
	s_and_saveexec_b64 s[12:13], s[38:39]
	s_waitcnt lgkmcnt(7)
	v_add_f32_e32 v146, v124, v146
	v_fma_f32 v146, v146, s17, 0.5
	v_trunc_f32_e32 v146, v146
	v_mul_f32_e32 v147, 0x2f800000, v146
	v_floor_f32_e32 v147, v147
	v_fmac_f32_e32 v146, 0xcf800000, v147
	v_cvt_u32_f32_e32 v146, v146
	v_cvt_u32_f32_e32 v147, v147
	global_atomic_add_x2 v139, v[146:147], s[4:5]
	s_waitcnt lgkmcnt(6)
	v_add_f32_e32 v148, v108, v148
	v_fma_f32 v148, v148, s17, 0.5
	v_trunc_f32_e32 v148, v148
	v_mul_f32_e32 v149, 0x2f800000, v148
	v_floor_f32_e32 v149, v149
	v_fmac_f32_e32 v148, 0xcf800000, v149
	v_cvt_u32_f32_e32 v148, v148
	v_cvt_u32_f32_e32 v149, v149
	global_atomic_add_x2 v139, v[148:149], s[4:5] offset:128
	s_waitcnt lgkmcnt(5)
	v_add_f32_e32 v150, v92, v150
	v_fma_f32 v150, v150, s17, 0.5
	v_trunc_f32_e32 v150, v150
	v_mul_f32_e32 v151, 0x2f800000, v150
	v_floor_f32_e32 v151, v151
	v_fmac_f32_e32 v150, 0xcf800000, v151
	v_cvt_u32_f32_e32 v150, v150
	v_cvt_u32_f32_e32 v151, v151
	global_atomic_add_x2 v139, v[150:151], s[4:5] offset:256
	s_waitcnt lgkmcnt(4)
	v_add_f32_e32 v152, v76, v152
	v_fma_f32 v152, v152, s17, 0.5
	v_trunc_f32_e32 v152, v152
	v_mul_f32_e32 v153, 0x2f800000, v152
	v_floor_f32_e32 v153, v153
	v_fmac_f32_e32 v152, 0xcf800000, v153
	v_cvt_u32_f32_e32 v152, v152
	v_cvt_u32_f32_e32 v153, v153
	global_atomic_add_x2 v139, v[152:153], s[4:5] offset:384
	s_waitcnt lgkmcnt(3)
	v_add_f32_e32 v154, v60, v154
	v_fma_f32 v154, v154, s17, 0.5
	v_trunc_f32_e32 v154, v154
	v_mul_f32_e32 v155, 0x2f800000, v154
	v_floor_f32_e32 v155, v155
	v_fmac_f32_e32 v154, 0xcf800000, v155
	v_cvt_u32_f32_e32 v154, v154
	v_cvt_u32_f32_e32 v155, v155
	global_atomic_add_x2 v139, v[154:155], s[4:5] offset:1024
	s_waitcnt lgkmcnt(2)
	v_add_f32_e32 v156, v44, v156
	v_fma_f32 v156, v156, s17, 0.5
	v_trunc_f32_e32 v156, v156
	v_mul_f32_e32 v157, 0x2f800000, v156
	v_floor_f32_e32 v157, v157
	v_fmac_f32_e32 v156, 0xcf800000, v157
	v_cvt_u32_f32_e32 v156, v156
	v_cvt_u32_f32_e32 v157, v157
	global_atomic_add_x2 v139, v[156:157], s[4:5] offset:1152
	s_waitcnt lgkmcnt(1)
	v_add_f32_e32 v162, v28, v162
	v_fma_f32 v162, v162, s17, 0.5
	v_trunc_f32_e32 v162, v162
	v_mul_f32_e32 v163, 0x2f800000, v162
	v_floor_f32_e32 v163, v163
	v_fmac_f32_e32 v162, 0xcf800000, v163
	v_cvt_u32_f32_e32 v162, v162
	v_cvt_u32_f32_e32 v163, v163
	global_atomic_add_x2 v139, v[162:163], s[4:5] offset:1280
	s_waitcnt lgkmcnt(0)
	v_add_f32_e32 v164, v12, v164
	v_fma_f32 v164, v164, s17, 0.5
	v_trunc_f32_e32 v164, v164
	v_mul_f32_e32 v165, 0x2f800000, v164
	v_floor_f32_e32 v165, v165
	v_fmac_f32_e32 v164, 0xcf800000, v165
	v_cvt_u32_f32_e32 v164, v164
	v_cvt_u32_f32_e32 v165, v165
	global_atomic_add_x2 v139, v[164:165], s[4:5] offset:1408
	s_mov_b64 exec, s[12:13]
	v_mov_b64_e32 v[172:173], v[244:245]
	s_andn2_b64 vcc, exec, s[40:41]
	s_mov_b64 s[12:13], -1
	s_cbranch_vccnz .LBB0_302
	s_andn2_b64 vcc, exec, s[0:1]
	s_cbranch_vccnz .LBB0_301
	s_barrier
	s_branch .LBB0_301

.LBB0_336:
	s_or_b64 exec, exec, s[6:7]
	s_lshl_b32 s7, s14, 6
	s_add_i32 s7, s7, s8
	v_or_b32_e32 v34, s7, v132
	v_readlane_b32 s48, v254, 8
	v_ashrrev_i32_e32 v35, 31, v34
	v_readlane_b32 s62, v254, 22
	v_readlane_b32 s63, v254, 23
	s_waitcnt lgkmcnt(0)
	s_barrier
	v_lshl_add_u64 v[36:37], v[34:35], 2, s[62:63]
	global_load_dword v34, v[36:37], off
	global_load_dword v33, v[36:37], off offset:128
	s_mulk_i32 s13, 0x2200
	s_add_i32 s6, s13, 0
	s_add_i32 s13, 0, 0x1c800
	v_lshl_add_u32 v36, v133, 3, s13
	ds_read_b64 v[36:37], v36
	v_lshl_add_u32 v35, v132, 2, s6
	s_movk_i32 s14, 0x440
	v_and_b32_e32 v32, 63, v130
	s_addk_i32 s10, 0x2000
	s_waitcnt lgkmcnt(0)
	v_add_f32_e32 v36, v36, v37
	v_fmamk_f32 v36, v36, 0x3c000000, v219
	v_rsq_f32_e32 v36, v36
	v_mad_u32_u24 v37, v131, s14, v35
	s_addk_i32 s40, 0x200
	s_cmpk_eq_u32 s10, 0x8000
	v_mul_f32_e32 v0, v0, v36
	v_mul_f32_e32 v16, v16, v36
	v_readlane_b32 s49, v254, 9
	v_readlane_b32 s50, v254, 10
	v_readlane_b32 s51, v254, 11
	v_readlane_b32 s52, v254, 12
	v_readlane_b32 s53, v254, 13
	v_readlane_b32 s54, v254, 14
	v_readlane_b32 s55, v254, 15
	v_readlane_b32 s56, v254, 16
	v_readlane_b32 s57, v254, 17
	v_readlane_b32 s58, v254, 18
	v_readlane_b32 s59, v254, 19
	v_readlane_b32 s60, v254, 20
	v_readlane_b32 s61, v254, 21
	s_waitcnt vmcnt(1)
	v_mul_f32_e32 v0, v34, v0
	s_waitcnt vmcnt(0)
	v_mul_f32_e32 v16, v33, v16
	ds_write2_b32 v37, v0, v16 offset1:32
	v_or_b32_e32 v0, 1, v134
	v_or_b32_e32 v16, s12, v0
	v_lshl_add_u32 v16, v16, 3, s13
	ds_read_b64 v[36:37], v16
	v_mad_u32_u24 v0, v0, s18, v35
	s_waitcnt lgkmcnt(0)
	v_add_f32_e32 v16, v36, v37
	v_fmamk_f32 v16, v16, 0x3c000000, v219
	v_rsq_f32_e32 v16, v16
	s_nop 0
	v_mul_f32_e32 v1, v1, v16
	v_mul_f32_e32 v16, v17, v16
	v_mul_f32_e32 v1, v34, v1
	v_mul_f32_e32 v16, v33, v16
	ds_write2_b32 v0, v1, v16 offset1:32
	v_lshlrev_b32_e32 v1, 3, v133
	v_or_b32_e32 v16, 16, v1
	v_add_u32_e32 v16, s13, v16
	ds_read_b64 v[16:17], v16
	s_waitcnt lgkmcnt(0)
	v_add_f32_e32 v16, v16, v17
	v_fmamk_f32 v16, v16, 0x3c000000, v219
	v_rsq_f32_e32 v16, v16
	s_nop 0
	v_mul_f32_e32 v2, v2, v16
	v_mul_f32_e32 v16, v18, v16
	v_mul_f32_e32 v2, v34, v2
	v_mul_f32_e32 v16, v33, v16
	ds_write2_b32 v0, v2, v16 offset0:68 offset1:100
	v_or_b32_e32 v2, 24, v1
	v_add_u32_e32 v2, s13, v2
	ds_read_b64 v[16:17], v2
	s_waitcnt lgkmcnt(0)
	v_add_f32_e32 v2, v16, v17
	v_fmamk_f32 v2, v2, 0x3c000000, v219
	v_rsq_f32_e32 v2, v2
	s_nop 0
	v_mul_f32_e32 v3, v3, v2
	v_mul_f32_e32 v2, v19, v2
	v_mul_f32_e32 v3, v34, v3
	v_mul_f32_e32 v2, v33, v2
	ds_write2_b32 v0, v3, v2 offset0:136 offset1:168
	v_or_b32_e32 v2, 64, v1
	v_add_u32_e32 v2, s13, v2
	ds_read_b64 v[2:3], v2
	s_waitcnt lgkmcnt(0)
	v_add_f32_e32 v2, v2, v3
	v_fmamk_f32 v2, v2, 0x3c000000, v219
	v_rsq_f32_e32 v2, v2
	s_nop 0
	v_mul_f32_e32 v3, v4, v2
	v_mul_f32_e32 v2, v20, v2
	v_mul_f32_e32 v3, v34, v3
	v_mul_f32_e32 v2, v33, v2
	v_add_u32_e32 v4, 0x400, v0
	ds_write2_b32 v4, v3, v2 offset0:220 offset1:252
	v_or_b32_e32 v2, 0x48, v1
	v_add_u32_e32 v2, s13, v2
	ds_read_b64 v[2:3], v2
	v_add_u32_e32 v4, 0x800, v0
	s_waitcnt lgkmcnt(0)
	v_add_f32_e32 v2, v2, v3
	v_fmamk_f32 v2, v2, 0x3c000000, v219
	v_rsq_f32_e32 v2, v2
	s_nop 0
	v_mul_f32_e32 v3, v5, v2
	v_mul_f32_e32 v2, v21, v2
	v_mul_f32_e32 v3, v34, v3
	v_mul_f32_e32 v2, v33, v2
	ds_write2_b32 v4, v3, v2 offset0:32 offset1:64
	v_or_b32_e32 v2, 0x50, v1
	v_add_u32_e32 v2, s13, v2
	ds_read_b64 v[2:3], v2
	v_lshrrev_b32_e32 v5, 3, v32
	s_waitcnt lgkmcnt(0)
	v_add_f32_e32 v2, v2, v3
	v_fmamk_f32 v2, v2, 0x3c000000, v219
	v_rsq_f32_e32 v2, v2
	s_nop 0
	v_mul_f32_e32 v3, v6, v2
	v_mul_f32_e32 v2, v22, v2
	v_mul_f32_e32 v3, v34, v3
	v_mul_f32_e32 v2, v33, v2
	ds_write2_b32 v4, v3, v2 offset0:100 offset1:132
	v_or_b32_e32 v2, 0x58, v1
	v_add_u32_e32 v2, s13, v2
	ds_read_b64 v[2:3], v2
	v_mul_u32_u24_e32 v6, 0x110, v5
	s_waitcnt lgkmcnt(0)
	v_add_f32_e32 v2, v2, v3
	v_fmamk_f32 v2, v2, 0x3c000000, v219
	v_rsq_f32_e32 v2, v2
	s_nop 0
	v_mul_f32_e32 v3, v7, v2
	v_mul_f32_e32 v2, v23, v2
	v_mul_f32_e32 v3, v34, v3
	v_mul_f32_e32 v2, v33, v2
	ds_write2_b32 v4, v3, v2 offset0:168 offset1:200
	v_or_b32_e32 v2, s12, v42
	v_lshl_add_u32 v2, v2, 3, s13
	ds_read_b64 v[2:3], v2
	v_add_u32_e32 v4, 0xe00, v0
	s_waitcnt lgkmcnt(0)
	v_add_f32_e32 v2, v2, v3
	v_fmamk_f32 v2, v2, 0x3c000000, v219
	v_rsq_f32_e32 v2, v2
	s_nop 0
	v_mul_f32_e32 v3, v8, v2
	v_mul_f32_e32 v2, v24, v2
	v_mul_f32_e32 v3, v34, v3
	v_mul_f32_e32 v2, v33, v2
	ds_write2_b32 v4, v3, v2 offset0:124 offset1:156
	v_or_b32_e32 v2, 0x88, v1
	v_add_u32_e32 v2, s13, v2
	ds_read_b64 v[2:3], v2
	v_add_u32_e32 v4, 0x1000, v0
	s_waitcnt lgkmcnt(0)
	v_add_f32_e32 v2, v2, v3
	v_fmamk_f32 v2, v2, 0x3c000000, v219
	v_rsq_f32_e32 v2, v2
	s_nop 0
	v_mul_f32_e32 v3, v9, v2
	v_mul_f32_e32 v2, v25, v2
	v_mul_f32_e32 v3, v34, v3
	v_mul_f32_e32 v2, v33, v2
	ds_write2_b32 v4, v3, v2 offset0:64 offset1:96
	v_or_b32_e32 v2, 0x90, v1
	v_add_u32_e32 v2, s13, v2
	ds_read_b64 v[2:3], v2
	s_waitcnt lgkmcnt(0)
	v_add_f32_e32 v2, v2, v3
	v_fmamk_f32 v2, v2, 0x3c000000, v219
	v_rsq_f32_e32 v2, v2
	s_nop 0
	v_mul_f32_e32 v3, v10, v2
	v_mul_f32_e32 v2, v26, v2
	v_mul_f32_e32 v3, v34, v3
	v_mul_f32_e32 v2, v33, v2
	ds_write2_b32 v4, v3, v2 offset0:132 offset1:164
	v_or_b32_e32 v2, 0x98, v1
	v_add_u32_e32 v2, s13, v2
	ds_read_b64 v[2:3], v2
	s_waitcnt lgkmcnt(0)
	v_add_f32_e32 v2, v2, v3
	v_fmamk_f32 v2, v2, 0x3c000000, v219
	v_rsq_f32_e32 v2, v2
	s_nop 0
	v_mul_f32_e32 v3, v11, v2
	v_mul_f32_e32 v2, v27, v2
	v_mul_f32_e32 v3, v34, v3
	v_mul_f32_e32 v2, v33, v2
	ds_write2_b32 v4, v3, v2 offset0:200 offset1:232
	v_or_b32_e32 v2, 0xc0, v1
	v_add_u32_e32 v2, s13, v2
	ds_read_b64 v[2:3], v2
	v_add_u32_e32 v4, 0x1800, v0
	v_add_u32_e32 v0, 0x1a00, v0
	s_waitcnt lgkmcnt(0)
	v_add_f32_e32 v2, v2, v3
	v_fmamk_f32 v2, v2, 0x3c000000, v219
	v_rsq_f32_e32 v2, v2
	s_nop 0
	v_mul_f32_e32 v3, v12, v2
	v_mul_f32_e32 v2, v28, v2
	v_mul_f32_e32 v3, v34, v3
	v_mul_f32_e32 v2, v33, v2
	ds_write2_b32 v4, v3, v2 offset0:28 offset1:60
	v_or_b32_e32 v2, 0xc8, v1
	v_add_u32_e32 v2, s13, v2
	ds_read_b64 v[2:3], v2
	s_waitcnt lgkmcnt(0)
	v_add_f32_e32 v2, v2, v3
	v_fmamk_f32 v2, v2, 0x3c000000, v219
	v_rsq_f32_e32 v2, v2
	s_nop 0
	v_mul_f32_e32 v3, v13, v2
	v_mul_f32_e32 v2, v29, v2
	v_mul_f32_e32 v3, v34, v3
	v_mul_f32_e32 v2, v33, v2
	ds_write2_b32 v4, v3, v2 offset0:96 offset1:128
	v_or_b32_e32 v2, 0xd0, v1
	v_add_u32_e32 v2, s13, v2
	ds_read_b64 v[2:3], v2
	v_or_b32_e32 v1, 0xd8, v1
	v_add_u32_e32 v1, s13, v1
	s_waitcnt lgkmcnt(0)
	v_add_f32_e32 v2, v2, v3
	v_fmamk_f32 v2, v2, 0x3c000000, v219
	v_rsq_f32_e32 v2, v2
	s_nop 0
	v_mul_f32_e32 v3, v14, v2
	v_mul_f32_e32 v2, v30, v2
	v_mul_f32_e32 v3, v34, v3
	v_mul_f32_e32 v2, v33, v2
	ds_write2_b32 v4, v3, v2 offset0:164 offset1:196
	ds_read_b64 v[2:3], v1
	s_waitcnt lgkmcnt(0)
	v_add_f32_e32 v1, v2, v3
	v_fmamk_f32 v1, v1, 0x3c000000, v219
	v_rsq_f32_e32 v1, v1
	s_nop 0
	v_mul_f32_e32 v2, v15, v1
	v_mul_f32_e32 v1, v31, v1
	v_mul_f32_e32 v2, v34, v2
	v_mul_f32_e32 v1, v33, v1
	ds_write2_b32 v0, v2, v1 offset0:104 offset1:136
	v_and_b32_e32 v0, 7, v130
	v_lshlrev_b32_e32 v4, 5, v0
	v_lshl_or_b32 v0, v0, 3, s7
	v_ashrrev_i32_e32 v1, 31, v0
	v_add3_u32 v6, s6, v4, v6
	v_or_b32_e32 v4, s11, v5
	v_lshlrev_b64 v[0:1], 1, v[0:1]
	v_ashrrev_i32_e32 v5, 31, v4
	v_lshl_add_u64 v[2:3], s[2:3], 0, v[0:1]
	v_lshlrev_b64 v[16:17], 10, v[4:5]
	s_waitcnt lgkmcnt(0)
	v_lshl_add_u64 v[16:17], v[2:3], 0, v[16:17]
	ds_read_b128 v[8:11], v6
	ds_read_b128 v[12:15], v6 offset:16
	flat_load_dwordx4 v[16:19], v[16:17]
	v_lshl_add_u64 v[0:1], s[0:1], 0, v[0:1]
	s_waitcnt vmcnt(0) lgkmcnt(0)
	v_lshlrev_b32_e32 v20, 16, v16
	v_and_b32_e32 v21, 0xffff0000, v16
	v_lshlrev_b32_e32 v16, 16, v17
	v_and_b32_e32 v17, 0xffff0000, v17
	v_pk_mul_f32 v[8:9], v[8:9], v[20:21]
	v_pk_mul_f32 v[10:11], v[10:11], v[16:17]
	v_cvt_pk_bf16_f32 v8, v8, v9
	v_cvt_pk_bf16_f32 v9, v10, v11
	v_lshlrev_b32_e32 v10, 16, v18
	v_and_b32_e32 v11, 0xffff0000, v18
	v_pk_mul_f32 v[10:11], v[12:13], v[10:11]
	v_lshlrev_b32_e32 v12, 16, v19
	v_and_b32_e32 v13, 0xffff0000, v19
	v_pk_mul_f32 v[12:13], v[14:15], v[12:13]
	v_or_b32_e32 v20, 8, v4
	v_cvt_pk_bf16_f32 v10, v10, v11
	v_cvt_pk_bf16_f32 v11, v12, v13
	v_lshlrev_b64 v[12:13], 11, v[4:5]
	v_ashrrev_i32_e32 v21, 31, v20
	v_lshl_add_u64 v[12:13], v[0:1], 0, v[12:13]
	v_lshlrev_b64 v[16:17], 10, v[20:21]
	flat_store_dwordx4 v[12:13], v[8:11] nt
	v_lshl_add_u64 v[16:17], v[2:3], 0, v[16:17]
	ds_read_b128 v[8:11], v6 offset:2176
	ds_read_b128 v[12:15], v6 offset:2192
	flat_load_dwordx4 v[16:19], v[16:17]
	s_waitcnt vmcnt(0) lgkmcnt(0)
	v_lshlrev_b32_e32 v22, 16, v16
	v_and_b32_e32 v23, 0xffff0000, v16
	v_lshlrev_b32_e32 v16, 16, v17
	v_and_b32_e32 v17, 0xffff0000, v17
	v_pk_mul_f32 v[8:9], v[8:9], v[22:23]
	v_pk_mul_f32 v[10:11], v[10:11], v[16:17]
	v_cvt_pk_bf16_f32 v8, v8, v9
	v_cvt_pk_bf16_f32 v9, v10, v11
	v_lshlrev_b32_e32 v10, 16, v18
	v_and_b32_e32 v11, 0xffff0000, v18
	v_pk_mul_f32 v[10:11], v[12:13], v[10:11]
	v_lshlrev_b32_e32 v12, 16, v19
	v_and_b32_e32 v13, 0xffff0000, v19
	v_pk_mul_f32 v[12:13], v[14:15], v[12:13]
	v_cvt_pk_bf16_f32 v10, v10, v11
	v_cvt_pk_bf16_f32 v11, v12, v13
	v_lshlrev_b64 v[12:13], 11, v[20:21]
	v_or_b32_e32 v20, 16, v4
	v_ashrrev_i32_e32 v21, 31, v20
	v_lshl_add_u64 v[12:13], v[0:1], 0, v[12:13]
	v_lshlrev_b64 v[16:17], 10, v[20:21]
	flat_store_dwordx4 v[12:13], v[8:11] nt
	v_lshl_add_u64 v[16:17], v[2:3], 0, v[16:17]
	ds_read_b128 v[8:11], v6 offset:4352
	ds_read_b128 v[12:15], v6 offset:4368
	flat_load_dwordx4 v[16:19], v[16:17]
	s_waitcnt vmcnt(0) lgkmcnt(0)
	v_lshlrev_b32_e32 v22, 16, v16
	v_and_b32_e32 v23, 0xffff0000, v16
	v_lshlrev_b32_e32 v16, 16, v17
	v_and_b32_e32 v17, 0xffff0000, v17
	v_pk_mul_f32 v[8:9], v[8:9], v[22:23]
	v_pk_mul_f32 v[10:11], v[10:11], v[16:17]
	v_cvt_pk_bf16_f32 v8, v8, v9
	v_cvt_pk_bf16_f32 v9, v10, v11
	v_lshlrev_b32_e32 v10, 16, v18
	v_and_b32_e32 v11, 0xffff0000, v18
	v_pk_mul_f32 v[10:11], v[12:13], v[10:11]
	v_lshlrev_b32_e32 v12, 16, v19
	v_and_b32_e32 v13, 0xffff0000, v19
	v_pk_mul_f32 v[12:13], v[14:15], v[12:13]
	v_cvt_pk_bf16_f32 v10, v10, v11
	v_cvt_pk_bf16_f32 v11, v12, v13
	v_lshlrev_b64 v[12:13], 11, v[20:21]
	v_lshl_add_u64 v[12:13], v[0:1], 0, v[12:13]
	flat_store_dwordx4 v[12:13], v[8:11] nt
	ds_read_b128 v[8:11], v6 offset:6528
	ds_read_b128 v[12:15], v6 offset:6544
	v_or_b32_e32 v6, 24, v4
	v_ashrrev_i32_e32 v7, 31, v6
	v_lshlrev_b64 v[4:5], 10, v[6:7]
	v_lshl_add_u64 v[2:3], v[2:3], 0, v[4:5]
	flat_load_dwordx4 v[2:5], v[2:3]
	v_lshlrev_b64 v[6:7], 11, v[6:7]
	v_lshl_add_u64 v[0:1], v[0:1], 0, v[6:7]
	s_waitcnt vmcnt(0) lgkmcnt(0)
	v_lshlrev_b32_e32 v16, 16, v2
	v_and_b32_e32 v17, 0xffff0000, v2
	v_pk_mul_f32 v[8:9], v[8:9], v[16:17]
	s_nop 0
	v_cvt_pk_bf16_f32 v2, v8, v9
	v_lshlrev_b32_e32 v8, 16, v3
	v_and_b32_e32 v9, 0xffff0000, v3
	v_pk_mul_f32 v[8:9], v[10:11], v[8:9]
	s_nop 0
	v_cvt_pk_bf16_f32 v3, v8, v9
	v_lshlrev_b32_e32 v8, 16, v4
	v_and_b32_e32 v9, 0xffff0000, v4
	v_pk_mul_f32 v[8:9], v[12:13], v[8:9]
	s_nop 0
	v_cvt_pk_bf16_f32 v4, v8, v9
	v_lshlrev_b32_e32 v8, 16, v5
	v_and_b32_e32 v9, 0xffff0000, v5
	v_pk_mul_f32 v[8:9], v[14:15], v[8:9]
	s_nop 0
	v_cvt_pk_bf16_f32 v5, v8, v9
	flat_store_dwordx4 v[0:1], v[2:5] nt
	s_waitcnt lgkmcnt(0)
	s_barrier
	s_cbranch_scc1 .LBB0_369

.LBB0_374:
	v_mov_b32_e32 v0, s6
	v_cndmask_b32_e32 v0, v111, v0, vcc
	v_add_u32_e32 v0, v0, v110
	v_lshl_or_b32 v0, v0, 2, v108
	s_xor_b32 s0, s6, 0x3ffffffe
	v_ashrrev_i32_e32 v1, 31, v0
	v_add_u32_e32 v4, s0, v109
	s_add_i32 s0, s6, 1
	v_lshlrev_b64 v[0:1], 16, v[0:1]
	v_mov_b32_e32 v5, s0
	v_lshl_add_u64 v[76:77], v[66:67], 0, v[0:1]
	v_cndmask_b32_e32 v4, v4, v5, vcc
	flat_load_dwordx4 v[0:3], v[76:77]
	v_add_u32_e32 v4, v4, v110
	v_lshl_or_b32 v4, v4, 2, v108
	v_ashrrev_i32_e32 v5, 31, v4
	s_xor_b32 s0, s6, 0x3ffffffd
	v_lshlrev_b64 v[4:5], 16, v[4:5]
	v_add_u32_e32 v8, s0, v109
	s_add_i32 s0, s6, 2
	v_lshl_add_u64 v[78:79], v[66:67], 0, v[4:5]
	v_mov_b32_e32 v9, s0
	flat_load_dwordx4 v[4:7], v[78:79]
	v_cndmask_b32_e32 v8, v8, v9, vcc
	v_add_u32_e32 v8, v8, v110
	v_lshl_or_b32 v8, v8, 2, v108
	v_ashrrev_i32_e32 v9, 31, v8
	s_xor_b32 s0, s6, 0x3ffffffc
	v_lshlrev_b64 v[8:9], 16, v[8:9]
	v_add_u32_e32 v12, s0, v109
	s_add_i32 s0, s6, 3
	v_lshl_add_u64 v[80:81], v[66:67], 0, v[8:9]
	v_mov_b32_e32 v13, s0
	flat_load_dwordx4 v[8:11], v[80:81]
	v_cndmask_b32_e32 v12, v12, v13, vcc
	v_add_u32_e32 v12, v12, v110
	v_lshl_or_b32 v12, v12, 2, v108
	v_ashrrev_i32_e32 v13, 31, v12
	s_xor_b32 s0, s6, 0x3ffffffb
	v_lshlrev_b64 v[12:13], 16, v[12:13]
	v_add_u32_e32 v16, s0, v109
	s_add_i32 s0, s6, 4
	v_lshl_add_u64 v[82:83], v[66:67], 0, v[12:13]
	v_mov_b32_e32 v17, s0
	flat_load_dwordx4 v[12:15], v[82:83]
	v_cndmask_b32_e32 v16, v16, v17, vcc
	v_add_u32_e32 v16, v16, v110
	v_lshl_or_b32 v16, v16, 2, v108
	v_ashrrev_i32_e32 v17, 31, v16
	s_xor_b32 s0, s6, 0x3ffffffa
	v_lshlrev_b64 v[16:17], 16, v[16:17]
	v_add_u32_e32 v20, s0, v109
	s_add_i32 s0, s6, 5
	v_lshl_add_u64 v[84:85], v[66:67], 0, v[16:17]
	v_mov_b32_e32 v21, s0
	flat_load_dwordx4 v[16:19], v[84:85]
	v_cndmask_b32_e32 v20, v20, v21, vcc
	v_add_u32_e32 v20, v20, v110
	v_lshl_or_b32 v20, v20, 2, v108
	v_ashrrev_i32_e32 v21, 31, v20
	s_xor_b32 s0, s6, 0x3ffffff9
	v_lshlrev_b64 v[20:21], 16, v[20:21]
	v_add_u32_e32 v24, s0, v109
	s_add_i32 s0, s6, 6
	v_lshl_add_u64 v[86:87], v[66:67], 0, v[20:21]
	v_mov_b32_e32 v25, s0
	flat_load_dwordx4 v[20:23], v[86:87]
	v_cndmask_b32_e32 v24, v24, v25, vcc
	v_add_u32_e32 v24, v24, v110
	v_lshl_or_b32 v24, v24, 2, v108
	v_ashrrev_i32_e32 v25, 31, v24
	s_xor_b32 s0, s6, 0x3ffffff8
	v_lshlrev_b64 v[24:25], 16, v[24:25]
	v_add_u32_e32 v28, s0, v109
	s_add_i32 s0, s6, 7
	v_lshl_add_u64 v[88:89], v[66:67], 0, v[24:25]
	v_mov_b32_e32 v29, s0
	flat_load_dwordx4 v[24:27], v[88:89]
	v_cndmask_b32_e32 v28, v28, v29, vcc
	v_add_u32_e32 v28, v28, v110
	v_lshl_or_b32 v28, v28, 2, v108
	v_ashrrev_i32_e32 v29, 31, v28
	s_xor_b32 s0, s6, 0x3ffffff7
	v_lshlrev_b64 v[28:29], 16, v[28:29]
	v_add_u32_e32 v32, s0, v109
	s_add_i32 s0, s6, 8
	v_lshl_add_u64 v[90:91], v[66:67], 0, v[28:29]
	v_mov_b32_e32 v33, s0
	flat_load_dwordx4 v[28:31], v[90:91]
	v_cndmask_b32_e32 v32, v32, v33, vcc
	v_add_u32_e32 v32, v32, v110
	v_lshl_or_b32 v32, v32, 2, v108
	v_ashrrev_i32_e32 v33, 31, v32
	s_xor_b32 s0, s6, 0x3ffffff6
	v_lshlrev_b64 v[32:33], 16, v[32:33]
	v_add_u32_e32 v36, s0, v109
	s_add_i32 s0, s6, 9
	v_lshl_add_u64 v[92:93], v[66:67], 0, v[32:33]
	v_mov_b32_e32 v37, s0
	flat_load_dwordx4 v[32:35], v[92:93]
	v_cndmask_b32_e32 v36, v36, v37, vcc
	v_add_u32_e32 v36, v36, v110
	v_lshl_or_b32 v36, v36, 2, v108
	v_ashrrev_i32_e32 v37, 31, v36
	s_xor_b32 s0, s6, 0x3ffffff5
	v_lshlrev_b64 v[36:37], 16, v[36:37]
	v_add_u32_e32 v40, s0, v109
	s_add_i32 s0, s6, 10
	v_lshl_add_u64 v[94:95], v[66:67], 0, v[36:37]
	v_mov_b32_e32 v41, s0
	flat_load_dwordx4 v[36:39], v[94:95]
	v_cndmask_b32_e32 v40, v40, v41, vcc
	v_add_u32_e32 v40, v40, v110
	v_lshl_or_b32 v40, v40, 2, v108
	v_ashrrev_i32_e32 v41, 31, v40
	s_xor_b32 s0, s6, 0x3ffffff4
	v_lshlrev_b64 v[40:41], 16, v[40:41]
	v_add_u32_e32 v44, s0, v109
	s_add_i32 s0, s6, 11
	v_lshl_add_u64 v[96:97], v[66:67], 0, v[40:41]
	v_mov_b32_e32 v45, s0
	flat_load_dwordx4 v[40:43], v[96:97]
	v_cndmask_b32_e32 v44, v44, v45, vcc
	v_add_u32_e32 v44, v44, v110
	v_lshl_or_b32 v44, v44, 2, v108
	v_ashrrev_i32_e32 v45, 31, v44
	s_xor_b32 s0, s6, 0x3ffffff3
	v_lshlrev_b64 v[44:45], 16, v[44:45]
	v_add_u32_e32 v48, s0, v109
	s_add_i32 s0, s6, 12
	v_lshl_add_u64 v[98:99], v[66:67], 0, v[44:45]
	v_mov_b32_e32 v49, s0
	flat_load_dwordx4 v[44:47], v[98:99]
	v_cndmask_b32_e32 v48, v48, v49, vcc
	v_add_u32_e32 v48, v48, v110
	v_lshl_or_b32 v48, v48, 2, v108
	s_xor_b32 s0, s6, 0x3ffffff2
	v_ashrrev_i32_e32 v49, 31, v48
	v_add_u32_e32 v52, s0, v109
	s_add_i32 s0, s6, 13
	v_lshlrev_b64 v[48:49], 16, v[48:49]
	v_mov_b32_e32 v53, s0
	s_xor_b32 s0, s6, 0x3ffffff1
	v_lshl_add_u64 v[100:101], v[66:67], 0, v[48:49]
	v_add_u32_e32 v56, s0, v109
	s_add_i32 s0, s6, 14
	flat_load_dwordx4 v[48:51], v[100:101]
	v_cndmask_b32_e32 v52, v52, v53, vcc
	v_mov_b32_e32 v57, s0
	s_xor_b32 s0, s6, 0x3ffffff0
	v_add_u32_e32 v52, v52, v110
	v_add_u32_e32 v60, s0, v109
	s_add_i32 s0, s6, 15
	v_lshl_or_b32 v52, v52, 2, v108
	v_mov_b32_e32 v61, s0
	v_ashrrev_i32_e32 v53, 31, v52
	v_cndmask_b32_e32 v56, v56, v57, vcc
	v_cndmask_b32_e32 v60, v60, v61, vcc
	v_lshlrev_b64 v[52:53], 16, v[52:53]
	v_add_u32_e32 v56, v56, v110
	v_add_u32_e32 v60, v60, v110
	v_lshl_add_u64 v[102:103], v[66:67], 0, v[52:53]
	v_lshl_or_b32 v56, v56, 2, v108
	v_lshl_or_b32 v60, v60, 2, v108
	flat_load_dwordx4 v[52:55], v[102:103]
	v_ashrrev_i32_e32 v57, 31, v56
	v_ashrrev_i32_e32 v61, 31, v60
	v_lshlrev_b64 v[56:57], 16, v[56:57]
	v_lshlrev_b64 v[60:61], 16, v[60:61]
	v_lshl_add_u64 v[104:105], v[66:67], 0, v[56:57]
	v_lshl_add_u64 v[106:107], v[66:67], 0, v[60:61]
	v_cvt_pk_bf16_f32 v112, v70, v71
	v_cvt_pk_bf16_f32 v113, v72, v73
	v_cvt_pk_bf16_f32 v114, v74, v75
	v_cvt_pk_bf16_f32 v115, v68, v69
	flat_load_dwordx4 v[56:59], v[104:105]
	flat_load_dwordx4 v[60:63], v[106:107]
	s_add_i32 s6, s6, 16
	flat_store_dwordx4 v[76:77], v[112:115] nt
	s_waitcnt vmcnt(0) lgkmcnt(0)
	v_lshlrev_b32_e32 v76, 16, v0
	v_and_b32_e32 v77, 0xffff0000, v0
	v_lshlrev_b32_e32 v0, 16, v1
	v_and_b32_e32 v1, 0xffff0000, v1
	v_pk_fma_f32 v[72:73], v[64:65], v[72:73], v[0:1]
	v_lshlrev_b32_e32 v0, 16, v2
	v_and_b32_e32 v1, 0xffff0000, v2
	v_pk_fma_f32 v[74:75], v[64:65], v[74:75], v[0:1]
	v_lshlrev_b32_e32 v0, 16, v3
	v_and_b32_e32 v1, 0xffff0000, v3
	v_pk_fma_f32 v[70:71], v[64:65], v[70:71], v[76:77]
	v_pk_fma_f32 v[68:69], v[64:65], v[68:69], v[0:1]
	v_cvt_pk_bf16_f32 v0, v70, v71
	v_cvt_pk_bf16_f32 v1, v72, v73
	v_cvt_pk_bf16_f32 v2, v74, v75
	v_cvt_pk_bf16_f32 v3, v68, v69
	flat_store_dwordx4 v[78:79], v[0:3] nt
	v_cmp_ge_u32_e64 s[0:1], s6, v109
	v_add_u32_e32 v111, -16, v111
	v_lshlrev_b32_e32 v0, 16, v4
	v_and_b32_e32 v1, 0xffff0000, v4
	v_pk_fma_f32 v[70:71], v[64:65], v[70:71], v[0:1]
	v_lshlrev_b32_e32 v0, 16, v5
	v_and_b32_e32 v1, 0xffff0000, v5
	v_pk_fma_f32 v[4:5], v[64:65], v[72:73], v[0:1]
	v_lshlrev_b32_e32 v0, 16, v6
	v_and_b32_e32 v1, 0xffff0000, v6
	v_pk_fma_f32 v[72:73], v[64:65], v[74:75], v[0:1]
	v_lshlrev_b32_e32 v0, 16, v7
	v_and_b32_e32 v1, 0xffff0000, v7
	v_pk_fma_f32 v[6:7], v[64:65], v[68:69], v[0:1]
	v_cvt_pk_bf16_f32 v0, v70, v71
	v_cvt_pk_bf16_f32 v1, v4, v5
	v_cvt_pk_bf16_f32 v2, v72, v73
	v_cvt_pk_bf16_f32 v3, v6, v7
	flat_store_dwordx4 v[80:81], v[0:3] nt
	s_or_b64 s[4:5], s[0:1], s[4:5]
	s_nop 0
	v_lshlrev_b32_e32 v0, 16, v8
	v_and_b32_e32 v1, 0xffff0000, v8
	v_pk_fma_f32 v[68:69], v[64:65], v[70:71], v[0:1]
	v_lshlrev_b32_e32 v0, 16, v9
	v_and_b32_e32 v1, 0xffff0000, v9
	v_pk_fma_f32 v[4:5], v[64:65], v[4:5], v[0:1]
	v_lshlrev_b32_e32 v0, 16, v10
	v_and_b32_e32 v1, 0xffff0000, v10
	v_pk_fma_f32 v[8:9], v[64:65], v[72:73], v[0:1]
	v_lshlrev_b32_e32 v0, 16, v11
	v_and_b32_e32 v1, 0xffff0000, v11
	v_pk_fma_f32 v[6:7], v[64:65], v[6:7], v[0:1]
	v_cvt_pk_bf16_f32 v0, v68, v69
	v_cvt_pk_bf16_f32 v1, v4, v5
	v_cvt_pk_bf16_f32 v2, v8, v9
	v_cvt_pk_bf16_f32 v3, v6, v7
	flat_store_dwordx4 v[82:83], v[0:3] nt
	s_nop 1
	v_lshlrev_b32_e32 v0, 16, v12
	v_and_b32_e32 v1, 0xffff0000, v12
	v_pk_fma_f32 v[10:11], v[64:65], v[68:69], v[0:1]
	v_lshlrev_b32_e32 v0, 16, v13
	v_and_b32_e32 v1, 0xffff0000, v13
	v_pk_fma_f32 v[4:5], v[64:65], v[4:5], v[0:1]
	v_lshlrev_b32_e32 v0, 16, v14
	v_and_b32_e32 v1, 0xffff0000, v14
	v_pk_fma_f32 v[8:9], v[64:65], v[8:9], v[0:1]
	v_lshlrev_b32_e32 v0, 16, v15
	v_and_b32_e32 v1, 0xffff0000, v15
	v_pk_fma_f32 v[6:7], v[64:65], v[6:7], v[0:1]
	v_cvt_pk_bf16_f32 v0, v10, v11
	v_cvt_pk_bf16_f32 v1, v4, v5
	v_cvt_pk_bf16_f32 v2, v8, v9
	v_cvt_pk_bf16_f32 v3, v6, v7
	flat_store_dwordx4 v[84:85], v[0:3] nt
	s_nop 1
	v_lshlrev_b32_e32 v0, 16, v16
	v_and_b32_e32 v1, 0xffff0000, v16
	v_pk_fma_f32 v[10:11], v[64:65], v[10:11], v[0:1]
	v_lshlrev_b32_e32 v0, 16, v17
	v_and_b32_e32 v1, 0xffff0000, v17
	v_pk_fma_f32 v[4:5], v[64:65], v[4:5], v[0:1]
	v_lshlrev_b32_e32 v0, 16, v18
	v_and_b32_e32 v1, 0xffff0000, v18
	v_pk_fma_f32 v[8:9], v[64:65], v[8:9], v[0:1]
	v_lshlrev_b32_e32 v0, 16, v19
	v_and_b32_e32 v1, 0xffff0000, v19
	v_pk_fma_f32 v[6:7], v[64:65], v[6:7], v[0:1]
	v_cvt_pk_bf16_f32 v0, v10, v11
	v_cvt_pk_bf16_f32 v1, v4, v5
	v_cvt_pk_bf16_f32 v2, v8, v9
	v_cvt_pk_bf16_f32 v3, v6, v7
	flat_store_dwordx4 v[86:87], v[0:3] nt
	s_nop 1
	v_lshlrev_b32_e32 v0, 16, v20
	v_and_b32_e32 v1, 0xffff0000, v20
	v_pk_fma_f32 v[10:11], v[64:65], v[10:11], v[0:1]
	v_lshlrev_b32_e32 v0, 16, v21
	v_and_b32_e32 v1, 0xffff0000, v21
	v_pk_fma_f32 v[4:5], v[64:65], v[4:5], v[0:1]
	v_lshlrev_b32_e32 v0, 16, v22
	v_and_b32_e32 v1, 0xffff0000, v22
	v_pk_fma_f32 v[8:9], v[64:65], v[8:9], v[0:1]
	v_lshlrev_b32_e32 v0, 16, v23
	v_and_b32_e32 v1, 0xffff0000, v23
	v_pk_fma_f32 v[6:7], v[64:65], v[6:7], v[0:1]
	v_cvt_pk_bf16_f32 v0, v10, v11
	v_cvt_pk_bf16_f32 v1, v4, v5
	v_cvt_pk_bf16_f32 v2, v8, v9
	v_cvt_pk_bf16_f32 v3, v6, v7
	flat_store_dwordx4 v[88:89], v[0:3] nt
	s_nop 1
	v_lshlrev_b32_e32 v0, 16, v24
	v_and_b32_e32 v1, 0xffff0000, v24
	v_pk_fma_f32 v[10:11], v[64:65], v[10:11], v[0:1]
	v_lshlrev_b32_e32 v0, 16, v25
	v_and_b32_e32 v1, 0xffff0000, v25
	v_pk_fma_f32 v[4:5], v[64:65], v[4:5], v[0:1]
	v_lshlrev_b32_e32 v0, 16, v26
	v_and_b32_e32 v1, 0xffff0000, v26
	v_pk_fma_f32 v[8:9], v[64:65], v[8:9], v[0:1]
	v_lshlrev_b32_e32 v0, 16, v27
	v_and_b32_e32 v1, 0xffff0000, v27
	v_pk_fma_f32 v[6:7], v[64:65], v[6:7], v[0:1]
	v_cvt_pk_bf16_f32 v0, v10, v11
	v_cvt_pk_bf16_f32 v1, v4, v5
	v_cvt_pk_bf16_f32 v2, v8, v9
	v_cvt_pk_bf16_f32 v3, v6, v7
	flat_store_dwordx4 v[90:91], v[0:3] nt
	s_nop 1
	v_lshlrev_b32_e32 v0, 16, v28
	v_and_b32_e32 v1, 0xffff0000, v28
	v_pk_fma_f32 v[10:11], v[64:65], v[10:11], v[0:1]
	v_lshlrev_b32_e32 v0, 16, v29
	v_and_b32_e32 v1, 0xffff0000, v29
	v_pk_fma_f32 v[4:5], v[64:65], v[4:5], v[0:1]
	v_lshlrev_b32_e32 v0, 16, v30
	v_and_b32_e32 v1, 0xffff0000, v30
	v_pk_fma_f32 v[8:9], v[64:65], v[8:9], v[0:1]
	v_lshlrev_b32_e32 v0, 16, v31
	v_and_b32_e32 v1, 0xffff0000, v31
	v_pk_fma_f32 v[6:7], v[64:65], v[6:7], v[0:1]
	v_cvt_pk_bf16_f32 v0, v10, v11
	v_cvt_pk_bf16_f32 v1, v4, v5
	v_cvt_pk_bf16_f32 v2, v8, v9
	v_cvt_pk_bf16_f32 v3, v6, v7
	flat_store_dwordx4 v[92:93], v[0:3] nt
	s_nop 1
	v_lshlrev_b32_e32 v0, 16, v32
	v_and_b32_e32 v1, 0xffff0000, v32
	v_pk_fma_f32 v[10:11], v[64:65], v[10:11], v[0:1]
	v_lshlrev_b32_e32 v0, 16, v33
	v_and_b32_e32 v1, 0xffff0000, v33
	v_pk_fma_f32 v[4:5], v[64:65], v[4:5], v[0:1]
	v_lshlrev_b32_e32 v0, 16, v34
	v_and_b32_e32 v1, 0xffff0000, v34
	v_pk_fma_f32 v[8:9], v[64:65], v[8:9], v[0:1]
	v_lshlrev_b32_e32 v0, 16, v35
	v_and_b32_e32 v1, 0xffff0000, v35
	v_pk_fma_f32 v[6:7], v[64:65], v[6:7], v[0:1]
	v_cvt_pk_bf16_f32 v0, v10, v11
	v_cvt_pk_bf16_f32 v1, v4, v5
	v_cvt_pk_bf16_f32 v2, v8, v9
	v_cvt_pk_bf16_f32 v3, v6, v7
	flat_store_dwordx4 v[94:95], v[0:3] nt
	s_nop 1
	v_lshlrev_b32_e32 v0, 16, v36
	v_and_b32_e32 v1, 0xffff0000, v36
	v_pk_fma_f32 v[10:11], v[64:65], v[10:11], v[0:1]
	v_lshlrev_b32_e32 v0, 16, v37
	v_and_b32_e32 v1, 0xffff0000, v37
	v_pk_fma_f32 v[4:5], v[64:65], v[4:5], v[0:1]
	v_lshlrev_b32_e32 v0, 16, v38
	v_and_b32_e32 v1, 0xffff0000, v38
	v_pk_fma_f32 v[8:9], v[64:65], v[8:9], v[0:1]
	v_lshlrev_b32_e32 v0, 16, v39
	v_and_b32_e32 v1, 0xffff0000, v39
	v_pk_fma_f32 v[6:7], v[64:65], v[6:7], v[0:1]
	v_cvt_pk_bf16_f32 v0, v10, v11
	v_cvt_pk_bf16_f32 v1, v4, v5
	v_cvt_pk_bf16_f32 v2, v8, v9
	v_cvt_pk_bf16_f32 v3, v6, v7
	flat_store_dwordx4 v[96:97], v[0:3] nt
	s_nop 1
	v_lshlrev_b32_e32 v0, 16, v40
	v_and_b32_e32 v1, 0xffff0000, v40
	v_pk_fma_f32 v[10:11], v[64:65], v[10:11], v[0:1]
	v_lshlrev_b32_e32 v0, 16, v41
	v_and_b32_e32 v1, 0xffff0000, v41
	v_pk_fma_f32 v[4:5], v[64:65], v[4:5], v[0:1]
	v_lshlrev_b32_e32 v0, 16, v42
	v_and_b32_e32 v1, 0xffff0000, v42
	v_pk_fma_f32 v[8:9], v[64:65], v[8:9], v[0:1]
	v_lshlrev_b32_e32 v0, 16, v43
	v_and_b32_e32 v1, 0xffff0000, v43
	v_pk_fma_f32 v[6:7], v[64:65], v[6:7], v[0:1]
	v_cvt_pk_bf16_f32 v0, v10, v11
	v_cvt_pk_bf16_f32 v1, v4, v5
	v_cvt_pk_bf16_f32 v2, v8, v9
	v_cvt_pk_bf16_f32 v3, v6, v7
	flat_store_dwordx4 v[98:99], v[0:3] nt
	s_nop 1
	v_lshlrev_b32_e32 v0, 16, v44
	v_and_b32_e32 v1, 0xffff0000, v44
	v_pk_fma_f32 v[10:11], v[64:65], v[10:11], v[0:1]
	v_lshlrev_b32_e32 v0, 16, v45
	v_and_b32_e32 v1, 0xffff0000, v45
	v_pk_fma_f32 v[4:5], v[64:65], v[4:5], v[0:1]
	v_lshlrev_b32_e32 v0, 16, v46
	v_and_b32_e32 v1, 0xffff0000, v46
	v_pk_fma_f32 v[8:9], v[64:65], v[8:9], v[0:1]
	v_lshlrev_b32_e32 v0, 16, v47
	v_and_b32_e32 v1, 0xffff0000, v47
	v_pk_fma_f32 v[6:7], v[64:65], v[6:7], v[0:1]
	v_cvt_pk_bf16_f32 v0, v10, v11
	v_cvt_pk_bf16_f32 v1, v4, v5
	v_cvt_pk_bf16_f32 v2, v8, v9
	v_cvt_pk_bf16_f32 v3, v6, v7
	flat_store_dwordx4 v[100:101], v[0:3] nt
	s_nop 1
	v_lshlrev_b32_e32 v0, 16, v48
	v_and_b32_e32 v1, 0xffff0000, v48
	v_pk_fma_f32 v[10:11], v[64:65], v[10:11], v[0:1]
	v_lshlrev_b32_e32 v0, 16, v49
	v_and_b32_e32 v1, 0xffff0000, v49
	v_pk_fma_f32 v[4:5], v[64:65], v[4:5], v[0:1]
	v_lshlrev_b32_e32 v0, 16, v50
	v_and_b32_e32 v1, 0xffff0000, v50
	v_pk_fma_f32 v[8:9], v[64:65], v[8:9], v[0:1]
	v_lshlrev_b32_e32 v0, 16, v51
	v_and_b32_e32 v1, 0xffff0000, v51
	v_pk_fma_f32 v[6:7], v[64:65], v[6:7], v[0:1]
	v_cvt_pk_bf16_f32 v0, v10, v11
	v_cvt_pk_bf16_f32 v1, v4, v5
	v_cvt_pk_bf16_f32 v2, v8, v9
	v_cvt_pk_bf16_f32 v3, v6, v7
	flat_store_dwordx4 v[102:103], v[0:3] nt
	s_nop 1
	v_lshlrev_b32_e32 v0, 16, v52
	v_and_b32_e32 v1, 0xffff0000, v52
	v_pk_fma_f32 v[10:11], v[64:65], v[10:11], v[0:1]
	v_lshlrev_b32_e32 v0, 16, v53
	v_and_b32_e32 v1, 0xffff0000, v53
	v_pk_fma_f32 v[4:5], v[64:65], v[4:5], v[0:1]
	v_lshlrev_b32_e32 v0, 16, v54
	v_and_b32_e32 v1, 0xffff0000, v54
	v_pk_fma_f32 v[8:9], v[64:65], v[8:9], v[0:1]
	v_lshlrev_b32_e32 v0, 16, v55
	v_and_b32_e32 v1, 0xffff0000, v55
	v_pk_fma_f32 v[6:7], v[64:65], v[6:7], v[0:1]
	v_cvt_pk_bf16_f32 v0, v10, v11
	v_cvt_pk_bf16_f32 v1, v4, v5
	v_cvt_pk_bf16_f32 v2, v8, v9
	v_cvt_pk_bf16_f32 v3, v6, v7
	flat_store_dwordx4 v[104:105], v[0:3] nt
	s_nop 1
	v_lshlrev_b32_e32 v0, 16, v56
	v_and_b32_e32 v1, 0xffff0000, v56
	v_pk_fma_f32 v[10:11], v[64:65], v[10:11], v[0:1]
	v_lshlrev_b32_e32 v0, 16, v57
	v_and_b32_e32 v1, 0xffff0000, v57
	v_pk_fma_f32 v[4:5], v[64:65], v[4:5], v[0:1]
	v_lshlrev_b32_e32 v0, 16, v58
	v_and_b32_e32 v1, 0xffff0000, v58
	v_pk_fma_f32 v[8:9], v[64:65], v[8:9], v[0:1]
	v_lshlrev_b32_e32 v0, 16, v59
	v_and_b32_e32 v1, 0xffff0000, v59
	v_pk_fma_f32 v[6:7], v[64:65], v[6:7], v[0:1]
	v_cvt_pk_bf16_f32 v0, v10, v11
	v_cvt_pk_bf16_f32 v1, v4, v5
	v_cvt_pk_bf16_f32 v2, v8, v9
	v_cvt_pk_bf16_f32 v3, v6, v7
	flat_store_dwordx4 v[106:107], v[0:3] nt
	s_nop 1
	v_lshlrev_b32_e32 v0, 16, v60
	v_and_b32_e32 v1, 0xffff0000, v60
	v_pk_fma_f32 v[70:71], v[64:65], v[10:11], v[0:1]
	v_lshlrev_b32_e32 v0, 16, v61
	v_and_b32_e32 v1, 0xffff0000, v61
	v_pk_fma_f32 v[72:73], v[64:65], v[4:5], v[0:1]
	v_lshlrev_b32_e32 v0, 16, v62
	v_and_b32_e32 v1, 0xffff0000, v62
	v_pk_fma_f32 v[74:75], v[64:65], v[8:9], v[0:1]
	v_lshlrev_b32_e32 v0, 16, v63
	v_and_b32_e32 v1, 0xffff0000, v63
	v_pk_fma_f32 v[68:69], v[64:65], v[6:7], v[0:1]
	s_andn2_b64 exec, exec, s[4:5]
	s_cbranch_execnz .LBB0_374

.LBB0_378:
	v_mov_b32_e32 v66, v218
	s_and_b32 s4, s7, 0xffffff80
	v_lshlrev_b32_e32 v0, 4, v66
	v_ashrrev_i32_e32 v13, 4, v66
	v_and_b32_e32 v160, 0xf0, v0
	v_add_u32_e32 v0, s4, v13
	v_ashrrev_i32_e32 v1, 31, v0
	v_lshl_add_u64 v[8:9], s[0:1], 0, v[160:161]
	v_lshlrev_b64 v[4:5], 10, v[0:1]
	v_lshl_add_u64 v[0:1], v[8:9], 0, v[4:5]
	flat_load_dwordx4 v[0:3], v[0:1]
	v_lshl_add_u64 v[10:11], s[2:3], 0, v[160:161]
	v_lshl_add_u64 v[4:5], v[10:11], 0, v[4:5]
	flat_load_dwordx4 v[4:7], v[4:5]
	v_add_u32_e32 v15, 0, v160
	v_mul_lo_u32 v19, v13, s23
	v_add_u32_e32 v20, v15, v19
	s_add_i32 s12, 0, 0x14000
	v_add_u32_e32 v18, s12, v160
	v_readfirstlane_b32 s5, v66
	s_ashr_i32 s11, s5, 6
	s_and_b32 s9, s11, 3
	s_add_i32 s13, 0, 0xa000
	v_bfe_u32 v68, v66, 5, 1
	v_and_b32_e32 v67, 31, v66
	s_mulk_i32 s11, 0x2200
	v_lshlrev_b32_e32 v67, 1, v67
	s_waitcnt vmcnt(0) lgkmcnt(0)
	ds_write_b128 v20, v[0:3]
	v_sub_u32_e32 v0, 0x7f, v13
	v_cvt_f32_i32_e32 v0, v0
	v_lshlrev_b32_e32 v2, 16, v4
	v_and_b32_e32 v3, 0xffff0000, v4
	v_mul_f32_e32 v0, v64, v0
	v_exp_f32_e32 v12, v0
	v_cvt_f32_i32_e32 v0, v13
	v_mul_f32_e32 v0, v65, v0
	v_exp_f32_e32 v14, v0
	v_pk_mul_f32 v[0:1], v[12:13], v[2:3] op_sel_hi:[0,1]
	v_cvt_pk_bf16_f32 v0, v0, v1
	v_pk_mul_f32 v[2:3], v[14:15], v[2:3] op_sel_hi:[0,1]
	v_cvt_pk_bf16_f32 v4, v2, v3
	v_lshlrev_b32_e32 v2, 16, v5
	v_and_b32_e32 v3, 0xffff0000, v5
	v_pk_mul_f32 v[16:17], v[12:13], v[2:3] op_sel_hi:[0,1]
	v_cvt_pk_bf16_f32 v1, v16, v17
	v_pk_mul_f32 v[2:3], v[14:15], v[2:3] op_sel_hi:[0,1]
	v_lshlrev_b32_e32 v16, 16, v6
	v_and_b32_e32 v17, 0xffff0000, v6
	v_cvt_pk_bf16_f32 v5, v2, v3
	v_pk_mul_f32 v[2:3], v[12:13], v[16:17] op_sel_hi:[0,1]
	v_pk_mul_f32 v[16:17], v[14:15], v[16:17] op_sel_hi:[0,1]
	v_cvt_pk_bf16_f32 v6, v16, v17
	v_lshlrev_b32_e32 v16, 16, v7
	v_and_b32_e32 v17, 0xffff0000, v7
	v_pk_mul_f32 v[12:13], v[12:13], v[16:17] op_sel_hi:[0,1]
	v_cvt_pk_bf16_f32 v2, v2, v3
	v_cvt_pk_bf16_f32 v3, v12, v13
	v_pk_mul_f32 v[12:13], v[14:15], v[16:17] op_sel_hi:[0,1]
	v_cvt_pk_bf16_f32 v7, v12, v13
	ds_write_b128 v20, v[0:3] offset:40960
	v_add_u32_e32 v0, v18, v19
	ds_write_b128 v0, v[4:7]
	v_add_u32_e32 v0, 0x200, v66
	v_ashrrev_i32_e32 v13, 4, v0
	v_add_u32_e32 v0, s4, v13
	v_ashrrev_i32_e32 v1, 31, v0
	v_lshlrev_b64 v[4:5], 10, v[0:1]
	v_lshl_add_u64 v[0:1], v[8:9], 0, v[4:5]
	flat_load_dwordx4 v[0:3], v[0:1]
	v_lshl_add_u64 v[4:5], v[10:11], 0, v[4:5]
	flat_load_dwordx4 v[4:7], v[4:5]
	v_mul_lo_u32 v19, v13, s23
	v_add_u32_e32 v20, v15, v19
	s_waitcnt vmcnt(0) lgkmcnt(0)
	ds_write_b128 v20, v[0:3]
	v_sub_u32_e32 v0, 0x7f, v13
	v_cvt_f32_i32_e32 v0, v0
	v_lshlrev_b32_e32 v2, 16, v4
	v_and_b32_e32 v3, 0xffff0000, v4
	v_mul_f32_e32 v0, v64, v0
	v_exp_f32_e32 v12, v0
	v_cvt_f32_i32_e32 v0, v13
	v_mul_f32_e32 v0, v65, v0
	v_exp_f32_e32 v14, v0
	v_pk_mul_f32 v[0:1], v[12:13], v[2:3] op_sel_hi:[0,1]
	v_cvt_pk_bf16_f32 v0, v0, v1
	v_pk_mul_f32 v[2:3], v[14:15], v[2:3] op_sel_hi:[0,1]
	v_cvt_pk_bf16_f32 v4, v2, v3
	v_lshlrev_b32_e32 v2, 16, v5
	v_and_b32_e32 v3, 0xffff0000, v5
	v_pk_mul_f32 v[16:17], v[12:13], v[2:3] op_sel_hi:[0,1]
	v_cvt_pk_bf16_f32 v1, v16, v17
	v_pk_mul_f32 v[2:3], v[14:15], v[2:3] op_sel_hi:[0,1]
	v_lshlrev_b32_e32 v16, 16, v6
	v_and_b32_e32 v17, 0xffff0000, v6
	v_cvt_pk_bf16_f32 v5, v2, v3
	v_pk_mul_f32 v[2:3], v[12:13], v[16:17] op_sel_hi:[0,1]
	v_pk_mul_f32 v[16:17], v[14:15], v[16:17] op_sel_hi:[0,1]
	v_cvt_pk_bf16_f32 v6, v16, v17
	v_lshlrev_b32_e32 v16, 16, v7
	v_and_b32_e32 v17, 0xffff0000, v7
	v_pk_mul_f32 v[12:13], v[12:13], v[16:17] op_sel_hi:[0,1]
	v_cvt_pk_bf16_f32 v2, v2, v3
	v_cvt_pk_bf16_f32 v3, v12, v13
	v_pk_mul_f32 v[12:13], v[14:15], v[16:17] op_sel_hi:[0,1]
	v_cvt_pk_bf16_f32 v7, v12, v13
	ds_write_b128 v20, v[0:3] offset:40960
	v_add_u32_e32 v0, v18, v19
	ds_write_b128 v0, v[4:7]
	v_add_u32_e32 v0, 0x400, v66
	v_ashrrev_i32_e32 v13, 4, v0
	v_add_u32_e32 v0, s4, v13
	v_ashrrev_i32_e32 v1, 31, v0
	v_lshlrev_b64 v[4:5], 10, v[0:1]
	v_lshl_add_u64 v[0:1], v[8:9], 0, v[4:5]
	flat_load_dwordx4 v[0:3], v[0:1]
	v_lshl_add_u64 v[4:5], v[10:11], 0, v[4:5]
	flat_load_dwordx4 v[4:7], v[4:5]
	v_mul_lo_u32 v19, v13, s23
	v_add_u32_e32 v20, v15, v19
	s_waitcnt vmcnt(0) lgkmcnt(0)
	ds_write_b128 v20, v[0:3]
	v_sub_u32_e32 v0, 0x7f, v13
	v_cvt_f32_i32_e32 v0, v0
	v_lshlrev_b32_e32 v2, 16, v4
	v_and_b32_e32 v3, 0xffff0000, v4
	v_mul_f32_e32 v0, v64, v0
	v_exp_f32_e32 v12, v0
	v_cvt_f32_i32_e32 v0, v13
	v_mul_f32_e32 v0, v65, v0
	v_exp_f32_e32 v14, v0
	v_pk_mul_f32 v[0:1], v[12:13], v[2:3] op_sel_hi:[0,1]
	v_cvt_pk_bf16_f32 v0, v0, v1
	v_pk_mul_f32 v[2:3], v[14:15], v[2:3] op_sel_hi:[0,1]
	v_cvt_pk_bf16_f32 v4, v2, v3
	v_lshlrev_b32_e32 v2, 16, v5
	v_and_b32_e32 v3, 0xffff0000, v5
	v_pk_mul_f32 v[16:17], v[12:13], v[2:3] op_sel_hi:[0,1]
	v_cvt_pk_bf16_f32 v1, v16, v17
	v_pk_mul_f32 v[2:3], v[14:15], v[2:3] op_sel_hi:[0,1]
	v_lshlrev_b32_e32 v16, 16, v6
	v_and_b32_e32 v17, 0xffff0000, v6
	v_cvt_pk_bf16_f32 v5, v2, v3
	v_pk_mul_f32 v[2:3], v[12:13], v[16:17] op_sel_hi:[0,1]
	v_pk_mul_f32 v[16:17], v[14:15], v[16:17] op_sel_hi:[0,1]
	v_cvt_pk_bf16_f32 v6, v16, v17
	v_lshlrev_b32_e32 v16, 16, v7
	v_and_b32_e32 v17, 0xffff0000, v7
	v_pk_mul_f32 v[12:13], v[12:13], v[16:17] op_sel_hi:[0,1]
	v_cvt_pk_bf16_f32 v2, v2, v3
	v_cvt_pk_bf16_f32 v3, v12, v13
	v_pk_mul_f32 v[12:13], v[14:15], v[16:17] op_sel_hi:[0,1]
	v_cvt_pk_bf16_f32 v7, v12, v13
	ds_write_b128 v20, v[0:3] offset:40960
	v_add_u32_e32 v0, v18, v19
	ds_write_b128 v0, v[4:7]
	v_add_u32_e32 v0, 0x600, v66
	v_ashrrev_i32_e32 v12, 4, v0
	v_add_u32_e32 v0, s4, v12
	v_ashrrev_i32_e32 v1, 31, v0
	v_lshlrev_b64 v[4:5], 10, v[0:1]
	v_lshl_add_u64 v[0:1], v[8:9], 0, v[4:5]
	flat_load_dwordx4 v[0:3], v[0:1]
	v_lshl_add_u64 v[4:5], v[10:11], 0, v[4:5]
	flat_load_dwordx4 v[4:7], v[4:5]
	v_mul_lo_u32 v11, v12, s23
	v_add_u32_e32 v14, v15, v11
	s_ashr_i32 s4, s5, 8
	s_cmpk_lt_u32 s5, 0x100
	s_cselect_b32 s5, s13, s12
	s_lshl_b32 s12, s9, 6
	s_add_i32 s12, s12, 0
	s_add_i32 s11, s11, 0
	s_waitcnt vmcnt(0) lgkmcnt(0)
	ds_write_b128 v14, v[0:3]
	v_sub_u32_e32 v0, 0x7f, v12
	v_cvt_f32_i32_e32 v0, v0
	v_lshlrev_b32_e32 v2, 16, v4
	v_and_b32_e32 v3, 0xffff0000, v4
	v_mul_f32_e32 v0, v64, v0
	v_exp_f32_e32 v8, v0
	v_cvt_f32_i32_e32 v0, v12
	v_mul_f32_e32 v0, v65, v0
	v_exp_f32_e32 v10, v0
	v_pk_mul_f32 v[0:1], v[8:9], v[2:3] op_sel_hi:[0,1]
	v_cvt_pk_bf16_f32 v0, v0, v1
	v_pk_mul_f32 v[2:3], v[10:11], v[2:3] op_sel_hi:[0,1]
	v_cvt_pk_bf16_f32 v4, v2, v3
	v_lshlrev_b32_e32 v2, 16, v5
	v_and_b32_e32 v3, 0xffff0000, v5
	v_pk_mul_f32 v[12:13], v[8:9], v[2:3] op_sel_hi:[0,1]
	v_cvt_pk_bf16_f32 v1, v12, v13
	v_pk_mul_f32 v[2:3], v[10:11], v[2:3] op_sel_hi:[0,1]
	v_lshlrev_b32_e32 v12, 16, v6
	v_and_b32_e32 v13, 0xffff0000, v6
	v_cvt_pk_bf16_f32 v5, v2, v3
	v_pk_mul_f32 v[2:3], v[8:9], v[12:13] op_sel_hi:[0,1]
	v_pk_mul_f32 v[12:13], v[10:11], v[12:13] op_sel_hi:[0,1]
	v_cvt_pk_bf16_f32 v6, v12, v13
	v_lshlrev_b32_e32 v12, 16, v7
	v_and_b32_e32 v13, 0xffff0000, v7
	v_pk_mul_f32 v[8:9], v[8:9], v[12:13] op_sel_hi:[0,1]
	v_cvt_pk_bf16_f32 v2, v2, v3
	v_cvt_pk_bf16_f32 v3, v8, v9
	v_pk_mul_f32 v[8:9], v[10:11], v[12:13] op_sel_hi:[0,1]
	v_cvt_pk_bf16_f32 v7, v8, v9
	ds_write_b128 v14, v[0:3] offset:40960
	v_add_u32_e32 v0, v18, v11
	ds_write_b128 v0, v[4:7]
	v_bfe_u32 v0, v66, 2, 2
	v_lshlrev_b32_e32 v1, 2, v66
	v_and_b32_e32 v2, 16, v66
	v_and_or_b32 v1, v1, 12, v2
	v_lshl_or_b32 v0, v68, 3, v0
	v_lshlrev_b32_e32 v4, 1, v1
	v_mul_u32_u24_e32 v5, 0x140, v0
	v_add3_u32 v69, s12, v4, v5
	v_add3_u32 v70, s5, v4, v5
	s_waitcnt lgkmcnt(0)
	s_barrier
	ds_read_b64_tr_b16 v[0:1], v69
	ds_read_b64_tr_b16 v[2:3], v69 offset:1280
	ds_read_b64_tr_b16 v[4:5], v70
	ds_read_b64_tr_b16 v[6:7], v70 offset:1280
	s_waitcnt lgkmcnt(0)
	v_mfma_f32_32x32x16_bf16 v[48:63], v[0:3], v[4:7], 0
	ds_read_b64_tr_b16 v[4:5], v70 offset:64
	ds_read_b64_tr_b16 v[6:7], v70 offset:1344
	v_mul_u32_u24_e32 v68, 0x440, v68
	v_add3_u32 v67, s11, v67, v68
	s_add_i32 s5, s6, s8
	s_add_i32 s4, s5, s4
	s_ashr_i32 s5, s4, 31
	s_lshl_b64 s[4:5], s[4:5], 15
	s_waitcnt lgkmcnt(0)
	v_mfma_f32_32x32x16_bf16 v[32:47], v[0:3], v[4:7], 0
	ds_read_b64_tr_b16 v[4:5], v70 offset:128
	ds_read_b64_tr_b16 v[6:7], v70 offset:1408
	s_add_u32 s4, s46, s4
	s_addc_u32 s5, s47, s5
	s_lshl_b32 s9, s9, 13
	s_add_u32 s4, s4, s9
	s_addc_u32 s5, s5, 0
	s_addk_i32 s8, 0x200
	s_waitcnt lgkmcnt(0)
	v_mfma_f32_32x32x16_bf16 v[16:31], v[0:3], v[4:7], 0
	ds_read_b64_tr_b16 v[4:5], v70 offset:192
	ds_read_b64_tr_b16 v[6:7], v70 offset:1472
	ds_read_b64_tr_b16 v[72:73], v69 offset:5120
	ds_read_b64_tr_b16 v[74:75], v69 offset:6400
	ds_read_b64_tr_b16 v[76:77], v70 offset:5120
	ds_read_b64_tr_b16 v[78:79], v70 offset:6400
	s_addk_i32 s7, 0x2000
	s_cmpk_eq_i32 s8, 0x800
	s_waitcnt lgkmcnt(0)
	v_mfma_f32_32x32x16_bf16 v[48:63], v[72:75], v[76:79], v[48:63]
	ds_read_b64_tr_b16 v[76:77], v70 offset:5184
	ds_read_b64_tr_b16 v[78:79], v70 offset:6464
	s_waitcnt lgkmcnt(0)
	v_mfma_f32_32x32x16_bf16 v[32:47], v[72:75], v[76:79], v[32:47]
	ds_read_b64_tr_b16 v[76:77], v70 offset:5248
	ds_read_b64_tr_b16 v[78:79], v70 offset:6528
	v_mfma_f32_32x32x16_bf16 v[0:15], v[0:3], v[4:7], 0
	s_waitcnt lgkmcnt(0)
	v_mfma_f32_32x32x16_bf16 v[16:31], v[72:75], v[76:79], v[16:31]
	ds_read_b64_tr_b16 v[76:77], v70 offset:5312
	ds_read_b64_tr_b16 v[78:79], v70 offset:6592
	s_waitcnt lgkmcnt(0)
	v_mfma_f32_32x32x16_bf16 v[0:15], v[72:75], v[76:79], v[0:15]
	ds_read_b64_tr_b16 v[72:73], v69 offset:10240
	ds_read_b64_tr_b16 v[74:75], v69 offset:11520
	ds_read_b64_tr_b16 v[76:77], v70 offset:10240
	ds_read_b64_tr_b16 v[78:79], v70 offset:11520
	s_waitcnt lgkmcnt(0)
	v_mfma_f32_32x32x16_bf16 v[48:63], v[72:75], v[76:79], v[48:63]
	ds_read_b64_tr_b16 v[76:77], v70 offset:10304
	ds_read_b64_tr_b16 v[78:79], v70 offset:11584
	s_waitcnt lgkmcnt(0)
	v_mfma_f32_32x32x16_bf16 v[32:47], v[72:75], v[76:79], v[32:47]
	ds_read_b64_tr_b16 v[76:77], v70 offset:10368
	ds_read_b64_tr_b16 v[78:79], v70 offset:11648
	s_waitcnt lgkmcnt(0)
	v_mfma_f32_32x32x16_bf16 v[16:31], v[72:75], v[76:79], v[16:31]
	ds_read_b64_tr_b16 v[76:77], v70 offset:10432
	ds_read_b64_tr_b16 v[78:79], v70 offset:11712
	s_waitcnt lgkmcnt(0)
	v_mfma_f32_32x32x16_bf16 v[0:15], v[72:75], v[76:79], v[0:15]
	ds_read_b64_tr_b16 v[72:73], v69 offset:15360
	ds_read_b64_tr_b16 v[74:75], v69 offset:16640
	ds_read_b64_tr_b16 v[76:77], v70 offset:15360
	ds_read_b64_tr_b16 v[78:79], v70 offset:16640
	s_waitcnt lgkmcnt(0)
	v_mfma_f32_32x32x16_bf16 v[48:63], v[72:75], v[76:79], v[48:63]
	ds_read_b64_tr_b16 v[76:77], v70 offset:15424
	ds_read_b64_tr_b16 v[78:79], v70 offset:16704
	s_waitcnt lgkmcnt(0)
	v_mfma_f32_32x32x16_bf16 v[32:47], v[72:75], v[76:79], v[32:47]
	ds_read_b64_tr_b16 v[76:77], v70 offset:15488
	ds_read_b64_tr_b16 v[78:79], v70 offset:16768
	s_waitcnt lgkmcnt(0)
	v_mfma_f32_32x32x16_bf16 v[16:31], v[72:75], v[76:79], v[16:31]
	ds_read_b64_tr_b16 v[76:77], v70 offset:15552
	ds_read_b64_tr_b16 v[78:79], v70 offset:16832
	s_waitcnt lgkmcnt(0)
	v_mfma_f32_32x32x16_bf16 v[0:15], v[72:75], v[76:79], v[0:15]
	ds_read_b64_tr_b16 v[72:73], v69 offset:20480
	ds_read_b64_tr_b16 v[74:75], v69 offset:21760
	ds_read_b64_tr_b16 v[76:77], v70 offset:20480
	ds_read_b64_tr_b16 v[78:79], v70 offset:21760
	s_waitcnt lgkmcnt(0)
	v_mfma_f32_32x32x16_bf16 v[48:63], v[72:75], v[76:79], v[48:63]
	ds_read_b64_tr_b16 v[76:77], v70 offset:20544
	ds_read_b64_tr_b16 v[78:79], v70 offset:21824
	s_waitcnt lgkmcnt(0)
	v_mfma_f32_32x32x16_bf16 v[32:47], v[72:75], v[76:79], v[32:47]
	ds_read_b64_tr_b16 v[76:77], v70 offset:20608
	ds_read_b64_tr_b16 v[78:79], v70 offset:21888
	s_waitcnt lgkmcnt(0)
	v_mfma_f32_32x32x16_bf16 v[16:31], v[72:75], v[76:79], v[16:31]
	ds_read_b64_tr_b16 v[76:77], v70 offset:20672
	ds_read_b64_tr_b16 v[78:79], v70 offset:21952
	s_waitcnt lgkmcnt(0)
	v_mfma_f32_32x32x16_bf16 v[0:15], v[72:75], v[76:79], v[0:15]
	ds_read_b64_tr_b16 v[72:73], v69 offset:25600
	ds_read_b64_tr_b16 v[74:75], v69 offset:26880
	ds_read_b64_tr_b16 v[76:77], v70 offset:25600
	ds_read_b64_tr_b16 v[78:79], v70 offset:26880
	s_waitcnt lgkmcnt(0)
	v_mfma_f32_32x32x16_bf16 v[48:63], v[72:75], v[76:79], v[48:63]
	ds_read_b64_tr_b16 v[76:77], v70 offset:25664
	ds_read_b64_tr_b16 v[78:79], v70 offset:26944
	s_waitcnt lgkmcnt(0)
	v_mfma_f32_32x32x16_bf16 v[32:47], v[72:75], v[76:79], v[32:47]
	ds_read_b64_tr_b16 v[76:77], v70 offset:25728
	ds_read_b64_tr_b16 v[78:79], v70 offset:27008
	s_waitcnt lgkmcnt(0)
	v_mfma_f32_32x32x16_bf16 v[16:31], v[72:75], v[76:79], v[16:31]
	ds_read_b64_tr_b16 v[76:77], v70 offset:25792
	ds_read_b64_tr_b16 v[78:79], v70 offset:27072
	s_waitcnt lgkmcnt(0)
	v_mfma_f32_32x32x16_bf16 v[0:15], v[72:75], v[76:79], v[0:15]
	ds_read_b64_tr_b16 v[72:73], v69 offset:30720
	ds_read_b64_tr_b16 v[74:75], v69 offset:32000
	ds_read_b64_tr_b16 v[76:77], v70 offset:30720
	ds_read_b64_tr_b16 v[78:79], v70 offset:32000
	s_waitcnt lgkmcnt(0)
	v_mfma_f32_32x32x16_bf16 v[48:63], v[72:75], v[76:79], v[48:63]
	ds_read_b64_tr_b16 v[76:77], v70 offset:30784
	ds_read_b64_tr_b16 v[78:79], v70 offset:32064
	s_waitcnt lgkmcnt(0)
	v_mfma_f32_32x32x16_bf16 v[32:47], v[72:75], v[76:79], v[32:47]
	ds_read_b64_tr_b16 v[76:77], v70 offset:30848
	ds_read_b64_tr_b16 v[78:79], v70 offset:32128
	s_waitcnt lgkmcnt(0)
	v_mfma_f32_32x32x16_bf16 v[16:31], v[72:75], v[76:79], v[16:31]
	ds_read_b64_tr_b16 v[76:77], v70 offset:30912
	ds_read_b64_tr_b16 v[78:79], v70 offset:32192
	s_waitcnt lgkmcnt(0)
	v_mfma_f32_32x32x16_bf16 v[0:15], v[72:75], v[76:79], v[0:15]
	ds_read_b64_tr_b16 v[72:73], v69 offset:35840
	ds_read_b64_tr_b16 v[74:75], v69 offset:37120
	ds_read_b64_tr_b16 v[76:77], v70 offset:35840
	ds_read_b64_tr_b16 v[78:79], v70 offset:37120
	s_waitcnt lgkmcnt(0)
	v_mfma_f32_32x32x16_bf16 v[48:63], v[72:75], v[76:79], v[48:63]
	ds_read_b64_tr_b16 v[76:77], v70 offset:35904
	ds_read_b64_tr_b16 v[78:79], v70 offset:37184
	s_waitcnt lgkmcnt(0)
	v_mfma_f32_32x32x16_bf16 v[32:47], v[72:75], v[76:79], v[32:47]
	ds_read_b64_tr_b16 v[76:77], v70 offset:35968
	ds_read_b64_tr_b16 v[78:79], v70 offset:37248
	s_nop 5
	v_cvt_pk_bf16_f32 v48, v48, s0
	s_waitcnt lgkmcnt(0)
	v_mfma_f32_32x32x16_bf16 v[16:31], v[72:75], v[76:79], v[16:31]
	ds_read_b64_tr_b16 v[76:77], v70 offset:36032
	ds_read_b64_tr_b16 v[78:79], v70 offset:37312
	v_cvt_pk_bf16_f32 v32, v32, s0
	s_waitcnt lgkmcnt(0)
	s_barrier
	ds_write_b16 v67, v48
	v_cvt_pk_bf16_f32 v48, v49, s0
	v_mfma_f32_32x32x16_bf16 v[0:15], v[72:75], v[76:79], v[0:15]
	s_nop 3
	v_cvt_pk_bf16_f32 v16, v16, s0
	ds_write_b16 v67, v32 offset:64
	v_cvt_pk_bf16_f32 v32, v33, s0
	ds_write_b16 v67, v16 offset:128
	v_cvt_pk_bf16_f32 v16, v17, s0
	ds_write_b16 v67, v48 offset:272
	v_cvt_pk_bf16_f32 v48, v50, s0
	s_nop 0
	v_cvt_pk_bf16_f32 v0, v0, s0
	ds_write_b16 v67, v0 offset:192
	v_cvt_pk_bf16_f32 v0, v1, s0
	ds_write_b16 v67, v32 offset:336
	v_cvt_pk_bf16_f32 v32, v34, s0
	ds_write_b16 v67, v16 offset:400
	v_cvt_pk_bf16_f32 v16, v18, s0
	ds_write_b16 v67, v0 offset:464
	v_cvt_pk_bf16_f32 v0, v2, s0
	ds_write_b16 v67, v48 offset:544
	v_cvt_pk_bf16_f32 v48, v51, s0
	ds_write_b16 v67, v32 offset:608
	v_cvt_pk_bf16_f32 v32, v35, s0
	ds_write_b16 v67, v16 offset:672
	v_cvt_pk_bf16_f32 v16, v19, s0
	ds_write_b16 v67, v0 offset:736
	v_cvt_pk_bf16_f32 v0, v3, s0
	ds_write_b16 v67, v48 offset:816
	v_cvt_pk_bf16_f32 v48, v52, s0
	ds_write_b16 v67, v32 offset:880
	v_cvt_pk_bf16_f32 v32, v36, s0
	ds_write_b16 v67, v16 offset:944
	v_cvt_pk_bf16_f32 v16, v20, s0
	ds_write_b16 v67, v0 offset:1008
	v_cvt_pk_bf16_f32 v0, v4, s0
	ds_write_b16 v67, v48 offset:2176
	v_cvt_pk_bf16_f32 v48, v53, s0
	ds_write_b16 v67, v32 offset:2240
	v_cvt_pk_bf16_f32 v32, v37, s0
	ds_write_b16 v67, v16 offset:2304
	v_cvt_pk_bf16_f32 v16, v21, s0
	ds_write_b16 v67, v0 offset:2368
	v_cvt_pk_bf16_f32 v0, v5, s0
	ds_write_b16 v67, v48 offset:2448
	v_cvt_pk_bf16_f32 v48, v54, s0
	ds_write_b16 v67, v32 offset:2512
	v_cvt_pk_bf16_f32 v32, v38, s0
	ds_write_b16 v67, v16 offset:2576
	v_cvt_pk_bf16_f32 v16, v22, s0
	ds_write_b16 v67, v0 offset:2640
	v_cvt_pk_bf16_f32 v0, v6, s0
	ds_write_b16 v67, v48 offset:2720
	v_cvt_pk_bf16_f32 v48, v55, s0
	ds_write_b16 v67, v32 offset:2784
	v_cvt_pk_bf16_f32 v32, v39, s0
	ds_write_b16 v67, v16 offset:2848
	v_cvt_pk_bf16_f32 v16, v23, s0
	ds_write_b16 v67, v0 offset:2912
	v_cvt_pk_bf16_f32 v0, v7, s0
	ds_write_b16 v67, v48 offset:2992
	v_cvt_pk_bf16_f32 v48, v56, s0
	ds_write_b16 v67, v32 offset:3056
	v_cvt_pk_bf16_f32 v32, v40, s0
	ds_write_b16 v67, v16 offset:3120
	v_cvt_pk_bf16_f32 v16, v24, s0
	ds_write_b16 v67, v0 offset:3184
	v_cvt_pk_bf16_f32 v0, v8, s0
	ds_write_b16 v67, v48 offset:4352
	v_cvt_pk_bf16_f32 v48, v57, s0
	ds_write_b16 v67, v32 offset:4416
	v_cvt_pk_bf16_f32 v32, v41, s0
	ds_write_b16 v67, v16 offset:4480
	v_cvt_pk_bf16_f32 v16, v25, s0
	ds_write_b16 v67, v0 offset:4544
	v_cvt_pk_bf16_f32 v0, v9, s0
	ds_write_b16 v67, v48 offset:4624
	v_cvt_pk_bf16_f32 v48, v58, s0
	ds_write_b16 v67, v32 offset:4688
	v_cvt_pk_bf16_f32 v32, v42, s0
	ds_write_b16 v67, v16 offset:4752
	v_cvt_pk_bf16_f32 v16, v26, s0
	ds_write_b16 v67, v0 offset:4816
	v_cvt_pk_bf16_f32 v0, v10, s0
	ds_write_b16 v67, v48 offset:4896
	v_cvt_pk_bf16_f32 v48, v59, s0
	ds_write_b16 v67, v32 offset:4960
	v_cvt_pk_bf16_f32 v32, v43, s0
	ds_write_b16 v67, v16 offset:5024
	v_cvt_pk_bf16_f32 v16, v27, s0
	ds_write_b16 v67, v0 offset:5088
	v_cvt_pk_bf16_f32 v0, v11, s0
	ds_write_b16 v67, v48 offset:5168
	v_cvt_pk_bf16_f32 v48, v60, s0
	ds_write_b16 v67, v32 offset:5232
	v_cvt_pk_bf16_f32 v32, v44, s0
	ds_write_b16 v67, v16 offset:5296
	v_cvt_pk_bf16_f32 v16, v28, s0
	ds_write_b16 v67, v0 offset:5360
	v_cvt_pk_bf16_f32 v0, v12, s0
	ds_write_b16 v67, v48 offset:6528
	v_cvt_pk_bf16_f32 v48, v61, s0
	ds_write_b16 v67, v32 offset:6592
	v_cvt_pk_bf16_f32 v32, v45, s0
	ds_write_b16 v67, v16 offset:6656
	v_cvt_pk_bf16_f32 v16, v29, s0
	ds_write_b16 v67, v0 offset:6720
	v_cvt_pk_bf16_f32 v0, v13, s0
	ds_write_b16 v67, v48 offset:6800
	v_cvt_pk_bf16_f32 v48, v62, s0
	ds_write_b16 v67, v32 offset:6864
	v_cvt_pk_bf16_f32 v32, v46, s0
	ds_write_b16 v67, v16 offset:6928
	v_cvt_pk_bf16_f32 v16, v30, s0
	ds_write_b16 v67, v0 offset:6992
	v_cvt_pk_bf16_f32 v0, v14, s0
	ds_write_b16 v67, v48 offset:7072
	v_cvt_pk_bf16_f32 v48, v63, s0
	ds_write_b16 v67, v32 offset:7136
	v_cvt_pk_bf16_f32 v32, v47, s0
	ds_write_b16 v67, v16 offset:7200
	v_cvt_pk_bf16_f32 v16, v31, s0
	ds_write_b16 v67, v0 offset:7264
	v_cvt_pk_bf16_f32 v0, v15, s0
	v_bfe_u32 v6, v66, 4, 2
	ds_write_b16 v67, v48 offset:7344
	ds_write_b16 v67, v32 offset:7408
	ds_write_b16 v67, v16 offset:7472
	ds_write_b16 v67, v0 offset:7536
	v_mul_u32_u24_e32 v0, 0x110, v6
	s_waitcnt lgkmcnt(0)
	v_add3_u32 v8, s11, v160, v0
	ds_read_b128 v[0:3], v8
	v_lshl_add_u64 v[4:5], s[4:5], 0, v[160:161]
	v_lshlrev_b32_e32 v160, 8, v6
	v_lshl_add_u64 v[6:7], v[4:5], 0, v[160:161]
	s_waitcnt lgkmcnt(0)
	flat_store_dwordx4 v[6:7], v[0:3] nt
	ds_read_b128 v[0:3], v8 offset:1088
	v_or_b32_e32 v6, 0x400, v160
	v_mov_b32_e32 v7, v161
	v_lshl_add_u64 v[6:7], v[4:5], 0, v[6:7]
	s_waitcnt lgkmcnt(0)
	flat_store_dwordx4 v[6:7], v[0:3] nt
	ds_read_b128 v[0:3], v8 offset:2176
	v_or_b32_e32 v6, 0x800, v160
	v_mov_b32_e32 v7, v161
	v_lshl_add_u64 v[6:7], v[4:5], 0, v[6:7]
	s_waitcnt lgkmcnt(0)
	flat_store_dwordx4 v[6:7], v[0:3] nt
	ds_read_b128 v[0:3], v8 offset:3264
	v_or_b32_e32 v6, 0xc00, v160
	v_mov_b32_e32 v7, v161
	v_lshl_add_u64 v[6:7], v[4:5], 0, v[6:7]
	s_waitcnt lgkmcnt(0)
	flat_store_dwordx4 v[6:7], v[0:3] nt
	ds_read_b128 v[0:3], v8 offset:4352
	v_or_b32_e32 v6, 0x1000, v160
	v_mov_b32_e32 v7, v161
	v_lshl_add_u64 v[6:7], v[4:5], 0, v[6:7]
	s_waitcnt lgkmcnt(0)
	flat_store_dwordx4 v[6:7], v[0:3] nt
	ds_read_b128 v[0:3], v8 offset:5440
	v_or_b32_e32 v6, 0x1400, v160
	v_mov_b32_e32 v7, v161
	v_lshl_add_u64 v[6:7], v[4:5], 0, v[6:7]
	s_waitcnt lgkmcnt(0)
	flat_store_dwordx4 v[6:7], v[0:3] nt
	ds_read_b128 v[0:3], v8 offset:6528
	v_or_b32_e32 v6, 0x1800, v160
	v_mov_b32_e32 v7, v161
	v_lshl_add_u64 v[6:7], v[4:5], 0, v[6:7]
	v_or_b32_e32 v160, 0x1c00, v160
	s_waitcnt lgkmcnt(0)
	flat_store_dwordx4 v[6:7], v[0:3] nt
	ds_read_b128 v[0:3], v8 offset:7616
	v_lshl_add_u64 v[4:5], v[4:5], 0, v[160:161]
	s_waitcnt lgkmcnt(0)
	flat_store_dwordx4 v[4:5], v[0:3] nt
	s_waitcnt lgkmcnt(0)
	s_barrier
	s_cbranch_scc0 .LBB0_378
	s_add_u32 s2, s94, 0x9a00000
	s_addc_u32 s3, s95, 0
	s_add_u32 s4, s94, 0x13a00000
	s_addc_u32 s5, s95, 0
	s_mov_b32 s11, 0
	s_branch .LBB0_381
.LBB0_380:
	s_or_b64 exec, exec, s[6:7]
	v_ashrrev_i32_e32 v5, 31, v4
	v_lshlrev_b64 v[0:1], 2, v[4:5]
	v_lshl_add_u64 v[34:35], s[64:65], 0, v[0:1]
	v_add_co_u32_e32 v6, vcc, 0x1000, v34
	s_movk_i32 s0, 0x2000
	s_nop 0
	v_addc_co_u32_e32 v7, vcc, 0, v35, vcc
	v_add_co_u32_e32 v10, vcc, s0, v34
	global_load_dword v2, v[34:35], off
	global_load_dword v5, v[6:7], off
	v_addc_co_u32_e32 v11, vcc, 0, v35, vcc
	v_add_co_u32_e32 v12, vcc, 0x3000, v34
	global_load_dword v3, v[34:35], off offset:2048
	s_nop 0
	v_addc_co_u32_e32 v13, vcc, 0, v35, vcc
	global_load_dword v6, v[6:7], off offset:2048
	s_nop 0
	global_load_dword v8, v[10:11], off
	global_load_dword v7, v[10:11], off offset:2048
	s_nop 0
	global_load_dword v10, v[12:13], off
	global_load_dword v9, v[12:13], off offset:2048
	v_add_co_u32_e32 v12, vcc, s33, v34
	s_movk_i32 s0, 0x5000
	s_nop 0
	v_addc_co_u32_e32 v13, vcc, 0, v35, vcc
	v_add_co_u32_e32 v20, vcc, s0, v34
	s_movk_i32 s0, 0x6000
	s_nop 0
	v_addc_co_u32_e32 v21, vcc, 0, v35, vcc
	v_add_co_u32_e32 v22, vcc, s0, v34
	s_movk_i32 s0, 0x7000
	s_nop 0
	v_addc_co_u32_e32 v23, vcc, 0, v35, vcc
	v_add_co_u32_e32 v24, vcc, s0, v34
	global_load_dword v14, v[20:21], off offset:-4096
	s_nop 0
	global_load_dword v13, v[12:13], off offset:2048
	s_nop 0
	global_load_dword v12, v[20:21], off
	global_load_dword v11, v[20:21], off offset:2048
	v_addc_co_u32_e32 v25, vcc, 0, v35, vcc
	global_load_dword v21, v[24:25], off offset:-4096
	global_load_dword v20, v[22:23], off offset:2048
	global_load_dword v16, v[24:25], off
	global_load_dword v15, v[24:25], off offset:2048
	v_add_co_u32_e32 v24, vcc, s42, v34
	s_mov_b32 s0, 0x9000
	s_nop 0
	v_addc_co_u32_e32 v25, vcc, 0, v35, vcc
	v_add_co_u32_e32 v26, vcc, s0, v34
	s_mov_b32 s0, 0xa000
	s_nop 0
	v_addc_co_u32_e32 v27, vcc, 0, v35, vcc
	global_load_dword v23, v[26:27], off offset:-4096
	global_load_dword v22, v[24:25], off offset:2048
	s_nop 0
	global_load_dword v25, v[26:27], off
	global_load_dword v24, v[26:27], off offset:2048
	v_add_co_u32_e32 v26, vcc, s0, v34
	s_mov_b32 s0, 0xb000
	s_nop 0
	v_addc_co_u32_e32 v27, vcc, 0, v35, vcc
	v_add_co_u32_e32 v30, vcc, s0, v34
	s_mov_b32 s0, 0xc000
	s_nop 0
	v_addc_co_u32_e32 v31, vcc, 0, v35, vcc
	global_load_dword v29, v[30:31], off offset:-4096
	global_load_dword v28, v[26:27], off offset:2048
	s_nop 0
	global_load_dword v27, v[30:31], off
	global_load_dword v26, v[30:31], off offset:2048
	v_add_co_u32_e32 v30, vcc, s0, v34
	s_mov_b32 s0, 0xd000
	s_nop 0
	v_addc_co_u32_e32 v31, vcc, 0, v35, vcc
	v_add_co_u32_e32 v36, vcc, s0, v34
	s_mov_b32 s0, 0xe000
	s_nop 0
	v_addc_co_u32_e32 v37, vcc, 0, v35, vcc
	global_load_dword v33, v[36:37], off offset:-4096
	global_load_dword v32, v[30:31], off offset:2048
	s_nop 0
	global_load_dword v31, v[36:37], off
	global_load_dword v30, v[36:37], off offset:2048
	v_add_co_u32_e32 v36, vcc, s0, v34
	s_mov_b32 s0, 0xf000
	s_nop 0
	v_addc_co_u32_e32 v37, vcc, 0, v35, vcc
	v_add_co_u32_e32 v38, vcc, s0, v34
	v_lshl_add_u64 v[0:1], s[66:67], 0, v[0:1]
	s_nop 0
	v_addc_co_u32_e32 v39, vcc, 0, v35, vcc
	v_lshl_add_u32 v79, v4, 1, 0
	global_load_dword v34, v[38:39], off offset:-4096
	s_nop 0
	global_load_dword v36, v[36:37], off offset:2048
	s_nop 0
	global_load_dword v35, v[38:39], off
	s_add_i32 s0, 0, 0x10000
	global_load_dword v0, v[0:1], off
	s_waitcnt lgkmcnt(0)
	s_barrier
	ds_read_u16 v1, v79
	ds_read_u16 v67, v79 offset:57344
	ds_read_u16 v69, v79 offset:58368
	ds_read_u16 v70, v79 offset:59392
	ds_read_u16 v71, v79 offset:60416
	ds_read_u16 v72, v79 offset:61440
	s_waitcnt lgkmcnt(0)
	v_lshlrev_b32_e32 v98, 16, v1
	ds_read_u16 v1, v79 offset:1024
	ds_read_u16 v37, v79 offset:32768
	ds_read_u16 v38, v79 offset:33792
	ds_read_u16 v39, v79 offset:34816
	ds_read_u16 v40, v79 offset:35840
	ds_read_u16 v41, v79 offset:36864
	ds_read_u16 v42, v79 offset:37888
	ds_read_u16 v43, v79 offset:38912
	ds_read_u16 v44, v79 offset:39936
	s_waitcnt lgkmcnt(0)
	v_lshlrev_b32_e32 v97, 16, v1
	ds_read_u16 v1, v79 offset:2048
	v_lshlrev_b32_e32 v37, 16, v37
	v_lshlrev_b32_e32 v38, 16, v38
	v_lshlrev_b32_e32 v39, 16, v39
	v_lshlrev_b32_e32 v40, 16, v40
	s_waitcnt lgkmcnt(0)
	v_lshlrev_b32_e32 v96, 16, v1
	ds_read_u16 v1, v79 offset:3072
	ds_read_u16 v45, v79 offset:40960
	ds_read_u16 v46, v79 offset:41984
	ds_read_u16 v47, v79 offset:43008
	ds_read_u16 v48, v79 offset:44032
	ds_read_u16 v49, v79 offset:45056
	ds_read_u16 v50, v79 offset:46080
	ds_read_u16 v51, v79 offset:47104
	ds_read_u16 v52, v79 offset:48128
	s_waitcnt lgkmcnt(0)
	v_lshlrev_b32_e32 v95, 16, v1
	ds_read_u16 v1, v79 offset:4096
	v_lshlrev_b32_e32 v41, 16, v41
	v_lshlrev_b32_e32 v42, 16, v42
	v_lshlrev_b32_e32 v43, 16, v43
	v_lshlrev_b32_e32 v44, 16, v44
	s_waitcnt lgkmcnt(0)
	v_lshlrev_b32_e32 v94, 16, v1
	ds_read_u16 v1, v79 offset:5120
	v_lshlrev_b32_e32 v45, 16, v45
	v_lshlrev_b32_e32 v46, 16, v46
	v_lshlrev_b32_e32 v47, 16, v47
	v_lshlrev_b32_e32 v48, 16, v48
	s_waitcnt lgkmcnt(0)
	v_lshlrev_b32_e32 v93, 16, v1
	ds_read_u16 v1, v79 offset:6144
	ds_read_u16 v53, v79 offset:49152
	ds_read_u16 v54, v79 offset:50176
	ds_read_u16 v55, v79 offset:51200
	ds_read_u16 v56, v79 offset:52224
	ds_read_u16 v57, v79 offset:53248
	ds_read_u16 v58, v79 offset:54272
	ds_read_u16 v59, v79 offset:55296
	ds_read_u16 v60, v79 offset:56320
	s_waitcnt lgkmcnt(0)
	v_lshlrev_b32_e32 v92, 16, v1
	ds_read_u16 v1, v79 offset:7168
	v_lshlrev_b32_e32 v49, 16, v49
	v_lshlrev_b32_e32 v50, 16, v50
	v_lshlrev_b32_e32 v51, 16, v51
	v_lshlrev_b32_e32 v52, 16, v52
	s_waitcnt lgkmcnt(0)
	v_lshlrev_b32_e32 v91, 16, v1
	ds_read_u16 v1, v79 offset:8192
	v_lshlrev_b32_e32 v53, 16, v53
	v_lshlrev_b32_e32 v54, 16, v54
	v_lshlrev_b32_e32 v55, 16, v55
	v_lshlrev_b32_e32 v56, 16, v56
	s_waitcnt lgkmcnt(0)
	v_lshlrev_b32_e32 v90, 16, v1
	ds_read_u16 v1, v79 offset:9216
	v_lshlrev_b32_e32 v57, 16, v57
	v_lshlrev_b32_e32 v58, 16, v58
	v_lshlrev_b32_e32 v59, 16, v59
	v_lshlrev_b32_e32 v60, 16, v60
	s_waitcnt lgkmcnt(0)
	v_lshlrev_b32_e32 v89, 16, v1
	ds_read_u16 v1, v79 offset:10240
	v_lshlrev_b32_e32 v67, 16, v67
	v_lshlrev_b32_e32 v69, 16, v69
	s_waitcnt vmcnt(0)
	v_fma_f32 v98, v2, v98, v0
	v_fmac_f32_e32 v98, v3, v97
	s_waitcnt lgkmcnt(0)
	v_lshlrev_b32_e32 v88, 16, v1
	ds_read_u16 v1, v79 offset:11264
	v_fma_f32 v97, v2, v97, v0
	v_fmac_f32_e32 v98, v5, v96
	v_fmac_f32_e32 v97, v3, v96
	v_fma_f32 v96, v2, v96, v0
	s_waitcnt lgkmcnt(0)
	v_lshlrev_b32_e32 v87, 16, v1
	ds_read_u16 v1, v79 offset:12288
	v_fmac_f32_e32 v98, v6, v95
	v_fmac_f32_e32 v97, v5, v95
	v_fmac_f32_e32 v96, v3, v95
	v_fma_f32 v95, v2, v95, v0
	s_waitcnt lgkmcnt(0)
	v_lshlrev_b32_e32 v86, 16, v1
	ds_read_u16 v1, v79 offset:13312
	v_fmac_f32_e32 v98, v8, v94
	v_fmac_f32_e32 v97, v6, v94
	v_fmac_f32_e32 v96, v5, v94
	v_fmac_f32_e32 v95, v3, v94
	s_waitcnt lgkmcnt(0)
	v_lshlrev_b32_e32 v85, 16, v1
	ds_read_u16 v1, v79 offset:14336
	v_fma_f32 v94, v2, v94, v0
	v_fmac_f32_e32 v98, v7, v93
	v_fmac_f32_e32 v97, v8, v93
	v_fmac_f32_e32 v96, v6, v93
	s_waitcnt lgkmcnt(0)
	v_lshlrev_b32_e32 v84, 16, v1
	ds_read_u16 v1, v79 offset:15360
	v_fmac_f32_e32 v95, v5, v93
	v_fmac_f32_e32 v94, v3, v93
	v_fma_f32 v93, v2, v93, v0
	v_fmac_f32_e32 v98, v10, v92
	s_waitcnt lgkmcnt(0)
	v_lshlrev_b32_e32 v83, 16, v1
	ds_read_u16 v1, v79 offset:16384
	v_fmac_f32_e32 v97, v7, v92
	v_fmac_f32_e32 v96, v8, v92
	v_fmac_f32_e32 v95, v6, v92
	v_fmac_f32_e32 v94, v5, v92
	s_waitcnt lgkmcnt(0)
	v_lshlrev_b32_e32 v82, 16, v1
	ds_read_u16 v1, v79 offset:17408
	v_fmac_f32_e32 v93, v3, v92
	v_fma_f32 v92, v2, v92, v0
	v_fmac_f32_e32 v98, v9, v91
	v_fmac_f32_e32 v97, v10, v91
	s_waitcnt lgkmcnt(0)
	v_lshlrev_b32_e32 v81, 16, v1
	ds_read_u16 v1, v79 offset:18432
	v_fmac_f32_e32 v96, v7, v91
	v_fmac_f32_e32 v95, v8, v91
	v_fmac_f32_e32 v94, v6, v91
	v_fmac_f32_e32 v93, v5, v91
	s_waitcnt lgkmcnt(0)
	v_lshlrev_b32_e32 v78, 16, v1
	ds_read_u16 v1, v79 offset:19456
	v_fmac_f32_e32 v92, v3, v91
	v_fma_f32 v91, v2, v91, v0
	v_fmac_f32_e32 v98, v14, v90
	v_fmac_f32_e32 v97, v9, v90
	s_waitcnt lgkmcnt(0)
	v_lshlrev_b32_e32 v77, 16, v1
	ds_read_u16 v1, v79 offset:20480
	v_fmac_f32_e32 v96, v10, v90
	v_fmac_f32_e32 v95, v7, v90
	v_fmac_f32_e32 v94, v8, v90
	v_fmac_f32_e32 v93, v6, v90
	s_waitcnt lgkmcnt(0)
	v_lshlrev_b32_e32 v76, 16, v1
	ds_read_u16 v1, v79 offset:21504
	v_fmac_f32_e32 v92, v5, v90
	v_fmac_f32_e32 v91, v3, v90
	v_fma_f32 v90, v2, v90, v0
	v_fmac_f32_e32 v98, v13, v89
	s_waitcnt lgkmcnt(0)
	v_lshlrev_b32_e32 v75, 16, v1
	ds_read_u16 v1, v79 offset:22528
	v_fmac_f32_e32 v97, v14, v89
	v_fmac_f32_e32 v96, v9, v89
	v_fmac_f32_e32 v95, v10, v89
	v_fmac_f32_e32 v94, v7, v89
	s_waitcnt lgkmcnt(0)
	v_lshlrev_b32_e32 v74, 16, v1
	ds_read_u16 v1, v79 offset:23552
	v_fmac_f32_e32 v93, v8, v89
	v_fmac_f32_e32 v92, v6, v89
	v_fmac_f32_e32 v91, v5, v89
	v_fmac_f32_e32 v90, v3, v89
	s_waitcnt lgkmcnt(0)
	v_lshlrev_b32_e32 v73, 16, v1
	ds_read_u16 v1, v79 offset:24576
	v_fma_f32 v89, v2, v89, v0
	v_fmac_f32_e32 v98, v12, v88
	v_fmac_f32_e32 v97, v13, v88
	v_fmac_f32_e32 v96, v14, v88
	s_waitcnt lgkmcnt(0)
	v_lshlrev_b32_e32 v68, 16, v1
	ds_read_u16 v1, v79 offset:25600
	v_fmac_f32_e32 v95, v9, v88
	v_fmac_f32_e32 v94, v10, v88
	v_fmac_f32_e32 v93, v7, v88
	v_fmac_f32_e32 v92, v8, v88
	s_waitcnt lgkmcnt(0)
	v_lshlrev_b32_e32 v66, 16, v1
	ds_read_u16 v1, v79 offset:26624
	v_fmac_f32_e32 v91, v6, v88
	v_fmac_f32_e32 v90, v5, v88
	v_fmac_f32_e32 v89, v3, v88
	v_fma_f32 v88, v2, v88, v0
	s_waitcnt lgkmcnt(0)
	v_lshlrev_b32_e32 v65, 16, v1
	ds_read_u16 v1, v79 offset:27648
	v_fmac_f32_e32 v98, v11, v87
	v_fmac_f32_e32 v97, v12, v87
	v_fmac_f32_e32 v96, v13, v87
	v_fmac_f32_e32 v95, v14, v87
	s_waitcnt lgkmcnt(0)
	v_lshlrev_b32_e32 v64, 16, v1
	ds_read_u16 v1, v79 offset:28672
	v_fmac_f32_e32 v94, v9, v87
	v_fmac_f32_e32 v93, v10, v87
	v_fmac_f32_e32 v92, v7, v87
	v_fmac_f32_e32 v91, v8, v87
	v_fmac_f32_e32 v90, v6, v87
	v_fmac_f32_e32 v89, v5, v87
	v_fmac_f32_e32 v88, v3, v87
	v_fma_f32 v87, v2, v87, v0
	v_fmac_f32_e32 v98, v21, v86
	v_fmac_f32_e32 v97, v11, v86
	v_fmac_f32_e32 v96, v12, v86
	v_fmac_f32_e32 v95, v13, v86
	v_fmac_f32_e32 v94, v14, v86
	v_fmac_f32_e32 v93, v9, v86
	v_fmac_f32_e32 v92, v10, v86
	v_fmac_f32_e32 v91, v7, v86
	v_fmac_f32_e32 v90, v8, v86
	v_fmac_f32_e32 v89, v6, v86
	v_fmac_f32_e32 v88, v5, v86
	v_fmac_f32_e32 v87, v3, v86
	v_fma_f32 v86, v2, v86, v0
	v_fmac_f32_e32 v98, v20, v85
	v_fmac_f32_e32 v97, v21, v85
	v_fmac_f32_e32 v96, v11, v85
	v_fmac_f32_e32 v95, v12, v85
	v_fmac_f32_e32 v94, v13, v85
	v_fmac_f32_e32 v93, v14, v85
	v_fmac_f32_e32 v92, v9, v85
	v_fmac_f32_e32 v91, v10, v85
	v_fmac_f32_e32 v90, v7, v85
	v_fmac_f32_e32 v89, v8, v85
	v_fmac_f32_e32 v88, v6, v85
	v_fmac_f32_e32 v87, v5, v85
	v_fmac_f32_e32 v86, v3, v85
	v_fma_f32 v85, v2, v85, v0
	s_waitcnt lgkmcnt(0)
	v_lshlrev_b32_e32 v63, 16, v1
	ds_read_u16 v1, v79 offset:29696
	v_fmac_f32_e32 v98, v16, v84
	v_fmac_f32_e32 v97, v20, v84
	v_fmac_f32_e32 v96, v21, v84
	v_fmac_f32_e32 v95, v11, v84
	v_fmac_f32_e32 v94, v12, v84
	v_fmac_f32_e32 v93, v13, v84
	v_fmac_f32_e32 v92, v14, v84
	v_fmac_f32_e32 v91, v9, v84
	v_fmac_f32_e32 v90, v10, v84
	v_fmac_f32_e32 v89, v7, v84
	v_fmac_f32_e32 v88, v8, v84
	v_fmac_f32_e32 v87, v6, v84
	v_fmac_f32_e32 v86, v5, v84
	v_fmac_f32_e32 v85, v3, v84
	v_fma_f32 v84, v2, v84, v0
	v_fmac_f32_e32 v98, v15, v83
	v_fmac_f32_e32 v97, v16, v83
	v_fmac_f32_e32 v96, v20, v83
	v_fmac_f32_e32 v95, v21, v83
	v_fmac_f32_e32 v94, v11, v83
	v_fmac_f32_e32 v93, v12, v83
	v_fmac_f32_e32 v92, v13, v83
	v_fmac_f32_e32 v91, v14, v83
	v_fmac_f32_e32 v90, v9, v83
	v_fmac_f32_e32 v89, v10, v83
	v_fmac_f32_e32 v88, v7, v83
	v_fmac_f32_e32 v87, v8, v83
	v_fmac_f32_e32 v86, v6, v83
	v_fmac_f32_e32 v85, v5, v83
	v_fmac_f32_e32 v84, v3, v83
	v_fma_f32 v83, v2, v83, v0
	v_fmac_f32_e32 v98, v23, v82
	v_fmac_f32_e32 v97, v15, v82
	v_fmac_f32_e32 v96, v16, v82
	v_fmac_f32_e32 v95, v20, v82
	v_fmac_f32_e32 v94, v21, v82
	v_fmac_f32_e32 v93, v11, v82
	v_fmac_f32_e32 v92, v12, v82
	v_fmac_f32_e32 v91, v13, v82
	v_fmac_f32_e32 v90, v14, v82
	v_fmac_f32_e32 v89, v9, v82
	v_fmac_f32_e32 v88, v10, v82
	v_fmac_f32_e32 v87, v7, v82
	v_fmac_f32_e32 v86, v8, v82
	v_fmac_f32_e32 v85, v6, v82
	v_fmac_f32_e32 v84, v5, v82
	v_fmac_f32_e32 v83, v3, v82
	v_fma_f32 v82, v2, v82, v0
	v_fmac_f32_e32 v98, v22, v81
	v_fmac_f32_e32 v97, v23, v81
	v_fmac_f32_e32 v96, v15, v81
	v_fmac_f32_e32 v95, v16, v81
	v_fmac_f32_e32 v94, v20, v81
	v_fmac_f32_e32 v93, v21, v81
	v_fmac_f32_e32 v92, v11, v81
	v_fmac_f32_e32 v91, v12, v81
	v_fmac_f32_e32 v90, v13, v81
	v_fmac_f32_e32 v89, v14, v81
	v_fmac_f32_e32 v88, v9, v81
	v_fmac_f32_e32 v87, v10, v81
	v_fmac_f32_e32 v86, v7, v81
	v_fmac_f32_e32 v85, v8, v81
	v_fmac_f32_e32 v84, v6, v81
	v_fmac_f32_e32 v83, v5, v81
	v_fmac_f32_e32 v82, v3, v81
	v_fma_f32 v81, v2, v81, v0
	v_fmac_f32_e32 v98, v25, v78
	v_fmac_f32_e32 v97, v22, v78
	v_fmac_f32_e32 v96, v23, v78
	v_fmac_f32_e32 v95, v15, v78
	v_fmac_f32_e32 v94, v16, v78
	v_fmac_f32_e32 v93, v20, v78
	v_fmac_f32_e32 v92, v21, v78
	v_fmac_f32_e32 v91, v11, v78
	v_fmac_f32_e32 v90, v12, v78
	v_fmac_f32_e32 v89, v13, v78
	v_fmac_f32_e32 v88, v14, v78
	v_fmac_f32_e32 v87, v9, v78
	v_fmac_f32_e32 v86, v10, v78
	v_fmac_f32_e32 v85, v7, v78
	v_fmac_f32_e32 v84, v8, v78
	v_fmac_f32_e32 v83, v6, v78
	v_fmac_f32_e32 v82, v5, v78
	v_fmac_f32_e32 v81, v3, v78
	v_fma_f32 v78, v2, v78, v0
	s_waitcnt lgkmcnt(0)
	v_lshlrev_b32_e32 v62, 16, v1
	ds_read_u16 v1, v79 offset:30720
	v_fmac_f32_e32 v98, v24, v77
	v_fmac_f32_e32 v97, v25, v77
	v_fmac_f32_e32 v96, v22, v77
	v_fmac_f32_e32 v95, v23, v77
	v_fmac_f32_e32 v94, v15, v77
	v_fmac_f32_e32 v93, v16, v77
	v_fmac_f32_e32 v92, v20, v77
	v_fmac_f32_e32 v91, v21, v77
	v_fmac_f32_e32 v90, v11, v77
	v_fmac_f32_e32 v89, v12, v77
	v_fmac_f32_e32 v88, v13, v77
	v_fmac_f32_e32 v87, v14, v77
	v_fmac_f32_e32 v86, v9, v77
	v_fmac_f32_e32 v85, v10, v77
	v_fmac_f32_e32 v84, v7, v77
	v_fmac_f32_e32 v83, v8, v77
	v_fmac_f32_e32 v82, v6, v77
	v_fmac_f32_e32 v81, v5, v77
	v_fmac_f32_e32 v78, v3, v77
	v_fma_f32 v77, v2, v77, v0
	v_fmac_f32_e32 v98, v29, v76
	v_fmac_f32_e32 v97, v24, v76
	v_fmac_f32_e32 v96, v25, v76
	v_fmac_f32_e32 v95, v22, v76
	v_fmac_f32_e32 v94, v23, v76
	v_fmac_f32_e32 v93, v15, v76
	v_fmac_f32_e32 v92, v16, v76
	v_fmac_f32_e32 v91, v20, v76
	v_fmac_f32_e32 v90, v21, v76
	v_fmac_f32_e32 v89, v11, v76
	v_fmac_f32_e32 v88, v12, v76
	v_fmac_f32_e32 v87, v13, v76
	v_fmac_f32_e32 v86, v14, v76
	v_fmac_f32_e32 v85, v9, v76
	v_fmac_f32_e32 v84, v10, v76
	v_fmac_f32_e32 v83, v7, v76
	v_fmac_f32_e32 v82, v8, v76
	v_fmac_f32_e32 v81, v6, v76
	v_fmac_f32_e32 v78, v5, v76
	v_fmac_f32_e32 v77, v3, v76
	v_fma_f32 v76, v2, v76, v0
	v_fmac_f32_e32 v98, v28, v75
	v_fmac_f32_e32 v97, v29, v75
	v_fmac_f32_e32 v96, v24, v75
	v_fmac_f32_e32 v95, v25, v75
	v_fmac_f32_e32 v94, v22, v75
	v_fmac_f32_e32 v93, v23, v75
	v_fmac_f32_e32 v92, v15, v75
	v_fmac_f32_e32 v91, v16, v75
	v_fmac_f32_e32 v90, v20, v75
	v_fmac_f32_e32 v89, v21, v75
	v_fmac_f32_e32 v88, v11, v75
	v_fmac_f32_e32 v87, v12, v75
	v_fmac_f32_e32 v86, v13, v75
	v_fmac_f32_e32 v85, v14, v75
	v_fmac_f32_e32 v84, v9, v75
	v_fmac_f32_e32 v83, v10, v75
	v_fmac_f32_e32 v82, v7, v75
	v_fmac_f32_e32 v81, v8, v75
	v_fmac_f32_e32 v78, v6, v75
	v_fmac_f32_e32 v77, v5, v75
	v_fmac_f32_e32 v76, v3, v75
	v_fma_f32 v75, v2, v75, v0
	v_fmac_f32_e32 v98, v27, v74
	v_fmac_f32_e32 v97, v28, v74
	v_fmac_f32_e32 v96, v29, v74
	v_fmac_f32_e32 v95, v24, v74
	v_fmac_f32_e32 v94, v25, v74
	v_fmac_f32_e32 v93, v22, v74
	v_fmac_f32_e32 v92, v23, v74
	v_fmac_f32_e32 v91, v15, v74
	v_fmac_f32_e32 v90, v16, v74
	v_fmac_f32_e32 v89, v20, v74
	v_fmac_f32_e32 v88, v21, v74
	v_fmac_f32_e32 v87, v11, v74
	v_fmac_f32_e32 v86, v12, v74
	v_fmac_f32_e32 v85, v13, v74
	v_fmac_f32_e32 v84, v14, v74
	v_fmac_f32_e32 v83, v9, v74
	v_fmac_f32_e32 v82, v10, v74
	v_fmac_f32_e32 v81, v7, v74
	v_fmac_f32_e32 v78, v8, v74
	v_fmac_f32_e32 v77, v6, v74
	v_fmac_f32_e32 v76, v5, v74
	v_fmac_f32_e32 v75, v3, v74
	v_fma_f32 v74, v2, v74, v0
	v_fmac_f32_e32 v98, v26, v73
	v_fmac_f32_e32 v97, v27, v73
	v_fmac_f32_e32 v96, v28, v73
	v_fmac_f32_e32 v95, v29, v73
	v_fmac_f32_e32 v94, v24, v73
	v_fmac_f32_e32 v93, v25, v73
	v_fmac_f32_e32 v92, v22, v73
	v_fmac_f32_e32 v91, v23, v73
	v_fmac_f32_e32 v90, v15, v73
	v_fmac_f32_e32 v89, v16, v73
	v_fmac_f32_e32 v88, v20, v73
	v_fmac_f32_e32 v87, v21, v73
	v_fmac_f32_e32 v86, v11, v73
	v_fmac_f32_e32 v85, v12, v73
	v_fmac_f32_e32 v84, v13, v73
	v_fmac_f32_e32 v83, v14, v73
	v_fmac_f32_e32 v82, v9, v73
	v_fmac_f32_e32 v81, v10, v73
	v_fmac_f32_e32 v78, v7, v73
	v_fmac_f32_e32 v77, v8, v73
	v_fmac_f32_e32 v76, v6, v73
	v_fmac_f32_e32 v75, v5, v73
	v_fmac_f32_e32 v74, v3, v73
	v_fma_f32 v73, v2, v73, v0
	s_waitcnt lgkmcnt(0)
	v_lshlrev_b32_e32 v61, 16, v1
	ds_read_u16 v1, v79 offset:31744
	v_fmac_f32_e32 v98, v33, v68
	v_fmac_f32_e32 v97, v26, v68
	v_fmac_f32_e32 v96, v27, v68
	v_fmac_f32_e32 v95, v28, v68
	v_fmac_f32_e32 v94, v29, v68
	v_fmac_f32_e32 v93, v24, v68
	v_fmac_f32_e32 v92, v25, v68
	v_fmac_f32_e32 v91, v22, v68
	v_fmac_f32_e32 v90, v23, v68
	v_fmac_f32_e32 v89, v15, v68
	v_fmac_f32_e32 v88, v16, v68
	v_fmac_f32_e32 v87, v20, v68
	v_fmac_f32_e32 v86, v21, v68
	v_fmac_f32_e32 v85, v11, v68
	v_fmac_f32_e32 v84, v12, v68
	v_fmac_f32_e32 v83, v13, v68
	v_fmac_f32_e32 v82, v14, v68
	v_fmac_f32_e32 v81, v9, v68
	v_fmac_f32_e32 v78, v10, v68
	v_fmac_f32_e32 v77, v7, v68
	v_fmac_f32_e32 v76, v8, v68
	v_fmac_f32_e32 v75, v6, v68
	v_fmac_f32_e32 v74, v5, v68
	v_fmac_f32_e32 v73, v3, v68
	v_fma_f32 v68, v2, v68, v0
	v_fmac_f32_e32 v98, v32, v66
	v_fmac_f32_e32 v97, v33, v66
	v_fmac_f32_e32 v96, v26, v66
	v_fmac_f32_e32 v95, v27, v66
	v_fmac_f32_e32 v94, v28, v66
	v_fmac_f32_e32 v93, v29, v66
	v_fmac_f32_e32 v92, v24, v66
	v_fmac_f32_e32 v91, v25, v66
	v_fmac_f32_e32 v90, v22, v66
	v_fmac_f32_e32 v89, v23, v66
	v_fmac_f32_e32 v88, v15, v66
	v_fmac_f32_e32 v87, v16, v66
	v_fmac_f32_e32 v86, v20, v66
	v_fmac_f32_e32 v85, v21, v66
	v_fmac_f32_e32 v84, v11, v66
	v_fmac_f32_e32 v83, v12, v66
	v_fmac_f32_e32 v82, v13, v66
	v_fmac_f32_e32 v81, v14, v66
	v_fmac_f32_e32 v78, v9, v66
	v_fmac_f32_e32 v77, v10, v66
	v_fmac_f32_e32 v76, v7, v66
	v_fmac_f32_e32 v75, v8, v66
	v_fmac_f32_e32 v74, v6, v66
	v_fmac_f32_e32 v73, v5, v66
	v_fmac_f32_e32 v68, v3, v66
	v_fma_f32 v66, v2, v66, v0
	v_fmac_f32_e32 v98, v31, v65
	v_fmac_f32_e32 v97, v32, v65
	v_fmac_f32_e32 v96, v33, v65
	v_fmac_f32_e32 v95, v26, v65
	v_fmac_f32_e32 v94, v27, v65
	v_fmac_f32_e32 v93, v28, v65
	v_fmac_f32_e32 v92, v29, v65
	v_fmac_f32_e32 v91, v24, v65
	v_fmac_f32_e32 v90, v25, v65
	v_fmac_f32_e32 v89, v22, v65
	v_fmac_f32_e32 v88, v23, v65
	v_fmac_f32_e32 v87, v15, v65
	v_fmac_f32_e32 v86, v16, v65
	v_fmac_f32_e32 v85, v20, v65
	v_fmac_f32_e32 v84, v21, v65
	v_fmac_f32_e32 v83, v11, v65
	v_fmac_f32_e32 v82, v12, v65
	v_fmac_f32_e32 v81, v13, v65
	v_fmac_f32_e32 v78, v14, v65
	v_fmac_f32_e32 v77, v9, v65
	v_fmac_f32_e32 v76, v10, v65
	v_fmac_f32_e32 v75, v7, v65
	v_fmac_f32_e32 v74, v8, v65
	v_fmac_f32_e32 v73, v6, v65
	v_fmac_f32_e32 v68, v5, v65
	v_fmac_f32_e32 v66, v3, v65
	v_fma_f32 v65, v2, v65, v0
	v_fmac_f32_e32 v98, v30, v64
	v_fmac_f32_e32 v97, v31, v64
	v_fmac_f32_e32 v96, v32, v64
	v_fmac_f32_e32 v95, v33, v64
	v_fmac_f32_e32 v94, v26, v64
	v_fmac_f32_e32 v93, v27, v64
	v_fmac_f32_e32 v92, v28, v64
	v_fmac_f32_e32 v91, v29, v64
	v_fmac_f32_e32 v90, v24, v64
	v_fmac_f32_e32 v89, v25, v64
	v_fmac_f32_e32 v88, v22, v64
	v_fmac_f32_e32 v87, v23, v64
	v_fmac_f32_e32 v86, v15, v64
	v_fmac_f32_e32 v85, v16, v64
	v_fmac_f32_e32 v84, v20, v64
	v_fmac_f32_e32 v83, v21, v64
	v_fmac_f32_e32 v82, v11, v64
	v_fmac_f32_e32 v81, v12, v64
	v_fmac_f32_e32 v78, v13, v64
	v_fmac_f32_e32 v77, v14, v64
	v_fmac_f32_e32 v76, v9, v64
	v_fmac_f32_e32 v75, v10, v64
	v_fmac_f32_e32 v74, v7, v64
	v_fmac_f32_e32 v73, v8, v64
	v_fmac_f32_e32 v68, v6, v64
	v_fmac_f32_e32 v66, v5, v64
	v_fmac_f32_e32 v65, v3, v64
	v_fma_f32 v64, v2, v64, v0
	v_fmac_f32_e32 v98, v34, v63
	v_fmac_f32_e32 v97, v30, v63
	v_fmac_f32_e32 v96, v31, v63
	v_fmac_f32_e32 v95, v32, v63
	v_fmac_f32_e32 v94, v33, v63
	v_fmac_f32_e32 v93, v26, v63
	v_fmac_f32_e32 v92, v27, v63
	v_fmac_f32_e32 v91, v28, v63
	v_fmac_f32_e32 v90, v29, v63
	v_fmac_f32_e32 v89, v24, v63
	v_fmac_f32_e32 v88, v25, v63
	v_fmac_f32_e32 v87, v22, v63
	v_fmac_f32_e32 v86, v23, v63
	v_fmac_f32_e32 v85, v15, v63
	v_fmac_f32_e32 v84, v16, v63
	v_fmac_f32_e32 v83, v20, v63
	v_fmac_f32_e32 v82, v21, v63
	v_fmac_f32_e32 v81, v11, v63
	v_fmac_f32_e32 v78, v12, v63
	v_fmac_f32_e32 v77, v13, v63
	v_fmac_f32_e32 v76, v14, v63
	v_fmac_f32_e32 v75, v9, v63
	v_fmac_f32_e32 v74, v10, v63
	v_fmac_f32_e32 v73, v7, v63
	v_fmac_f32_e32 v68, v8, v63
	v_fmac_f32_e32 v66, v6, v63
	v_fmac_f32_e32 v65, v5, v63
	v_fmac_f32_e32 v64, v3, v63
	v_fma_f32 v63, v2, v63, v0
	s_waitcnt lgkmcnt(0)
	v_lshlrev_b32_e32 v1, 16, v1
	v_fmac_f32_e32 v98, v36, v62
	v_fmac_f32_e32 v97, v34, v62
	v_fmac_f32_e32 v96, v30, v62
	v_fmac_f32_e32 v95, v31, v62
	v_fmac_f32_e32 v94, v32, v62
	v_fmac_f32_e32 v93, v33, v62
	v_fmac_f32_e32 v92, v26, v62
	v_fmac_f32_e32 v91, v27, v62
	v_fmac_f32_e32 v90, v28, v62
	v_fmac_f32_e32 v89, v29, v62
	v_fmac_f32_e32 v88, v24, v62
	v_fmac_f32_e32 v87, v25, v62
	v_fmac_f32_e32 v86, v22, v62
	v_fmac_f32_e32 v85, v23, v62
	v_fmac_f32_e32 v84, v15, v62
	v_fmac_f32_e32 v83, v16, v62
	v_fmac_f32_e32 v82, v20, v62
	v_fmac_f32_e32 v81, v21, v62
	v_fmac_f32_e32 v78, v11, v62
	v_fmac_f32_e32 v77, v12, v62
	v_fmac_f32_e32 v76, v13, v62
	v_fmac_f32_e32 v75, v14, v62
	v_fmac_f32_e32 v74, v9, v62
	v_fmac_f32_e32 v73, v10, v62
	v_fmac_f32_e32 v68, v7, v62
	v_fmac_f32_e32 v66, v8, v62
	v_fmac_f32_e32 v65, v6, v62
	v_fmac_f32_e32 v64, v5, v62
	v_fmac_f32_e32 v63, v3, v62
	v_fma_f32 v62, v2, v62, v0
	v_fmac_f32_e32 v98, v35, v61
	v_fmac_f32_e32 v97, v36, v61
	v_fmac_f32_e32 v96, v34, v61
	v_fmac_f32_e32 v95, v30, v61
	v_fmac_f32_e32 v94, v31, v61
	v_fmac_f32_e32 v93, v32, v61
	v_fmac_f32_e32 v92, v33, v61
	v_fmac_f32_e32 v91, v26, v61
	v_fmac_f32_e32 v90, v27, v61
	v_fmac_f32_e32 v89, v28, v61
	v_fmac_f32_e32 v88, v29, v61
	v_fmac_f32_e32 v87, v24, v61
	v_fmac_f32_e32 v86, v25, v61
	v_fmac_f32_e32 v85, v22, v61
	v_fmac_f32_e32 v84, v23, v61
	v_fmac_f32_e32 v83, v15, v61
	v_fmac_f32_e32 v82, v16, v61
	v_fmac_f32_e32 v81, v20, v61
	v_fmac_f32_e32 v78, v21, v61
	v_fmac_f32_e32 v77, v11, v61
	v_fmac_f32_e32 v76, v12, v61
	v_fmac_f32_e32 v75, v13, v61
	v_fmac_f32_e32 v74, v14, v61
	v_fmac_f32_e32 v73, v9, v61
	v_fmac_f32_e32 v68, v10, v61
	v_fmac_f32_e32 v66, v7, v61
	v_fmac_f32_e32 v65, v8, v61
	v_fmac_f32_e32 v64, v6, v61
	v_fmac_f32_e32 v63, v5, v61
	v_fmac_f32_e32 v62, v3, v61
	v_fma_f32 v61, v2, v61, v0
	v_fmac_f32_e32 v0, v2, v1
	v_fmac_f32_e32 v61, v3, v1
	v_fmac_f32_e32 v0, v3, v37
	v_fmac_f32_e32 v61, v5, v37
	v_fmac_f32_e32 v0, v5, v38
	v_fmac_f32_e32 v61, v6, v38
	v_fmac_f32_e32 v0, v6, v39
	v_fmac_f32_e32 v61, v8, v39
	v_fmac_f32_e32 v0, v8, v40
	v_fmac_f32_e32 v61, v7, v40
	v_fmac_f32_e32 v0, v7, v41
	v_fmac_f32_e32 v61, v10, v41
	v_fmac_f32_e32 v0, v10, v42
	v_fmac_f32_e32 v61, v9, v42
	v_fmac_f32_e32 v0, v9, v43
	v_fmac_f32_e32 v61, v14, v43
	v_fmac_f32_e32 v0, v14, v44
	v_fmac_f32_e32 v61, v13, v44
	v_fmac_f32_e32 v0, v13, v45
	v_fmac_f32_e32 v61, v12, v45
	v_fmac_f32_e32 v0, v12, v46
	v_fmac_f32_e32 v61, v11, v46
	v_fmac_f32_e32 v0, v11, v47
	v_fmac_f32_e32 v61, v21, v47
	v_fmac_f32_e32 v0, v21, v48
	v_fmac_f32_e32 v62, v5, v1
	v_fmac_f32_e32 v61, v20, v48
	v_fmac_f32_e32 v0, v20, v49
	v_fmac_f32_e32 v63, v6, v1
	v_fmac_f32_e32 v62, v6, v37
	v_fmac_f32_e32 v61, v16, v49
	v_fmac_f32_e32 v0, v16, v50
	v_fmac_f32_e32 v64, v8, v1
	v_fmac_f32_e32 v63, v8, v37
	v_fmac_f32_e32 v62, v8, v38
	v_fmac_f32_e32 v61, v15, v50
	v_fmac_f32_e32 v0, v15, v51
	v_fmac_f32_e32 v65, v7, v1
	v_fmac_f32_e32 v64, v7, v37
	v_fmac_f32_e32 v63, v7, v38
	v_fmac_f32_e32 v62, v7, v39
	v_fmac_f32_e32 v61, v23, v51
	v_fmac_f32_e32 v0, v23, v52
	v_fmac_f32_e32 v66, v10, v1
	v_fmac_f32_e32 v65, v10, v37
	v_fmac_f32_e32 v64, v10, v38
	v_fmac_f32_e32 v63, v10, v39
	v_fmac_f32_e32 v62, v10, v40
	v_fmac_f32_e32 v61, v22, v52
	v_fmac_f32_e32 v0, v22, v53
	v_fmac_f32_e32 v68, v9, v1
	v_fmac_f32_e32 v66, v9, v37
	v_fmac_f32_e32 v65, v9, v38
	v_fmac_f32_e32 v64, v9, v39
	v_fmac_f32_e32 v63, v9, v40
	v_fmac_f32_e32 v62, v9, v41
	v_fmac_f32_e32 v61, v25, v53
	v_fmac_f32_e32 v0, v25, v54
	v_fmac_f32_e32 v73, v14, v1
	v_fmac_f32_e32 v68, v14, v37
	v_fmac_f32_e32 v66, v14, v38
	v_fmac_f32_e32 v65, v14, v39
	v_fmac_f32_e32 v64, v14, v40
	v_fmac_f32_e32 v63, v14, v41
	v_fmac_f32_e32 v62, v14, v42
	v_fmac_f32_e32 v61, v24, v54
	v_fmac_f32_e32 v0, v24, v55
	v_fmac_f32_e32 v74, v13, v1
	v_fmac_f32_e32 v73, v13, v37
	v_fmac_f32_e32 v68, v13, v38
	v_fmac_f32_e32 v66, v13, v39
	v_fmac_f32_e32 v65, v13, v40
	v_fmac_f32_e32 v64, v13, v41
	v_fmac_f32_e32 v63, v13, v42
	v_fmac_f32_e32 v62, v13, v43
	v_fmac_f32_e32 v61, v29, v55
	v_fmac_f32_e32 v0, v29, v56
	v_fmac_f32_e32 v75, v12, v1
	v_fmac_f32_e32 v74, v12, v37
	v_fmac_f32_e32 v73, v12, v38
	v_fmac_f32_e32 v68, v12, v39
	v_fmac_f32_e32 v66, v12, v40
	v_fmac_f32_e32 v65, v12, v41
	v_fmac_f32_e32 v64, v12, v42
	v_fmac_f32_e32 v63, v12, v43
	v_fmac_f32_e32 v62, v12, v44
	v_fmac_f32_e32 v61, v28, v56
	v_fmac_f32_e32 v0, v28, v57
	v_fmac_f32_e32 v76, v11, v1
	v_fmac_f32_e32 v75, v11, v37
	v_fmac_f32_e32 v74, v11, v38
	v_fmac_f32_e32 v73, v11, v39
	v_fmac_f32_e32 v68, v11, v40
	v_fmac_f32_e32 v66, v11, v41
	v_fmac_f32_e32 v65, v11, v42
	v_fmac_f32_e32 v64, v11, v43
	v_fmac_f32_e32 v63, v11, v44
	v_fmac_f32_e32 v62, v11, v45
	v_fmac_f32_e32 v61, v27, v57
	v_fmac_f32_e32 v0, v27, v58
	v_fmac_f32_e32 v77, v21, v1
	v_fmac_f32_e32 v76, v21, v37
	v_fmac_f32_e32 v75, v21, v38
	v_fmac_f32_e32 v74, v21, v39
	v_fmac_f32_e32 v73, v21, v40
	v_fmac_f32_e32 v68, v21, v41
	v_fmac_f32_e32 v66, v21, v42
	v_fmac_f32_e32 v65, v21, v43
	v_fmac_f32_e32 v64, v21, v44
	v_fmac_f32_e32 v63, v21, v45
	v_fmac_f32_e32 v62, v21, v46
	v_fmac_f32_e32 v61, v26, v58
	v_fmac_f32_e32 v0, v26, v59
	ds_read_u16 v79, v79 offset:62464
	v_fmac_f32_e32 v78, v20, v1
	v_fmac_f32_e32 v77, v20, v37
	v_fmac_f32_e32 v76, v20, v38
	v_fmac_f32_e32 v75, v20, v39
	v_fmac_f32_e32 v74, v20, v40
	v_fmac_f32_e32 v73, v20, v41
	v_fmac_f32_e32 v68, v20, v42
	v_fmac_f32_e32 v66, v20, v43
	v_fmac_f32_e32 v65, v20, v44
	v_fmac_f32_e32 v64, v20, v45
	v_fmac_f32_e32 v63, v20, v46
	v_fmac_f32_e32 v62, v20, v47
	v_fmac_f32_e32 v61, v33, v59
	v_fmac_f32_e32 v0, v33, v60
	v_fmac_f32_e32 v81, v16, v1
	v_fmac_f32_e32 v78, v16, v37
	v_fmac_f32_e32 v77, v16, v38
	v_fmac_f32_e32 v76, v16, v39
	v_fmac_f32_e32 v75, v16, v40
	v_fmac_f32_e32 v74, v16, v41
	v_fmac_f32_e32 v73, v16, v42
	v_fmac_f32_e32 v68, v16, v43
	v_fmac_f32_e32 v66, v16, v44
	v_fmac_f32_e32 v65, v16, v45
	v_fmac_f32_e32 v64, v16, v46
	v_fmac_f32_e32 v63, v16, v47
	v_fmac_f32_e32 v62, v16, v48
	v_fmac_f32_e32 v61, v32, v60
	v_fmac_f32_e32 v0, v32, v67
	v_lshlrev_b32_e32 v70, 16, v70
	v_fmac_f32_e32 v82, v15, v1
	v_fmac_f32_e32 v81, v15, v37
	v_fmac_f32_e32 v78, v15, v38
	v_fmac_f32_e32 v77, v15, v39
	v_fmac_f32_e32 v76, v15, v40
	v_fmac_f32_e32 v75, v15, v41
	v_fmac_f32_e32 v74, v15, v42
	v_fmac_f32_e32 v73, v15, v43
	v_fmac_f32_e32 v68, v15, v44
	v_fmac_f32_e32 v66, v15, v45
	v_fmac_f32_e32 v65, v15, v46
	v_fmac_f32_e32 v64, v15, v47
	v_fmac_f32_e32 v63, v15, v48
	v_fmac_f32_e32 v62, v15, v49
	v_fmac_f32_e32 v61, v31, v67
	v_fmac_f32_e32 v0, v31, v69
	v_lshlrev_b32_e32 v71, 16, v71
	v_fmac_f32_e32 v83, v23, v1
	v_fmac_f32_e32 v82, v23, v37
	v_fmac_f32_e32 v81, v23, v38
	v_fmac_f32_e32 v78, v23, v39
	v_fmac_f32_e32 v77, v23, v40
	v_fmac_f32_e32 v76, v23, v41
	v_fmac_f32_e32 v75, v23, v42
	v_fmac_f32_e32 v74, v23, v43
	v_fmac_f32_e32 v73, v23, v44
	v_fmac_f32_e32 v68, v23, v45
	v_fmac_f32_e32 v66, v23, v46
	v_fmac_f32_e32 v65, v23, v47
	v_fmac_f32_e32 v64, v23, v48
	v_fmac_f32_e32 v63, v23, v49
	v_fmac_f32_e32 v62, v23, v50
	v_fmac_f32_e32 v61, v30, v69
	v_fmac_f32_e32 v0, v30, v70
	v_lshlrev_b32_e32 v72, 16, v72
	v_fmac_f32_e32 v84, v22, v1
	v_fmac_f32_e32 v83, v22, v37
	v_fmac_f32_e32 v82, v22, v38
	v_fmac_f32_e32 v81, v22, v39
	v_fmac_f32_e32 v78, v22, v40
	v_fmac_f32_e32 v77, v22, v41
	v_fmac_f32_e32 v76, v22, v42
	v_fmac_f32_e32 v75, v22, v43
	v_fmac_f32_e32 v74, v22, v44
	v_fmac_f32_e32 v73, v22, v45
	v_fmac_f32_e32 v68, v22, v46
	v_fmac_f32_e32 v66, v22, v47
	v_fmac_f32_e32 v65, v22, v48
	v_fmac_f32_e32 v64, v22, v49
	v_fmac_f32_e32 v63, v22, v50
	v_fmac_f32_e32 v62, v22, v51
	v_fmac_f32_e32 v61, v34, v70
	v_fmac_f32_e32 v0, v34, v71
	s_waitcnt lgkmcnt(0)
	v_lshlrev_b32_e32 v79, 16, v79
	v_fmac_f32_e32 v85, v25, v1
	v_fmac_f32_e32 v84, v25, v37
	v_fmac_f32_e32 v83, v25, v38
	v_fmac_f32_e32 v82, v25, v39
	v_fmac_f32_e32 v81, v25, v40
	v_fmac_f32_e32 v78, v25, v41
	v_fmac_f32_e32 v77, v25, v42
	v_fmac_f32_e32 v76, v25, v43
	v_fmac_f32_e32 v75, v25, v44
	v_fmac_f32_e32 v74, v25, v45
	v_fmac_f32_e32 v73, v25, v46
	v_fmac_f32_e32 v68, v25, v47
	v_fmac_f32_e32 v66, v25, v48
	v_fmac_f32_e32 v65, v25, v49
	v_fmac_f32_e32 v64, v25, v50
	v_fmac_f32_e32 v63, v25, v51
	v_fmac_f32_e32 v62, v25, v52
	v_fmac_f32_e32 v61, v36, v71
	v_fmac_f32_e32 v0, v36, v72
	v_lshl_add_u32 v80, v4, 2, s0
	v_fmac_f32_e32 v86, v24, v1
	v_fmac_f32_e32 v85, v24, v37
	v_fmac_f32_e32 v84, v24, v38
	v_fmac_f32_e32 v83, v24, v39
	v_fmac_f32_e32 v82, v24, v40
	v_fmac_f32_e32 v81, v24, v41
	v_fmac_f32_e32 v78, v24, v42
	v_fmac_f32_e32 v77, v24, v43
	v_fmac_f32_e32 v76, v24, v44
	v_fmac_f32_e32 v75, v24, v45
	v_fmac_f32_e32 v74, v24, v46
	v_fmac_f32_e32 v73, v24, v47
	v_fmac_f32_e32 v68, v24, v48
	v_fmac_f32_e32 v66, v24, v49
	v_fmac_f32_e32 v65, v24, v50
	v_fmac_f32_e32 v64, v24, v51
	v_fmac_f32_e32 v63, v24, v52
	v_fmac_f32_e32 v62, v24, v53
	v_fmac_f32_e32 v61, v35, v72
	v_fmac_f32_e32 v0, v35, v79
	v_fmac_f32_e32 v87, v29, v1
	v_fmac_f32_e32 v86, v29, v37
	v_fmac_f32_e32 v85, v29, v38
	v_fmac_f32_e32 v84, v29, v39
	v_fmac_f32_e32 v83, v29, v40
	v_fmac_f32_e32 v82, v29, v41
	v_fmac_f32_e32 v81, v29, v42
	v_fmac_f32_e32 v78, v29, v43
	v_fmac_f32_e32 v77, v29, v44
	v_fmac_f32_e32 v76, v29, v45
	v_fmac_f32_e32 v75, v29, v46
	v_fmac_f32_e32 v74, v29, v47
	v_fmac_f32_e32 v73, v29, v48
	v_fmac_f32_e32 v68, v29, v49
	v_fmac_f32_e32 v66, v29, v50
	v_fmac_f32_e32 v65, v29, v51
	v_fmac_f32_e32 v64, v29, v52
	v_fmac_f32_e32 v63, v29, v53
	v_fmac_f32_e32 v62, v29, v54
	ds_write2st64_b32 v80, v61, v0 offset0:240 offset1:248
	v_lshlrev_b32_e32 v0, 3, v4
	v_fmac_f32_e32 v88, v28, v1
	v_fmac_f32_e32 v87, v28, v37
	v_fmac_f32_e32 v86, v28, v38
	v_fmac_f32_e32 v85, v28, v39
	v_fmac_f32_e32 v84, v28, v40
	v_fmac_f32_e32 v83, v28, v41
	v_fmac_f32_e32 v82, v28, v42
	v_fmac_f32_e32 v81, v28, v43
	v_fmac_f32_e32 v78, v28, v44
	v_fmac_f32_e32 v77, v28, v45
	v_fmac_f32_e32 v76, v28, v46
	v_fmac_f32_e32 v75, v28, v47
	v_fmac_f32_e32 v74, v28, v48
	v_fmac_f32_e32 v73, v28, v49
	v_fmac_f32_e32 v68, v28, v50
	v_fmac_f32_e32 v66, v28, v51
	v_fmac_f32_e32 v65, v28, v52
	v_fmac_f32_e32 v64, v28, v53
	v_fmac_f32_e32 v63, v28, v54
	v_fmac_f32_e32 v62, v28, v55
	v_and_b32_e32 v28, 0x1f8, v0
	v_and_b32_e32 v0, 64, v223
	v_fmac_f32_e32 v97, v35, v1
	v_fmac_f32_e32 v96, v36, v1
	v_fmac_f32_e32 v95, v34, v1
	v_fmac_f32_e32 v94, v30, v1
	v_fmac_f32_e32 v93, v31, v1
	v_fmac_f32_e32 v92, v32, v1
	v_fmac_f32_e32 v91, v33, v1
	v_fmac_f32_e32 v90, v26, v1
	v_fmac_f32_e32 v89, v27, v1
	v_add_u32_e32 v0, 64, v0
	v_xor_b32_e32 v1, 1, v223
	v_cmp_lt_i32_e32 vcc, v1, v0
	v_fmac_f32_e32 v88, v27, v37
	v_fmac_f32_e32 v87, v27, v38
	v_cndmask_b32_e32 v1, v223, v1, vcc
	v_lshlrev_b32_e32 v21, 2, v1
	v_xor_b32_e32 v1, 2, v223
	v_cmp_lt_i32_e32 vcc, v1, v0
	v_fmac_f32_e32 v86, v27, v39
	v_fmac_f32_e32 v85, v27, v40
	v_cndmask_b32_e32 v1, v223, v1, vcc
	v_lshlrev_b32_e32 v22, 2, v1
	v_xor_b32_e32 v1, 4, v223
	v_cmp_lt_i32_e32 vcc, v1, v0
	v_fmac_f32_e32 v84, v27, v41
	v_fmac_f32_e32 v83, v27, v42
	v_cndmask_b32_e32 v1, v223, v1, vcc
	v_lshlrev_b32_e32 v23, 2, v1
	v_xor_b32_e32 v1, 8, v223
	v_fmac_f32_e32 v82, v27, v43
	v_fmac_f32_e32 v81, v27, v44
	v_fmac_f32_e32 v78, v27, v45
	v_fmac_f32_e32 v77, v27, v46
	v_fmac_f32_e32 v76, v27, v47
	v_fmac_f32_e32 v75, v27, v48
	v_fmac_f32_e32 v74, v27, v49
	v_fmac_f32_e32 v73, v27, v50
	v_fmac_f32_e32 v68, v27, v51
	v_fmac_f32_e32 v66, v27, v52
	v_fmac_f32_e32 v65, v27, v53
	v_fmac_f32_e32 v64, v27, v54
	v_fmac_f32_e32 v63, v27, v55
	v_fmac_f32_e32 v62, v27, v56
	v_cmp_lt_i32_e32 vcc, v1, v0
	v_fmac_f32_e32 v89, v26, v37
	v_fmac_f32_e32 v88, v26, v38
	v_fmac_f32_e32 v87, v26, v39
	v_fmac_f32_e32 v86, v26, v40
	v_fmac_f32_e32 v85, v26, v41
	v_fmac_f32_e32 v84, v26, v42
	v_fmac_f32_e32 v83, v26, v43
	v_fmac_f32_e32 v82, v26, v44
	v_fmac_f32_e32 v81, v26, v45
	v_fmac_f32_e32 v78, v26, v46
	v_fmac_f32_e32 v77, v26, v47
	v_fmac_f32_e32 v76, v26, v48
	v_fmac_f32_e32 v75, v26, v49
	v_fmac_f32_e32 v74, v26, v50
	v_fmac_f32_e32 v73, v26, v51
	v_fmac_f32_e32 v68, v26, v52
	v_fmac_f32_e32 v66, v26, v53
	v_fmac_f32_e32 v65, v26, v54
	v_fmac_f32_e32 v64, v26, v55
	v_fmac_f32_e32 v63, v26, v56
	v_fmac_f32_e32 v62, v26, v57
	v_cndmask_b32_e32 v1, v223, v1, vcc
	v_fmac_f32_e32 v90, v33, v37
	v_fmac_f32_e32 v89, v33, v38
	v_fmac_f32_e32 v88, v33, v39
	v_fmac_f32_e32 v87, v33, v40
	v_fmac_f32_e32 v86, v33, v41
	v_fmac_f32_e32 v85, v33, v42
	v_fmac_f32_e32 v84, v33, v43
	v_fmac_f32_e32 v83, v33, v44
	v_fmac_f32_e32 v82, v33, v45
	v_fmac_f32_e32 v81, v33, v46
	v_fmac_f32_e32 v78, v33, v47
	v_fmac_f32_e32 v77, v33, v48
	v_fmac_f32_e32 v76, v33, v49
	v_fmac_f32_e32 v75, v33, v50
	v_fmac_f32_e32 v74, v33, v51
	v_fmac_f32_e32 v73, v33, v52
	v_fmac_f32_e32 v68, v33, v53
	v_fmac_f32_e32 v66, v33, v54
	v_fmac_f32_e32 v65, v33, v55
	v_fmac_f32_e32 v64, v33, v56
	v_fmac_f32_e32 v63, v33, v57
	v_fmac_f32_e32 v62, v33, v58
	v_lshlrev_b32_e32 v24, 2, v1
	v_xor_b32_e32 v1, 16, v223
	v_fmac_f32_e32 v91, v32, v37
	v_fmac_f32_e32 v90, v32, v38
	v_fmac_f32_e32 v89, v32, v39
	v_fmac_f32_e32 v88, v32, v40
	v_fmac_f32_e32 v87, v32, v41
	v_fmac_f32_e32 v86, v32, v42
	v_fmac_f32_e32 v85, v32, v43
	v_fmac_f32_e32 v84, v32, v44
	v_fmac_f32_e32 v83, v32, v45
	v_fmac_f32_e32 v82, v32, v46
	v_fmac_f32_e32 v81, v32, v47
	v_fmac_f32_e32 v78, v32, v48
	v_fmac_f32_e32 v77, v32, v49
	v_fmac_f32_e32 v76, v32, v50
	v_fmac_f32_e32 v75, v32, v51
	v_fmac_f32_e32 v74, v32, v52
	v_fmac_f32_e32 v73, v32, v53
	v_fmac_f32_e32 v68, v32, v54
	v_fmac_f32_e32 v66, v32, v55
	v_fmac_f32_e32 v65, v32, v56
	v_fmac_f32_e32 v64, v32, v57
	v_fmac_f32_e32 v63, v32, v58
	v_fmac_f32_e32 v62, v32, v59
	v_cmp_lt_i32_e32 vcc, v1, v0
	v_fmac_f32_e32 v92, v31, v37
	v_fmac_f32_e32 v91, v31, v38
	v_fmac_f32_e32 v90, v31, v39
	v_fmac_f32_e32 v89, v31, v40
	v_fmac_f32_e32 v88, v31, v41
	v_fmac_f32_e32 v87, v31, v42
	v_fmac_f32_e32 v86, v31, v43
	v_fmac_f32_e32 v85, v31, v44
	v_fmac_f32_e32 v84, v31, v45
	v_fmac_f32_e32 v83, v31, v46
	v_fmac_f32_e32 v82, v31, v47
	v_fmac_f32_e32 v81, v31, v48
	v_fmac_f32_e32 v78, v31, v49
	v_fmac_f32_e32 v77, v31, v50
	v_fmac_f32_e32 v76, v31, v51
	v_fmac_f32_e32 v75, v31, v52
	v_fmac_f32_e32 v74, v31, v53
	v_fmac_f32_e32 v73, v31, v54
	v_fmac_f32_e32 v68, v31, v55
	v_fmac_f32_e32 v66, v31, v56
	v_fmac_f32_e32 v65, v31, v57
	v_fmac_f32_e32 v64, v31, v58
	v_fmac_f32_e32 v63, v31, v59
	v_fmac_f32_e32 v62, v31, v60
	v_cndmask_b32_e32 v1, v223, v1, vcc
	v_fmac_f32_e32 v93, v30, v37
	v_fmac_f32_e32 v92, v30, v38
	v_fmac_f32_e32 v91, v30, v39
	v_fmac_f32_e32 v90, v30, v40
	v_fmac_f32_e32 v89, v30, v41
	v_fmac_f32_e32 v88, v30, v42
	v_fmac_f32_e32 v87, v30, v43
	v_fmac_f32_e32 v86, v30, v44
	v_fmac_f32_e32 v85, v30, v45
	v_fmac_f32_e32 v84, v30, v46
	v_fmac_f32_e32 v83, v30, v47
	v_fmac_f32_e32 v82, v30, v48
	v_fmac_f32_e32 v81, v30, v49
	v_fmac_f32_e32 v78, v30, v50
	v_fmac_f32_e32 v77, v30, v51
	v_fmac_f32_e32 v76, v30, v52
	v_fmac_f32_e32 v75, v30, v53
	v_fmac_f32_e32 v74, v30, v54
	v_fmac_f32_e32 v73, v30, v55
	v_fmac_f32_e32 v68, v30, v56
	v_fmac_f32_e32 v66, v30, v57
	v_fmac_f32_e32 v65, v30, v58
	v_fmac_f32_e32 v64, v30, v59
	v_fmac_f32_e32 v63, v30, v60
	v_fmac_f32_e32 v62, v30, v67
	v_lshlrev_b32_e32 v25, 2, v1
	v_xor_b32_e32 v1, 32, v223
	v_fmac_f32_e32 v94, v34, v37
	v_fmac_f32_e32 v93, v34, v38
	v_fmac_f32_e32 v92, v34, v39
	v_fmac_f32_e32 v91, v34, v40
	v_fmac_f32_e32 v90, v34, v41
	v_fmac_f32_e32 v89, v34, v42
	v_fmac_f32_e32 v88, v34, v43
	v_fmac_f32_e32 v87, v34, v44
	v_fmac_f32_e32 v86, v34, v45
	v_fmac_f32_e32 v85, v34, v46
	v_fmac_f32_e32 v84, v34, v47
	v_fmac_f32_e32 v83, v34, v48
	v_fmac_f32_e32 v82, v34, v49
	v_fmac_f32_e32 v81, v34, v50
	v_fmac_f32_e32 v78, v34, v51
	v_fmac_f32_e32 v77, v34, v52
	v_fmac_f32_e32 v76, v34, v53
	v_fmac_f32_e32 v75, v34, v54
	v_fmac_f32_e32 v74, v34, v55
	v_fmac_f32_e32 v73, v34, v56
	v_fmac_f32_e32 v68, v34, v57
	v_fmac_f32_e32 v66, v34, v58
	v_fmac_f32_e32 v65, v34, v59
	v_fmac_f32_e32 v64, v34, v60
	v_fmac_f32_e32 v63, v34, v67
	v_fmac_f32_e32 v62, v34, v69
	v_lshlrev_b32_e32 v20, 2, v28
	v_cmp_lt_i32_e32 vcc, v1, v0
	v_fmac_f32_e32 v95, v36, v37
	v_fmac_f32_e32 v94, v36, v38
	v_fmac_f32_e32 v93, v36, v39
	v_fmac_f32_e32 v92, v36, v40
	v_fmac_f32_e32 v91, v36, v41
	v_fmac_f32_e32 v90, v36, v42
	v_fmac_f32_e32 v89, v36, v43
	v_fmac_f32_e32 v88, v36, v44
	v_fmac_f32_e32 v87, v36, v45
	v_fmac_f32_e32 v86, v36, v46
	v_fmac_f32_e32 v85, v36, v47
	v_fmac_f32_e32 v84, v36, v48
	v_fmac_f32_e32 v83, v36, v49
	v_fmac_f32_e32 v82, v36, v50
	v_fmac_f32_e32 v81, v36, v51
	v_fmac_f32_e32 v78, v36, v52
	v_fmac_f32_e32 v77, v36, v53
	v_fmac_f32_e32 v76, v36, v54
	v_fmac_f32_e32 v75, v36, v55
	v_fmac_f32_e32 v74, v36, v56
	v_fmac_f32_e32 v73, v36, v57
	v_fmac_f32_e32 v68, v36, v58
	v_fmac_f32_e32 v66, v36, v59
	v_fmac_f32_e32 v65, v36, v60
	v_fmac_f32_e32 v64, v36, v67
	v_fmac_f32_e32 v63, v36, v69
	v_fmac_f32_e32 v62, v36, v70
	v_add_u32_e32 v26, s0, v20
	v_cndmask_b32_e32 v0, v223, v1, vcc
	v_ashrrev_i32_e32 v29, 6, v4
	v_fmac_f32_e32 v96, v35, v37
	v_fmac_f32_e32 v95, v35, v38
	v_fmac_f32_e32 v94, v35, v39
	v_fmac_f32_e32 v93, v35, v40
	v_fmac_f32_e32 v92, v35, v41
	v_fmac_f32_e32 v91, v35, v42
	v_fmac_f32_e32 v90, v35, v43
	v_fmac_f32_e32 v89, v35, v44
	v_fmac_f32_e32 v88, v35, v45
	v_fmac_f32_e32 v87, v35, v46
	v_fmac_f32_e32 v86, v35, v47
	v_fmac_f32_e32 v85, v35, v48
	v_fmac_f32_e32 v84, v35, v49
	v_fmac_f32_e32 v83, v35, v50
	v_fmac_f32_e32 v82, v35, v51
	v_fmac_f32_e32 v81, v35, v52
	v_fmac_f32_e32 v78, v35, v53
	v_fmac_f32_e32 v77, v35, v54
	v_fmac_f32_e32 v76, v35, v55
	v_fmac_f32_e32 v75, v35, v56
	v_fmac_f32_e32 v74, v35, v57
	v_fmac_f32_e32 v73, v35, v58
	v_fmac_f32_e32 v68, v35, v59
	v_fmac_f32_e32 v66, v35, v60
	v_fmac_f32_e32 v65, v35, v67
	v_fmac_f32_e32 v64, v35, v69
	v_fmac_f32_e32 v63, v35, v70
	v_fmac_f32_e32 v62, v35, v71
	v_lshlrev_b32_e32 v27, 2, v0
	v_lshl_add_u32 v0, v29, 11, v26
	ds_write2st64_b32 v80, v98, v97 offset1:8
	ds_write2st64_b32 v80, v96, v95 offset0:16 offset1:24
	ds_write2st64_b32 v80, v94, v93 offset0:32 offset1:40
	ds_write2st64_b32 v80, v92, v91 offset0:48 offset1:56
	ds_write2st64_b32 v80, v90, v89 offset0:64 offset1:72
	ds_write2st64_b32 v80, v88, v87 offset0:80 offset1:88
	ds_write2st64_b32 v80, v86, v85 offset0:96 offset1:104
	ds_write2st64_b32 v80, v84, v83 offset0:112 offset1:120
	ds_write2st64_b32 v80, v82, v81 offset0:128 offset1:136
	ds_write2st64_b32 v80, v78, v77 offset0:144 offset1:152
	ds_write2st64_b32 v80, v76, v75 offset0:160 offset1:168
	ds_write2st64_b32 v80, v74, v73 offset0:176 offset1:184
	ds_write2st64_b32 v80, v68, v66 offset0:192 offset1:200
	ds_write2st64_b32 v80, v65, v64 offset0:208 offset1:216
	ds_write2st64_b32 v80, v63, v62 offset0:224 offset1:232
	s_waitcnt lgkmcnt(0)
	s_barrier
	ds_read_b128 v[8:11], v0
	ds_read_b128 v[0:3], v0 offset:16
	v_add_u32_e32 v19, 0x200, v4
	v_add_u32_e32 v18, 0x400, v4
	v_add_u32_e32 v17, 0x600, v4
	s_waitcnt lgkmcnt(1)
	v_mul_f32_e32 v4, v9, v9
	v_mul_f32_e32 v5, v11, v11
	v_fmac_f32_e32 v4, v8, v8
	v_fmac_f32_e32 v5, v10, v10
	v_add_f32_e32 v14, v4, v5
	s_waitcnt lgkmcnt(0)
	v_pk_mul_f32 v[4:5], v[2:3], v[2:3]
	v_pk_mul_f32 v[6:7], v[0:1], v[0:1]
	v_mov_b32_e32 v12, v4
	v_mov_b32_e32 v13, v6
	v_mov_b32_e32 v6, v5
	v_pk_add_f32 v[4:5], v[12:13], v[6:7]
	v_lshlrev_b32_e32 v160, 1, v28
	v_add_f32_e32 v5, v14, v5
	v_add_f32_e32 v4, v4, v5
	ds_bpermute_b32 v5, v21, v4
	s_add_i32 s11, s11, 1
	s_cmp_eq_u32 s11, 4
	s_waitcnt lgkmcnt(0)
	v_add_f32_e32 v4, v4, v5
	ds_bpermute_b32 v5, v22, v4
	s_waitcnt lgkmcnt(0)
	v_add_f32_e32 v4, v4, v5
	ds_bpermute_b32 v5, v23, v4
	s_waitcnt lgkmcnt(0)
	v_add_f32_e32 v4, v4, v5
	ds_bpermute_b32 v5, v24, v4
	s_waitcnt lgkmcnt(0)
	v_add_f32_e32 v4, v4, v5
	ds_bpermute_b32 v5, v25, v4
	s_waitcnt lgkmcnt(0)
	v_add_f32_e32 v4, v4, v5
	ds_bpermute_b32 v5, v27, v4
	s_waitcnt lgkmcnt(0)
	v_add_f32_e32 v4, v4, v5
	v_fmamk_f32 v4, v4, 0x3b000000, v219
	v_rsq_f32_e32 v16, v4
	global_load_dwordx4 v[4:7], v20, s[68:69] offset:16
	global_load_dwordx4 v[12:15], v20, s[68:69]
	v_pk_mul_f32 v[8:9], v[8:9], v[16:17] op_sel_hi:[1,0]
	v_pk_mul_f32 v[10:11], v[10:11], v[16:17] op_sel_hi:[1,0]
	v_pk_mul_f32 v[0:1], v[0:1], v[16:17] op_sel_hi:[1,0]
	s_waitcnt vmcnt(0)
	v_pk_mul_f32 v[8:9], v[12:13], v[8:9]
	s_nop 0
	v_mul_f32_e32 v12, 0xbfb8aa3b, v8
	v_mul_f32_e32 v13, 0xbfb8aa3b, v9
	v_exp_f32_e32 v12, v12
	v_exp_f32_e32 v13, v13
	v_pk_mul_f32 v[10:11], v[14:15], v[10:11]
	v_pk_mul_f32 v[0:1], v[4:5], v[0:1]
	v_add_f32_e32 v12, 1.0, v12
	v_add_f32_e32 v13, 1.0, v13
	v_rcp_f32_e32 v12, v12
	v_rcp_f32_e32 v13, v13
	v_mul_f32_e32 v4, 0xbfb8aa3b, v0
	v_mul_f32_e32 v5, 0xbfb8aa3b, v1
	v_exp_f32_e32 v4, v4
	v_pk_mul_f32 v[8:9], v[8:9], v[12:13]
	v_exp_f32_e32 v5, v5
	v_cvt_pk_bf16_f32 v8, v8, v9
	v_mul_f32_e32 v9, 0xbfb8aa3b, v10
	v_exp_f32_e32 v9, v9
	v_add_f32_e32 v4, 1.0, v4
	v_add_f32_e32 v5, 1.0, v5
	v_rcp_f32_e32 v4, v4
	v_add_f32_e32 v9, 1.0, v9
	v_rcp_f32_e32 v12, v9
	v_mul_f32_e32 v9, 0xbfb8aa3b, v11
	v_exp_f32_e32 v9, v9
	v_rcp_f32_e32 v5, v5
	v_add_f32_e32 v9, 1.0, v9
	v_rcp_f32_e32 v13, v9
	v_pk_mul_f32 v[0:1], v[0:1], v[4:5]
	v_pk_mul_f32 v[10:11], v[10:11], v[12:13]
	s_nop 0
	v_cvt_pk_bf16_f32 v9, v10, v11
	v_cvt_pk_bf16_f32 v10, v0, v1
	v_pk_mul_f32 v[0:1], v[2:3], v[16:17] op_sel_hi:[1,0]
	v_ashrrev_i32_e32 v16, 6, v19
	v_pk_mul_f32 v[0:1], v[6:7], v[0:1]
	s_nop 0
	v_mul_f32_e32 v2, 0xbfb8aa3b, v0
	v_mul_f32_e32 v3, 0xbfb8aa3b, v1
	v_exp_f32_e32 v2, v2
	v_exp_f32_e32 v3, v3
	v_add_f32_e32 v2, 1.0, v2
	v_add_f32_e32 v3, 1.0, v3
	v_rcp_f32_e32 v2, v2
	v_rcp_f32_e32 v3, v3
	s_nop 0
	v_pk_mul_f32 v[0:1], v[0:1], v[2:3]
	s_nop 0
	v_cvt_pk_bf16_f32 v11, v0, v1
	v_add_u32_e32 v0, s12, v29
	v_ashrrev_i32_e32 v1, 31, v0
	v_lshlrev_b64 v[0:1], 11, v[0:1]
	v_lshl_add_u64 v[0:1], s[2:3], 0, v[0:1]
	v_lshl_add_u64 v[0:1], v[0:1], 0, v[160:161]
	flat_store_dwordx4 v[0:1], v[8:11] offset:1024 nt
	v_lshl_add_u32 v0, v16, 11, v26
	ds_read_b128 v[8:11], v0
	ds_read_b128 v[0:3], v0 offset:16
	s_waitcnt lgkmcnt(0)
	v_mul_f32_e32 v4, v9, v9
	v_mul_f32_e32 v5, v11, v11
	v_fmac_f32_e32 v4, v8, v8
	v_fmac_f32_e32 v5, v10, v10
	v_add_f32_e32 v14, v4, v5
	v_pk_mul_f32 v[4:5], v[2:3], v[2:3]
	v_pk_mul_f32 v[6:7], v[0:1], v[0:1]
	v_mov_b32_e32 v12, v4
	v_mov_b32_e32 v13, v6
	v_mov_b32_e32 v6, v5
	v_pk_add_f32 v[4:5], v[12:13], v[6:7]
	s_nop 0
	v_add_f32_e32 v5, v14, v5
	v_add_f32_e32 v4, v4, v5
	ds_bpermute_b32 v5, v21, v4
	s_waitcnt lgkmcnt(0)
	v_add_f32_e32 v4, v4, v5
	ds_bpermute_b32 v5, v22, v4
	s_waitcnt lgkmcnt(0)
	v_add_f32_e32 v4, v4, v5
	ds_bpermute_b32 v5, v23, v4
	s_waitcnt lgkmcnt(0)
	v_add_f32_e32 v4, v4, v5
	ds_bpermute_b32 v5, v24, v4
	s_waitcnt lgkmcnt(0)
	v_add_f32_e32 v4, v4, v5
	ds_bpermute_b32 v5, v25, v4
	s_waitcnt lgkmcnt(0)
	v_add_f32_e32 v4, v4, v5
	ds_bpermute_b32 v5, v27, v4
	s_waitcnt lgkmcnt(0)
	v_add_f32_e32 v4, v4, v5
	v_fmamk_f32 v4, v4, 0x3b000000, v219
	v_rsq_f32_e32 v12, v4
	global_load_dwordx4 v[4:7], v20, s[68:69] offset:16
	global_load_dwordx4 v[28:31], v20, s[68:69]
	v_pk_mul_f32 v[8:9], v[8:9], v[12:13] op_sel_hi:[1,0]
	s_waitcnt vmcnt(0)
	v_pk_mul_f32 v[8:9], v[28:29], v[8:9]
	s_nop 0
	v_mul_f32_e32 v13, 0xbfb8aa3b, v8
	v_exp_f32_e32 v13, v13
	s_nop 0
	v_add_f32_e32 v13, 1.0, v13
	v_rcp_f32_e32 v14, v13
	v_mul_f32_e32 v13, 0xbfb8aa3b, v9
	v_exp_f32_e32 v13, v13
	s_nop 0
	v_add_f32_e32 v13, 1.0, v13
	v_rcp_f32_e32 v15, v13
	v_pk_mul_f32 v[10:11], v[10:11], v[12:13] op_sel_hi:[1,0]
	v_pk_mul_f32 v[0:1], v[0:1], v[12:13] op_sel_hi:[1,0]
	v_pk_mul_f32 v[10:11], v[30:31], v[10:11]
	v_pk_mul_f32 v[8:9], v[8:9], v[14:15]
	v_pk_mul_f32 v[0:1], v[4:5], v[0:1]
	v_cvt_pk_bf16_f32 v8, v8, v9
	v_mul_f32_e32 v9, 0xbfb8aa3b, v10
	v_exp_f32_e32 v9, v9
	v_mul_f32_e32 v4, 0xbfb8aa3b, v0
	v_mul_f32_e32 v5, 0xbfb8aa3b, v1
	v_exp_f32_e32 v4, v4
	v_add_f32_e32 v9, 1.0, v9
	v_rcp_f32_e32 v14, v9
	v_mul_f32_e32 v9, 0xbfb8aa3b, v11
	v_exp_f32_e32 v9, v9
	v_exp_f32_e32 v5, v5
	v_add_f32_e32 v4, 1.0, v4
	v_rcp_f32_e32 v4, v4
	v_add_f32_e32 v9, 1.0, v9
	v_add_f32_e32 v5, 1.0, v5
	v_rcp_f32_e32 v15, v9
	v_rcp_f32_e32 v5, v5
	v_pk_mul_f32 v[10:11], v[10:11], v[14:15]
	v_pk_mul_f32 v[0:1], v[0:1], v[4:5]
	v_cvt_pk_bf16_f32 v9, v10, v11
	v_cvt_pk_bf16_f32 v10, v0, v1
	v_pk_mul_f32 v[0:1], v[2:3], v[12:13] op_sel_hi:[1,0]
	s_nop 0
	v_pk_mul_f32 v[0:1], v[6:7], v[0:1]
	s_nop 0
	v_mul_f32_e32 v2, 0xbfb8aa3b, v0
	v_mul_f32_e32 v3, 0xbfb8aa3b, v1
	v_exp_f32_e32 v2, v2
	v_exp_f32_e32 v3, v3
	v_add_f32_e32 v2, 1.0, v2
	v_add_f32_e32 v3, 1.0, v3
	v_rcp_f32_e32 v2, v2
	v_rcp_f32_e32 v3, v3
	s_nop 0
	v_pk_mul_f32 v[0:1], v[0:1], v[2:3]
	s_nop 0
	v_cvt_pk_bf16_f32 v11, v0, v1
	v_add_u32_e32 v0, s12, v16
	v_ashrrev_i32_e32 v1, 31, v0
	v_lshlrev_b64 v[0:1], 11, v[0:1]
	v_lshl_add_u64 v[0:1], s[2:3], 0, v[0:1]
	v_lshl_add_u64 v[0:1], v[0:1], 0, v[160:161]
	v_ashrrev_i32_e32 v16, 6, v18
	flat_store_dwordx4 v[0:1], v[8:11] offset:1024 nt
	v_lshl_add_u32 v0, v16, 11, v26
	ds_read_b128 v[8:11], v0
	ds_read_b128 v[0:3], v0 offset:16
	v_ashrrev_i32_e32 v18, 6, v17
	s_waitcnt lgkmcnt(0)
	v_mul_f32_e32 v4, v9, v9
	v_mul_f32_e32 v5, v11, v11
	v_fmac_f32_e32 v4, v8, v8
	v_fmac_f32_e32 v5, v10, v10
	v_add_f32_e32 v14, v4, v5
	v_pk_mul_f32 v[4:5], v[2:3], v[2:3]
	v_pk_mul_f32 v[6:7], v[0:1], v[0:1]
	v_mov_b32_e32 v12, v4
	v_mov_b32_e32 v13, v6
	v_mov_b32_e32 v6, v5
	v_pk_add_f32 v[4:5], v[12:13], v[6:7]
	s_nop 0
	v_add_f32_e32 v5, v14, v5
	v_add_f32_e32 v4, v4, v5
	ds_bpermute_b32 v5, v21, v4
	s_waitcnt lgkmcnt(0)
	v_add_f32_e32 v4, v4, v5
	ds_bpermute_b32 v5, v22, v4
	s_waitcnt lgkmcnt(0)
	v_add_f32_e32 v4, v4, v5
	ds_bpermute_b32 v5, v23, v4
	s_waitcnt lgkmcnt(0)
	v_add_f32_e32 v4, v4, v5
	ds_bpermute_b32 v5, v24, v4
	s_waitcnt lgkmcnt(0)
	v_add_f32_e32 v4, v4, v5
	ds_bpermute_b32 v5, v25, v4
	s_waitcnt lgkmcnt(0)
	v_add_f32_e32 v4, v4, v5
	ds_bpermute_b32 v5, v27, v4
	s_waitcnt lgkmcnt(0)
	v_add_f32_e32 v4, v4, v5
	v_fmamk_f32 v4, v4, 0x3b000000, v219
	v_rsq_f32_e32 v12, v4
	global_load_dwordx4 v[4:7], v20, s[68:69] offset:16
	global_load_dwordx4 v[28:31], v20, s[68:69]
	v_pk_mul_f32 v[8:9], v[8:9], v[12:13] op_sel_hi:[1,0]
	s_waitcnt vmcnt(0)
	v_pk_mul_f32 v[8:9], v[28:29], v[8:9]
	s_nop 0
	v_mul_f32_e32 v13, 0xbfb8aa3b, v8
	v_exp_f32_e32 v13, v13
	s_nop 0
	v_add_f32_e32 v13, 1.0, v13
	v_rcp_f32_e32 v14, v13
	v_mul_f32_e32 v13, 0xbfb8aa3b, v9
	v_exp_f32_e32 v13, v13
	s_nop 0
	v_add_f32_e32 v13, 1.0, v13
	v_rcp_f32_e32 v15, v13
	v_pk_mul_f32 v[10:11], v[10:11], v[12:13] op_sel_hi:[1,0]
	v_pk_mul_f32 v[0:1], v[0:1], v[12:13] op_sel_hi:[1,0]
	v_pk_mul_f32 v[10:11], v[30:31], v[10:11]
	v_pk_mul_f32 v[8:9], v[8:9], v[14:15]
	v_pk_mul_f32 v[0:1], v[4:5], v[0:1]
	v_cvt_pk_bf16_f32 v8, v8, v9
	v_mul_f32_e32 v9, 0xbfb8aa3b, v10
	v_exp_f32_e32 v9, v9
	v_mul_f32_e32 v4, 0xbfb8aa3b, v0
	v_mul_f32_e32 v5, 0xbfb8aa3b, v1
	v_exp_f32_e32 v4, v4
	v_add_f32_e32 v9, 1.0, v9
	v_rcp_f32_e32 v14, v9
	v_mul_f32_e32 v9, 0xbfb8aa3b, v11
	v_exp_f32_e32 v9, v9
	v_exp_f32_e32 v5, v5
	v_add_f32_e32 v4, 1.0, v4
	v_rcp_f32_e32 v4, v4
	v_add_f32_e32 v9, 1.0, v9
	v_add_f32_e32 v5, 1.0, v5
	v_rcp_f32_e32 v15, v9
	v_rcp_f32_e32 v5, v5
	v_pk_mul_f32 v[10:11], v[10:11], v[14:15]
	v_pk_mul_f32 v[0:1], v[0:1], v[4:5]
	v_cvt_pk_bf16_f32 v9, v10, v11
	v_cvt_pk_bf16_f32 v10, v0, v1
	v_pk_mul_f32 v[0:1], v[2:3], v[12:13] op_sel_hi:[1,0]
	s_nop 0
	v_pk_mul_f32 v[0:1], v[6:7], v[0:1]
	s_nop 0
	v_mul_f32_e32 v2, 0xbfb8aa3b, v0
	v_mul_f32_e32 v3, 0xbfb8aa3b, v1
	v_exp_f32_e32 v2, v2
	v_exp_f32_e32 v3, v3
	v_add_f32_e32 v2, 1.0, v2
	v_add_f32_e32 v3, 1.0, v3
	v_rcp_f32_e32 v2, v2
	v_rcp_f32_e32 v3, v3
	s_nop 0
	v_pk_mul_f32 v[0:1], v[0:1], v[2:3]
	s_nop 0
	v_cvt_pk_bf16_f32 v11, v0, v1
	v_add_u32_e32 v0, s12, v16
	v_ashrrev_i32_e32 v1, 31, v0
	v_lshlrev_b64 v[0:1], 11, v[0:1]
	v_lshl_add_u64 v[0:1], s[2:3], 0, v[0:1]
	v_lshl_add_u64 v[0:1], v[0:1], 0, v[160:161]
	flat_store_dwordx4 v[0:1], v[8:11] offset:1024 nt
	v_lshl_add_u32 v0, v18, 11, v26
	ds_read_b128 v[8:11], v0
	ds_read_b128 v[0:3], v0 offset:16
	s_waitcnt lgkmcnt(0)
	v_mul_f32_e32 v4, v9, v9
	v_mul_f32_e32 v5, v11, v11
	v_fmac_f32_e32 v4, v8, v8
	v_fmac_f32_e32 v5, v10, v10
	v_add_f32_e32 v14, v4, v5
	v_pk_mul_f32 v[4:5], v[2:3], v[2:3]
	v_pk_mul_f32 v[6:7], v[0:1], v[0:1]
	v_mov_b32_e32 v12, v4
	v_mov_b32_e32 v13, v6
	v_mov_b32_e32 v6, v5
	v_pk_add_f32 v[4:5], v[12:13], v[6:7]
	s_nop 0
	v_add_f32_e32 v5, v14, v5
	v_add_f32_e32 v4, v4, v5
	ds_bpermute_b32 v5, v21, v4
	s_waitcnt lgkmcnt(0)
	v_add_f32_e32 v4, v4, v5
	ds_bpermute_b32 v5, v22, v4
	s_waitcnt lgkmcnt(0)
	v_add_f32_e32 v4, v4, v5
	ds_bpermute_b32 v5, v23, v4
	s_waitcnt lgkmcnt(0)
	v_add_f32_e32 v4, v4, v5
	ds_bpermute_b32 v5, v24, v4
	s_waitcnt lgkmcnt(0)
	v_add_f32_e32 v4, v4, v5
	ds_bpermute_b32 v5, v25, v4
	s_waitcnt lgkmcnt(0)
	v_add_f32_e32 v4, v4, v5
	ds_bpermute_b32 v5, v27, v4
	s_waitcnt lgkmcnt(0)
	v_add_f32_e32 v4, v4, v5
	v_fmamk_f32 v4, v4, 0x3b000000, v219
	v_rsq_f32_e32 v12, v4
	global_load_dwordx4 v[4:7], v20, s[68:69] offset:16
	global_load_dwordx4 v[14:17], v20, s[68:69]
	v_pk_mul_f32 v[8:9], v[8:9], v[12:13] op_sel_hi:[1,0]
	s_waitcnt vmcnt(0)
	v_pk_mul_f32 v[8:9], v[14:15], v[8:9]
	s_nop 0
	v_mul_f32_e32 v13, 0xbfb8aa3b, v8
	v_exp_f32_e32 v13, v13
	s_nop 0
	v_add_f32_e32 v13, 1.0, v13
	v_rcp_f32_e32 v14, v13
	v_mul_f32_e32 v13, 0xbfb8aa3b, v9
	v_exp_f32_e32 v13, v13
	s_nop 0
	v_add_f32_e32 v13, 1.0, v13
	v_rcp_f32_e32 v15, v13
	v_pk_mul_f32 v[10:11], v[10:11], v[12:13] op_sel_hi:[1,0]
	v_pk_mul_f32 v[0:1], v[0:1], v[12:13] op_sel_hi:[1,0]
	v_pk_mul_f32 v[10:11], v[16:17], v[10:11]
	v_pk_mul_f32 v[8:9], v[8:9], v[14:15]
	v_pk_mul_f32 v[0:1], v[4:5], v[0:1]
	v_cvt_pk_bf16_f32 v8, v8, v9
	v_mul_f32_e32 v9, 0xbfb8aa3b, v10
	v_exp_f32_e32 v9, v9
	v_mul_f32_e32 v4, 0xbfb8aa3b, v0
	v_mul_f32_e32 v5, 0xbfb8aa3b, v1
	v_exp_f32_e32 v4, v4
	v_add_f32_e32 v9, 1.0, v9
	v_rcp_f32_e32 v14, v9
	v_mul_f32_e32 v9, 0xbfb8aa3b, v11
	v_exp_f32_e32 v9, v9
	v_exp_f32_e32 v5, v5
	v_add_f32_e32 v4, 1.0, v4
	v_rcp_f32_e32 v4, v4
	v_add_f32_e32 v9, 1.0, v9
	v_add_f32_e32 v5, 1.0, v5
	v_rcp_f32_e32 v15, v9
	v_rcp_f32_e32 v5, v5
	v_pk_mul_f32 v[10:11], v[10:11], v[14:15]
	v_pk_mul_f32 v[0:1], v[0:1], v[4:5]
	v_cvt_pk_bf16_f32 v9, v10, v11
	v_cvt_pk_bf16_f32 v10, v0, v1
	v_pk_mul_f32 v[0:1], v[2:3], v[12:13] op_sel_hi:[1,0]
	s_nop 0
	v_pk_mul_f32 v[0:1], v[6:7], v[0:1]
	s_nop 0
	v_mul_f32_e32 v2, 0xbfb8aa3b, v0
	v_mul_f32_e32 v3, 0xbfb8aa3b, v1
	v_exp_f32_e32 v2, v2
	v_exp_f32_e32 v3, v3
	v_add_f32_e32 v2, 1.0, v2
	v_add_f32_e32 v3, 1.0, v3
	v_rcp_f32_e32 v2, v2
	v_rcp_f32_e32 v3, v3
	s_nop 0
	v_pk_mul_f32 v[0:1], v[0:1], v[2:3]
	s_nop 0
	v_cvt_pk_bf16_f32 v11, v0, v1
	v_add_u32_e32 v0, s12, v18
	v_ashrrev_i32_e32 v1, 31, v0
	v_lshlrev_b64 v[0:1], 11, v[0:1]
	v_lshl_add_u64 v[0:1], s[2:3], 0, v[0:1]
	v_lshl_add_u64 v[0:1], v[0:1], 0, v[160:161]
	flat_store_dwordx4 v[0:1], v[8:11] offset:1024 nt
	s_waitcnt lgkmcnt(0)
	s_barrier
	s_cbranch_scc1 .LBB0_386

.LBB0_405:
	s_cmp_gt_u32 s35, 7
	s_cbranch_scc0 .LBB0_407
	v_lshl_add_u32 v130, s44, 8, v156
	v_ashrrev_i32_e32 v131, 31, v130
	v_lshl_add_u64 v[146:147], v[130:131], 3, s[36:37]
	v_or_b32_e32 v128, 0xfffffc00, v158
	v_lshl_add_u32 v128, s35, 7, v128
	v_mov_b32_e32 v129, v161
	v_lshl_add_u64 v[128:129], v[128:129], 1, s[46:47]
	s_mov_b32 s0, 0x20000
	s_waitcnt vmcnt(0) lgkmcnt(0)
	v_mov_b64_e32 v[144:145], v[196:197]
	v_ffbh_u32_e32 v148, v145
	v_min_u32_e32 v148, 32, v148
	v_lshlrev_b64 v[144:145], v148, v[144:145]
	v_min_u32_e32 v144, 1, v144
	v_or_b32_e32 v144, v145, v144
	v_cvt_f32_u32_e32 v144, v144
	v_sub_u32_e32 v145, 32, v148
	v_ldexp_f32 v144, v144, v145
	v_mul_f32_e32 v144, 0x35800000, v144
	v_fmamk_f32 v144, v144, 0x3a800000, v219
	v_rsq_f32_e32 v144, v144
	s_nop 0
	v_mul_f32_e32 v145, v120, v144
	v_mul_f32_e32 v145, 0xbfb8aa3b, v145
	v_exp_f32_e32 v145, v145
	s_nop 0
	v_add_f32_e32 v145, 1.0, v145
	v_rcp_f32_e32 v148, v145
	v_mul_f32_e32 v145, v121, v144
	v_mul_f32_e32 v145, 0xbfb8aa3b, v145
	v_exp_f32_e32 v145, v145
	s_nop 0
	v_add_f32_e32 v145, 1.0, v145
	v_rcp_f32_e32 v149, v145
	v_pk_mul_f32 v[150:151], v[124:125], v[144:145] op_sel_hi:[1,0]
	v_mul_f32_e32 v145, v122, v144
	v_mul_f32_e32 v145, 0xbfb8aa3b, v145
	v_exp_f32_e32 v145, v145
	v_pk_mul_f32 v[148:149], v[150:151], v[148:149]
	v_add_f32_e32 v145, 1.0, v145
	v_rcp_f32_e32 v150, v145
	v_mul_f32_e32 v145, v123, v144
	v_mul_f32_e32 v145, 0xbfb8aa3b, v145
	v_exp_f32_e32 v145, v145
	v_cvt_pk_bf16_f32 v148, v148, v149
	v_add_f32_e32 v145, 1.0, v145
	v_rcp_f32_e32 v151, v145
	v_pk_mul_f32 v[152:153], v[126:127], v[144:145] op_sel_hi:[1,0]
	v_mul_f32_e32 v145, v112, v144
	v_mul_f32_e32 v145, 0xbfb8aa3b, v145
	v_exp_f32_e32 v145, v145
	v_pk_mul_f32 v[150:151], v[152:153], v[150:151]
	v_add_f32_e32 v145, 1.0, v145
	v_rcp_f32_e32 v152, v145
	v_mul_f32_e32 v145, v113, v144
	v_mul_f32_e32 v145, 0xbfb8aa3b, v145
	v_exp_f32_e32 v145, v145
	v_cvt_pk_bf16_f32 v149, v150, v151
	v_add_f32_e32 v145, 1.0, v145
	v_rcp_f32_e32 v153, v145
	v_pk_mul_f32 v[154:155], v[116:117], v[144:145] op_sel_hi:[1,0]
	v_mul_f32_e32 v145, v114, v144
	v_mul_f32_e32 v145, 0xbfb8aa3b, v145
	v_exp_f32_e32 v145, v145
	v_pk_mul_f32 v[152:153], v[154:155], v[152:153]
	v_add_f32_e32 v145, 1.0, v145
	v_rcp_f32_e32 v154, v145
	v_mul_f32_e32 v145, v115, v144
	v_mul_f32_e32 v145, 0xbfb8aa3b, v145
	v_exp_f32_e32 v145, v145
	v_cvt_pk_bf16_f32 v150, v152, v153
	v_add_f32_e32 v145, 1.0, v145
	v_rcp_f32_e32 v155, v145
	v_pk_mul_f32 v[144:145], v[118:119], v[144:145] op_sel_hi:[1,0]
	s_nop 0
	v_pk_mul_f32 v[154:155], v[144:145], v[154:155]
	v_lshlrev_b64 v[144:145], 10, v[130:131]
	v_lshl_add_u64 v[144:145], v[128:129], 0, v[144:145]
	v_cvt_pk_bf16_f32 v151, v154, v155
	global_store_dwordx4 v[144:145], v[148:151], off nt
	s_nop 1
	v_or_b32_e32 v148, 16, v130
	v_ashrrev_i32_e32 v149, 31, v148
	v_lshl_add_u64 v[150:151], v[148:149], 3, s[36:37]
	s_nop 1
	v_mov_b64_e32 v[150:151], v[198:199]
	v_lshlrev_b64 v[148:149], 10, v[148:149]
	v_lshl_add_u64 v[166:167], v[128:129], 0, v[148:149]
	v_ffbh_u32_e32 v131, v151
	v_min_u32_e32 v131, 32, v131
	v_lshlrev_b64 v[150:151], v131, v[150:151]
	v_min_u32_e32 v150, 1, v150
	v_or_b32_e32 v150, v151, v150
	v_cvt_f32_u32_e32 v150, v150
	v_sub_u32_e32 v131, 32, v131
	v_ldexp_f32 v131, v150, v131
	v_mul_f32_e32 v131, 0x35800000, v131
	v_fmamk_f32 v131, v131, 0x3a800000, v219
	v_rsq_f32_e32 v150, v131
	s_nop 0
	v_mul_f32_e32 v131, v104, v150
	v_mul_f32_e32 v131, 0xbfb8aa3b, v131
	v_exp_f32_e32 v131, v131
	v_pk_mul_f32 v[154:155], v[108:109], v[150:151] op_sel_hi:[1,0]
	v_pk_mul_f32 v[162:163], v[110:111], v[150:151] op_sel_hi:[1,0]
	v_pk_mul_f32 v[164:165], v[100:101], v[150:151] op_sel_hi:[1,0]
	v_add_f32_e32 v131, 1.0, v131
	v_rcp_f32_e32 v152, v131
	v_mul_f32_e32 v131, v105, v150
	v_mul_f32_e32 v131, 0xbfb8aa3b, v131
	v_exp_f32_e32 v131, v131
	s_nop 0
	v_add_f32_e32 v131, 1.0, v131
	v_rcp_f32_e32 v153, v131
	v_mul_f32_e32 v131, v106, v150
	v_mul_f32_e32 v131, 0xbfb8aa3b, v131
	v_exp_f32_e32 v131, v131
	v_pk_mul_f32 v[152:153], v[154:155], v[152:153]
	v_add_f32_e32 v131, 1.0, v131
	v_rcp_f32_e32 v154, v131
	v_mul_f32_e32 v131, v107, v150
	v_mul_f32_e32 v131, 0xbfb8aa3b, v131
	v_exp_f32_e32 v131, v131
	v_cvt_pk_bf16_f32 v148, v152, v153
	v_add_f32_e32 v131, 1.0, v131
	v_rcp_f32_e32 v155, v131
	v_mul_f32_e32 v131, v96, v150
	v_mul_f32_e32 v131, 0xbfb8aa3b, v131
	v_exp_f32_e32 v131, v131
	v_pk_mul_f32 v[154:155], v[162:163], v[154:155]
	v_add_f32_e32 v131, 1.0, v131
	v_rcp_f32_e32 v162, v131
	v_mul_f32_e32 v131, v97, v150
	v_mul_f32_e32 v131, 0xbfb8aa3b, v131
	v_exp_f32_e32 v131, v131
	v_cvt_pk_bf16_f32 v149, v154, v155
	v_add_f32_e32 v131, 1.0, v131
	v_rcp_f32_e32 v163, v131
	v_mul_f32_e32 v131, v98, v150
	v_mul_f32_e32 v131, 0xbfb8aa3b, v131
	v_exp_f32_e32 v131, v131
	v_pk_mul_f32 v[162:163], v[164:165], v[162:163]
	v_add_f32_e32 v131, 1.0, v131
	v_rcp_f32_e32 v164, v131
	v_mul_f32_e32 v131, v99, v150
	v_mul_f32_e32 v131, 0xbfb8aa3b, v131
	v_exp_f32_e32 v131, v131
	v_pk_mul_f32 v[150:151], v[102:103], v[150:151] op_sel_hi:[1,0]
	v_add_f32_e32 v131, 1.0, v131
	v_rcp_f32_e32 v165, v131
	s_nop 0
	v_pk_mul_f32 v[164:165], v[150:151], v[164:165]
	v_cvt_pk_bf16_f32 v150, v162, v163
	v_cvt_pk_bf16_f32 v151, v164, v165
	global_store_dwordx4 v[166:167], v[148:151], off nt
	s_nop 1
	v_or_b32_e32 v148, 32, v130
	v_ashrrev_i32_e32 v149, 31, v148
	v_lshl_add_u64 v[150:151], v[148:149], 3, s[36:37]
	s_nop 1
	v_mov_b64_e32 v[150:151], v[200:201]
	v_lshlrev_b64 v[148:149], 10, v[148:149]
	v_lshl_add_u64 v[166:167], v[128:129], 0, v[148:149]
	v_or_b32_e32 v130, 48, v130
	v_ffbh_u32_e32 v131, v151
	v_min_u32_e32 v131, 32, v131
	v_lshlrev_b64 v[150:151], v131, v[150:151]
	v_min_u32_e32 v150, 1, v150
	v_or_b32_e32 v150, v151, v150
	v_cvt_f32_u32_e32 v150, v150
	v_sub_u32_e32 v131, 32, v131
	v_ldexp_f32 v131, v150, v131
	v_mul_f32_e32 v131, 0x35800000, v131
	v_fmamk_f32 v131, v131, 0x3a800000, v219
	v_rsq_f32_e32 v150, v131
	s_nop 0
	v_mul_f32_e32 v131, v88, v150
	v_mul_f32_e32 v131, 0xbfb8aa3b, v131
	v_exp_f32_e32 v131, v131
	v_pk_mul_f32 v[154:155], v[92:93], v[150:151] op_sel_hi:[1,0]
	v_pk_mul_f32 v[162:163], v[94:95], v[150:151] op_sel_hi:[1,0]
	v_pk_mul_f32 v[164:165], v[84:85], v[150:151] op_sel_hi:[1,0]
	v_add_f32_e32 v131, 1.0, v131
	v_rcp_f32_e32 v152, v131
	v_mul_f32_e32 v131, v89, v150
	v_mul_f32_e32 v131, 0xbfb8aa3b, v131
	v_exp_f32_e32 v131, v131
	s_nop 0
	v_add_f32_e32 v131, 1.0, v131
	v_rcp_f32_e32 v153, v131
	v_mul_f32_e32 v131, v90, v150
	v_mul_f32_e32 v131, 0xbfb8aa3b, v131
	v_exp_f32_e32 v131, v131
	v_pk_mul_f32 v[152:153], v[154:155], v[152:153]
	v_add_f32_e32 v131, 1.0, v131
	v_rcp_f32_e32 v154, v131
	v_mul_f32_e32 v131, v91, v150
	v_mul_f32_e32 v131, 0xbfb8aa3b, v131
	v_exp_f32_e32 v131, v131
	v_cvt_pk_bf16_f32 v148, v152, v153
	v_add_f32_e32 v131, 1.0, v131
	v_rcp_f32_e32 v155, v131
	v_mul_f32_e32 v131, v80, v150
	v_mul_f32_e32 v131, 0xbfb8aa3b, v131
	v_exp_f32_e32 v131, v131
	v_pk_mul_f32 v[154:155], v[162:163], v[154:155]
	v_add_f32_e32 v131, 1.0, v131
	v_rcp_f32_e32 v162, v131
	v_mul_f32_e32 v131, v81, v150
	v_mul_f32_e32 v131, 0xbfb8aa3b, v131
	v_exp_f32_e32 v131, v131
	v_cvt_pk_bf16_f32 v149, v154, v155
	v_add_f32_e32 v131, 1.0, v131
	v_rcp_f32_e32 v163, v131
	v_mul_f32_e32 v131, v82, v150
	v_mul_f32_e32 v131, 0xbfb8aa3b, v131
	v_exp_f32_e32 v131, v131
	v_pk_mul_f32 v[162:163], v[164:165], v[162:163]
	v_add_f32_e32 v131, 1.0, v131
	v_rcp_f32_e32 v164, v131
	v_mul_f32_e32 v131, v83, v150
	v_mul_f32_e32 v131, 0xbfb8aa3b, v131
	v_exp_f32_e32 v131, v131
	v_pk_mul_f32 v[150:151], v[86:87], v[150:151] op_sel_hi:[1,0]
	v_add_f32_e32 v131, 1.0, v131
	v_rcp_f32_e32 v165, v131
	v_ashrrev_i32_e32 v131, 31, v130
	v_pk_mul_f32 v[164:165], v[150:151], v[164:165]
	v_cvt_pk_bf16_f32 v150, v162, v163
	v_cvt_pk_bf16_f32 v151, v164, v165
	global_store_dwordx4 v[166:167], v[148:151], off nt
	s_nop 1
	v_lshl_add_u64 v[148:149], v[130:131], 3, s[36:37]
	s_nop 1
	v_mov_b64_e32 v[148:149], v[202:203]
	v_lshlrev_b64 v[130:131], 10, v[130:131]
	v_ffbh_u32_e32 v150, v149
	v_min_u32_e32 v150, 32, v150
	v_lshlrev_b64 v[148:149], v150, v[148:149]
	v_min_u32_e32 v148, 1, v148
	v_or_b32_e32 v148, v149, v148
	v_cvt_f32_u32_e32 v148, v148
	v_sub_u32_e32 v149, 32, v150
	v_ldexp_f32 v148, v148, v149
	v_mul_f32_e32 v148, 0x35800000, v148
	v_fmamk_f32 v148, v148, 0x3a800000, v219
	v_rsq_f32_e32 v154, v148
	s_nop 0
	v_mul_f32_e32 v148, v72, v154
	v_mul_f32_e32 v149, v73, v154
	v_mul_f32_e32 v148, 0xbfb8aa3b, v148
	v_mul_f32_e32 v149, 0xbfb8aa3b, v149
	v_exp_f32_e32 v148, v148
	v_exp_f32_e32 v149, v149
	v_pk_mul_f32 v[150:151], v[76:77], v[154:155] op_sel_hi:[1,0]
	v_pk_mul_f32 v[152:153], v[78:79], v[154:155] op_sel_hi:[1,0]
	v_add_f32_e32 v148, 1.0, v148
	v_add_f32_e32 v149, 1.0, v149
	v_rcp_f32_e32 v148, v148
	v_rcp_f32_e32 v149, v149
	v_pk_mul_f32 v[162:163], v[68:69], v[154:155] op_sel_hi:[1,0]
	v_mul_f32_e32 v155, v66, v154
	v_mul_f32_e32 v155, 0xbfb8aa3b, v155
	v_pk_mul_f32 v[148:149], v[150:151], v[148:149]
	v_mul_f32_e32 v150, v74, v154
	v_mul_f32_e32 v151, v75, v154
	v_mul_f32_e32 v150, 0xbfb8aa3b, v150
	v_mul_f32_e32 v151, 0xbfb8aa3b, v151
	v_exp_f32_e32 v150, v150
	v_exp_f32_e32 v151, v151
	v_exp_f32_e32 v155, v155
	v_add_f32_e32 v150, 1.0, v150
	v_add_f32_e32 v151, 1.0, v151
	v_rcp_f32_e32 v150, v150
	v_rcp_f32_e32 v151, v151
	v_add_f32_e32 v155, 1.0, v155
	v_pk_mul_f32 v[150:151], v[152:153], v[150:151]
	v_mul_f32_e32 v152, v64, v154
	v_mul_f32_e32 v153, v65, v154
	v_mul_f32_e32 v152, 0xbfb8aa3b, v152
	v_mul_f32_e32 v153, 0xbfb8aa3b, v153
	v_exp_f32_e32 v152, v152
	v_exp_f32_e32 v153, v153
	v_add_f32_e32 v152, 1.0, v152
	v_add_f32_e32 v153, 1.0, v153
	v_rcp_f32_e32 v152, v152
	v_rcp_f32_e32 v153, v153
	s_nop 0
	v_pk_mul_f32 v[152:153], v[162:163], v[152:153]
	v_rcp_f32_e32 v162, v155
	v_mul_f32_e32 v155, v67, v154
	v_mul_f32_e32 v155, 0xbfb8aa3b, v155
	v_exp_f32_e32 v155, v155
	s_nop 0
	v_add_f32_e32 v155, 1.0, v155
	v_rcp_f32_e32 v163, v155
	v_pk_mul_f32 v[154:155], v[70:71], v[154:155] op_sel_hi:[1,0]
	s_nop 0
	v_pk_mul_f32 v[154:155], v[154:155], v[162:163]
	v_lshl_add_u64 v[162:163], v[128:129], 0, v[130:131]
	v_cvt_pk_bf16_f32 v128, v148, v149
	v_cvt_pk_bf16_f32 v129, v150, v151
	v_cvt_pk_bf16_f32 v130, v152, v153
	v_cvt_pk_bf16_f32 v131, v154, v155
	global_store_dwordx4 v[162:163], v[128:131], off nt
	s_nop 1
	v_mov_b64_e32 v[128:129], v[204:205]
	v_ffbh_u32_e32 v130, v129
	v_min_u32_e32 v130, 32, v130
	v_lshlrev_b64 v[128:129], v130, v[128:129]
	v_min_u32_e32 v128, 1, v128
	v_or_b32_e32 v128, v129, v128
	v_cvt_f32_u32_e32 v128, v128
	v_sub_u32_e32 v129, 32, v130
	v_ldexp_f32 v128, v128, v129
	v_mul_f32_e32 v128, 0x35800000, v128
	v_fmamk_f32 v128, v128, 0x3a800000, v219
	v_rsq_f32_e32 v128, v128
	s_nop 0
	v_mul_f32_e32 v129, v56, v128
	v_mul_f32_e32 v129, 0xbfb8aa3b, v129
	v_exp_f32_e32 v129, v129
	s_nop 0
	v_add_f32_e32 v129, 1.0, v129
	v_rcp_f32_e32 v130, v129
	v_mul_f32_e32 v129, v57, v128
	v_mul_f32_e32 v129, 0xbfb8aa3b, v129
	v_exp_f32_e32 v129, v129
	s_nop 0
	v_add_f32_e32 v129, 1.0, v129
	v_rcp_f32_e32 v131, v129
	v_pk_mul_f32 v[148:149], v[60:61], v[128:129] op_sel_hi:[1,0]
	v_mul_f32_e32 v129, v58, v128
	v_mul_f32_e32 v129, 0xbfb8aa3b, v129
	v_exp_f32_e32 v129, v129
	v_pk_mul_f32 v[130:131], v[148:149], v[130:131]
	v_add_f32_e32 v129, 1.0, v129
	v_rcp_f32_e32 v148, v129
	v_mul_f32_e32 v129, v59, v128
	v_mul_f32_e32 v129, 0xbfb8aa3b, v129
	v_exp_f32_e32 v129, v129
	s_nop 0
	v_add_f32_e32 v129, 1.0, v129
	v_rcp_f32_e32 v149, v129
	v_pk_mul_f32 v[150:151], v[62:63], v[128:129] op_sel_hi:[1,0]
	v_mul_f32_e32 v129, v48, v128
	v_mul_f32_e32 v129, 0xbfb8aa3b, v129
	v_exp_f32_e32 v129, v129
	v_pk_mul_f32 v[148:149], v[150:151], v[148:149]
	v_add_f32_e32 v129, 1.0, v129
	v_rcp_f32_e32 v150, v129
	v_mul_f32_e32 v129, v49, v128
	v_mul_f32_e32 v129, 0xbfb8aa3b, v129
	v_exp_f32_e32 v129, v129
	s_nop 0
	v_add_f32_e32 v129, 1.0, v129
	v_rcp_f32_e32 v151, v129
	v_pk_mul_f32 v[152:153], v[52:53], v[128:129] op_sel_hi:[1,0]
	v_mul_f32_e32 v129, v50, v128
	v_mul_f32_e32 v129, 0xbfb8aa3b, v129
	v_exp_f32_e32 v129, v129
	v_pk_mul_f32 v[150:151], v[152:153], v[150:151]
	v_add_f32_e32 v129, 1.0, v129
	v_rcp_f32_e32 v152, v129
	v_mul_f32_e32 v129, v51, v128
	v_mul_f32_e32 v129, 0xbfb8aa3b, v129
	v_exp_f32_e32 v129, v129
	s_nop 0
	v_add_f32_e32 v129, 1.0, v129
	v_rcp_f32_e32 v153, v129
	v_pk_mul_f32 v[128:129], v[54:55], v[128:129] op_sel_hi:[1,0]
	s_nop 0
	v_pk_mul_f32 v[152:153], v[128:129], v[152:153]
	v_cvt_pk_bf16_f32 v129, v148, v149
	v_add_co_u32_e32 v148, vcc, s0, v144
	v_cvt_pk_bf16_f32 v128, v130, v131
	v_cvt_pk_bf16_f32 v130, v150, v151
	v_cvt_pk_bf16_f32 v131, v152, v153
	v_addc_co_u32_e32 v149, vcc, 0, v145, vcc
	global_store_dwordx4 v[148:149], v[128:131], off nt
	s_nop 1
	v_mov_b64_e32 v[128:129], v[206:207]
	s_mov_b32 s0, 0x24000
	v_ffbh_u32_e32 v130, v129
	v_min_u32_e32 v130, 32, v130
	v_lshlrev_b64 v[128:129], v130, v[128:129]
	v_min_u32_e32 v128, 1, v128
	v_or_b32_e32 v128, v129, v128
	v_cvt_f32_u32_e32 v128, v128
	v_sub_u32_e32 v129, 32, v130
	v_ldexp_f32 v128, v128, v129
	v_mul_f32_e32 v128, 0x35800000, v128
	v_fmamk_f32 v128, v128, 0x3a800000, v219
	v_rsq_f32_e32 v128, v128
	s_nop 0
	v_mul_f32_e32 v129, v40, v128
	v_mul_f32_e32 v129, 0xbfb8aa3b, v129
	v_exp_f32_e32 v129, v129
	s_nop 0
	v_add_f32_e32 v129, 1.0, v129
	v_rcp_f32_e32 v130, v129
	v_mul_f32_e32 v129, v41, v128
	v_mul_f32_e32 v129, 0xbfb8aa3b, v129
	v_exp_f32_e32 v129, v129
	s_nop 0
	v_add_f32_e32 v129, 1.0, v129
	v_rcp_f32_e32 v131, v129
	v_pk_mul_f32 v[148:149], v[44:45], v[128:129] op_sel_hi:[1,0]
	v_mul_f32_e32 v129, v42, v128
	v_mul_f32_e32 v129, 0xbfb8aa3b, v129
	v_exp_f32_e32 v129, v129
	v_pk_mul_f32 v[130:131], v[148:149], v[130:131]
	v_add_f32_e32 v129, 1.0, v129
	v_rcp_f32_e32 v148, v129
	v_mul_f32_e32 v129, v43, v128
	v_mul_f32_e32 v129, 0xbfb8aa3b, v129
	v_exp_f32_e32 v129, v129
	s_nop 0
	v_add_f32_e32 v129, 1.0, v129
	v_rcp_f32_e32 v149, v129
	v_pk_mul_f32 v[150:151], v[46:47], v[128:129] op_sel_hi:[1,0]
	v_mul_f32_e32 v129, v32, v128
	v_mul_f32_e32 v129, 0xbfb8aa3b, v129
	v_exp_f32_e32 v129, v129
	v_pk_mul_f32 v[148:149], v[150:151], v[148:149]
	v_add_f32_e32 v129, 1.0, v129
	v_rcp_f32_e32 v150, v129
	v_mul_f32_e32 v129, v33, v128
	v_mul_f32_e32 v129, 0xbfb8aa3b, v129
	v_exp_f32_e32 v129, v129
	s_nop 0
	v_add_f32_e32 v129, 1.0, v129
	v_rcp_f32_e32 v151, v129
	v_pk_mul_f32 v[152:153], v[36:37], v[128:129] op_sel_hi:[1,0]
	v_mul_f32_e32 v129, v34, v128
	v_mul_f32_e32 v129, 0xbfb8aa3b, v129
	v_exp_f32_e32 v129, v129
	v_pk_mul_f32 v[150:151], v[152:153], v[150:151]
	v_add_f32_e32 v129, 1.0, v129
	v_rcp_f32_e32 v152, v129
	v_mul_f32_e32 v129, v35, v128
	v_mul_f32_e32 v129, 0xbfb8aa3b, v129
	v_exp_f32_e32 v129, v129
	s_nop 0
	v_add_f32_e32 v129, 1.0, v129
	v_rcp_f32_e32 v153, v129
	v_pk_mul_f32 v[128:129], v[38:39], v[128:129] op_sel_hi:[1,0]
	s_nop 0
	v_pk_mul_f32 v[152:153], v[128:129], v[152:153]
	v_cvt_pk_bf16_f32 v129, v148, v149
	v_add_co_u32_e32 v148, vcc, s0, v144
	v_cvt_pk_bf16_f32 v128, v130, v131
	v_cvt_pk_bf16_f32 v130, v150, v151
	v_cvt_pk_bf16_f32 v131, v152, v153
	v_addc_co_u32_e32 v149, vcc, 0, v145, vcc
	global_store_dwordx4 v[148:149], v[128:131], off nt
	s_nop 1
	v_mov_b64_e32 v[128:129], v[208:209]
	s_mov_b32 s0, 0x28000
	v_ffbh_u32_e32 v130, v129
	v_min_u32_e32 v130, 32, v130
	v_lshlrev_b64 v[128:129], v130, v[128:129]
	v_min_u32_e32 v128, 1, v128
	v_or_b32_e32 v128, v129, v128
	v_cvt_f32_u32_e32 v128, v128
	v_sub_u32_e32 v129, 32, v130
	v_ldexp_f32 v128, v128, v129
	v_mul_f32_e32 v128, 0x35800000, v128
	v_fmamk_f32 v128, v128, 0x3a800000, v219
	v_rsq_f32_e32 v128, v128
	s_nop 0
	v_mul_f32_e32 v129, v24, v128
	v_mul_f32_e32 v129, 0xbfb8aa3b, v129
	v_exp_f32_e32 v129, v129
	s_nop 0
	v_add_f32_e32 v129, 1.0, v129
	v_rcp_f32_e32 v130, v129
	v_mul_f32_e32 v129, v25, v128
	v_mul_f32_e32 v129, 0xbfb8aa3b, v129
	v_exp_f32_e32 v129, v129
	s_nop 0
	v_add_f32_e32 v129, 1.0, v129
	v_rcp_f32_e32 v131, v129
	v_pk_mul_f32 v[148:149], v[28:29], v[128:129] op_sel_hi:[1,0]
	v_mul_f32_e32 v129, v26, v128
	v_mul_f32_e32 v129, 0xbfb8aa3b, v129
	v_exp_f32_e32 v129, v129
	v_pk_mul_f32 v[130:131], v[148:149], v[130:131]
	v_add_f32_e32 v129, 1.0, v129
	v_rcp_f32_e32 v148, v129
	v_mul_f32_e32 v129, v27, v128
	v_mul_f32_e32 v129, 0xbfb8aa3b, v129
	v_exp_f32_e32 v129, v129
	s_nop 0
	v_add_f32_e32 v129, 1.0, v129
	v_rcp_f32_e32 v149, v129
	v_pk_mul_f32 v[150:151], v[30:31], v[128:129] op_sel_hi:[1,0]
	v_mul_f32_e32 v129, v16, v128
	v_mul_f32_e32 v129, 0xbfb8aa3b, v129
	v_exp_f32_e32 v129, v129
	v_pk_mul_f32 v[148:149], v[150:151], v[148:149]
	v_add_f32_e32 v129, 1.0, v129
	v_rcp_f32_e32 v150, v129
	v_mul_f32_e32 v129, v17, v128
	v_mul_f32_e32 v129, 0xbfb8aa3b, v129
	v_exp_f32_e32 v129, v129
	s_nop 0
	v_add_f32_e32 v129, 1.0, v129
	v_rcp_f32_e32 v151, v129
	v_pk_mul_f32 v[152:153], v[20:21], v[128:129] op_sel_hi:[1,0]
	v_mul_f32_e32 v129, v18, v128
	v_mul_f32_e32 v129, 0xbfb8aa3b, v129
	v_exp_f32_e32 v129, v129
	v_pk_mul_f32 v[150:151], v[152:153], v[150:151]
	v_add_f32_e32 v129, 1.0, v129
	v_rcp_f32_e32 v152, v129
	v_mul_f32_e32 v129, v19, v128
	v_mul_f32_e32 v129, 0xbfb8aa3b, v129
	v_exp_f32_e32 v129, v129
	s_nop 0
	v_add_f32_e32 v129, 1.0, v129
	v_rcp_f32_e32 v153, v129
	v_pk_mul_f32 v[128:129], v[22:23], v[128:129] op_sel_hi:[1,0]
	s_nop 0
	v_pk_mul_f32 v[152:153], v[128:129], v[152:153]
	v_cvt_pk_bf16_f32 v129, v148, v149
	v_add_co_u32_e32 v148, vcc, s0, v144
	v_cvt_pk_bf16_f32 v128, v130, v131
	v_cvt_pk_bf16_f32 v130, v150, v151
	v_cvt_pk_bf16_f32 v131, v152, v153
	v_addc_co_u32_e32 v149, vcc, 0, v145, vcc
	global_store_dwordx4 v[148:149], v[128:131], off nt
	s_nop 1
	v_mov_b64_e32 v[128:129], v[210:211]
	v_add_co_u32_e32 v144, vcc, 0x2c000, v144
	s_mov_b64 s[0:1], 0
	s_nop 0
	v_addc_co_u32_e32 v145, vcc, 0, v145, vcc
	v_ffbh_u32_e32 v130, v129
	v_min_u32_e32 v130, 32, v130
	v_lshlrev_b64 v[128:129], v130, v[128:129]
	v_min_u32_e32 v128, 1, v128
	v_or_b32_e32 v128, v129, v128
	v_cvt_f32_u32_e32 v128, v128
	v_sub_u32_e32 v129, 32, v130
	v_ldexp_f32 v128, v128, v129
	v_mul_f32_e32 v128, 0x35800000, v128
	v_fmamk_f32 v128, v128, 0x3a800000, v219
	v_rsq_f32_e32 v128, v128
	s_nop 0
	v_mul_f32_e32 v129, v8, v128
	v_mul_f32_e32 v129, 0xbfb8aa3b, v129
	v_exp_f32_e32 v129, v129
	s_nop 0
	v_add_f32_e32 v129, 1.0, v129
	v_rcp_f32_e32 v130, v129
	v_mul_f32_e32 v129, v9, v128
	v_mul_f32_e32 v129, 0xbfb8aa3b, v129
	v_exp_f32_e32 v129, v129
	s_nop 0
	v_add_f32_e32 v129, 1.0, v129
	v_rcp_f32_e32 v131, v129
	v_pk_mul_f32 v[146:147], v[12:13], v[128:129] op_sel_hi:[1,0]
	v_mul_f32_e32 v129, v10, v128
	v_mul_f32_e32 v129, 0xbfb8aa3b, v129
	v_exp_f32_e32 v129, v129
	v_pk_mul_f32 v[130:131], v[146:147], v[130:131]
	v_add_f32_e32 v129, 1.0, v129
	v_rcp_f32_e32 v146, v129
	v_mul_f32_e32 v129, v11, v128
	v_mul_f32_e32 v129, 0xbfb8aa3b, v129
	v_exp_f32_e32 v129, v129
	s_nop 0
	v_add_f32_e32 v129, 1.0, v129
	v_rcp_f32_e32 v147, v129
	v_pk_mul_f32 v[148:149], v[14:15], v[128:129] op_sel_hi:[1,0]
	v_mul_f32_e32 v129, v0, v128
	v_mul_f32_e32 v129, 0xbfb8aa3b, v129
	v_exp_f32_e32 v129, v129
	v_pk_mul_f32 v[146:147], v[148:149], v[146:147]
	v_add_f32_e32 v129, 1.0, v129
	v_rcp_f32_e32 v148, v129
	v_mul_f32_e32 v129, v1, v128
	v_mul_f32_e32 v129, 0xbfb8aa3b, v129
	v_exp_f32_e32 v129, v129
	s_nop 0
	v_add_f32_e32 v129, 1.0, v129
	v_rcp_f32_e32 v149, v129
	v_pk_mul_f32 v[150:151], v[4:5], v[128:129] op_sel_hi:[1,0]
	v_mul_f32_e32 v129, v2, v128
	v_mul_f32_e32 v129, 0xbfb8aa3b, v129
	v_exp_f32_e32 v129, v129
	v_pk_mul_f32 v[148:149], v[150:151], v[148:149]
	v_add_f32_e32 v129, 1.0, v129
	v_rcp_f32_e32 v150, v129
	v_mul_f32_e32 v129, v3, v128
	v_mul_f32_e32 v129, 0xbfb8aa3b, v129
	v_exp_f32_e32 v129, v129
	s_nop 0
	v_add_f32_e32 v129, 1.0, v129
	v_rcp_f32_e32 v151, v129
	v_pk_mul_f32 v[128:129], v[6:7], v[128:129] op_sel_hi:[1,0]
	s_nop 0
	v_pk_mul_f32 v[150:151], v[128:129], v[150:151]
	v_cvt_pk_bf16_f32 v128, v130, v131
	v_cvt_pk_bf16_f32 v129, v146, v147
	v_cvt_pk_bf16_f32 v130, v148, v149
	v_cvt_pk_bf16_f32 v131, v150, v151
	global_store_dwordx4 v[144:145], v[128:131], off nt
.LBB0_407:
	s_andn2_b64 vcc, exec, s[0:1]
	s_cbranch_vccnz .LBB0_409
	s_add_i32 s7, s35, -4
	s_cmp_lt_u32 s7, 2
	s_mov_b32 s0, 0xfa00000
	s_cselect_b32 s0, s0, 0x11a00000
	s_add_u32 s0, s94, s0
	s_addc_u32 s1, s95, 0
	s_cmp_gt_u32 s7, 1
	s_cselect_b64 vcc, -1, 0
	s_lshl_b32 s7, s7, 8
	v_lshl_add_u32 v146, s44, 8, v156
	s_and_b32 s7, s7, 0x100
	v_or_b32_e32 v128, s7, v158
	v_ashrrev_i32_e32 v147, 31, v146
	v_lshlrev_b32_e32 v128, 1, v128
	v_mov_b32_e32 v129, v161
	v_lshl_add_u64 v[130:131], v[146:147], 3, s[36:37]
	v_lshl_add_u64 v[144:145], s[0:1], 0, v[128:129]
	s_mov_b64 s[0:1], 0x20000
	s_waitcnt vmcnt(0) lgkmcnt(0)
	v_mov_b64_e32 v[128:129], v[196:197]
	v_ffbh_u32_e32 v148, v129
	v_min_u32_e32 v148, 32, v148
	v_lshlrev_b64 v[128:129], v148, v[128:129]
	v_min_u32_e32 v128, 1, v128
	v_or_b32_e32 v128, v129, v128
	v_cvt_f32_u32_e32 v128, v128
	v_sub_u32_e32 v129, 32, v148
	v_ldexp_f32 v128, v128, v129
	v_mul_f32_e32 v128, 0x35800000, v128
	v_fmamk_f32 v128, v128, 0x3a800000, v219
	v_rsq_f32_e32 v148, v128
	v_lshlrev_b64 v[128:129], 10, v[146:147]
	v_lshl_add_u64 v[128:129], v[144:145], 0, v[128:129]
	v_mul_f32_e32 v147, v124, v148
	v_mul_f32_e32 v149, 0xbfb8aa3b, v147
	v_exp_f32_e32 v149, v149
	s_nop 0
	v_add_f32_e32 v149, 1.0, v149
	v_rcp_f32_e32 v149, v149
	s_nop 0
	v_mul_f32_e32 v149, v147, v149
	v_cndmask_b32_e32 v147, v147, v149, vcc
	v_mul_f32_e32 v149, v125, v148
	v_mul_f32_e32 v150, 0xbfb8aa3b, v149
	v_exp_f32_e32 v150, v150
	s_nop 0
	v_add_f32_e32 v150, 1.0, v150
	v_rcp_f32_e32 v150, v150
	s_nop 0
	v_mul_f32_e32 v150, v149, v150
	v_cndmask_b32_e32 v149, v149, v150, vcc
	v_mul_f32_e32 v150, v126, v148
	v_mul_f32_e32 v151, 0xbfb8aa3b, v150
	v_exp_f32_e32 v151, v151
	s_nop 0
	v_add_f32_e32 v151, 1.0, v151
	v_rcp_f32_e32 v151, v151
	s_nop 0
	v_mul_f32_e32 v151, v150, v151
	v_cndmask_b32_e32 v151, v150, v151, vcc
	v_mul_f32_e32 v150, v127, v148
	v_mul_f32_e32 v152, 0xbfb8aa3b, v150
	v_exp_f32_e32 v152, v152
	s_nop 0
	v_add_f32_e32 v152, 1.0, v152
	v_rcp_f32_e32 v152, v152
	s_nop 0
	v_mul_f32_e32 v152, v150, v152
	v_cndmask_b32_e32 v152, v150, v152, vcc
	v_mul_f32_e32 v150, v116, v148
	v_mul_f32_e32 v153, 0xbfb8aa3b, v150
	v_exp_f32_e32 v153, v153
	v_cvt_pk_bf16_f32 v151, v151, v152
	v_add_f32_e32 v153, 1.0, v153
	v_rcp_f32_e32 v153, v153
	s_nop 0
	v_mul_f32_e32 v153, v150, v153
	v_cndmask_b32_e32 v153, v150, v153, vcc
	v_mul_f32_e32 v150, v117, v148
	v_mul_f32_e32 v154, 0xbfb8aa3b, v150
	v_exp_f32_e32 v154, v154
	s_nop 0
	v_add_f32_e32 v154, 1.0, v154
	v_rcp_f32_e32 v154, v154
	s_nop 0
	v_mul_f32_e32 v154, v150, v154
	v_cndmask_b32_e32 v154, v150, v154, vcc
	v_mul_f32_e32 v150, v118, v148
	v_mul_f32_e32 v155, 0xbfb8aa3b, v150
	v_exp_f32_e32 v155, v155
	v_cvt_pk_bf16_f32 v152, v153, v154
	v_add_f32_e32 v155, 1.0, v155
	v_rcp_f32_e32 v155, v155
	s_nop 0
	v_mul_f32_e32 v155, v150, v155
	v_cndmask_b32_e32 v155, v150, v155, vcc
	v_mul_f32_e32 v150, v119, v148
	v_mul_f32_e32 v162, 0xbfb8aa3b, v150
	v_exp_f32_e32 v162, v162
	s_nop 0
	v_add_f32_e32 v162, 1.0, v162
	v_rcp_f32_e32 v162, v162
	s_nop 0
	v_mul_f32_e32 v162, v150, v162
	v_cndmask_b32_e32 v162, v150, v162, vcc
	v_cvt_pk_bf16_f32 v150, v147, v149
	v_mul_f32_e32 v147, v120, v148
	v_mul_f32_e32 v149, 0xbfb8aa3b, v147
	v_exp_f32_e32 v149, v149
	v_cvt_pk_bf16_f32 v153, v155, v162
	global_store_dwordx4 v[128:129], v[150:153], off nt
	v_add_f32_e32 v149, 1.0, v149
	v_rcp_f32_e32 v149, v149
	s_nop 0
	v_mul_f32_e32 v149, v147, v149
	v_cndmask_b32_e32 v147, v147, v149, vcc
	v_mul_f32_e32 v149, v121, v148
	v_mul_f32_e32 v150, 0xbfb8aa3b, v149
	v_exp_f32_e32 v150, v150
	s_nop 0
	v_add_f32_e32 v150, 1.0, v150
	v_rcp_f32_e32 v150, v150
	s_nop 0
	v_mul_f32_e32 v150, v149, v150
	v_cndmask_b32_e32 v149, v149, v150, vcc
	v_mul_f32_e32 v150, v122, v148
	v_mul_f32_e32 v151, 0xbfb8aa3b, v150
	v_exp_f32_e32 v151, v151
	s_nop 0
	v_add_f32_e32 v151, 1.0, v151
	v_rcp_f32_e32 v151, v151
	s_nop 0
	v_mul_f32_e32 v151, v150, v151
	v_cndmask_b32_e32 v150, v150, v151, vcc
	v_mul_f32_e32 v151, v123, v148
	v_mul_f32_e32 v152, 0xbfb8aa3b, v151
	v_exp_f32_e32 v152, v152
	s_nop 0
	v_add_f32_e32 v152, 1.0, v152
	v_rcp_f32_e32 v152, v152
	s_nop 0
	v_mul_f32_e32 v152, v151, v152
	v_cndmask_b32_e32 v151, v151, v152, vcc
	v_mul_f32_e32 v152, v112, v148
	v_mul_f32_e32 v153, 0xbfb8aa3b, v152
	v_exp_f32_e32 v153, v153
	s_nop 0
	v_add_f32_e32 v153, 1.0, v153
	v_rcp_f32_e32 v153, v153
	s_nop 0
	v_mul_f32_e32 v153, v152, v153
	v_cndmask_b32_e32 v152, v152, v153, vcc
	v_mul_f32_e32 v153, v113, v148
	v_mul_f32_e32 v154, 0xbfb8aa3b, v153
	v_exp_f32_e32 v154, v154
	s_nop 0
	v_add_f32_e32 v154, 1.0, v154
	v_rcp_f32_e32 v154, v154
	s_nop 0
	v_mul_f32_e32 v154, v153, v154
	v_cndmask_b32_e32 v153, v153, v154, vcc
	v_mul_f32_e32 v154, v114, v148
	v_mul_f32_e32 v155, 0xbfb8aa3b, v154
	v_exp_f32_e32 v155, v155
	v_mul_f32_e32 v148, v115, v148
	v_add_f32_e32 v155, 1.0, v155
	v_rcp_f32_e32 v155, v155
	s_nop 0
	v_mul_f32_e32 v155, v154, v155
	v_cndmask_b32_e32 v154, v154, v155, vcc
	v_mul_f32_e32 v155, 0xbfb8aa3b, v148
	v_exp_f32_e32 v155, v155
	s_nop 0
	v_add_f32_e32 v155, 1.0, v155
	v_rcp_f32_e32 v155, v155
	s_nop 0
	v_mul_f32_e32 v155, v148, v155
	v_cndmask_b32_e32 v155, v148, v155, vcc
	v_cvt_pk_bf16_f32 v148, v147, v149
	v_cvt_pk_bf16_f32 v149, v150, v151
	v_cvt_pk_bf16_f32 v150, v152, v153
	v_cvt_pk_bf16_f32 v151, v154, v155
	global_store_dwordx4 v[128:129], v[148:151], off offset:256 nt
	s_nop 1
	v_or_b32_e32 v148, 16, v146
	v_ashrrev_i32_e32 v149, 31, v148
	v_lshl_add_u64 v[150:151], v[148:149], 3, s[36:37]
	s_nop 1
	v_mov_b64_e32 v[150:151], v[198:199]
	v_lshlrev_b64 v[148:149], 10, v[148:149]
	v_lshl_add_u64 v[148:149], v[144:145], 0, v[148:149]
	v_ffbh_u32_e32 v147, v151
	v_min_u32_e32 v147, 32, v147
	v_lshlrev_b64 v[150:151], v147, v[150:151]
	v_min_u32_e32 v150, 1, v150
	v_or_b32_e32 v150, v151, v150
	v_cvt_f32_u32_e32 v150, v150
	v_sub_u32_e32 v147, 32, v147
	v_ldexp_f32 v147, v150, v147
	v_mul_f32_e32 v147, 0x35800000, v147
	v_fmamk_f32 v147, v147, 0x3a800000, v219
	v_rsq_f32_e32 v147, v147
	s_nop 0
	v_mul_f32_e32 v150, v108, v147
	v_mul_f32_e32 v151, 0xbfb8aa3b, v150
	v_exp_f32_e32 v151, v151
	s_nop 0
	v_add_f32_e32 v151, 1.0, v151
	v_rcp_f32_e32 v151, v151
	s_nop 0
	v_mul_f32_e32 v151, v150, v151
	v_cndmask_b32_e32 v150, v150, v151, vcc
	v_mul_f32_e32 v151, v109, v147
	v_mul_f32_e32 v152, 0xbfb8aa3b, v151
	v_exp_f32_e32 v152, v152
	s_nop 0
	v_add_f32_e32 v152, 1.0, v152
	v_rcp_f32_e32 v152, v152
	s_nop 0
	v_mul_f32_e32 v152, v151, v152
	v_cndmask_b32_e32 v151, v151, v152, vcc
	v_mul_f32_e32 v152, v110, v147
	v_mul_f32_e32 v153, 0xbfb8aa3b, v152
	v_exp_f32_e32 v153, v153
	v_cvt_pk_bf16_f32 v150, v150, v151
	v_add_f32_e32 v153, 1.0, v153
	v_rcp_f32_e32 v153, v153
	s_nop 0
	v_mul_f32_e32 v153, v152, v153
	v_cndmask_b32_e32 v152, v152, v153, vcc
	v_mul_f32_e32 v153, v111, v147
	v_mul_f32_e32 v154, 0xbfb8aa3b, v153
	v_exp_f32_e32 v154, v154
	s_nop 0
	v_add_f32_e32 v154, 1.0, v154
	v_rcp_f32_e32 v154, v154
	s_nop 0
	v_mul_f32_e32 v154, v153, v154
	v_cndmask_b32_e32 v153, v153, v154, vcc
	v_mul_f32_e32 v154, v100, v147
	v_mul_f32_e32 v155, 0xbfb8aa3b, v154
	v_exp_f32_e32 v155, v155
	v_cvt_pk_bf16_f32 v151, v152, v153
	v_add_f32_e32 v155, 1.0, v155
	v_rcp_f32_e32 v155, v155
	s_nop 0
	v_mul_f32_e32 v155, v154, v155
	v_cndmask_b32_e32 v154, v154, v155, vcc
	v_mul_f32_e32 v155, v101, v147
	v_mul_f32_e32 v162, 0xbfb8aa3b, v155
	v_exp_f32_e32 v162, v162
	s_nop 0
	v_add_f32_e32 v162, 1.0, v162
	v_rcp_f32_e32 v162, v162
	s_nop 0
	v_mul_f32_e32 v162, v155, v162
	v_cndmask_b32_e32 v155, v155, v162, vcc
	v_mul_f32_e32 v162, v102, v147
	v_mul_f32_e32 v163, 0xbfb8aa3b, v162
	v_exp_f32_e32 v163, v163
	v_cvt_pk_bf16_f32 v152, v154, v155
	v_add_f32_e32 v163, 1.0, v163
	v_rcp_f32_e32 v163, v163
	s_nop 0
	v_mul_f32_e32 v163, v162, v163
	v_cndmask_b32_e32 v162, v162, v163, vcc
	v_mul_f32_e32 v163, v103, v147
	v_mul_f32_e32 v164, 0xbfb8aa3b, v163
	v_exp_f32_e32 v164, v164
	s_nop 0
	v_add_f32_e32 v164, 1.0, v164
	v_rcp_f32_e32 v164, v164
	s_nop 0
	v_mul_f32_e32 v164, v163, v164
	v_cndmask_b32_e32 v163, v163, v164, vcc
	v_cvt_pk_bf16_f32 v153, v162, v163
	global_store_dwordx4 v[148:149], v[150:153], off nt
	s_nop 1
	v_mul_f32_e32 v150, v104, v147
	v_mul_f32_e32 v151, 0xbfb8aa3b, v150
	v_exp_f32_e32 v151, v151
	s_nop 0
	v_add_f32_e32 v151, 1.0, v151
	v_rcp_f32_e32 v151, v151
	s_nop 0
	v_mul_f32_e32 v151, v150, v151
	v_cndmask_b32_e32 v150, v150, v151, vcc
	v_mul_f32_e32 v151, v105, v147
	v_mul_f32_e32 v152, 0xbfb8aa3b, v151
	v_exp_f32_e32 v152, v152
	s_nop 0
	v_add_f32_e32 v152, 1.0, v152
	v_rcp_f32_e32 v152, v152
	s_nop 0
	v_mul_f32_e32 v152, v151, v152
	v_cndmask_b32_e32 v151, v151, v152, vcc
	v_mul_f32_e32 v152, v106, v147
	v_mul_f32_e32 v153, 0xbfb8aa3b, v152
	v_exp_f32_e32 v153, v153
	v_cvt_pk_bf16_f32 v150, v150, v151
	v_add_f32_e32 v153, 1.0, v153
	v_rcp_f32_e32 v153, v153
	s_nop 0
	v_mul_f32_e32 v153, v152, v153
	v_cndmask_b32_e32 v152, v152, v153, vcc
	v_mul_f32_e32 v153, v107, v147
	v_mul_f32_e32 v154, 0xbfb8aa3b, v153
	v_exp_f32_e32 v154, v154
	s_nop 0
	v_add_f32_e32 v154, 1.0, v154
	v_rcp_f32_e32 v154, v154
	s_nop 0
	v_mul_f32_e32 v154, v153, v154
	v_cndmask_b32_e32 v153, v153, v154, vcc
	v_mul_f32_e32 v154, v96, v147
	v_mul_f32_e32 v155, 0xbfb8aa3b, v154
	v_exp_f32_e32 v155, v155
	v_cvt_pk_bf16_f32 v151, v152, v153
	v_add_f32_e32 v155, 1.0, v155
	v_rcp_f32_e32 v155, v155
	s_nop 0
	v_mul_f32_e32 v155, v154, v155
	v_cndmask_b32_e32 v154, v154, v155, vcc
	v_mul_f32_e32 v155, v97, v147
	v_mul_f32_e32 v162, 0xbfb8aa3b, v155
	v_exp_f32_e32 v162, v162
	s_nop 0
	v_add_f32_e32 v162, 1.0, v162
	v_rcp_f32_e32 v162, v162
	s_nop 0
	v_mul_f32_e32 v162, v155, v162
	v_cndmask_b32_e32 v155, v155, v162, vcc
	v_mul_f32_e32 v162, v98, v147
	v_mul_f32_e32 v163, 0xbfb8aa3b, v162
	v_exp_f32_e32 v163, v163
	v_mul_f32_e32 v147, v99, v147
	v_cvt_pk_bf16_f32 v152, v154, v155
	v_add_f32_e32 v163, 1.0, v163
	v_rcp_f32_e32 v163, v163
	s_nop 0
	v_mul_f32_e32 v163, v162, v163
	v_cndmask_b32_e32 v162, v162, v163, vcc
	v_mul_f32_e32 v163, 0xbfb8aa3b, v147
	v_exp_f32_e32 v163, v163
	s_nop 0
	v_add_f32_e32 v163, 1.0, v163
	v_rcp_f32_e32 v163, v163
	s_nop 0
	v_mul_f32_e32 v163, v147, v163
	v_cndmask_b32_e32 v147, v147, v163, vcc
	v_cvt_pk_bf16_f32 v153, v162, v147
	global_store_dwordx4 v[148:149], v[150:153], off offset:256 nt
	v_or_b32_e32 v148, 32, v146
	v_ashrrev_i32_e32 v149, 31, v148
	v_lshl_add_u64 v[150:151], v[148:149], 3, s[36:37]
	s_nop 1
	v_mov_b64_e32 v[150:151], v[200:201]
	v_lshlrev_b64 v[148:149], 10, v[148:149]
	v_lshl_add_u64 v[148:149], v[144:145], 0, v[148:149]
	v_or_b32_e32 v146, 48, v146
	v_ffbh_u32_e32 v147, v151
	v_min_u32_e32 v147, 32, v147
	v_lshlrev_b64 v[150:151], v147, v[150:151]
	v_min_u32_e32 v150, 1, v150
	v_or_b32_e32 v150, v151, v150
	v_cvt_f32_u32_e32 v150, v150
	v_sub_u32_e32 v147, 32, v147
	v_ldexp_f32 v147, v150, v147
	v_mul_f32_e32 v147, 0x35800000, v147
	v_fmamk_f32 v147, v147, 0x3a800000, v219
	v_rsq_f32_e32 v147, v147
	s_nop 0
	v_mul_f32_e32 v150, v92, v147
	v_mul_f32_e32 v151, 0xbfb8aa3b, v150
	v_exp_f32_e32 v151, v151
	s_nop 0
	v_add_f32_e32 v151, 1.0, v151
	v_rcp_f32_e32 v151, v151
	s_nop 0
	v_mul_f32_e32 v151, v150, v151
	v_cndmask_b32_e32 v150, v150, v151, vcc
	v_mul_f32_e32 v151, v93, v147
	v_mul_f32_e32 v152, 0xbfb8aa3b, v151
	v_exp_f32_e32 v152, v152
	s_nop 0
	v_add_f32_e32 v152, 1.0, v152
	v_rcp_f32_e32 v152, v152
	s_nop 0
	v_mul_f32_e32 v152, v151, v152
	v_cndmask_b32_e32 v151, v151, v152, vcc
	v_mul_f32_e32 v152, v94, v147
	v_mul_f32_e32 v153, 0xbfb8aa3b, v152
	v_exp_f32_e32 v153, v153
	v_cvt_pk_bf16_f32 v150, v150, v151
	v_add_f32_e32 v153, 1.0, v153
	v_rcp_f32_e32 v153, v153
	s_nop 0
	v_mul_f32_e32 v153, v152, v153
	v_cndmask_b32_e32 v152, v152, v153, vcc
	v_mul_f32_e32 v153, v95, v147
	v_mul_f32_e32 v154, 0xbfb8aa3b, v153
	v_exp_f32_e32 v154, v154
	s_nop 0
	v_add_f32_e32 v154, 1.0, v154
	v_rcp_f32_e32 v154, v154
	s_nop 0
	v_mul_f32_e32 v154, v153, v154
	v_cndmask_b32_e32 v153, v153, v154, vcc
	v_mul_f32_e32 v154, v84, v147
	v_mul_f32_e32 v155, 0xbfb8aa3b, v154
	v_exp_f32_e32 v155, v155
	v_cvt_pk_bf16_f32 v151, v152, v153
	v_add_f32_e32 v155, 1.0, v155
	v_rcp_f32_e32 v155, v155
	s_nop 0
	v_mul_f32_e32 v155, v154, v155
	v_cndmask_b32_e32 v154, v154, v155, vcc
	v_mul_f32_e32 v155, v85, v147
	v_mul_f32_e32 v162, 0xbfb8aa3b, v155
	v_exp_f32_e32 v162, v162
	s_nop 0
	v_add_f32_e32 v162, 1.0, v162
	v_rcp_f32_e32 v162, v162
	s_nop 0
	v_mul_f32_e32 v162, v155, v162
	v_cndmask_b32_e32 v155, v155, v162, vcc
	v_mul_f32_e32 v162, v86, v147
	v_mul_f32_e32 v163, 0xbfb8aa3b, v162
	v_exp_f32_e32 v163, v163
	v_cvt_pk_bf16_f32 v152, v154, v155
	v_add_f32_e32 v163, 1.0, v163
	v_rcp_f32_e32 v163, v163
	s_nop 0
	v_mul_f32_e32 v163, v162, v163
	v_cndmask_b32_e32 v162, v162, v163, vcc
	v_mul_f32_e32 v163, v87, v147
	v_mul_f32_e32 v164, 0xbfb8aa3b, v163
	v_exp_f32_e32 v164, v164
	s_nop 0
	v_add_f32_e32 v164, 1.0, v164
	v_rcp_f32_e32 v164, v164
	s_nop 0
	v_mul_f32_e32 v164, v163, v164
	v_cndmask_b32_e32 v163, v163, v164, vcc
	v_cvt_pk_bf16_f32 v153, v162, v163
	global_store_dwordx4 v[148:149], v[150:153], off nt
	s_nop 1
	v_mul_f32_e32 v150, v88, v147
	v_mul_f32_e32 v151, 0xbfb8aa3b, v150
	v_exp_f32_e32 v151, v151
	s_nop 0
	v_add_f32_e32 v151, 1.0, v151
	v_rcp_f32_e32 v151, v151
	s_nop 0
	v_mul_f32_e32 v151, v150, v151
	v_cndmask_b32_e32 v150, v150, v151, vcc
	v_mul_f32_e32 v151, v89, v147
	v_mul_f32_e32 v152, 0xbfb8aa3b, v151
	v_exp_f32_e32 v152, v152
	s_nop 0
	v_add_f32_e32 v152, 1.0, v152
	v_rcp_f32_e32 v152, v152
	s_nop 0
	v_mul_f32_e32 v152, v151, v152
	v_cndmask_b32_e32 v151, v151, v152, vcc
	v_mul_f32_e32 v152, v90, v147
	v_mul_f32_e32 v153, 0xbfb8aa3b, v152
	v_exp_f32_e32 v153, v153
	v_cvt_pk_bf16_f32 v150, v150, v151
	v_add_f32_e32 v153, 1.0, v153
	v_rcp_f32_e32 v153, v153
	s_nop 0
	v_mul_f32_e32 v153, v152, v153
	v_cndmask_b32_e32 v152, v152, v153, vcc
	v_mul_f32_e32 v153, v91, v147
	v_mul_f32_e32 v154, 0xbfb8aa3b, v153
	v_exp_f32_e32 v154, v154
	s_nop 0
	v_add_f32_e32 v154, 1.0, v154
	v_rcp_f32_e32 v154, v154
	s_nop 0
	v_mul_f32_e32 v154, v153, v154
	v_cndmask_b32_e32 v153, v153, v154, vcc
	v_mul_f32_e32 v154, v80, v147
	v_mul_f32_e32 v155, 0xbfb8aa3b, v154
	v_exp_f32_e32 v155, v155
	v_cvt_pk_bf16_f32 v151, v152, v153
	v_add_f32_e32 v155, 1.0, v155
	v_rcp_f32_e32 v155, v155
	s_nop 0
	v_mul_f32_e32 v155, v154, v155
	v_cndmask_b32_e32 v154, v154, v155, vcc
	v_mul_f32_e32 v155, v81, v147
	v_mul_f32_e32 v162, 0xbfb8aa3b, v155
	v_exp_f32_e32 v162, v162
	s_nop 0
	v_add_f32_e32 v162, 1.0, v162
	v_rcp_f32_e32 v162, v162
	s_nop 0
	v_mul_f32_e32 v162, v155, v162
	v_cndmask_b32_e32 v155, v155, v162, vcc
	v_mul_f32_e32 v162, v82, v147
	v_mul_f32_e32 v163, 0xbfb8aa3b, v162
	v_exp_f32_e32 v163, v163
	v_mul_f32_e32 v147, v83, v147
	v_cvt_pk_bf16_f32 v152, v154, v155
	v_add_f32_e32 v163, 1.0, v163
	v_rcp_f32_e32 v163, v163
	s_nop 0
	v_mul_f32_e32 v163, v162, v163
	v_cndmask_b32_e32 v162, v162, v163, vcc
	v_mul_f32_e32 v163, 0xbfb8aa3b, v147
	v_exp_f32_e32 v163, v163
	s_nop 0
	v_add_f32_e32 v163, 1.0, v163
	v_rcp_f32_e32 v163, v163
	s_nop 0
	v_mul_f32_e32 v163, v147, v163
	v_cndmask_b32_e32 v147, v147, v163, vcc
	v_cvt_pk_bf16_f32 v153, v162, v147
	global_store_dwordx4 v[148:149], v[150:153], off offset:256 nt
	v_ashrrev_i32_e32 v147, 31, v146
	v_lshl_add_u64 v[148:149], v[146:147], 3, s[36:37]
	s_nop 1
	v_mov_b64_e32 v[148:149], v[202:203]
	v_lshlrev_b64 v[146:147], 10, v[146:147]
	v_lshl_add_u64 v[144:145], v[144:145], 0, v[146:147]
	v_ffbh_u32_e32 v150, v149
	v_min_u32_e32 v150, 32, v150
	v_lshlrev_b64 v[148:149], v150, v[148:149]
	v_min_u32_e32 v148, 1, v148
	v_or_b32_e32 v148, v149, v148
	v_cvt_f32_u32_e32 v148, v148
	v_sub_u32_e32 v149, 32, v150
	v_ldexp_f32 v148, v148, v149
	v_mul_f32_e32 v148, 0x35800000, v148
	v_fmamk_f32 v148, v148, 0x3a800000, v219
	v_rsq_f32_e32 v150, v148
	s_nop 0
	v_mul_f32_e32 v146, v76, v150
	v_mul_f32_e32 v147, 0xbfb8aa3b, v146
	v_exp_f32_e32 v147, v147
	s_nop 0
	v_add_f32_e32 v147, 1.0, v147
	v_rcp_f32_e32 v147, v147
	s_nop 0
	v_mul_f32_e32 v147, v146, v147
	v_cndmask_b32_e32 v146, v146, v147, vcc
	v_mul_f32_e32 v147, v77, v150
	v_mul_f32_e32 v148, 0xbfb8aa3b, v147
	v_exp_f32_e32 v148, v148
	s_nop 0
	v_add_f32_e32 v148, 1.0, v148
	v_rcp_f32_e32 v148, v148
	s_nop 0
	v_mul_f32_e32 v148, v147, v148
	v_cndmask_b32_e32 v147, v147, v148, vcc
	v_mul_f32_e32 v148, v78, v150
	v_mul_f32_e32 v149, 0xbfb8aa3b, v148
	v_exp_f32_e32 v149, v149
	v_cvt_pk_bf16_f32 v146, v146, v147
	v_add_f32_e32 v149, 1.0, v149
	v_rcp_f32_e32 v149, v149
	s_nop 0
	v_mul_f32_e32 v149, v148, v149
	v_cndmask_b32_e32 v148, v148, v149, vcc
	v_mul_f32_e32 v149, v79, v150
	v_mul_f32_e32 v151, 0xbfb8aa3b, v149
	v_exp_f32_e32 v151, v151
	s_nop 0
	v_add_f32_e32 v151, 1.0, v151
	v_rcp_f32_e32 v151, v151
	s_nop 0
	v_mul_f32_e32 v151, v149, v151
	v_cndmask_b32_e32 v149, v149, v151, vcc
	v_mul_f32_e32 v151, v68, v150
	v_mul_f32_e32 v152, 0xbfb8aa3b, v151
	v_exp_f32_e32 v152, v152
	v_cvt_pk_bf16_f32 v147, v148, v149
	v_add_f32_e32 v152, 1.0, v152
	v_rcp_f32_e32 v152, v152
	s_nop 0
	v_mul_f32_e32 v152, v151, v152
	v_cndmask_b32_e32 v151, v151, v152, vcc
	v_mul_f32_e32 v152, v69, v150
	v_mul_f32_e32 v153, 0xbfb8aa3b, v152
	v_exp_f32_e32 v153, v153
	s_nop 0
	v_add_f32_e32 v153, 1.0, v153
	v_rcp_f32_e32 v153, v153
	s_nop 0
	v_mul_f32_e32 v153, v152, v153
	v_cndmask_b32_e32 v152, v152, v153, vcc
	v_mul_f32_e32 v153, v70, v150
	v_mul_f32_e32 v154, 0xbfb8aa3b, v153
	v_exp_f32_e32 v154, v154
	v_cvt_pk_bf16_f32 v148, v151, v152
	v_add_f32_e32 v154, 1.0, v154
	v_rcp_f32_e32 v154, v154
	s_nop 0
	v_mul_f32_e32 v154, v153, v154
	v_cndmask_b32_e32 v153, v153, v154, vcc
	v_mul_f32_e32 v154, v71, v150
	v_mul_f32_e32 v155, 0xbfb8aa3b, v154
	v_exp_f32_e32 v155, v155
	s_nop 0
	v_add_f32_e32 v155, 1.0, v155
	v_rcp_f32_e32 v155, v155
	s_nop 0
	v_mul_f32_e32 v155, v154, v155
	v_cndmask_b32_e32 v154, v154, v155, vcc
	v_cvt_pk_bf16_f32 v149, v153, v154
	global_store_dwordx4 v[144:145], v[146:149], off nt
	s_nop 1
	v_mul_f32_e32 v146, v72, v150
	v_mul_f32_e32 v147, 0xbfb8aa3b, v146
	v_exp_f32_e32 v147, v147
	s_nop 0
	v_add_f32_e32 v147, 1.0, v147
	v_rcp_f32_e32 v147, v147
	s_nop 0
	v_mul_f32_e32 v147, v146, v147
	v_cndmask_b32_e32 v146, v146, v147, vcc
	v_mul_f32_e32 v147, v73, v150
	v_mul_f32_e32 v148, 0xbfb8aa3b, v147
	v_exp_f32_e32 v148, v148
	s_nop 0
	v_add_f32_e32 v148, 1.0, v148
	v_rcp_f32_e32 v148, v148
	s_nop 0
	v_mul_f32_e32 v148, v147, v148
	v_cndmask_b32_e32 v147, v147, v148, vcc
	v_mul_f32_e32 v148, v74, v150
	v_mul_f32_e32 v149, 0xbfb8aa3b, v148
	v_exp_f32_e32 v149, v149
	v_cvt_pk_bf16_f32 v146, v146, v147
	v_add_f32_e32 v149, 1.0, v149
	v_rcp_f32_e32 v149, v149
	s_nop 0
	v_mul_f32_e32 v149, v148, v149
	v_cndmask_b32_e32 v148, v148, v149, vcc
	v_mul_f32_e32 v149, v75, v150
	v_mul_f32_e32 v151, 0xbfb8aa3b, v149
	v_exp_f32_e32 v151, v151
	s_nop 0
	v_add_f32_e32 v151, 1.0, v151
	v_rcp_f32_e32 v151, v151
	s_nop 0
	v_mul_f32_e32 v151, v149, v151
	v_cndmask_b32_e32 v149, v149, v151, vcc
	v_mul_f32_e32 v151, v64, v150
	v_mul_f32_e32 v152, 0xbfb8aa3b, v151
	v_exp_f32_e32 v152, v152
	v_cvt_pk_bf16_f32 v147, v148, v149
	v_add_f32_e32 v152, 1.0, v152
	v_rcp_f32_e32 v152, v152
	s_nop 0
	v_mul_f32_e32 v152, v151, v152
	v_cndmask_b32_e32 v151, v151, v152, vcc
	v_mul_f32_e32 v152, v65, v150
	v_mul_f32_e32 v153, 0xbfb8aa3b, v152
	v_exp_f32_e32 v153, v153
	s_nop 0
	v_add_f32_e32 v153, 1.0, v153
	v_rcp_f32_e32 v153, v153
	s_nop 0
	v_mul_f32_e32 v153, v152, v153
	v_cndmask_b32_e32 v152, v152, v153, vcc
	v_mul_f32_e32 v153, v66, v150
	v_mul_f32_e32 v154, 0xbfb8aa3b, v153
	v_exp_f32_e32 v154, v154
	v_mul_f32_e32 v150, v67, v150
	v_cvt_pk_bf16_f32 v148, v151, v152
	v_add_f32_e32 v154, 1.0, v154
	v_rcp_f32_e32 v154, v154
	s_nop 0
	v_mul_f32_e32 v154, v153, v154
	v_cndmask_b32_e32 v153, v153, v154, vcc
	v_mul_f32_e32 v154, 0xbfb8aa3b, v150
	v_exp_f32_e32 v154, v154
	s_nop 0
	v_add_f32_e32 v154, 1.0, v154
	v_rcp_f32_e32 v154, v154
	s_nop 0
	v_mul_f32_e32 v154, v150, v154
	v_cndmask_b32_e32 v150, v150, v154, vcc
	v_cvt_pk_bf16_f32 v149, v153, v150
	global_store_dwordx4 v[144:145], v[146:149], off offset:256 nt
	s_nop 1
	v_mov_b64_e32 v[144:145], v[204:205]
	v_ffbh_u32_e32 v146, v145
	v_min_u32_e32 v146, 32, v146
	v_lshlrev_b64 v[144:145], v146, v[144:145]
	v_min_u32_e32 v144, 1, v144
	v_or_b32_e32 v144, v145, v144
	v_cvt_f32_u32_e32 v144, v144
	v_sub_u32_e32 v145, 32, v146
	v_ldexp_f32 v144, v144, v145
	v_mul_f32_e32 v144, 0x35800000, v144
	v_fmamk_f32 v144, v144, 0x3a800000, v219
	v_rsq_f32_e32 v152, v144
	v_lshl_add_u64 v[144:145], v[128:129], 0, s[0:1]
	s_mov_b32 s0, 0x20000
	v_mul_f32_e32 v146, v60, v152
	v_mul_f32_e32 v147, 0xbfb8aa3b, v146
	v_exp_f32_e32 v147, v147
	s_nop 0
	v_add_f32_e32 v147, 1.0, v147
	v_rcp_f32_e32 v147, v147
	s_nop 0
	v_mul_f32_e32 v147, v146, v147
	v_cndmask_b32_e32 v146, v146, v147, vcc
	v_mul_f32_e32 v147, v61, v152
	v_mul_f32_e32 v148, 0xbfb8aa3b, v147
	v_exp_f32_e32 v148, v148
	s_nop 0
	v_add_f32_e32 v148, 1.0, v148
	v_rcp_f32_e32 v148, v148
	s_nop 0
	v_mul_f32_e32 v148, v147, v148
	v_cndmask_b32_e32 v147, v147, v148, vcc
	v_mul_f32_e32 v148, v62, v152
	v_mul_f32_e32 v149, 0xbfb8aa3b, v148
	v_exp_f32_e32 v149, v149
	v_cvt_pk_bf16_f32 v146, v146, v147
	v_add_f32_e32 v149, 1.0, v149
	v_rcp_f32_e32 v149, v149
	s_nop 0
	v_mul_f32_e32 v149, v148, v149
	v_cndmask_b32_e32 v148, v148, v149, vcc
	v_mul_f32_e32 v149, v63, v152
	v_mul_f32_e32 v150, 0xbfb8aa3b, v149
	v_exp_f32_e32 v150, v150
	s_nop 0
	v_add_f32_e32 v150, 1.0, v150
	v_rcp_f32_e32 v150, v150
	s_nop 0
	v_mul_f32_e32 v150, v149, v150
	v_cndmask_b32_e32 v149, v149, v150, vcc
	v_mul_f32_e32 v150, v52, v152
	v_mul_f32_e32 v151, 0xbfb8aa3b, v150
	v_exp_f32_e32 v151, v151
	v_cvt_pk_bf16_f32 v147, v148, v149
	v_add_f32_e32 v151, 1.0, v151
	v_rcp_f32_e32 v151, v151
	s_nop 0
	v_mul_f32_e32 v151, v150, v151
	v_cndmask_b32_e32 v150, v150, v151, vcc
	v_mul_f32_e32 v151, v53, v152
	v_mul_f32_e32 v153, 0xbfb8aa3b, v151
	v_exp_f32_e32 v153, v153
	s_nop 0
	v_add_f32_e32 v153, 1.0, v153
	v_rcp_f32_e32 v153, v153
	s_nop 0
	v_mul_f32_e32 v153, v151, v153
	v_cndmask_b32_e32 v151, v151, v153, vcc
	v_mul_f32_e32 v153, v54, v152
	v_mul_f32_e32 v154, 0xbfb8aa3b, v153
	v_exp_f32_e32 v154, v154
	v_cvt_pk_bf16_f32 v148, v150, v151
	v_add_co_u32_e64 v150, s[0:1], s0, v128
	v_add_f32_e32 v154, 1.0, v154
	v_rcp_f32_e32 v154, v154
	v_addc_co_u32_e64 v151, s[0:1], 0, v129, s[0:1]
	s_mov_b64 s[0:1], 0x24000
	v_mul_f32_e32 v154, v153, v154
	v_cndmask_b32_e32 v153, v153, v154, vcc
	v_mul_f32_e32 v154, v55, v152
	v_mul_f32_e32 v155, 0xbfb8aa3b, v154
	v_exp_f32_e32 v155, v155
	s_nop 0
	v_add_f32_e32 v155, 1.0, v155
	v_rcp_f32_e32 v155, v155
	s_nop 0
	v_mul_f32_e32 v155, v154, v155
	v_cndmask_b32_e32 v154, v154, v155, vcc
	v_cvt_pk_bf16_f32 v149, v153, v154
	global_store_dwordx4 v[150:151], v[146:149], off nt
	s_nop 1
	v_mul_f32_e32 v146, v56, v152
	v_mul_f32_e32 v147, 0xbfb8aa3b, v146
	v_exp_f32_e32 v147, v147
	s_nop 0
	v_add_f32_e32 v147, 1.0, v147
	v_rcp_f32_e32 v147, v147
	s_nop 0
	v_mul_f32_e32 v147, v146, v147
	v_cndmask_b32_e32 v146, v146, v147, vcc
	v_mul_f32_e32 v147, v57, v152
	v_mul_f32_e32 v148, 0xbfb8aa3b, v147
	v_exp_f32_e32 v148, v148
	s_nop 0
	v_add_f32_e32 v148, 1.0, v148
	v_rcp_f32_e32 v148, v148
	s_nop 0
	v_mul_f32_e32 v148, v147, v148
	v_cndmask_b32_e32 v147, v147, v148, vcc
	v_mul_f32_e32 v148, v58, v152
	v_mul_f32_e32 v149, 0xbfb8aa3b, v148
	v_exp_f32_e32 v149, v149
	v_cvt_pk_bf16_f32 v146, v146, v147
	v_add_f32_e32 v149, 1.0, v149
	v_rcp_f32_e32 v149, v149
	s_nop 0
	v_mul_f32_e32 v149, v148, v149
	v_cndmask_b32_e32 v148, v148, v149, vcc
	v_mul_f32_e32 v149, v59, v152
	v_mul_f32_e32 v150, 0xbfb8aa3b, v149
	v_exp_f32_e32 v150, v150
	s_nop 0
	v_add_f32_e32 v150, 1.0, v150
	v_rcp_f32_e32 v150, v150
	s_nop 0
	v_mul_f32_e32 v150, v149, v150
	v_cndmask_b32_e32 v149, v149, v150, vcc
	v_mul_f32_e32 v150, v48, v152
	v_mul_f32_e32 v151, 0xbfb8aa3b, v150
	v_exp_f32_e32 v151, v151
	v_cvt_pk_bf16_f32 v147, v148, v149
	v_add_f32_e32 v151, 1.0, v151
	v_rcp_f32_e32 v151, v151
	s_nop 0
	v_mul_f32_e32 v151, v150, v151
	v_cndmask_b32_e32 v150, v150, v151, vcc
	v_mul_f32_e32 v151, v49, v152
	v_mul_f32_e32 v153, 0xbfb8aa3b, v151
	v_exp_f32_e32 v153, v153
	s_nop 0
	v_add_f32_e32 v153, 1.0, v153
	v_rcp_f32_e32 v153, v153
	s_nop 0
	v_mul_f32_e32 v153, v151, v153
	v_cndmask_b32_e32 v151, v151, v153, vcc
	v_mul_f32_e32 v153, v50, v152
	v_mul_f32_e32 v154, 0xbfb8aa3b, v153
	v_exp_f32_e32 v154, v154
	v_mul_f32_e32 v152, v51, v152
	v_cvt_pk_bf16_f32 v148, v150, v151
	v_add_f32_e32 v154, 1.0, v154
	v_rcp_f32_e32 v154, v154
	s_nop 0
	v_mul_f32_e32 v154, v153, v154
	v_cndmask_b32_e32 v153, v153, v154, vcc
	v_mul_f32_e32 v154, 0xbfb8aa3b, v152
	v_exp_f32_e32 v154, v154
	s_nop 0
	v_add_f32_e32 v154, 1.0, v154
	v_rcp_f32_e32 v154, v154
	s_nop 0
	v_mul_f32_e32 v154, v152, v154
	v_cndmask_b32_e32 v152, v152, v154, vcc
	v_cvt_pk_bf16_f32 v149, v153, v152
	global_store_dwordx4 v[144:145], v[146:149], off offset:256 nt
	s_nop 1
	v_mov_b64_e32 v[144:145], v[206:207]
	v_ffbh_u32_e32 v146, v145
	v_min_u32_e32 v146, 32, v146
	v_lshlrev_b64 v[144:145], v146, v[144:145]
	v_min_u32_e32 v144, 1, v144
	v_or_b32_e32 v144, v145, v144
	v_cvt_f32_u32_e32 v144, v144
	v_sub_u32_e32 v145, 32, v146
	v_ldexp_f32 v144, v144, v145
	v_mul_f32_e32 v144, 0x35800000, v144
	v_fmamk_f32 v144, v144, 0x3a800000, v219
	v_rsq_f32_e32 v152, v144
	v_lshl_add_u64 v[144:145], v[128:129], 0, s[0:1]
	s_mov_b32 s0, 0x24000
	v_mul_f32_e32 v146, v44, v152
	v_mul_f32_e32 v147, 0xbfb8aa3b, v146
	v_exp_f32_e32 v147, v147
	s_nop 0
	v_add_f32_e32 v147, 1.0, v147
	v_rcp_f32_e32 v147, v147
	s_nop 0
	v_mul_f32_e32 v147, v146, v147
	v_cndmask_b32_e32 v146, v146, v147, vcc
	v_mul_f32_e32 v147, v45, v152
	v_mul_f32_e32 v148, 0xbfb8aa3b, v147
	v_exp_f32_e32 v148, v148
	s_nop 0
	v_add_f32_e32 v148, 1.0, v148
	v_rcp_f32_e32 v148, v148
	s_nop 0
	v_mul_f32_e32 v148, v147, v148
	v_cndmask_b32_e32 v147, v147, v148, vcc
	v_mul_f32_e32 v148, v46, v152
	v_mul_f32_e32 v149, 0xbfb8aa3b, v148
	v_exp_f32_e32 v149, v149
	v_cvt_pk_bf16_f32 v146, v146, v147
	v_add_f32_e32 v149, 1.0, v149
	v_rcp_f32_e32 v149, v149
	s_nop 0
	v_mul_f32_e32 v149, v148, v149
	v_cndmask_b32_e32 v148, v148, v149, vcc
	v_mul_f32_e32 v149, v47, v152
	v_mul_f32_e32 v150, 0xbfb8aa3b, v149
	v_exp_f32_e32 v150, v150
	s_nop 0
	v_add_f32_e32 v150, 1.0, v150
	v_rcp_f32_e32 v150, v150
	s_nop 0
	v_mul_f32_e32 v150, v149, v150
	v_cndmask_b32_e32 v149, v149, v150, vcc
	v_mul_f32_e32 v150, v36, v152
	v_mul_f32_e32 v151, 0xbfb8aa3b, v150
	v_exp_f32_e32 v151, v151
	v_cvt_pk_bf16_f32 v147, v148, v149
	v_add_f32_e32 v151, 1.0, v151
	v_rcp_f32_e32 v151, v151
	s_nop 0
	v_mul_f32_e32 v151, v150, v151
	v_cndmask_b32_e32 v150, v150, v151, vcc
	v_mul_f32_e32 v151, v37, v152
	v_mul_f32_e32 v153, 0xbfb8aa3b, v151
	v_exp_f32_e32 v153, v153
	s_nop 0
	v_add_f32_e32 v153, 1.0, v153
	v_rcp_f32_e32 v153, v153
	s_nop 0
	v_mul_f32_e32 v153, v151, v153
	v_cndmask_b32_e32 v151, v151, v153, vcc
	v_mul_f32_e32 v153, v38, v152
	v_mul_f32_e32 v154, 0xbfb8aa3b, v153
	v_exp_f32_e32 v154, v154
	v_cvt_pk_bf16_f32 v148, v150, v151
	v_add_co_u32_e64 v150, s[0:1], s0, v128
	v_add_f32_e32 v154, 1.0, v154
	v_rcp_f32_e32 v154, v154
	v_addc_co_u32_e64 v151, s[0:1], 0, v129, s[0:1]
	s_mov_b64 s[0:1], 0x28000
	v_mul_f32_e32 v154, v153, v154
	v_cndmask_b32_e32 v153, v153, v154, vcc
	v_mul_f32_e32 v154, v39, v152
	v_mul_f32_e32 v155, 0xbfb8aa3b, v154
	v_exp_f32_e32 v155, v155
	s_nop 0
	v_add_f32_e32 v155, 1.0, v155
	v_rcp_f32_e32 v155, v155
	s_nop 0
	v_mul_f32_e32 v155, v154, v155
	v_cndmask_b32_e32 v154, v154, v155, vcc
	v_cvt_pk_bf16_f32 v149, v153, v154
	global_store_dwordx4 v[150:151], v[146:149], off nt
	s_nop 1
	v_mul_f32_e32 v146, v40, v152
	v_mul_f32_e32 v147, 0xbfb8aa3b, v146
	v_exp_f32_e32 v147, v147
	s_nop 0
	v_add_f32_e32 v147, 1.0, v147
	v_rcp_f32_e32 v147, v147
	s_nop 0
	v_mul_f32_e32 v147, v146, v147
	v_cndmask_b32_e32 v146, v146, v147, vcc
	v_mul_f32_e32 v147, v41, v152
	v_mul_f32_e32 v148, 0xbfb8aa3b, v147
	v_exp_f32_e32 v148, v148
	s_nop 0
	v_add_f32_e32 v148, 1.0, v148
	v_rcp_f32_e32 v148, v148
	s_nop 0
	v_mul_f32_e32 v148, v147, v148
	v_cndmask_b32_e32 v147, v147, v148, vcc
	v_mul_f32_e32 v148, v42, v152
	v_mul_f32_e32 v149, 0xbfb8aa3b, v148
	v_exp_f32_e32 v149, v149
	v_cvt_pk_bf16_f32 v146, v146, v147
	v_add_f32_e32 v149, 1.0, v149
	v_rcp_f32_e32 v149, v149
	s_nop 0
	v_mul_f32_e32 v149, v148, v149
	v_cndmask_b32_e32 v148, v148, v149, vcc
	v_mul_f32_e32 v149, v43, v152
	v_mul_f32_e32 v150, 0xbfb8aa3b, v149
	v_exp_f32_e32 v150, v150
	s_nop 0
	v_add_f32_e32 v150, 1.0, v150
	v_rcp_f32_e32 v150, v150
	s_nop 0
	v_mul_f32_e32 v150, v149, v150
	v_cndmask_b32_e32 v149, v149, v150, vcc
	v_mul_f32_e32 v150, v32, v152
	v_mul_f32_e32 v151, 0xbfb8aa3b, v150
	v_exp_f32_e32 v151, v151
	v_cvt_pk_bf16_f32 v147, v148, v149
	v_add_f32_e32 v151, 1.0, v151
	v_rcp_f32_e32 v151, v151
	s_nop 0
	v_mul_f32_e32 v151, v150, v151
	v_cndmask_b32_e32 v150, v150, v151, vcc
	v_mul_f32_e32 v151, v33, v152
	v_mul_f32_e32 v153, 0xbfb8aa3b, v151
	v_exp_f32_e32 v153, v153
	s_nop 0
	v_add_f32_e32 v153, 1.0, v153
	v_rcp_f32_e32 v153, v153
	s_nop 0
	v_mul_f32_e32 v153, v151, v153
	v_cndmask_b32_e32 v151, v151, v153, vcc
	v_mul_f32_e32 v153, v34, v152
	v_mul_f32_e32 v154, 0xbfb8aa3b, v153
	v_exp_f32_e32 v154, v154
	v_mul_f32_e32 v152, v35, v152
	v_cvt_pk_bf16_f32 v148, v150, v151
	v_add_f32_e32 v154, 1.0, v154
	v_rcp_f32_e32 v154, v154
	s_nop 0
	v_mul_f32_e32 v154, v153, v154
	v_cndmask_b32_e32 v153, v153, v154, vcc
	v_mul_f32_e32 v154, 0xbfb8aa3b, v152
	v_exp_f32_e32 v154, v154
	s_nop 0
	v_add_f32_e32 v154, 1.0, v154
	v_rcp_f32_e32 v154, v154
	s_nop 0
	v_mul_f32_e32 v154, v152, v154
	v_cndmask_b32_e32 v152, v152, v154, vcc
	v_cvt_pk_bf16_f32 v149, v153, v152
	global_store_dwordx4 v[144:145], v[146:149], off offset:256 nt
	s_nop 1
	v_mov_b64_e32 v[144:145], v[208:209]
	v_ffbh_u32_e32 v146, v145
	v_min_u32_e32 v146, 32, v146
	v_lshlrev_b64 v[144:145], v146, v[144:145]
	v_min_u32_e32 v144, 1, v144
	v_or_b32_e32 v144, v145, v144
	v_cvt_f32_u32_e32 v144, v144
	v_sub_u32_e32 v145, 32, v146
	v_ldexp_f32 v144, v144, v145
	v_mul_f32_e32 v144, 0x35800000, v144
	v_fmamk_f32 v144, v144, 0x3a800000, v219
	v_rsq_f32_e32 v152, v144
	v_lshl_add_u64 v[144:145], v[128:129], 0, s[0:1]
	s_mov_b32 s0, 0x28000
	v_mul_f32_e32 v146, v28, v152
	v_mul_f32_e32 v147, 0xbfb8aa3b, v146
	v_exp_f32_e32 v147, v147
	s_nop 0
	v_add_f32_e32 v147, 1.0, v147
	v_rcp_f32_e32 v147, v147
	s_nop 0
	v_mul_f32_e32 v147, v146, v147
	v_cndmask_b32_e32 v146, v146, v147, vcc
	v_mul_f32_e32 v147, v29, v152
	v_mul_f32_e32 v148, 0xbfb8aa3b, v147
	v_exp_f32_e32 v148, v148
	s_nop 0
	v_add_f32_e32 v148, 1.0, v148
	v_rcp_f32_e32 v148, v148
	s_nop 0
	v_mul_f32_e32 v148, v147, v148
	v_cndmask_b32_e32 v147, v147, v148, vcc
	v_mul_f32_e32 v148, v30, v152
	v_mul_f32_e32 v149, 0xbfb8aa3b, v148
	v_exp_f32_e32 v149, v149
	v_cvt_pk_bf16_f32 v146, v146, v147
	v_add_f32_e32 v149, 1.0, v149
	v_rcp_f32_e32 v149, v149
	s_nop 0
	v_mul_f32_e32 v149, v148, v149
	v_cndmask_b32_e32 v148, v148, v149, vcc
	v_mul_f32_e32 v149, v31, v152
	v_mul_f32_e32 v150, 0xbfb8aa3b, v149
	v_exp_f32_e32 v150, v150
	s_nop 0
	v_add_f32_e32 v150, 1.0, v150
	v_rcp_f32_e32 v150, v150
	s_nop 0
	v_mul_f32_e32 v150, v149, v150
	v_cndmask_b32_e32 v149, v149, v150, vcc
	v_mul_f32_e32 v150, v20, v152
	v_mul_f32_e32 v151, 0xbfb8aa3b, v150
	v_exp_f32_e32 v151, v151
	v_cvt_pk_bf16_f32 v147, v148, v149
	v_add_f32_e32 v151, 1.0, v151
	v_rcp_f32_e32 v151, v151
	s_nop 0
	v_mul_f32_e32 v151, v150, v151
	v_cndmask_b32_e32 v150, v150, v151, vcc
	v_mul_f32_e32 v151, v21, v152
	v_mul_f32_e32 v153, 0xbfb8aa3b, v151
	v_exp_f32_e32 v153, v153
	s_nop 0
	v_add_f32_e32 v153, 1.0, v153
	v_rcp_f32_e32 v153, v153
	s_nop 0
	v_mul_f32_e32 v153, v151, v153
	v_cndmask_b32_e32 v151, v151, v153, vcc
	v_mul_f32_e32 v153, v22, v152
	v_mul_f32_e32 v154, 0xbfb8aa3b, v153
	v_exp_f32_e32 v154, v154
	v_cvt_pk_bf16_f32 v148, v150, v151
	v_add_co_u32_e64 v150, s[0:1], s0, v128
	v_add_f32_e32 v154, 1.0, v154
	v_rcp_f32_e32 v154, v154
	v_addc_co_u32_e64 v151, s[0:1], 0, v129, s[0:1]
	s_mov_b64 s[0:1], 0x2c000
	v_mul_f32_e32 v154, v153, v154
	v_cndmask_b32_e32 v153, v153, v154, vcc
	v_mul_f32_e32 v154, v23, v152
	v_mul_f32_e32 v155, 0xbfb8aa3b, v154
	v_exp_f32_e32 v155, v155
	s_nop 0
	v_add_f32_e32 v155, 1.0, v155
	v_rcp_f32_e32 v155, v155
	s_nop 0
	v_mul_f32_e32 v155, v154, v155
	v_cndmask_b32_e32 v154, v154, v155, vcc
	v_cvt_pk_bf16_f32 v149, v153, v154
	global_store_dwordx4 v[150:151], v[146:149], off nt
	s_nop 1
	v_mul_f32_e32 v146, v24, v152
	v_mul_f32_e32 v147, 0xbfb8aa3b, v146
	v_exp_f32_e32 v147, v147
	s_nop 0
	v_add_f32_e32 v147, 1.0, v147
	v_rcp_f32_e32 v147, v147
	s_nop 0
	v_mul_f32_e32 v147, v146, v147
	v_cndmask_b32_e32 v146, v146, v147, vcc
	v_mul_f32_e32 v147, v25, v152
	v_mul_f32_e32 v148, 0xbfb8aa3b, v147
	v_exp_f32_e32 v148, v148
	s_nop 0
	v_add_f32_e32 v148, 1.0, v148
	v_rcp_f32_e32 v148, v148
	s_nop 0
	v_mul_f32_e32 v148, v147, v148
	v_cndmask_b32_e32 v147, v147, v148, vcc
	v_mul_f32_e32 v148, v26, v152
	v_mul_f32_e32 v149, 0xbfb8aa3b, v148
	v_exp_f32_e32 v149, v149
	v_cvt_pk_bf16_f32 v146, v146, v147
	v_add_f32_e32 v149, 1.0, v149
	v_rcp_f32_e32 v149, v149
	s_nop 0
	v_mul_f32_e32 v149, v148, v149
	v_cndmask_b32_e32 v148, v148, v149, vcc
	v_mul_f32_e32 v149, v27, v152
	v_mul_f32_e32 v150, 0xbfb8aa3b, v149
	v_exp_f32_e32 v150, v150
	s_nop 0
	v_add_f32_e32 v150, 1.0, v150
	v_rcp_f32_e32 v150, v150
	s_nop 0
	v_mul_f32_e32 v150, v149, v150
	v_cndmask_b32_e32 v149, v149, v150, vcc
	v_mul_f32_e32 v150, v16, v152
	v_mul_f32_e32 v151, 0xbfb8aa3b, v150
	v_exp_f32_e32 v151, v151
	v_cvt_pk_bf16_f32 v147, v148, v149
	v_add_f32_e32 v151, 1.0, v151
	v_rcp_f32_e32 v151, v151
	s_nop 0
	v_mul_f32_e32 v151, v150, v151
	v_cndmask_b32_e32 v150, v150, v151, vcc
	v_mul_f32_e32 v151, v17, v152
	v_mul_f32_e32 v153, 0xbfb8aa3b, v151
	v_exp_f32_e32 v153, v153
	s_nop 0
	v_add_f32_e32 v153, 1.0, v153
	v_rcp_f32_e32 v153, v153
	s_nop 0
	v_mul_f32_e32 v153, v151, v153
	v_cndmask_b32_e32 v151, v151, v153, vcc
	v_mul_f32_e32 v153, v18, v152
	v_mul_f32_e32 v154, 0xbfb8aa3b, v153
	v_exp_f32_e32 v154, v154
	v_mul_f32_e32 v152, v19, v152
	v_cvt_pk_bf16_f32 v148, v150, v151
	v_add_f32_e32 v154, 1.0, v154
	v_rcp_f32_e32 v154, v154
	s_nop 0
	v_mul_f32_e32 v154, v153, v154
	v_cndmask_b32_e32 v153, v153, v154, vcc
	v_mul_f32_e32 v154, 0xbfb8aa3b, v152
	v_exp_f32_e32 v154, v154
	s_nop 0
	v_add_f32_e32 v154, 1.0, v154
	v_rcp_f32_e32 v154, v154
	s_nop 0
	v_mul_f32_e32 v154, v152, v154
	v_cndmask_b32_e32 v152, v152, v154, vcc
	v_cvt_pk_bf16_f32 v149, v153, v152
	global_store_dwordx4 v[144:145], v[146:149], off offset:256 nt
	s_nop 1
	v_mov_b64_e32 v[130:131], v[210:211]
	v_ffbh_u32_e32 v144, v131
	v_min_u32_e32 v144, 32, v144
	v_lshlrev_b64 v[130:131], v144, v[130:131]
	v_min_u32_e32 v130, 1, v130
	v_or_b32_e32 v130, v131, v130
	v_cvt_f32_u32_e32 v130, v130
	v_sub_u32_e32 v131, 32, v144
	v_ldexp_f32 v130, v130, v131
	v_mul_f32_e32 v130, 0x35800000, v130
	v_fmamk_f32 v130, v130, 0x3a800000, v219
	v_rsq_f32_e32 v148, v130
	v_lshl_add_u64 v[130:131], v[128:129], 0, s[0:1]
	s_mov_b32 s0, 0x2c000
	v_add_co_u32_e64 v128, s[0:1], s0, v128
	v_mul_f32_e32 v144, v12, v148
	v_mul_f32_e32 v145, 0xbfb8aa3b, v144
	v_exp_f32_e32 v145, v145
	v_addc_co_u32_e64 v129, s[0:1], 0, v129, s[0:1]
	v_add_f32_e32 v145, 1.0, v145
	v_rcp_f32_e32 v145, v145
	s_nop 0
	v_mul_f32_e32 v145, v144, v145
	v_cndmask_b32_e32 v144, v144, v145, vcc
	v_mul_f32_e32 v145, v13, v148
	v_mul_f32_e32 v146, 0xbfb8aa3b, v145
	v_exp_f32_e32 v146, v146
	s_nop 0
	v_add_f32_e32 v146, 1.0, v146
	v_rcp_f32_e32 v146, v146
	s_nop 0
	v_mul_f32_e32 v146, v145, v146
	v_cndmask_b32_e32 v145, v145, v146, vcc
	v_mul_f32_e32 v146, v14, v148
	v_mul_f32_e32 v147, 0xbfb8aa3b, v146
	v_exp_f32_e32 v147, v147
	v_cvt_pk_bf16_f32 v144, v144, v145
	v_add_f32_e32 v147, 1.0, v147
	v_rcp_f32_e32 v147, v147
	s_nop 0
	v_mul_f32_e32 v147, v146, v147
	v_cndmask_b32_e32 v146, v146, v147, vcc
	v_mul_f32_e32 v147, v15, v148
	v_mul_f32_e32 v149, 0xbfb8aa3b, v147
	v_exp_f32_e32 v149, v149
	s_nop 0
	v_add_f32_e32 v149, 1.0, v149
	v_rcp_f32_e32 v149, v149
	s_nop 0
	v_mul_f32_e32 v149, v147, v149
	v_cndmask_b32_e32 v147, v147, v149, vcc
	v_mul_f32_e32 v149, v4, v148
	v_mul_f32_e32 v150, 0xbfb8aa3b, v149
	v_exp_f32_e32 v150, v150
	v_cvt_pk_bf16_f32 v145, v146, v147
	v_add_f32_e32 v150, 1.0, v150
	v_rcp_f32_e32 v150, v150
	s_nop 0
	v_mul_f32_e32 v150, v149, v150
	v_cndmask_b32_e32 v149, v149, v150, vcc
	v_mul_f32_e32 v150, v5, v148
	v_mul_f32_e32 v151, 0xbfb8aa3b, v150
	v_exp_f32_e32 v151, v151
	s_nop 0
	v_add_f32_e32 v151, 1.0, v151
	v_rcp_f32_e32 v151, v151
	s_nop 0
	v_mul_f32_e32 v151, v150, v151
	v_cndmask_b32_e32 v150, v150, v151, vcc
	v_mul_f32_e32 v151, v6, v148
	v_mul_f32_e32 v152, 0xbfb8aa3b, v151
	v_exp_f32_e32 v152, v152
	v_cvt_pk_bf16_f32 v146, v149, v150
	v_add_f32_e32 v152, 1.0, v152
	v_rcp_f32_e32 v152, v152
	s_nop 0
	v_mul_f32_e32 v152, v151, v152
	v_cndmask_b32_e32 v151, v151, v152, vcc
	v_mul_f32_e32 v152, v7, v148
	v_mul_f32_e32 v153, 0xbfb8aa3b, v152
	v_exp_f32_e32 v153, v153
	s_nop 0
	v_add_f32_e32 v153, 1.0, v153
	v_rcp_f32_e32 v153, v153
	s_nop 0
	v_mul_f32_e32 v153, v152, v153
	v_cndmask_b32_e32 v152, v152, v153, vcc
	v_cvt_pk_bf16_f32 v147, v151, v152
	global_store_dwordx4 v[128:129], v[144:147], off nt
	v_mul_f32_e32 v128, v8, v148
	v_mul_f32_e32 v129, 0xbfb8aa3b, v128
	v_exp_f32_e32 v129, v129
	s_nop 0
	v_add_f32_e32 v129, 1.0, v129
	v_rcp_f32_e32 v129, v129
	s_nop 0
	v_mul_f32_e32 v129, v128, v129
	v_cndmask_b32_e32 v128, v128, v129, vcc
	v_mul_f32_e32 v129, v9, v148
	v_mul_f32_e32 v144, 0xbfb8aa3b, v129
	v_exp_f32_e32 v144, v144
	s_nop 0
	v_add_f32_e32 v144, 1.0, v144
	v_rcp_f32_e32 v144, v144
	s_nop 0
	v_mul_f32_e32 v144, v129, v144
	v_cndmask_b32_e32 v129, v129, v144, vcc
	v_mul_f32_e32 v144, v10, v148
	v_mul_f32_e32 v145, 0xbfb8aa3b, v144
	v_exp_f32_e32 v145, v145
	s_nop 0
	v_add_f32_e32 v145, 1.0, v145
	v_rcp_f32_e32 v145, v145
	s_nop 0
	v_mul_f32_e32 v145, v144, v145
	v_cndmask_b32_e32 v145, v144, v145, vcc
	v_mul_f32_e32 v144, v11, v148
	v_mul_f32_e32 v146, 0xbfb8aa3b, v144
	v_exp_f32_e32 v146, v146
	s_nop 0
	v_add_f32_e32 v146, 1.0, v146
	v_rcp_f32_e32 v146, v146
	s_nop 0
	v_mul_f32_e32 v146, v144, v146
	v_cndmask_b32_e32 v146, v144, v146, vcc
	v_mul_f32_e32 v144, v0, v148
	v_mul_f32_e32 v147, 0xbfb8aa3b, v144
	v_exp_f32_e32 v147, v147
	v_cvt_pk_bf16_f32 v145, v145, v146
	v_add_f32_e32 v147, 1.0, v147
	v_rcp_f32_e32 v147, v147
	s_nop 0
	v_mul_f32_e32 v147, v144, v147
	v_cndmask_b32_e32 v147, v144, v147, vcc
	v_mul_f32_e32 v144, v1, v148
	v_mul_f32_e32 v149, 0xbfb8aa3b, v144
	v_exp_f32_e32 v149, v149
	s_nop 0
	v_add_f32_e32 v149, 1.0, v149
	v_rcp_f32_e32 v149, v149
	s_nop 0
	v_mul_f32_e32 v149, v144, v149
	v_cndmask_b32_e32 v149, v144, v149, vcc
	v_mul_f32_e32 v144, v2, v148
	v_mul_f32_e32 v150, 0xbfb8aa3b, v144
	v_exp_f32_e32 v150, v150
	v_cvt_pk_bf16_f32 v146, v147, v149
	v_add_f32_e32 v150, 1.0, v150
	v_rcp_f32_e32 v150, v150
	s_nop 0
	v_mul_f32_e32 v150, v144, v150
	v_cndmask_b32_e32 v150, v144, v150, vcc
	v_mul_f32_e32 v144, v3, v148
	v_mul_f32_e32 v148, 0xbfb8aa3b, v144
	v_exp_f32_e32 v148, v148
	s_nop 0
	v_add_f32_e32 v148, 1.0, v148
	v_rcp_f32_e32 v148, v148
	s_nop 0
	v_mul_f32_e32 v148, v144, v148
	v_cndmask_b32_e32 v148, v144, v148, vcc
	v_cvt_pk_bf16_f32 v144, v128, v129
	v_cvt_pk_bf16_f32 v147, v150, v148
	global_store_dwordx4 v[130:131], v[144:147], off offset:256 nt

.LBB0_410:
	s_lshl_b32 s0, s35, 1
	s_and_b32 s0, s0, 2
	s_or_b32 s7, s0, s34
	s_cmp_lt_i32 s35, 2
	s_cselect_b64 s[0:1], -1, 0
	v_mov_b32_e32 v128, 0x3db504f3
	v_cndmask_b32_e64 v146, v128, 1.0, s[0:1]
	s_and_b64 s[0:1], s[0:1], exec
	s_mov_b32 s0, 0x9a00000
	s_cselect_b32 s1, s0, 0xda00000
	s_cselect_b32 s0, 10, 9
	s_add_u32 s1, s94, s1
	s_addc_u32 s9, s95, 0
	s_lshl_b32 s7, s7, 8
	v_lshl_add_u32 v130, s44, 8, v156
	s_add_u32 s8, s1, s7
	s_movk_i32 s1, 0x4000
	v_cmp_gt_i32_e32 vcc, s1, v130
	s_addc_u32 s9, s9, 0
	v_lshl_add_u64 v[128:129], s[8:9], 0, v[160:161]
	v_cndmask_b32_e32 v131, v228, v229, vcc
	v_and_b32_e32 v147, v131, v130
	v_ashrrev_i32_e32 v131, 31, v130
	v_lshl_add_u64 v[144:145], v[130:131], 3, s[36:37]
	s_waitcnt vmcnt(0) lgkmcnt(0)
	v_mov_b64_e32 v[148:149], v[196:197]
	v_ffbh_u32_e32 v150, v149
	v_min_u32_e32 v150, 32, v150
	v_lshlrev_b64 v[148:149], v150, v[148:149]
	v_min_u32_e32 v148, 1, v148
	v_or_b32_e32 v148, v149, v148
	v_cvt_f32_u32_e32 v148, v148
	v_sub_u32_e32 v149, 32, v150
	v_ldexp_f32 v148, v148, v149
	v_mul_f32_e32 v148, 0x35800000, v148
	v_fmamk_f32 v148, v148, 0x3a800000, v219
	v_rsq_f32_e32 v148, v148
	v_mov_b32_e32 v149, v161
	v_mul_f32_e32 v162, v146, v148
	v_lshl_or_b32 v148, v147, 9, v174
	v_lshl_add_u64 v[164:165], s[94:95], 0, v[148:149]
	global_load_dwordx4 v[148:151], v[164:165], off
	global_load_dwordx4 v[152:155], v[164:165], off offset:16
	v_pk_mul_f32 v[120:121], v[120:121], v[162:163] op_sel_hi:[1,0]
	v_pk_mul_f32 v[124:125], v[124:125], v[162:163] op_sel_hi:[1,0]
	v_pk_mul_f32 v[122:123], v[122:123], v[162:163] op_sel_hi:[1,0]
	v_pk_mul_f32 v[126:127], v[126:127], v[162:163] op_sel_hi:[1,0]
	v_pk_mul_f32 v[118:119], v[118:119], v[162:163] op_sel_hi:[1,0]
	v_pk_mul_f32 v[116:117], v[116:117], v[162:163] op_sel_hi:[1,0]
	v_pk_mul_f32 v[114:115], v[114:115], v[162:163] op_sel_hi:[1,0]
	v_pk_mul_f32 v[112:113], v[112:113], v[162:163] op_sel_hi:[1,0]
	s_waitcnt vmcnt(0) lgkmcnt(0)
	v_mov_b32_e32 v166, v148
	v_mov_b32_e32 v167, v150
	v_mov_b32_e32 v150, v149
	v_pk_mul_f32 v[148:149], v[150:151], v[120:121]
	v_pk_mul_f32 v[120:121], v[166:167], v[120:121]
	v_pk_fma_f32 v[148:149], v[166:167], v[124:125], v[148:149] neg_lo:[0,0,1] neg_hi:[0,0,1]
	v_pk_fma_f32 v[150:151], v[150:151], v[124:125], v[120:121]
	v_mov_b32_e32 v121, v154
	v_mov_b32_e32 v154, v153
	v_mov_b32_e32 v120, v152
	v_pk_mul_f32 v[124:125], v[154:155], v[122:123]
	s_nop 0
	v_pk_fma_f32 v[152:153], v[120:121], v[126:127], v[124:125] neg_lo:[0,0,1] neg_hi:[0,0,1]
	v_pk_mul_f32 v[120:121], v[120:121], v[122:123]
	s_nop 0
	v_pk_fma_f32 v[154:155], v[154:155], v[126:127], v[120:121]
	global_load_dwordx4 v[120:123], v[164:165], off offset:32
	global_load_dwordx4 v[124:127], v[164:165], off offset:48
	s_waitcnt vmcnt(0) lgkmcnt(0)
	v_mov_b32_e32 v162, v120
	v_mov_b32_e32 v163, v122
	v_mov_b32_e32 v122, v121
	v_pk_mul_f32 v[120:121], v[122:123], v[112:113]
	v_pk_mul_f32 v[112:113], v[162:163], v[112:113]
	v_pk_fma_f32 v[120:121], v[162:163], v[116:117], v[120:121] neg_lo:[0,0,1] neg_hi:[0,0,1]
	v_pk_fma_f32 v[116:117], v[122:123], v[116:117], v[112:113]
	v_mov_b32_e32 v113, v126
	v_mov_b32_e32 v126, v125
	v_mov_b32_e32 v112, v124
	v_pk_mul_f32 v[122:123], v[126:127], v[114:115]
	s_nop 0
	v_pk_fma_f32 v[122:123], v[112:113], v[118:119], v[122:123] neg_lo:[0,0,1] neg_hi:[0,0,1]
	v_pk_mul_f32 v[112:113], v[112:113], v[114:115]
	v_cvt_pk_bf16_f32 v114, v120, v121
	v_pk_fma_f32 v[118:119], v[126:127], v[118:119], v[112:113]
	v_lshlrev_b64 v[112:113], s0, v[130:131]
	v_lshl_add_u64 v[124:125], v[112:113], 1, v[128:129]
	v_cvt_pk_bf16_f32 v112, v148, v149
	v_cvt_pk_bf16_f32 v113, v152, v153
	v_cvt_pk_bf16_f32 v115, v122, v123
	global_store_dwordx4 v[124:125], v[112:115], off nt
	s_nop 1
	v_cvt_pk_bf16_f32 v112, v150, v151
	v_cvt_pk_bf16_f32 v113, v154, v155
	v_cvt_pk_bf16_f32 v114, v116, v117
	v_cvt_pk_bf16_f32 v115, v118, v119
	global_store_dwordx4 v[124:125], v[112:115], off offset:128 nt
	s_nop 1
	v_or_b32_e32 v112, 16, v130
	v_cmp_gt_i32_e32 vcc, s1, v112
	s_nop 1
	v_cndmask_b32_e32 v113, v230, v231, vcc
	v_bitop3_b32 v116, v113, v130, 16 bitop3:0xe0
	v_ashrrev_i32_e32 v113, 31, v112
	v_lshl_add_u64 v[114:115], v[112:113], 3, s[36:37]
	s_nop 1
	v_mov_b64_e32 v[114:115], v[198:199]
	v_lshl_or_b32 v116, v116, 9, v174
	v_ffbh_u32_e32 v117, v115
	v_min_u32_e32 v117, 32, v117
	v_lshlrev_b64 v[114:115], v117, v[114:115]
	v_min_u32_e32 v114, 1, v114
	v_or_b32_e32 v114, v115, v114
	v_sub_u32_e32 v115, 32, v117
	v_mov_b32_e32 v117, v161
	v_lshl_add_u64 v[116:117], s[94:95], 0, v[116:117]
	global_load_dwordx4 v[118:121], v[116:117], off
	global_load_dwordx4 v[122:125], v[116:117], off offset:16
	v_cvt_f32_u32_e32 v114, v114
	v_ldexp_f32 v114, v114, v115
	v_mul_f32_e32 v114, 0x35800000, v114
	v_fmamk_f32 v114, v114, 0x3a800000, v219
	v_rsq_f32_e32 v114, v114
	s_waitcnt vmcnt(0) lgkmcnt(0)
	v_mov_b32_e32 v126, v118
	v_mul_f32_e32 v114, v146, v114
	v_pk_mul_f32 v[104:105], v[104:105], v[114:115] op_sel_hi:[1,0]
	v_mov_b32_e32 v127, v120
	v_mov_b32_e32 v120, v119
	v_pk_mul_f32 v[108:109], v[108:109], v[114:115] op_sel_hi:[1,0]
	v_pk_mul_f32 v[118:119], v[120:121], v[104:105]
	v_pk_mul_f32 v[104:105], v[126:127], v[104:105]
	v_pk_mul_f32 v[106:107], v[106:107], v[114:115] op_sel_hi:[1,0]
	v_pk_fma_f32 v[120:121], v[120:121], v[108:109], v[104:105]
	v_mov_b32_e32 v105, v124
	v_mov_b32_e32 v124, v123
	v_pk_mul_f32 v[110:111], v[110:111], v[114:115] op_sel_hi:[1,0]
	v_pk_fma_f32 v[118:119], v[126:127], v[108:109], v[118:119] neg_lo:[0,0,1] neg_hi:[0,0,1]
	v_mov_b32_e32 v104, v122
	v_pk_mul_f32 v[108:109], v[124:125], v[106:107]
	v_pk_mul_f32 v[102:103], v[102:103], v[114:115] op_sel_hi:[1,0]
	v_pk_fma_f32 v[122:123], v[104:105], v[110:111], v[108:109] neg_lo:[0,0,1] neg_hi:[0,0,1]
	v_pk_mul_f32 v[104:105], v[104:105], v[106:107]
	v_pk_mul_f32 v[100:101], v[100:101], v[114:115] op_sel_hi:[1,0]
	v_pk_fma_f32 v[124:125], v[124:125], v[110:111], v[104:105]
	global_load_dwordx4 v[104:107], v[116:117], off offset:32
	global_load_dwordx4 v[108:111], v[116:117], off offset:48
	v_pk_mul_f32 v[98:99], v[98:99], v[114:115] op_sel_hi:[1,0]
	v_pk_mul_f32 v[96:97], v[96:97], v[114:115] op_sel_hi:[1,0]
	s_waitcnt vmcnt(0) lgkmcnt(0)
	v_mov_b32_e32 v114, v104
	v_mov_b32_e32 v115, v106
	v_mov_b32_e32 v106, v105
	v_pk_mul_f32 v[104:105], v[106:107], v[96:97]
	v_pk_mul_f32 v[96:97], v[114:115], v[96:97]
	v_pk_fma_f32 v[104:105], v[114:115], v[100:101], v[104:105] neg_lo:[0,0,1] neg_hi:[0,0,1]
	v_pk_fma_f32 v[100:101], v[106:107], v[100:101], v[96:97]
	v_mov_b32_e32 v97, v110
	v_mov_b32_e32 v110, v109
	v_mov_b32_e32 v96, v108
	v_pk_mul_f32 v[106:107], v[110:111], v[98:99]
	s_nop 0
	v_pk_fma_f32 v[106:107], v[96:97], v[102:103], v[106:107] neg_lo:[0,0,1] neg_hi:[0,0,1]
	v_pk_mul_f32 v[96:97], v[96:97], v[98:99]
	v_cvt_pk_bf16_f32 v98, v104, v105
	v_pk_fma_f32 v[102:103], v[110:111], v[102:103], v[96:97]
	v_lshlrev_b64 v[96:97], s0, v[112:113]
	v_lshl_add_u64 v[108:109], v[96:97], 1, v[128:129]
	v_cvt_pk_bf16_f32 v96, v118, v119
	v_cvt_pk_bf16_f32 v97, v122, v123
	v_cvt_pk_bf16_f32 v99, v106, v107
	global_store_dwordx4 v[108:109], v[96:99], off nt
	s_nop 1
	v_cvt_pk_bf16_f32 v96, v120, v121
	v_cvt_pk_bf16_f32 v97, v124, v125
	v_cvt_pk_bf16_f32 v98, v100, v101
	v_cvt_pk_bf16_f32 v99, v102, v103
	global_store_dwordx4 v[108:109], v[96:99], off offset:128 nt
	s_nop 1
	v_or_b32_e32 v96, 32, v130
	v_cmp_gt_i32_e32 vcc, s1, v96
	s_nop 1
	v_cndmask_b32_e32 v97, v222, v236, vcc
	v_bitop3_b32 v100, v97, v130, 32 bitop3:0xe0
	v_ashrrev_i32_e32 v97, 31, v96
	v_lshl_add_u64 v[98:99], v[96:97], 3, s[36:37]
	s_nop 1
	v_mov_b64_e32 v[98:99], v[200:201]
	v_lshl_or_b32 v100, v100, 9, v174
	v_ffbh_u32_e32 v101, v99
	v_min_u32_e32 v101, 32, v101
	v_lshlrev_b64 v[98:99], v101, v[98:99]
	v_min_u32_e32 v98, 1, v98
	v_or_b32_e32 v98, v99, v98
	v_sub_u32_e32 v99, 32, v101
	v_mov_b32_e32 v101, v161
	v_lshl_add_u64 v[100:101], s[94:95], 0, v[100:101]
	global_load_dwordx4 v[102:105], v[100:101], off
	global_load_dwordx4 v[106:109], v[100:101], off offset:16
	v_cvt_f32_u32_e32 v98, v98
	v_ldexp_f32 v98, v98, v99
	v_mul_f32_e32 v98, 0x35800000, v98
	v_fmamk_f32 v98, v98, 0x3a800000, v219
	v_rsq_f32_e32 v98, v98
	s_waitcnt vmcnt(0) lgkmcnt(0)
	v_mov_b32_e32 v110, v102
	v_mul_f32_e32 v98, v146, v98
	v_pk_mul_f32 v[88:89], v[88:89], v[98:99] op_sel_hi:[1,0]
	v_mov_b32_e32 v111, v104
	v_mov_b32_e32 v104, v103
	v_pk_mul_f32 v[92:93], v[92:93], v[98:99] op_sel_hi:[1,0]
	v_pk_mul_f32 v[102:103], v[104:105], v[88:89]
	v_pk_mul_f32 v[88:89], v[110:111], v[88:89]
	v_pk_mul_f32 v[90:91], v[90:91], v[98:99] op_sel_hi:[1,0]
	v_pk_fma_f32 v[104:105], v[104:105], v[92:93], v[88:89]
	v_mov_b32_e32 v89, v108
	v_mov_b32_e32 v108, v107
	v_pk_mul_f32 v[94:95], v[94:95], v[98:99] op_sel_hi:[1,0]
	v_pk_fma_f32 v[102:103], v[110:111], v[92:93], v[102:103] neg_lo:[0,0,1] neg_hi:[0,0,1]
	v_mov_b32_e32 v88, v106
	v_pk_mul_f32 v[92:93], v[108:109], v[90:91]
	v_pk_mul_f32 v[86:87], v[86:87], v[98:99] op_sel_hi:[1,0]
	v_pk_fma_f32 v[106:107], v[88:89], v[94:95], v[92:93] neg_lo:[0,0,1] neg_hi:[0,0,1]
	v_pk_mul_f32 v[88:89], v[88:89], v[90:91]
	v_pk_mul_f32 v[84:85], v[84:85], v[98:99] op_sel_hi:[1,0]
	v_pk_fma_f32 v[108:109], v[108:109], v[94:95], v[88:89]
	global_load_dwordx4 v[88:91], v[100:101], off offset:32
	global_load_dwordx4 v[92:95], v[100:101], off offset:48
	v_pk_mul_f32 v[82:83], v[82:83], v[98:99] op_sel_hi:[1,0]
	v_pk_mul_f32 v[80:81], v[80:81], v[98:99] op_sel_hi:[1,0]
	s_waitcnt vmcnt(0) lgkmcnt(0)
	v_mov_b32_e32 v98, v88
	v_mov_b32_e32 v99, v90
	v_mov_b32_e32 v90, v89
	v_pk_mul_f32 v[88:89], v[90:91], v[80:81]
	v_pk_mul_f32 v[80:81], v[98:99], v[80:81]
	v_pk_fma_f32 v[88:89], v[98:99], v[84:85], v[88:89] neg_lo:[0,0,1] neg_hi:[0,0,1]
	v_pk_fma_f32 v[84:85], v[90:91], v[84:85], v[80:81]
	v_mov_b32_e32 v81, v94
	v_mov_b32_e32 v94, v93
	v_mov_b32_e32 v80, v92
	v_pk_mul_f32 v[90:91], v[94:95], v[82:83]
	s_nop 0
	v_pk_fma_f32 v[90:91], v[80:81], v[86:87], v[90:91] neg_lo:[0,0,1] neg_hi:[0,0,1]
	v_pk_mul_f32 v[80:81], v[80:81], v[82:83]
	v_cvt_pk_bf16_f32 v82, v88, v89
	v_pk_fma_f32 v[86:87], v[94:95], v[86:87], v[80:81]
	v_lshlrev_b64 v[80:81], s0, v[96:97]
	v_lshl_add_u64 v[92:93], v[80:81], 1, v[128:129]
	v_cvt_pk_bf16_f32 v80, v102, v103
	v_cvt_pk_bf16_f32 v81, v106, v107
	v_cvt_pk_bf16_f32 v83, v90, v91
	global_store_dwordx4 v[92:93], v[80:83], off nt
	s_nop 1
	v_cvt_pk_bf16_f32 v80, v104, v105
	v_cvt_pk_bf16_f32 v81, v108, v109
	v_cvt_pk_bf16_f32 v82, v84, v85
	v_cvt_pk_bf16_f32 v83, v86, v87
	global_store_dwordx4 v[92:93], v[80:83], off offset:128 nt
	s_nop 1
	v_or_b32_e32 v80, 48, v130
	v_cmp_gt_i32_e32 vcc, s1, v80
	s_movk_i32 s1, 0x3f80
	s_nop 0
	v_cndmask_b32_e32 v81, v232, v243, vcc
	v_bitop3_b32 v84, v81, v130, 48 bitop3:0xe0
	v_ashrrev_i32_e32 v81, 31, v80
	v_lshl_add_u64 v[82:83], v[80:81], 3, s[36:37]
	s_nop 1
	v_mov_b64_e32 v[82:83], v[202:203]
	v_lshl_or_b32 v84, v84, 9, v174
	v_cmp_gt_i32_e32 vcc, s1, v130
	s_movk_i32 s1, 0x3f70
	v_ffbh_u32_e32 v85, v83
	v_min_u32_e32 v85, 32, v85
	v_lshlrev_b64 v[82:83], v85, v[82:83]
	v_min_u32_e32 v82, 1, v82
	v_or_b32_e32 v82, v83, v82
	v_sub_u32_e32 v83, 32, v85
	v_mov_b32_e32 v85, v161
	v_lshl_add_u64 v[84:85], s[94:95], 0, v[84:85]
	global_load_dwordx4 v[86:89], v[84:85], off
	global_load_dwordx4 v[90:93], v[84:85], off offset:16
	v_cvt_f32_u32_e32 v82, v82
	v_ldexp_f32 v82, v82, v83
	v_mul_f32_e32 v82, 0x35800000, v82
	v_fmamk_f32 v82, v82, 0x3a800000, v219
	v_rsq_f32_e32 v82, v82
	s_waitcnt vmcnt(0) lgkmcnt(0)
	v_mov_b32_e32 v94, v86
	v_mul_f32_e32 v82, v146, v82
	v_pk_mul_f32 v[72:73], v[72:73], v[82:83] op_sel_hi:[1,0]
	v_mov_b32_e32 v95, v88
	v_mov_b32_e32 v88, v87
	v_pk_mul_f32 v[76:77], v[76:77], v[82:83] op_sel_hi:[1,0]
	v_pk_mul_f32 v[86:87], v[88:89], v[72:73]
	v_pk_mul_f32 v[72:73], v[94:95], v[72:73]
	v_pk_mul_f32 v[74:75], v[74:75], v[82:83] op_sel_hi:[1,0]
	v_pk_fma_f32 v[88:89], v[88:89], v[76:77], v[72:73]
	v_mov_b32_e32 v73, v92
	v_mov_b32_e32 v92, v91
	v_pk_mul_f32 v[78:79], v[78:79], v[82:83] op_sel_hi:[1,0]
	v_pk_fma_f32 v[86:87], v[94:95], v[76:77], v[86:87] neg_lo:[0,0,1] neg_hi:[0,0,1]
	v_mov_b32_e32 v72, v90
	v_pk_mul_f32 v[76:77], v[92:93], v[74:75]
	v_pk_mul_f32 v[70:71], v[70:71], v[82:83] op_sel_hi:[1,0]
	v_pk_fma_f32 v[90:91], v[72:73], v[78:79], v[76:77] neg_lo:[0,0,1] neg_hi:[0,0,1]
	v_pk_mul_f32 v[72:73], v[72:73], v[74:75]
	v_pk_mul_f32 v[68:69], v[68:69], v[82:83] op_sel_hi:[1,0]
	v_pk_fma_f32 v[92:93], v[92:93], v[78:79], v[72:73]
	global_load_dwordx4 v[72:75], v[84:85], off offset:32
	global_load_dwordx4 v[76:79], v[84:85], off offset:48
	v_pk_mul_f32 v[66:67], v[66:67], v[82:83] op_sel_hi:[1,0]
	v_pk_mul_f32 v[64:65], v[64:65], v[82:83] op_sel_hi:[1,0]
	s_waitcnt vmcnt(0) lgkmcnt(0)
	v_mov_b32_e32 v82, v72
	v_mov_b32_e32 v83, v74
	v_mov_b32_e32 v74, v73
	v_pk_mul_f32 v[72:73], v[74:75], v[64:65]
	v_pk_mul_f32 v[64:65], v[82:83], v[64:65]
	v_pk_fma_f32 v[72:73], v[82:83], v[68:69], v[72:73] neg_lo:[0,0,1] neg_hi:[0,0,1]
	v_pk_fma_f32 v[68:69], v[74:75], v[68:69], v[64:65]
	v_mov_b32_e32 v65, v78
	v_mov_b32_e32 v78, v77
	v_mov_b32_e32 v64, v76
	v_pk_mul_f32 v[74:75], v[78:79], v[66:67]
	s_nop 0
	v_pk_fma_f32 v[74:75], v[64:65], v[70:71], v[74:75] neg_lo:[0,0,1] neg_hi:[0,0,1]
	v_pk_mul_f32 v[64:65], v[64:65], v[66:67]
	v_cvt_pk_bf16_f32 v66, v72, v73
	v_pk_fma_f32 v[70:71], v[78:79], v[70:71], v[64:65]
	v_lshlrev_b64 v[64:65], s0, v[80:81]
	v_lshl_add_u64 v[76:77], v[64:65], 1, v[128:129]
	v_cvt_pk_bf16_f32 v64, v86, v87
	v_cvt_pk_bf16_f32 v65, v90, v91
	v_cvt_pk_bf16_f32 v67, v74, v75
	global_store_dwordx4 v[76:77], v[64:67], off nt
	s_nop 1
	v_cvt_pk_bf16_f32 v64, v88, v89
	v_cvt_pk_bf16_f32 v65, v92, v93
	v_cvt_pk_bf16_f32 v66, v68, v69
	v_cvt_pk_bf16_f32 v67, v70, v71
	global_store_dwordx4 v[76:77], v[64:67], off offset:128 nt
	s_nop 1
	v_mov_b64_e32 v[66:67], v[204:205]
	v_ffbh_u32_e32 v69, v67
	v_min_u32_e32 v69, 32, v69
	v_add_u32_e32 v64, 0x80, v130
	v_cndmask_b32_e32 v65, v228, v229, vcc
	v_lshlrev_b64 v[66:67], v69, v[66:67]
	v_and_b32_e32 v68, v65, v64
	v_min_u32_e32 v66, 1, v66
	v_or_b32_e32 v66, v67, v66
	v_sub_u32_e32 v67, 32, v69
	v_lshl_or_b32 v68, v68, 9, v174
	v_mov_b32_e32 v69, v161
	v_lshl_add_u64 v[68:69], s[94:95], 0, v[68:69]
	global_load_dwordx4 v[70:73], v[68:69], off
	global_load_dwordx4 v[74:77], v[68:69], off offset:16
	v_cvt_f32_u32_e32 v66, v66
	v_ashrrev_i32_e32 v65, 31, v64
	v_cmp_gt_i32_e32 vcc, s1, v130
	s_movk_i32 s1, 0x3f60
	v_ldexp_f32 v66, v66, v67
	v_mul_f32_e32 v66, 0x35800000, v66
	v_fmamk_f32 v66, v66, 0x3a800000, v219
	v_rsq_f32_e32 v66, v66
	s_waitcnt vmcnt(0) lgkmcnt(0)
	v_mov_b32_e32 v78, v70
	v_mul_f32_e32 v66, v146, v66
	v_pk_mul_f32 v[56:57], v[56:57], v[66:67] op_sel_hi:[1,0]
	v_mov_b32_e32 v79, v72
	v_mov_b32_e32 v72, v71
	v_pk_mul_f32 v[60:61], v[60:61], v[66:67] op_sel_hi:[1,0]
	v_pk_mul_f32 v[70:71], v[72:73], v[56:57]
	v_pk_mul_f32 v[56:57], v[78:79], v[56:57]
	v_pk_mul_f32 v[58:59], v[58:59], v[66:67] op_sel_hi:[1,0]
	v_pk_fma_f32 v[72:73], v[72:73], v[60:61], v[56:57]
	v_mov_b32_e32 v57, v76
	v_mov_b32_e32 v76, v75
	v_pk_mul_f32 v[62:63], v[62:63], v[66:67] op_sel_hi:[1,0]
	v_pk_fma_f32 v[70:71], v[78:79], v[60:61], v[70:71] neg_lo:[0,0,1] neg_hi:[0,0,1]
	v_mov_b32_e32 v56, v74
	v_pk_mul_f32 v[60:61], v[76:77], v[58:59]
	v_pk_mul_f32 v[54:55], v[54:55], v[66:67] op_sel_hi:[1,0]
	v_pk_fma_f32 v[74:75], v[56:57], v[62:63], v[60:61] neg_lo:[0,0,1] neg_hi:[0,0,1]
	v_pk_mul_f32 v[56:57], v[56:57], v[58:59]
	v_pk_mul_f32 v[52:53], v[52:53], v[66:67] op_sel_hi:[1,0]
	v_pk_fma_f32 v[76:77], v[76:77], v[62:63], v[56:57]
	global_load_dwordx4 v[56:59], v[68:69], off offset:32
	global_load_dwordx4 v[60:63], v[68:69], off offset:48
	v_pk_mul_f32 v[50:51], v[50:51], v[66:67] op_sel_hi:[1,0]
	v_pk_mul_f32 v[48:49], v[48:49], v[66:67] op_sel_hi:[1,0]
	s_waitcnt vmcnt(0) lgkmcnt(0)
	v_mov_b32_e32 v66, v56
	v_mov_b32_e32 v67, v58
	v_mov_b32_e32 v58, v57
	v_pk_mul_f32 v[56:57], v[58:59], v[48:49]
	v_pk_mul_f32 v[48:49], v[66:67], v[48:49]
	v_pk_fma_f32 v[56:57], v[66:67], v[52:53], v[56:57] neg_lo:[0,0,1] neg_hi:[0,0,1]
	v_pk_fma_f32 v[52:53], v[58:59], v[52:53], v[48:49]
	v_mov_b32_e32 v49, v62
	v_mov_b32_e32 v62, v61
	v_mov_b32_e32 v48, v60
	v_pk_mul_f32 v[58:59], v[62:63], v[50:51]
	s_nop 0
	v_pk_fma_f32 v[58:59], v[48:49], v[54:55], v[58:59] neg_lo:[0,0,1] neg_hi:[0,0,1]
	v_pk_mul_f32 v[48:49], v[48:49], v[50:51]
	v_cvt_pk_bf16_f32 v50, v56, v57
	v_pk_fma_f32 v[54:55], v[62:63], v[54:55], v[48:49]
	v_lshlrev_b64 v[48:49], s0, v[64:65]
	v_lshl_add_u64 v[60:61], v[48:49], 1, v[128:129]
	v_cvt_pk_bf16_f32 v48, v70, v71
	v_cvt_pk_bf16_f32 v49, v74, v75
	v_cvt_pk_bf16_f32 v51, v58, v59
	global_store_dwordx4 v[60:61], v[48:51], off nt
	s_nop 1
	v_cvt_pk_bf16_f32 v48, v72, v73
	v_cvt_pk_bf16_f32 v49, v76, v77
	v_cvt_pk_bf16_f32 v50, v52, v53
	v_cvt_pk_bf16_f32 v51, v54, v55
	global_store_dwordx4 v[60:61], v[48:51], off offset:128 nt
	s_nop 1
	v_mov_b64_e32 v[50:51], v[206:207]
	v_ffbh_u32_e32 v53, v51
	v_min_u32_e32 v53, 32, v53
	v_add_u32_e32 v48, 0x90, v130
	v_cndmask_b32_e32 v49, v230, v231, vcc
	v_lshlrev_b64 v[50:51], v53, v[50:51]
	v_and_b32_e32 v52, v49, v48
	v_min_u32_e32 v50, 1, v50
	v_or_b32_e32 v50, v51, v50
	v_sub_u32_e32 v51, 32, v53
	v_lshl_or_b32 v52, v52, 9, v174
	v_mov_b32_e32 v53, v161
	v_lshl_add_u64 v[52:53], s[94:95], 0, v[52:53]
	global_load_dwordx4 v[54:57], v[52:53], off
	global_load_dwordx4 v[58:61], v[52:53], off offset:16
	v_cvt_f32_u32_e32 v50, v50
	v_ashrrev_i32_e32 v49, 31, v48
	v_cmp_gt_i32_e32 vcc, s1, v130
	s_movk_i32 s1, 0x3f50
	v_ldexp_f32 v50, v50, v51
	v_mul_f32_e32 v50, 0x35800000, v50
	v_fmamk_f32 v50, v50, 0x3a800000, v219
	v_rsq_f32_e32 v50, v50
	s_waitcnt vmcnt(0) lgkmcnt(0)
	v_mov_b32_e32 v62, v54
	v_mul_f32_e32 v50, v146, v50
	v_pk_mul_f32 v[40:41], v[40:41], v[50:51] op_sel_hi:[1,0]
	v_mov_b32_e32 v63, v56
	v_mov_b32_e32 v56, v55
	v_pk_mul_f32 v[44:45], v[44:45], v[50:51] op_sel_hi:[1,0]
	v_pk_mul_f32 v[54:55], v[56:57], v[40:41]
	v_pk_mul_f32 v[40:41], v[62:63], v[40:41]
	v_pk_mul_f32 v[42:43], v[42:43], v[50:51] op_sel_hi:[1,0]
	v_pk_fma_f32 v[56:57], v[56:57], v[44:45], v[40:41]
	v_mov_b32_e32 v41, v60
	v_mov_b32_e32 v60, v59
	v_pk_mul_f32 v[46:47], v[46:47], v[50:51] op_sel_hi:[1,0]
	v_pk_fma_f32 v[54:55], v[62:63], v[44:45], v[54:55] neg_lo:[0,0,1] neg_hi:[0,0,1]
	v_mov_b32_e32 v40, v58
	v_pk_mul_f32 v[44:45], v[60:61], v[42:43]
	v_pk_mul_f32 v[38:39], v[38:39], v[50:51] op_sel_hi:[1,0]
	v_pk_fma_f32 v[58:59], v[40:41], v[46:47], v[44:45] neg_lo:[0,0,1] neg_hi:[0,0,1]
	v_pk_mul_f32 v[40:41], v[40:41], v[42:43]
	v_pk_mul_f32 v[36:37], v[36:37], v[50:51] op_sel_hi:[1,0]
	v_pk_fma_f32 v[60:61], v[60:61], v[46:47], v[40:41]
	global_load_dwordx4 v[40:43], v[52:53], off offset:32
	global_load_dwordx4 v[44:47], v[52:53], off offset:48
	v_pk_mul_f32 v[34:35], v[34:35], v[50:51] op_sel_hi:[1,0]
	v_pk_mul_f32 v[32:33], v[32:33], v[50:51] op_sel_hi:[1,0]
	s_waitcnt vmcnt(0) lgkmcnt(0)
	v_mov_b32_e32 v50, v40
	v_mov_b32_e32 v51, v42
	v_mov_b32_e32 v42, v41
	v_pk_mul_f32 v[40:41], v[42:43], v[32:33]
	v_pk_mul_f32 v[32:33], v[50:51], v[32:33]
	v_pk_fma_f32 v[40:41], v[50:51], v[36:37], v[40:41] neg_lo:[0,0,1] neg_hi:[0,0,1]
	v_pk_fma_f32 v[36:37], v[42:43], v[36:37], v[32:33]
	v_mov_b32_e32 v33, v46
	v_mov_b32_e32 v46, v45
	v_mov_b32_e32 v32, v44
	v_pk_mul_f32 v[42:43], v[46:47], v[34:35]
	s_nop 0
	v_pk_fma_f32 v[42:43], v[32:33], v[38:39], v[42:43] neg_lo:[0,0,1] neg_hi:[0,0,1]
	v_pk_mul_f32 v[32:33], v[32:33], v[34:35]
	v_cvt_pk_bf16_f32 v34, v40, v41
	v_pk_fma_f32 v[38:39], v[46:47], v[38:39], v[32:33]
	v_lshlrev_b64 v[32:33], s0, v[48:49]
	v_lshl_add_u64 v[44:45], v[32:33], 1, v[128:129]
	v_cvt_pk_bf16_f32 v32, v54, v55
	v_cvt_pk_bf16_f32 v33, v58, v59
	v_cvt_pk_bf16_f32 v35, v42, v43
	global_store_dwordx4 v[44:45], v[32:35], off nt
	s_nop 1
	v_cvt_pk_bf16_f32 v32, v56, v57
	v_cvt_pk_bf16_f32 v33, v60, v61
	v_cvt_pk_bf16_f32 v34, v36, v37
	v_cvt_pk_bf16_f32 v35, v38, v39
	global_store_dwordx4 v[44:45], v[32:35], off offset:128 nt
	s_nop 1
	v_mov_b64_e32 v[34:35], v[208:209]
	v_ffbh_u32_e32 v37, v35
	v_min_u32_e32 v37, 32, v37
	v_add_u32_e32 v32, 0xa0, v130
	v_cndmask_b32_e32 v33, v222, v236, vcc
	v_lshlrev_b64 v[34:35], v37, v[34:35]
	v_and_b32_e32 v36, v33, v32
	v_min_u32_e32 v34, 1, v34
	v_or_b32_e32 v34, v35, v34
	v_sub_u32_e32 v35, 32, v37
	v_lshl_or_b32 v36, v36, 9, v174
	v_mov_b32_e32 v37, v161
	v_lshl_add_u64 v[36:37], s[94:95], 0, v[36:37]
	global_load_dwordx4 v[38:41], v[36:37], off
	global_load_dwordx4 v[42:45], v[36:37], off offset:16
	v_cvt_f32_u32_e32 v34, v34
	v_ashrrev_i32_e32 v33, 31, v32
	v_cmp_gt_i32_e32 vcc, s1, v130
	v_ldexp_f32 v34, v34, v35
	v_mul_f32_e32 v34, 0x35800000, v34
	v_fmamk_f32 v34, v34, 0x3a800000, v219
	v_rsq_f32_e32 v34, v34
	s_waitcnt vmcnt(0) lgkmcnt(0)
	v_mov_b32_e32 v46, v38
	v_mul_f32_e32 v34, v146, v34
	v_pk_mul_f32 v[24:25], v[24:25], v[34:35] op_sel_hi:[1,0]
	v_mov_b32_e32 v47, v40
	v_mov_b32_e32 v40, v39
	v_pk_mul_f32 v[28:29], v[28:29], v[34:35] op_sel_hi:[1,0]
	v_pk_mul_f32 v[38:39], v[40:41], v[24:25]
	v_pk_mul_f32 v[24:25], v[46:47], v[24:25]
	v_pk_mul_f32 v[26:27], v[26:27], v[34:35] op_sel_hi:[1,0]
	v_pk_fma_f32 v[40:41], v[40:41], v[28:29], v[24:25]
	v_mov_b32_e32 v25, v44
	v_mov_b32_e32 v44, v43
	v_pk_mul_f32 v[30:31], v[30:31], v[34:35] op_sel_hi:[1,0]
	v_pk_fma_f32 v[38:39], v[46:47], v[28:29], v[38:39] neg_lo:[0,0,1] neg_hi:[0,0,1]
	v_mov_b32_e32 v24, v42
	v_pk_mul_f32 v[28:29], v[44:45], v[26:27]
	v_pk_mul_f32 v[22:23], v[22:23], v[34:35] op_sel_hi:[1,0]
	v_pk_fma_f32 v[42:43], v[24:25], v[30:31], v[28:29] neg_lo:[0,0,1] neg_hi:[0,0,1]
	v_pk_mul_f32 v[24:25], v[24:25], v[26:27]
	v_pk_mul_f32 v[20:21], v[20:21], v[34:35] op_sel_hi:[1,0]
	v_pk_fma_f32 v[44:45], v[44:45], v[30:31], v[24:25]
	global_load_dwordx4 v[24:27], v[36:37], off offset:32
	global_load_dwordx4 v[28:31], v[36:37], off offset:48
	v_pk_mul_f32 v[18:19], v[18:19], v[34:35] op_sel_hi:[1,0]
	v_pk_mul_f32 v[16:17], v[16:17], v[34:35] op_sel_hi:[1,0]
	s_waitcnt vmcnt(0) lgkmcnt(0)
	v_mov_b32_e32 v34, v24
	v_mov_b32_e32 v35, v26
	v_mov_b32_e32 v26, v25
	v_pk_mul_f32 v[24:25], v[26:27], v[16:17]
	v_pk_mul_f32 v[16:17], v[34:35], v[16:17]
	v_pk_fma_f32 v[24:25], v[34:35], v[20:21], v[24:25] neg_lo:[0,0,1] neg_hi:[0,0,1]
	v_pk_fma_f32 v[20:21], v[26:27], v[20:21], v[16:17]
	v_mov_b32_e32 v17, v30
	v_mov_b32_e32 v30, v29
	v_mov_b32_e32 v16, v28
	v_pk_mul_f32 v[26:27], v[30:31], v[18:19]
	s_nop 0
	v_pk_fma_f32 v[26:27], v[16:17], v[22:23], v[26:27] neg_lo:[0,0,1] neg_hi:[0,0,1]
	v_pk_mul_f32 v[16:17], v[16:17], v[18:19]
	v_cvt_pk_bf16_f32 v18, v24, v25
	v_pk_fma_f32 v[22:23], v[30:31], v[22:23], v[16:17]
	v_lshlrev_b64 v[16:17], s0, v[32:33]
	v_lshl_add_u64 v[28:29], v[16:17], 1, v[128:129]
	v_cvt_pk_bf16_f32 v16, v38, v39
	v_cvt_pk_bf16_f32 v17, v42, v43
	v_cvt_pk_bf16_f32 v19, v26, v27
	global_store_dwordx4 v[28:29], v[16:19], off nt
	s_nop 1
	v_cvt_pk_bf16_f32 v16, v40, v41
	v_cvt_pk_bf16_f32 v17, v44, v45
	v_cvt_pk_bf16_f32 v18, v20, v21
	v_cvt_pk_bf16_f32 v19, v22, v23
	global_store_dwordx4 v[28:29], v[16:19], off offset:128 nt
	s_nop 1
	v_mov_b64_e32 v[18:19], v[210:211]
	v_ffbh_u32_e32 v21, v19
	v_min_u32_e32 v21, 32, v21
	v_add_u32_e32 v16, 0xb0, v130
	v_cndmask_b32_e32 v17, v232, v243, vcc
	v_lshlrev_b64 v[18:19], v21, v[18:19]
	v_and_b32_e32 v20, v17, v16
	v_min_u32_e32 v18, 1, v18
	v_or_b32_e32 v18, v19, v18
	v_sub_u32_e32 v19, 32, v21
	v_lshl_or_b32 v20, v20, 9, v174
	v_mov_b32_e32 v21, v161
	v_lshl_add_u64 v[20:21], s[94:95], 0, v[20:21]
	global_load_dwordx4 v[22:25], v[20:21], off
	global_load_dwordx4 v[26:29], v[20:21], off offset:16
	v_cvt_f32_u32_e32 v18, v18
	v_ashrrev_i32_e32 v17, 31, v16
	v_lshlrev_b64 v[16:17], s0, v[16:17]
	v_lshl_add_u64 v[16:17], v[16:17], 1, v[128:129]
	v_ldexp_f32 v18, v18, v19
	v_mul_f32_e32 v18, 0x35800000, v18
	v_fmamk_f32 v18, v18, 0x3a800000, v219
	v_rsq_f32_e32 v18, v18
	s_waitcnt vmcnt(0) lgkmcnt(0)
	v_mov_b32_e32 v32, v22
	v_mul_f32_e32 v18, v146, v18
	v_pk_mul_f32 v[8:9], v[8:9], v[18:19] op_sel_hi:[1,0]
	v_mov_b32_e32 v33, v24
	v_mov_b32_e32 v24, v23
	v_pk_mul_f32 v[30:31], v[14:15], v[18:19] op_sel_hi:[1,0]
	v_pk_mul_f32 v[14:15], v[12:13], v[18:19] op_sel_hi:[1,0]
	v_pk_mul_f32 v[10:11], v[10:11], v[18:19] op_sel_hi:[1,0]
	v_pk_mul_f32 v[12:13], v[24:25], v[8:9]
	v_pk_mul_f32 v[8:9], v[32:33], v[8:9]
	v_mov_b32_e32 v22, v26
	v_mov_b32_e32 v23, v28
	v_mov_b32_e32 v28, v27
	v_pk_fma_f32 v[12:13], v[32:33], v[14:15], v[12:13] neg_lo:[0,0,1] neg_hi:[0,0,1]
	v_pk_fma_f32 v[8:9], v[24:25], v[14:15], v[8:9]
	v_pk_mul_f32 v[14:15], v[28:29], v[10:11]
	v_pk_mul_f32 v[10:11], v[22:23], v[10:11]
	v_pk_fma_f32 v[14:15], v[22:23], v[30:31], v[14:15] neg_lo:[0,0,1] neg_hi:[0,0,1]
	v_pk_fma_f32 v[10:11], v[28:29], v[30:31], v[10:11]
	global_load_dwordx4 v[22:25], v[20:21], off offset:32
	global_load_dwordx4 v[26:29], v[20:21], off offset:48
	v_pk_mul_f32 v[20:21], v[6:7], v[18:19] op_sel_hi:[1,0]
	v_pk_mul_f32 v[6:7], v[4:5], v[18:19] op_sel_hi:[1,0]
	v_pk_mul_f32 v[2:3], v[2:3], v[18:19] op_sel_hi:[1,0]
	v_pk_mul_f32 v[0:1], v[0:1], v[18:19] op_sel_hi:[1,0]
	v_cvt_pk_bf16_f32 v12, v12, v13
	v_cvt_pk_bf16_f32 v13, v14, v15
	s_waitcnt vmcnt(0) lgkmcnt(0)
	v_mov_b32_e32 v19, v24
	v_mov_b32_e32 v24, v23
	v_mov_b32_e32 v18, v22
	v_pk_mul_f32 v[4:5], v[24:25], v[0:1]
	v_pk_mul_f32 v[0:1], v[18:19], v[0:1]
	v_pk_fma_f32 v[4:5], v[18:19], v[6:7], v[4:5] neg_lo:[0,0,1] neg_hi:[0,0,1]
	v_mov_b32_e32 v18, v26
	v_mov_b32_e32 v19, v28
	v_mov_b32_e32 v28, v27
	v_pk_fma_f32 v[0:1], v[24:25], v[6:7], v[0:1]
	v_pk_mul_f32 v[6:7], v[28:29], v[2:3]
	v_pk_mul_f32 v[2:3], v[18:19], v[2:3]
	v_pk_fma_f32 v[6:7], v[18:19], v[20:21], v[6:7] neg_lo:[0,0,1] neg_hi:[0,0,1]
	v_pk_fma_f32 v[2:3], v[28:29], v[20:21], v[2:3]
	v_cvt_pk_bf16_f32 v14, v4, v5
	v_cvt_pk_bf16_f32 v15, v6, v7
	v_cvt_pk_bf16_f32 v4, v8, v9
	v_cvt_pk_bf16_f32 v5, v10, v11
	v_cvt_pk_bf16_f32 v6, v0, v1
	v_cvt_pk_bf16_f32 v7, v2, v3
	global_store_dwordx4 v[16:17], v[12:15], off nt
	global_store_dwordx4 v[16:17], v[4:7], off offset:128 nt
	s_andn2_b64 vcc, exec, s[38:39]
	s_mov_b64 s[0:1], -1
	s_cbranch_vccnz .LBB0_395

.LBB0_486:
	v_add_u32_e32 v9, 0x840, v17
	ds_write2_b32 v9, v4, v5 offset1:1
	v_add_u32_e32 v4, 0x848, v17
	s_mul_hi_i32 s0, s12, 0xb00000
	s_mul_i32 s12, s12, 0xb00000
	ds_write2_b32 v4, v6, v7 offset1:1
	v_pk_mul_f32 v[0:1], v[0:1], v[8:9] op_sel_hi:[1,0]
	v_add_u32_e32 v4, 0xc60, v17
	s_add_u32 s6, s94, s12
	ds_write2_b32 v4, v0, v1 offset1:1
	v_pk_mul_f32 v[0:1], v[2:3], v[8:9] op_sel_hi:[1,0]
	v_add_u32_e32 v2, 0xc68, v17
	s_addc_u32 s7, s95, s0
	ds_write2_b32 v2, v0, v1 offset1:1
	s_lshl_b64 s[0:1], s[4:5], 1
	s_waitcnt lgkmcnt(0)
	s_add_u32 s0, s6, s0
	s_addc_u32 s1, s7, s1
	v_lshlrev_b32_e32 v160, 1, v36
	ds_read_b32 v2, v63
	ds_read_b32 v3, v63 offset:132
	ds_read_b32 v6, v63 offset:264
	ds_read_b32 v7, v63 offset:396
	ds_read_b32 v8, v63 offset:528
	ds_read_b32 v9, v63 offset:660
	ds_read_b32 v10, v63 offset:792
	ds_read_b32 v11, v63 offset:924
	v_lshl_add_u64 v[0:1], s[0:1], 0, v[160:161]
	s_mov_b64 s[0:1], 0x800000
	v_lshl_add_u64 v[4:5], v[0:1], 0, s[0:1]
	s_waitcnt lgkmcnt(0)
	v_cvt_pk_bf16_f32 v1, v6, v7
	v_or_b32_e32 v6, s11, v32
	v_ashrrev_i32_e32 v7, 31, v6
	v_lshlrev_b64 v[6:7], 11, v[6:7]
	v_cvt_pk_bf16_f32 v0, v2, v3
	v_cvt_pk_bf16_f32 v2, v8, v9
	v_cvt_pk_bf16_f32 v3, v10, v11
	v_lshl_add_u64 v[6:7], v[4:5], 0, v[6:7]
	flat_store_dwordx4 v[6:7], v[0:3] nt
	ds_read_b32 v0, v63 offset:32
	ds_read_b32 v1, v63 offset:164
	ds_read_b32 v2, v63 offset:296
	ds_read_b32 v3, v63 offset:428
	ds_read_b32 v6, v63 offset:560
	ds_read_b32 v7, v63 offset:692
	ds_read_b32 v8, v63 offset:824
	ds_read_b32 v9, v63 offset:956
	s_waitcnt lgkmcnt(0)
	v_cvt_pk_bf16_f32 v0, v0, v1
	v_cvt_pk_bf16_f32 v1, v2, v3
	v_cvt_pk_bf16_f32 v2, v6, v7
	v_or_b32_e32 v6, s11, v60
	v_ashrrev_i32_e32 v7, 31, v6
	v_lshlrev_b64 v[6:7], 11, v[6:7]
	v_cvt_pk_bf16_f32 v3, v8, v9
	v_lshl_add_u64 v[6:7], v[4:5], 0, v[6:7]
	flat_store_dwordx4 v[6:7], v[0:3] nt
	ds_read_b32 v0, v63 offset:64
	ds_read_b32 v1, v63 offset:196
	ds_read_b32 v2, v63 offset:328
	ds_read_b32 v3, v63 offset:460
	ds_read_b32 v6, v63 offset:592
	ds_read_b32 v7, v63 offset:724
	ds_read_b32 v8, v63 offset:856
	ds_read_b32 v9, v63 offset:988
	s_waitcnt lgkmcnt(0)
	v_cvt_pk_bf16_f32 v0, v0, v1
	v_cvt_pk_bf16_f32 v1, v2, v3
	v_cvt_pk_bf16_f32 v2, v6, v7
	v_or_b32_e32 v6, s11, v61
	v_ashrrev_i32_e32 v7, 31, v6
	v_lshlrev_b64 v[6:7], 11, v[6:7]
	v_cvt_pk_bf16_f32 v3, v8, v9
	v_lshl_add_u64 v[6:7], v[4:5], 0, v[6:7]
	flat_store_dwordx4 v[6:7], v[0:3] nt
	ds_read_b32 v0, v63 offset:96
	ds_read_b32 v1, v63 offset:228
	ds_read_b32 v2, v63 offset:360
	ds_read_b32 v3, v63 offset:492
	ds_read_b32 v6, v63 offset:624
	ds_read_b32 v7, v63 offset:756
	ds_read_b32 v8, v63 offset:888
	ds_read_b32 v9, v63 offset:1020
	s_waitcnt lgkmcnt(0)
	v_cvt_pk_bf16_f32 v0, v0, v1
	v_cvt_pk_bf16_f32 v1, v2, v3
	v_cvt_pk_bf16_f32 v2, v6, v7
	v_or_b32_e32 v6, s11, v62
	v_ashrrev_i32_e32 v7, 31, v6
	v_lshlrev_b64 v[6:7], 11, v[6:7]
	v_cvt_pk_bf16_f32 v3, v8, v9
	v_lshl_add_u64 v[4:5], v[4:5], 0, v[6:7]
	flat_store_dwordx4 v[4:5], v[0:3] nt
	s_waitcnt lgkmcnt(0)

.LBB0_488:
	s_cmpk_gt_i32 s10, 0x2bff
	s_mov_b64 s[0:1], -1
	s_cbranch_scc0 .LBB0_512
	s_cmpk_gt_u32 s10, 0x41ff
	s_cbranch_scc0 .LBB0_509
	s_cmpk_gt_u32 s10, 0x47ff
	s_cbranch_scc0 .LBB0_502
	s_cmpk_gt_u32 s10, 0x4dff
	s_cbranch_scc0 .LBB0_497
	s_and_b32 s4, s9, 0x3e0
	s_cmpk_gt_u32 s10, 0x4fff
	v_or_b32_e32 v5, s4, v32
	v_or_b32_e32 v4, s4, v60
	v_or_b32_e32 v3, s4, v61
	v_or_b32_e32 v2, s4, v62
	s_cbranch_scc0 .LBB0_494
	s_add_i32 s0, s8, 0xfffffc00
	s_and_b32 s0, s0, 0x1ffc0
	v_or_b32_e32 v6, s0, v32
	s_lshl_b32 s42, s4, 2
	v_lshl_add_u64 v[0:1], v[38:39], 0, s[42:43]
	v_lshlrev_b32_e32 v160, 12, v6
	v_lshl_add_u64 v[0:1], v[0:1], 0, v[160:161]
	v_add_co_u32_e32 v10, vcc, 0x8000, v0
	s_mov_b32 s1, 0x10000
	s_nop 0
	v_addc_co_u32_e32 v11, vcc, 0, v1, vcc
	global_load_dwordx4 v[6:9], v[0:1], off
	v_add_co_u32_e32 v14, vcc, s1, v0
	global_load_dwordx4 v[10:13], v[10:11], off
	s_nop 0
	v_addc_co_u32_e32 v15, vcc, 0, v1, vcc
	s_mov_b32 s1, 0x18000
	global_load_dwordx4 v[14:17], v[14:15], off
	v_add_co_u32_e32 v18, vcc, s1, v0
	s_lshl_b32 s42, s0, 1
	s_nop 0
	v_addc_co_u32_e32 v19, vcc, 0, v1, vcc
	global_load_dwordx4 v[18:21], v[18:19], off
	v_add_co_u32_e32 v22, vcc, 0x20000, v0
	v_lshlrev_b32_e32 v160, 11, v5
	s_nop 0
	v_addc_co_u32_e32 v23, vcc, 0, v1, vcc
	global_load_dwordx4 v[22:25], v[22:23], off
	v_add_co_u32_e32 v26, vcc, 0x28000, v0
	s_movk_i32 s33, 0x4000
	s_nop 0
	v_addc_co_u32_e32 v27, vcc, 0, v1, vcc
	global_load_dwordx4 v[26:29], v[26:27], off
	v_add_co_u32_e32 v30, vcc, 0x30000, v0
	s_mov_b64 s[0:1], 0
	s_nop 0
	v_addc_co_u32_e32 v31, vcc, 0, v1, vcc
	global_load_dwordx4 v[70:73], v[30:31], off
	v_add_co_u32_e32 v0, vcc, 0x38000, v0
	s_nop 1
	v_addc_co_u32_e32 v1, vcc, 0, v1, vcc
	global_load_dwordx4 v[74:77], v[0:1], off
	v_add_u32_e32 v0, v57, v59
	v_add_u32_e32 v1, 0x420, v0
	s_waitcnt vmcnt(0)
	ds_write2_b32 v0, v6, v7 offset1:1
	ds_write2_b32 v0, v8, v9 offset0:2 offset1:3
	ds_write2_b32 v1, v10, v11 offset1:1
	v_add_u32_e32 v1, 0x428, v0
	ds_write2_b32 v1, v12, v13 offset1:1
	v_add_u32_e32 v1, 0x840, v0
	ds_write2_b32 v1, v14, v15 offset1:1
	v_add_u32_e32 v1, 0x848, v0
	ds_write2_b32 v1, v16, v17 offset1:1
	v_add_u32_e32 v1, 0xc60, v0
	ds_write2_b32 v1, v18, v19 offset1:1
	v_add_u32_e32 v1, 0xc68, v0
	ds_write2_b32 v1, v20, v21 offset1:1
	v_add_u32_e32 v1, 0x1080, v0
	ds_write2_b32 v1, v22, v23 offset1:1
	v_add_u32_e32 v1, 0x1088, v0
	ds_write2_b32 v1, v24, v25 offset1:1
	v_add_u32_e32 v1, 0x14a0, v0
	ds_write2_b32 v1, v26, v27 offset1:1
	v_add_u32_e32 v1, 0x14a8, v0
	ds_write2_b32 v1, v28, v29 offset1:1
	v_add_u32_e32 v1, 0x18c0, v0
	ds_write2_b32 v1, v70, v71 offset1:1
	v_add_u32_e32 v1, 0x18c8, v0
	ds_write2_b32 v1, v72, v73 offset1:1
	v_add_u32_e32 v1, 0x1ce0, v0
	v_add_u32_e32 v0, 0x1ce8, v0
	ds_write2_b32 v1, v74, v75 offset1:1
	ds_write2_b32 v0, v76, v77 offset1:1
	s_waitcnt lgkmcnt(0)
	ds_read_b32 v6, v63
	ds_read_b32 v7, v63 offset:132
	v_lshl_add_u64 v[0:1], v[46:47], 0, s[42:43]
	s_mov_b32 s42, 0x8000
	s_waitcnt lgkmcnt(0)
	v_cvt_pk_bf16_f32 v6, v6, v7
	ds_read_b32 v7, v63 offset:264
	ds_read_b32 v8, v63 offset:396
	s_waitcnt lgkmcnt(0)
	v_cvt_pk_bf16_f32 v7, v7, v8
	ds_read_b32 v8, v63 offset:528
	ds_read_b32 v9, v63 offset:660
	s_waitcnt lgkmcnt(0)
	v_cvt_pk_bf16_f32 v8, v8, v9
	ds_read_b32 v9, v63 offset:792
	ds_read_b32 v10, v63 offset:924
	s_waitcnt lgkmcnt(0)
	v_cvt_pk_bf16_f32 v9, v9, v10
	v_lshl_add_u64 v[10:11], v[0:1], 0, v[160:161]
	flat_store_dwordx4 v[10:11], v[6:9] nt
	ds_read_b32 v6, v63 offset:32
	ds_read_b32 v7, v63 offset:164
	v_lshlrev_b32_e32 v160, 11, v4
	s_waitcnt lgkmcnt(0)
	v_cvt_pk_bf16_f32 v6, v6, v7
	ds_read_b32 v7, v63 offset:296
	ds_read_b32 v8, v63 offset:428
	s_waitcnt lgkmcnt(0)
	v_cvt_pk_bf16_f32 v7, v7, v8
	ds_read_b32 v8, v63 offset:560
	ds_read_b32 v9, v63 offset:692
	s_waitcnt lgkmcnt(0)
	v_cvt_pk_bf16_f32 v8, v8, v9
	ds_read_b32 v9, v63 offset:824
	ds_read_b32 v10, v63 offset:956
	s_waitcnt lgkmcnt(0)
	v_cvt_pk_bf16_f32 v9, v9, v10
	v_lshl_add_u64 v[10:11], v[0:1], 0, v[160:161]
	flat_store_dwordx4 v[10:11], v[6:9] nt
	ds_read_b32 v6, v63 offset:64
	ds_read_b32 v7, v63 offset:196
	v_lshlrev_b32_e32 v160, 11, v3
	s_waitcnt lgkmcnt(0)
	v_cvt_pk_bf16_f32 v6, v6, v7
	ds_read_b32 v7, v63 offset:328
	ds_read_b32 v8, v63 offset:460
	s_waitcnt lgkmcnt(0)
	v_cvt_pk_bf16_f32 v7, v7, v8
	ds_read_b32 v8, v63 offset:592
	ds_read_b32 v9, v63 offset:724
	s_waitcnt lgkmcnt(0)
	v_cvt_pk_bf16_f32 v8, v8, v9
	ds_read_b32 v9, v63 offset:856
	ds_read_b32 v10, v63 offset:988
	s_waitcnt lgkmcnt(0)
	v_cvt_pk_bf16_f32 v9, v9, v10
	v_lshl_add_u64 v[10:11], v[0:1], 0, v[160:161]
	flat_store_dwordx4 v[10:11], v[6:9] nt
	ds_read_b32 v6, v63 offset:96
	ds_read_b32 v7, v63 offset:228
	v_lshlrev_b32_e32 v160, 11, v2
	v_lshl_add_u64 v[0:1], v[0:1], 0, v[160:161]
	s_waitcnt lgkmcnt(0)
	v_cvt_pk_bf16_f32 v6, v6, v7
	ds_read_b32 v7, v63 offset:360
	ds_read_b32 v8, v63 offset:492
	s_waitcnt lgkmcnt(0)
	v_cvt_pk_bf16_f32 v7, v7, v8
	ds_read_b32 v8, v63 offset:624
	ds_read_b32 v9, v63 offset:756
	s_waitcnt lgkmcnt(0)
	v_cvt_pk_bf16_f32 v8, v8, v9
	ds_read_b32 v9, v63 offset:888
	ds_read_b32 v10, v63 offset:1020
	s_waitcnt lgkmcnt(0)
	v_cvt_pk_bf16_f32 v9, v9, v10
	flat_store_dwordx4 v[0:1], v[6:9] nt
	s_waitcnt lgkmcnt(0)
.LBB0_494:
	s_andn2_b64 vcc, exec, s[0:1]
	s_cbranch_vccnz .LBB0_496
	s_and_b32 s0, s8, 0x1ffc0
	v_or_b32_e32 v6, s0, v32
	s_lshl_b32 s42, s4, 2
	v_lshl_add_u64 v[0:1], v[40:41], 0, s[42:43]
	v_lshlrev_b32_e32 v160, 12, v6
	v_lshl_add_u64 v[0:1], v[0:1], 0, v[160:161]
	v_add_co_u32_e32 v10, vcc, 0x8000, v0
	s_mov_b32 s1, 0x10000
	s_nop 0
	v_addc_co_u32_e32 v11, vcc, 0, v1, vcc
	global_load_dwordx4 v[6:9], v[0:1], off
	v_add_co_u32_e32 v14, vcc, s1, v0
	global_load_dwordx4 v[10:13], v[10:11], off
	s_nop 0
	v_addc_co_u32_e32 v15, vcc, 0, v1, vcc
	s_mov_b32 s1, 0x18000
	global_load_dwordx4 v[14:17], v[14:15], off
	v_add_co_u32_e32 v18, vcc, s1, v0
	s_lshl_b32 s42, s0, 1
	s_nop 0
	v_addc_co_u32_e32 v19, vcc, 0, v1, vcc
	global_load_dwordx4 v[18:21], v[18:19], off
	v_add_co_u32_e32 v22, vcc, 0x20000, v0
	v_lshlrev_b32_e32 v160, 11, v5
	s_nop 0
	v_addc_co_u32_e32 v23, vcc, 0, v1, vcc
	global_load_dwordx4 v[22:25], v[22:23], off
	v_add_co_u32_e32 v26, vcc, 0x28000, v0
	s_movk_i32 s33, 0x4000
	s_nop 0
	v_addc_co_u32_e32 v27, vcc, 0, v1, vcc
	global_load_dwordx4 v[26:29], v[26:27], off
	v_add_co_u32_e32 v30, vcc, 0x30000, v0
	s_nop 1
	v_addc_co_u32_e32 v31, vcc, 0, v1, vcc
	global_load_dwordx4 v[70:73], v[30:31], off
	v_add_co_u32_e32 v0, vcc, 0x38000, v0
	s_nop 1
	v_addc_co_u32_e32 v1, vcc, 0, v1, vcc
	global_load_dwordx4 v[74:77], v[0:1], off
	v_add_u32_e32 v0, v57, v59
	v_add_u32_e32 v1, 0x420, v0
	s_waitcnt vmcnt(0)
	ds_write2_b32 v0, v6, v7 offset1:1
	ds_write2_b32 v0, v8, v9 offset0:2 offset1:3
	ds_write2_b32 v1, v10, v11 offset1:1
	v_add_u32_e32 v1, 0x428, v0
	ds_write2_b32 v1, v12, v13 offset1:1
	v_add_u32_e32 v1, 0x840, v0
	ds_write2_b32 v1, v14, v15 offset1:1
	v_add_u32_e32 v1, 0x848, v0
	ds_write2_b32 v1, v16, v17 offset1:1
	v_add_u32_e32 v1, 0xc60, v0
	ds_write2_b32 v1, v18, v19 offset1:1
	v_add_u32_e32 v1, 0xc68, v0
	ds_write2_b32 v1, v20, v21 offset1:1
	v_add_u32_e32 v1, 0x1080, v0
	ds_write2_b32 v1, v22, v23 offset1:1
	v_add_u32_e32 v1, 0x1088, v0
	ds_write2_b32 v1, v24, v25 offset1:1
	v_add_u32_e32 v1, 0x14a0, v0
	ds_write2_b32 v1, v26, v27 offset1:1
	v_add_u32_e32 v1, 0x14a8, v0
	ds_write2_b32 v1, v28, v29 offset1:1
	v_add_u32_e32 v1, 0x18c0, v0
	ds_write2_b32 v1, v70, v71 offset1:1
	v_add_u32_e32 v1, 0x18c8, v0
	ds_write2_b32 v1, v72, v73 offset1:1
	v_add_u32_e32 v1, 0x1ce0, v0
	v_add_u32_e32 v0, 0x1ce8, v0
	ds_write2_b32 v1, v74, v75 offset1:1
	ds_write2_b32 v0, v76, v77 offset1:1
	s_waitcnt lgkmcnt(0)
	ds_read_b32 v6, v63
	ds_read_b32 v7, v63 offset:132
	v_lshl_add_u64 v[0:1], v[48:49], 0, s[42:43]
	s_mov_b32 s42, 0x8000
	s_waitcnt lgkmcnt(0)
	v_cvt_pk_bf16_f32 v6, v6, v7
	ds_read_b32 v7, v63 offset:264
	ds_read_b32 v8, v63 offset:396
	s_waitcnt lgkmcnt(0)
	v_cvt_pk_bf16_f32 v7, v7, v8
	ds_read_b32 v8, v63 offset:528
	ds_read_b32 v9, v63 offset:660
	s_waitcnt lgkmcnt(0)
	v_cvt_pk_bf16_f32 v8, v8, v9
	ds_read_b32 v9, v63 offset:792
	ds_read_b32 v10, v63 offset:924
	s_waitcnt lgkmcnt(0)
	v_cvt_pk_bf16_f32 v9, v9, v10
	v_lshl_add_u64 v[10:11], v[0:1], 0, v[160:161]
	flat_store_dwordx4 v[10:11], v[6:9] nt
	ds_read_b32 v5, v63 offset:32
	ds_read_b32 v6, v63 offset:164
	v_lshlrev_b32_e32 v160, 11, v4
	s_waitcnt lgkmcnt(0)
	v_cvt_pk_bf16_f32 v6, v5, v6
	ds_read_b32 v5, v63 offset:296
	ds_read_b32 v7, v63 offset:428
	s_waitcnt lgkmcnt(0)
	v_cvt_pk_bf16_f32 v7, v5, v7
	ds_read_b32 v5, v63 offset:560
	ds_read_b32 v8, v63 offset:692
	s_waitcnt lgkmcnt(0)
	v_cvt_pk_bf16_f32 v8, v5, v8
	ds_read_b32 v5, v63 offset:824
	ds_read_b32 v9, v63 offset:956
	s_waitcnt lgkmcnt(0)
	v_cvt_pk_bf16_f32 v9, v5, v9
	v_lshl_add_u64 v[4:5], v[0:1], 0, v[160:161]
	flat_store_dwordx4 v[4:5], v[6:9] nt
	ds_read_b32 v4, v63 offset:64
	ds_read_b32 v5, v63 offset:196
	v_lshlrev_b32_e32 v160, 11, v3
	s_waitcnt lgkmcnt(0)
	v_cvt_pk_bf16_f32 v4, v4, v5
	ds_read_b32 v5, v63 offset:328
	ds_read_b32 v6, v63 offset:460
	s_waitcnt lgkmcnt(0)
	v_cvt_pk_bf16_f32 v5, v5, v6
	ds_read_b32 v6, v63 offset:592
	ds_read_b32 v7, v63 offset:724
	s_waitcnt lgkmcnt(0)
	v_cvt_pk_bf16_f32 v6, v6, v7
	ds_read_b32 v7, v63 offset:856
	ds_read_b32 v8, v63 offset:988
	s_waitcnt lgkmcnt(0)
	v_cvt_pk_bf16_f32 v7, v7, v8
	v_lshl_add_u64 v[8:9], v[0:1], 0, v[160:161]
	flat_store_dwordx4 v[8:9], v[4:7] nt
	ds_read_b32 v3, v63 offset:96
	ds_read_b32 v4, v63 offset:228
	v_lshlrev_b32_e32 v160, 11, v2
	v_lshl_add_u64 v[0:1], v[0:1], 0, v[160:161]
	s_waitcnt lgkmcnt(0)
	v_cvt_pk_bf16_f32 v4, v3, v4
	ds_read_b32 v3, v63 offset:360
	ds_read_b32 v5, v63 offset:492
	s_waitcnt lgkmcnt(0)
	v_cvt_pk_bf16_f32 v5, v3, v5
	ds_read_b32 v3, v63 offset:624
	ds_read_b32 v6, v63 offset:756
	s_waitcnt lgkmcnt(0)
	v_cvt_pk_bf16_f32 v6, v3, v6
	ds_read_b32 v3, v63 offset:888
	ds_read_b32 v7, v63 offset:1020
	s_waitcnt lgkmcnt(0)
	v_cvt_pk_bf16_f32 v7, v3, v7
	flat_store_dwordx4 v[0:1], v[4:7] nt
	s_waitcnt lgkmcnt(0)

.LBB0_500:
	s_lshl_b32 s1, s1, 6
	s_and_b32 s1, s1, 0xffc0
	s_lshl_b32 s42, s5, 2
	v_or_b32_e32 v54, s1, v32
	v_lshl_add_u64 v[0:1], v[42:43], 0, s[42:43]
	s_movk_i32 s4, 0x3000
	v_mad_u64_u32 v[2:3], s[4:5], v54, s4, v[0:1]
	v_readlane_b32 s4, v254, 4
	global_load_dwordx4 v[12:15], v[2:3], off
	v_mul_u32_u24_e32 v2, 0xc00, v54
	v_lshlrev_b32_e32 v54, 2, v54
	v_readlane_b32 s5, v254, 5
	v_lshlrev_b32_e32 v160, 2, v2
	v_lshl_add_u64 v[0:1], v[0:1], 0, v[160:161]
	v_add_co_u32_e32 v2, vcc, 0x18000, v0
	s_lshl_b32 s42, s1, 1
	s_nop 0
	global_load_dword v54, v54, s[4:5]
	v_addc_co_u32_e32 v3, vcc, 0, v1, vcc
	global_load_dwordx4 v[16:19], v[2:3], off
	v_add_co_u32_e32 v2, vcc, 0x30000, v0
	s_movk_i32 s33, 0x4000
	s_nop 0
	v_addc_co_u32_e32 v3, vcc, 0, v1, vcc
	global_load_dwordx4 v[20:23], v[2:3], off
	v_add_co_u32_e32 v2, vcc, 0x48000, v0
	s_waitcnt vmcnt(0)
	v_pk_mul_f32 v[12:13], v[12:13], v[54:55] op_sel_hi:[1,0]
	v_add_u32_e32 v55, v57, v59
	ds_write2_b32 v55, v12, v13 offset1:1
	v_pk_mul_f32 v[12:13], v[14:15], v[54:55] op_sel_hi:[1,0]
	ds_write2_b32 v55, v12, v13 offset0:2 offset1:3
	v_or_b32_e32 v12, s1, v60
	v_lshlrev_b32_e32 v12, 2, v12
	global_load_dword v12, v12, s[4:5]
	v_addc_co_u32_e32 v3, vcc, 0, v1, vcc
	global_load_dwordx4 v[24:27], v[2:3], off
	v_add_co_u32_e32 v2, vcc, 0x60000, v0
	s_waitcnt vmcnt(0)
	v_pk_mul_f32 v[14:15], v[16:17], v[12:13] op_sel_hi:[1,0]
	v_add_u32_e32 v13, 0x420, v55
	ds_write2_b32 v13, v14, v15 offset1:1
	v_pk_mul_f32 v[12:13], v[18:19], v[12:13] op_sel_hi:[1,0]
	v_add_u32_e32 v14, 0x428, v55
	ds_write2_b32 v14, v12, v13 offset1:1
	v_or_b32_e32 v12, s1, v61
	v_lshlrev_b32_e32 v12, 2, v12
	global_load_dword v12, v12, s[4:5]
	v_addc_co_u32_e32 v3, vcc, 0, v1, vcc
	global_load_dwordx4 v[28:31], v[2:3], off
	v_add_u32_e32 v16, v57, v65
	v_add_co_u32_e32 v2, vcc, 0x78000, v0
	s_waitcnt vmcnt(0)
	v_pk_mul_f32 v[14:15], v[20:21], v[12:13] op_sel_hi:[1,0]
	v_add_u32_e32 v13, 0x840, v55
	ds_write2_b32 v13, v14, v15 offset1:1
	v_pk_mul_f32 v[12:13], v[22:23], v[12:13] op_sel_hi:[1,0]
	v_add_u32_e32 v14, 0x848, v55
	ds_write2_b32 v14, v12, v13 offset1:1
	v_or_b32_e32 v12, s1, v62
	v_lshlrev_b32_e32 v12, 2, v12
	global_load_dword v12, v12, s[4:5]
	v_addc_co_u32_e32 v3, vcc, 0, v1, vcc
	global_load_dwordx4 v[8:11], v[2:3], off
	v_add_co_u32_e32 v2, vcc, 0x90000, v0
	s_waitcnt vmcnt(0)
	v_pk_mul_f32 v[14:15], v[24:25], v[12:13] op_sel_hi:[1,0]
	v_add_u32_e32 v13, 0xc60, v55
	ds_write2_b32 v13, v14, v15 offset1:1
	v_pk_mul_f32 v[12:13], v[26:27], v[12:13] op_sel_hi:[1,0]
	v_add_u32_e32 v14, 0xc68, v55
	ds_write2_b32 v14, v12, v13 offset1:1
	v_or_b32_e32 v12, s1, v64
	v_lshlrev_b32_e32 v12, 2, v12
	global_load_dword v12, v12, s[4:5]
	v_addc_co_u32_e32 v3, vcc, 0, v1, vcc
	global_load_dwordx4 v[4:7], v[2:3], off
	v_add_co_u32_e32 v0, vcc, 0xa8000, v0
	s_waitcnt vmcnt(0)
	v_pk_mul_f32 v[14:15], v[28:29], v[12:13] op_sel_hi:[1,0]
	v_pk_mul_f32 v[12:13], v[30:31], v[12:13] op_sel_hi:[1,0]
	ds_write2_b32 v16, v12, v13 offset0:2 offset1:3
	v_or_b32_e32 v12, s1, v66
	v_lshlrev_b32_e32 v12, 2, v12
	global_load_dword v12, v12, s[4:5]
	v_addc_co_u32_e32 v1, vcc, 0, v1, vcc
	global_load_dwordx4 v[0:3], v[0:1], off
	ds_write2_b32 v16, v14, v15 offset1:1
	s_waitcnt vmcnt(0)
	v_pk_mul_f32 v[8:9], v[8:9], v[12:13] op_sel_hi:[1,0]
	v_add_u32_e32 v13, 0x420, v16
	ds_write2_b32 v13, v8, v9 offset1:1
	v_pk_mul_f32 v[8:9], v[10:11], v[12:13] op_sel_hi:[1,0]
	v_add_u32_e32 v10, 0x428, v16
	ds_write2_b32 v10, v8, v9 offset1:1
	v_or_b32_e32 v8, s1, v67
	v_lshlrev_b32_e32 v8, 2, v8
	global_load_dword v8, v8, s[4:5]
	s_waitcnt vmcnt(0)
	v_pk_mul_f32 v[4:5], v[4:5], v[8:9] op_sel_hi:[1,0]
	v_add_u32_e32 v9, 0x840, v16
	ds_write2_b32 v9, v4, v5 offset1:1
	v_pk_mul_f32 v[4:5], v[6:7], v[8:9] op_sel_hi:[1,0]
	v_add_u32_e32 v6, 0x848, v16
	ds_write2_b32 v6, v4, v5 offset1:1
	v_or_b32_e32 v4, s1, v68
	v_lshlrev_b32_e32 v4, 2, v4
	global_load_dword v4, v4, s[4:5]
	s_waitcnt vmcnt(0)
	v_pk_mul_f32 v[0:1], v[0:1], v[4:5] op_sel_hi:[1,0]
	v_add_u32_e32 v5, 0xc60, v16
	ds_write2_b32 v5, v0, v1 offset1:1
	v_pk_mul_f32 v[0:1], v[2:3], v[4:5] op_sel_hi:[1,0]
	v_add_u32_e32 v2, 0xc68, v16
	ds_write2_b32 v2, v0, v1 offset1:1
	s_waitcnt lgkmcnt(0)
	ds_read_b32 v0, v63
	ds_read_b32 v1, v63 offset:132
	v_lshl_add_u64 v[4:5], v[50:51], 0, s[42:43]
	s_mov_b32 s42, 0x8000
	s_waitcnt lgkmcnt(0)
	v_cvt_pk_bf16_f32 v0, v0, v1
	ds_read_b32 v1, v63 offset:264
	ds_read_b32 v2, v63 offset:396
	s_waitcnt lgkmcnt(0)
	v_cvt_pk_bf16_f32 v1, v1, v2
	ds_read_b32 v2, v63 offset:528
	ds_read_b32 v3, v63 offset:660
	s_waitcnt lgkmcnt(0)
	v_cvt_pk_bf16_f32 v2, v2, v3
	ds_read_b32 v3, v63 offset:792
	ds_read_b32 v6, v63 offset:924
	s_waitcnt lgkmcnt(0)
	v_cvt_pk_bf16_f32 v3, v3, v6
	v_or_b32_e32 v6, s0, v32
	v_lshlrev_b32_e32 v160, 11, v6
	v_lshl_add_u64 v[6:7], v[4:5], 0, v[160:161]
	flat_store_dwordx4 v[6:7], v[0:3] nt
	ds_read_b32 v0, v63 offset:32
	ds_read_b32 v1, v63 offset:164
	s_waitcnt lgkmcnt(0)
	v_cvt_pk_bf16_f32 v0, v0, v1
	ds_read_b32 v1, v63 offset:296
	ds_read_b32 v2, v63 offset:428
	s_waitcnt lgkmcnt(0)
	v_cvt_pk_bf16_f32 v1, v1, v2
	ds_read_b32 v2, v63 offset:560
	ds_read_b32 v3, v63 offset:692
	s_waitcnt lgkmcnt(0)
	v_cvt_pk_bf16_f32 v2, v2, v3
	ds_read_b32 v3, v63 offset:824
	ds_read_b32 v6, v63 offset:956
	s_waitcnt lgkmcnt(0)
	v_cvt_pk_bf16_f32 v3, v3, v6
	v_or_b32_e32 v6, s0, v60
	v_lshlrev_b32_e32 v160, 11, v6
	v_lshl_add_u64 v[6:7], v[4:5], 0, v[160:161]
	flat_store_dwordx4 v[6:7], v[0:3] nt
	ds_read_b32 v0, v63 offset:64
	ds_read_b32 v1, v63 offset:196
	s_waitcnt lgkmcnt(0)
	v_cvt_pk_bf16_f32 v0, v0, v1
	ds_read_b32 v1, v63 offset:328
	ds_read_b32 v2, v63 offset:460
	s_waitcnt lgkmcnt(0)
	v_cvt_pk_bf16_f32 v1, v1, v2
	ds_read_b32 v2, v63 offset:592
	ds_read_b32 v3, v63 offset:724
	s_waitcnt lgkmcnt(0)
	v_cvt_pk_bf16_f32 v2, v2, v3
	ds_read_b32 v3, v63 offset:856
	ds_read_b32 v6, v63 offset:988
	s_waitcnt lgkmcnt(0)
	v_cvt_pk_bf16_f32 v3, v3, v6
	v_or_b32_e32 v6, s0, v61
	v_lshlrev_b32_e32 v160, 11, v6
	v_lshl_add_u64 v[6:7], v[4:5], 0, v[160:161]
	flat_store_dwordx4 v[6:7], v[0:3] nt
	ds_read_b32 v0, v63 offset:96
	ds_read_b32 v1, v63 offset:228
	s_waitcnt lgkmcnt(0)
	v_cvt_pk_bf16_f32 v0, v0, v1
	ds_read_b32 v1, v63 offset:360
	ds_read_b32 v2, v63 offset:492
	s_waitcnt lgkmcnt(0)
	v_cvt_pk_bf16_f32 v1, v1, v2
	ds_read_b32 v2, v63 offset:624
	ds_read_b32 v3, v63 offset:756
	s_waitcnt lgkmcnt(0)
	v_cvt_pk_bf16_f32 v2, v2, v3
	ds_read_b32 v3, v63 offset:888
	ds_read_b32 v6, v63 offset:1020
	s_waitcnt lgkmcnt(0)
	v_cvt_pk_bf16_f32 v3, v3, v6
	v_or_b32_e32 v6, s0, v62
	v_lshlrev_b32_e32 v160, 11, v6
	v_lshl_add_u64 v[4:5], v[4:5], 0, v[160:161]
	flat_store_dwordx4 v[4:5], v[0:3] nt
	s_waitcnt lgkmcnt(0)

.LBB0_507:
	s_lshl_b32 s0, s5, 6
	s_and_b32 s0, s0, 0xffc0
	v_or_b32_e32 v54, s0, v32
	v_lshl_add_u64 v[0:1], s[42:43], 2, v[44:45]
	s_movk_i32 s1, 0x3000
	v_mad_u64_u32 v[2:3], s[6:7], v54, s1, v[0:1]
	v_readlane_b32 s6, v254, 6
	global_load_dwordx4 v[12:15], v[2:3], off
	v_mul_u32_u24_e32 v2, 0xc00, v54
	v_lshlrev_b32_e32 v54, 2, v54
	v_readlane_b32 s7, v254, 7
	v_lshlrev_b32_e32 v160, 2, v2
	v_lshl_add_u64 v[0:1], v[0:1], 0, v[160:161]
	v_add_co_u32_e32 v2, vcc, 0x18000, v0
	s_lshl_b32 s42, s0, 1
	s_nop 0
	global_load_dword v54, v54, s[6:7]
	v_addc_co_u32_e32 v3, vcc, 0, v1, vcc
	global_load_dwordx4 v[16:19], v[2:3], off
	v_add_co_u32_e32 v2, vcc, 0x30000, v0
	s_movk_i32 s33, 0x4000
	s_nop 0
	v_addc_co_u32_e32 v3, vcc, 0, v1, vcc
	global_load_dwordx4 v[20:23], v[2:3], off
	v_add_co_u32_e32 v2, vcc, 0x48000, v0
	s_waitcnt vmcnt(0)
	v_pk_mul_f32 v[12:13], v[12:13], v[54:55] op_sel_hi:[1,0]
	v_add_u32_e32 v55, v57, v59
	ds_write2_b32 v55, v12, v13 offset1:1
	v_pk_mul_f32 v[12:13], v[14:15], v[54:55] op_sel_hi:[1,0]
	ds_write2_b32 v55, v12, v13 offset0:2 offset1:3
	v_or_b32_e32 v12, s0, v60
	v_lshlrev_b32_e32 v12, 2, v12
	global_load_dword v12, v12, s[6:7]
	v_addc_co_u32_e32 v3, vcc, 0, v1, vcc
	global_load_dwordx4 v[24:27], v[2:3], off
	v_add_co_u32_e32 v2, vcc, 0x60000, v0
	s_waitcnt vmcnt(0)
	v_pk_mul_f32 v[14:15], v[16:17], v[12:13] op_sel_hi:[1,0]
	v_add_u32_e32 v13, 0x420, v55
	ds_write2_b32 v13, v14, v15 offset1:1
	v_pk_mul_f32 v[12:13], v[18:19], v[12:13] op_sel_hi:[1,0]
	v_add_u32_e32 v14, 0x428, v55
	ds_write2_b32 v14, v12, v13 offset1:1
	v_or_b32_e32 v12, s0, v61
	v_lshlrev_b32_e32 v12, 2, v12
	global_load_dword v12, v12, s[6:7]
	v_addc_co_u32_e32 v3, vcc, 0, v1, vcc
	global_load_dwordx4 v[28:31], v[2:3], off
	v_add_u32_e32 v16, v57, v65
	v_add_co_u32_e32 v2, vcc, 0x78000, v0
	s_waitcnt vmcnt(0)
	v_pk_mul_f32 v[14:15], v[20:21], v[12:13] op_sel_hi:[1,0]
	v_add_u32_e32 v13, 0x840, v55
	ds_write2_b32 v13, v14, v15 offset1:1
	v_pk_mul_f32 v[12:13], v[22:23], v[12:13] op_sel_hi:[1,0]
	v_add_u32_e32 v14, 0x848, v55
	ds_write2_b32 v14, v12, v13 offset1:1
	v_or_b32_e32 v12, s0, v62
	v_lshlrev_b32_e32 v12, 2, v12
	global_load_dword v12, v12, s[6:7]
	v_addc_co_u32_e32 v3, vcc, 0, v1, vcc
	global_load_dwordx4 v[8:11], v[2:3], off
	v_add_co_u32_e32 v2, vcc, 0x90000, v0
	s_waitcnt vmcnt(0)
	v_pk_mul_f32 v[14:15], v[24:25], v[12:13] op_sel_hi:[1,0]
	v_add_u32_e32 v13, 0xc60, v55
	ds_write2_b32 v13, v14, v15 offset1:1
	v_pk_mul_f32 v[12:13], v[26:27], v[12:13] op_sel_hi:[1,0]
	v_add_u32_e32 v14, 0xc68, v55
	ds_write2_b32 v14, v12, v13 offset1:1
	v_or_b32_e32 v12, s0, v64
	v_lshlrev_b32_e32 v12, 2, v12
	global_load_dword v12, v12, s[6:7]
	v_addc_co_u32_e32 v3, vcc, 0, v1, vcc
	global_load_dwordx4 v[4:7], v[2:3], off
	v_add_co_u32_e32 v0, vcc, 0xa8000, v0
	s_waitcnt vmcnt(0)
	v_pk_mul_f32 v[14:15], v[28:29], v[12:13] op_sel_hi:[1,0]
	v_pk_mul_f32 v[12:13], v[30:31], v[12:13] op_sel_hi:[1,0]
	ds_write2_b32 v16, v12, v13 offset0:2 offset1:3
	v_or_b32_e32 v12, s0, v66
	v_lshlrev_b32_e32 v12, 2, v12
	global_load_dword v12, v12, s[6:7]
	v_addc_co_u32_e32 v1, vcc, 0, v1, vcc
	global_load_dwordx4 v[0:3], v[0:1], off
	ds_write2_b32 v16, v14, v15 offset1:1
	s_waitcnt vmcnt(0)
	v_pk_mul_f32 v[8:9], v[8:9], v[12:13] op_sel_hi:[1,0]
	v_add_u32_e32 v13, 0x420, v16
	ds_write2_b32 v13, v8, v9 offset1:1
	v_pk_mul_f32 v[8:9], v[10:11], v[12:13] op_sel_hi:[1,0]
	v_add_u32_e32 v10, 0x428, v16
	ds_write2_b32 v10, v8, v9 offset1:1
	v_or_b32_e32 v8, s0, v67
	v_lshlrev_b32_e32 v8, 2, v8
	global_load_dword v8, v8, s[6:7]
	s_waitcnt vmcnt(0)
	v_pk_mul_f32 v[4:5], v[4:5], v[8:9] op_sel_hi:[1,0]
	v_add_u32_e32 v9, 0x840, v16
	ds_write2_b32 v9, v4, v5 offset1:1
	v_pk_mul_f32 v[4:5], v[6:7], v[8:9] op_sel_hi:[1,0]
	v_add_u32_e32 v6, 0x848, v16
	ds_write2_b32 v6, v4, v5 offset1:1
	v_or_b32_e32 v4, s0, v68
	v_lshlrev_b32_e32 v4, 2, v4
	global_load_dword v4, v4, s[6:7]
	s_waitcnt vmcnt(0)
	v_pk_mul_f32 v[0:1], v[0:1], v[4:5] op_sel_hi:[1,0]
	v_add_u32_e32 v5, 0xc60, v16
	ds_write2_b32 v5, v0, v1 offset1:1
	v_pk_mul_f32 v[0:1], v[2:3], v[4:5] op_sel_hi:[1,0]
	v_add_u32_e32 v2, 0xc68, v16
	ds_write2_b32 v2, v0, v1 offset1:1
	s_waitcnt lgkmcnt(0)
	ds_read_b32 v0, v63
	ds_read_b32 v1, v63 offset:132
	v_lshl_add_u64 v[4:5], v[52:53], 0, s[42:43]
	s_mov_b32 s42, 0x8000
	s_waitcnt lgkmcnt(0)
	v_cvt_pk_bf16_f32 v0, v0, v1
	ds_read_b32 v1, v63 offset:264
	ds_read_b32 v2, v63 offset:396
	s_waitcnt lgkmcnt(0)
	v_cvt_pk_bf16_f32 v1, v1, v2
	ds_read_b32 v2, v63 offset:528
	ds_read_b32 v3, v63 offset:660
	s_waitcnt lgkmcnt(0)
	v_cvt_pk_bf16_f32 v2, v2, v3
	ds_read_b32 v3, v63 offset:792
	ds_read_b32 v6, v63 offset:924
	s_waitcnt lgkmcnt(0)
	v_cvt_pk_bf16_f32 v3, v3, v6
	v_or_b32_e32 v6, s4, v32
	v_lshlrev_b32_e32 v160, 11, v6
	v_lshl_add_u64 v[6:7], v[4:5], 0, v[160:161]
	flat_store_dwordx4 v[6:7], v[0:3] nt
	ds_read_b32 v0, v63 offset:32
	ds_read_b32 v1, v63 offset:164
	s_waitcnt lgkmcnt(0)
	v_cvt_pk_bf16_f32 v0, v0, v1
	ds_read_b32 v1, v63 offset:296
	ds_read_b32 v2, v63 offset:428
	s_waitcnt lgkmcnt(0)
	v_cvt_pk_bf16_f32 v1, v1, v2
	ds_read_b32 v2, v63 offset:560
	ds_read_b32 v3, v63 offset:692
	s_waitcnt lgkmcnt(0)
	v_cvt_pk_bf16_f32 v2, v2, v3
	ds_read_b32 v3, v63 offset:824
	ds_read_b32 v6, v63 offset:956
	s_waitcnt lgkmcnt(0)
	v_cvt_pk_bf16_f32 v3, v3, v6
	v_or_b32_e32 v6, s4, v60
	v_lshlrev_b32_e32 v160, 11, v6
	v_lshl_add_u64 v[6:7], v[4:5], 0, v[160:161]
	flat_store_dwordx4 v[6:7], v[0:3] nt
	ds_read_b32 v0, v63 offset:64
	ds_read_b32 v1, v63 offset:196
	s_waitcnt lgkmcnt(0)
	v_cvt_pk_bf16_f32 v0, v0, v1
	ds_read_b32 v1, v63 offset:328
	ds_read_b32 v2, v63 offset:460
	s_waitcnt lgkmcnt(0)
	v_cvt_pk_bf16_f32 v1, v1, v2
	ds_read_b32 v2, v63 offset:592
	ds_read_b32 v3, v63 offset:724
	s_waitcnt lgkmcnt(0)
	v_cvt_pk_bf16_f32 v2, v2, v3
	ds_read_b32 v3, v63 offset:856
	ds_read_b32 v6, v63 offset:988
	s_waitcnt lgkmcnt(0)
	v_cvt_pk_bf16_f32 v3, v3, v6
	v_or_b32_e32 v6, s4, v61
	v_lshlrev_b32_e32 v160, 11, v6
	v_lshl_add_u64 v[6:7], v[4:5], 0, v[160:161]
	flat_store_dwordx4 v[6:7], v[0:3] nt
	ds_read_b32 v0, v63 offset:96
	ds_read_b32 v1, v63 offset:228
	s_waitcnt lgkmcnt(0)
	v_cvt_pk_bf16_f32 v0, v0, v1
	ds_read_b32 v1, v63 offset:360
	ds_read_b32 v2, v63 offset:492
	s_waitcnt lgkmcnt(0)
	v_cvt_pk_bf16_f32 v1, v1, v2
	ds_read_b32 v2, v63 offset:624
	ds_read_b32 v3, v63 offset:756
	s_waitcnt lgkmcnt(0)
	v_cvt_pk_bf16_f32 v2, v2, v3
	ds_read_b32 v3, v63 offset:888
	ds_read_b32 v6, v63 offset:1020
	s_waitcnt lgkmcnt(0)
	v_cvt_pk_bf16_f32 v3, v3, v6
	v_or_b32_e32 v6, s4, v62
	v_lshlrev_b32_e32 v160, 11, v6
	v_lshl_add_u64 v[4:5], v[4:5], 0, v[160:161]
	flat_store_dwordx4 v[4:5], v[0:3] nt
	s_waitcnt lgkmcnt(0)

.LBB0_509:
	s_andn2_b64 vcc, exec, s[0:1]
	s_cbranch_vccnz .LBB0_511
	s_add_i32 s0, s10, 0xd400
	s_and_b32 s1, s0, 0xffff
	s_mul_i32 s1, s1, 0xba2f
	s_lshr_b32 s1, s1, 26
	v_readlane_b32 s44, v254, 8
	s_mul_i32 s4, s1, 0xb00000
	v_readlane_b32 s52, v254, 16
	v_readlane_b32 s53, v254, 17
	s_add_u32 s4, s52, s4
	s_addc_u32 s5, s53, 0
	s_mul_i32 s6, s1, 0x580000
	s_add_u32 s6, s94, s6
	s_mulk_i32 s1, 0x580
	s_addc_u32 s7, s95, 0
	s_sub_i32 s0, s0, s1
	s_lshl_b32 s1, s0, 1
	s_lshl_b32 s0, s0, 5
	s_and_b32 s0, s0, 0x3e0
	s_and_b32 s1, s1, 0xfc0
	s_lshl_b32 s11, s0, 2
	s_add_u32 s4, s4, s11
	v_or_b32_e32 v2, s1, v32
	s_addc_u32 s5, s5, 0
	v_lshlrev_b32_e32 v160, 2, v34
	v_lshl_add_u64 v[0:1], s[4:5], 0, v[160:161]
	v_lshlrev_b32_e32 v160, 12, v2
	v_lshl_add_u64 v[28:29], v[0:1], 0, v[160:161]
	v_add_co_u32_e32 v4, vcc, s42, v28
	global_load_dwordx4 v[0:3], v[28:29], off
	s_nop 0
	v_addc_co_u32_e32 v5, vcc, 0, v29, vcc
	s_mov_b32 s4, 0x10000
	global_load_dwordx4 v[4:7], v[4:5], off
	v_add_co_u32_e32 v8, vcc, s4, v28
	s_mov_b32 s4, 0x18000
	s_nop 0
	v_addc_co_u32_e32 v9, vcc, 0, v29, vcc
	global_load_dwordx4 v[8:11], v[8:9], off
	v_add_co_u32_e32 v12, vcc, s4, v28
	s_mov_b32 s4, 0x20000
	s_nop 0
	v_addc_co_u32_e32 v13, vcc, 0, v29, vcc
	global_load_dwordx4 v[12:15], v[12:13], off
	v_add_co_u32_e32 v16, vcc, s4, v28
	s_mov_b32 s4, 0x28000
	s_nop 0
	v_addc_co_u32_e32 v17, vcc, 0, v29, vcc
	global_load_dwordx4 v[16:19], v[16:17], off
	v_add_co_u32_e32 v20, vcc, s4, v28
	s_mov_b32 s4, 0x30000
	s_nop 0
	v_addc_co_u32_e32 v21, vcc, 0, v29, vcc
	global_load_dwordx4 v[20:23], v[20:21], off
	v_add_co_u32_e32 v24, vcc, s4, v28
	s_mov_b32 s4, 0x38000
	s_nop 0
	v_addc_co_u32_e32 v25, vcc, 0, v29, vcc
	global_load_dwordx4 v[24:27], v[24:25], off
	v_add_co_u32_e32 v28, vcc, s4, v28
	v_add_u32_e32 v54, v57, v59
	s_nop 0
	v_addc_co_u32_e32 v29, vcc, 0, v29, vcc
	global_load_dwordx4 v[28:31], v[28:29], off
	s_lshl_b32 s1, s1, 1
	s_add_u32 s4, s6, s1
	s_addc_u32 s5, s7, 0
	v_lshlrev_b32_e32 v160, 1, v36
	v_readlane_b32 s45, v254, 9
	s_mov_b64 s[44:45], 0x100000
	v_readlane_b32 s46, v254, 10
	v_readlane_b32 s47, v254, 11
	v_readlane_b32 s48, v254, 12
	v_readlane_b32 s49, v254, 13
	v_readlane_b32 s50, v254, 14
	v_readlane_b32 s51, v254, 15
	v_readlane_b32 s54, v254, 18
	v_readlane_b32 s55, v254, 19
	v_readlane_b32 s56, v254, 20
	v_readlane_b32 s57, v254, 21
	v_readlane_b32 s58, v254, 22
	v_readlane_b32 s59, v254, 23
	s_waitcnt vmcnt(0)
	ds_write2_b32 v54, v0, v1 offset1:1
	ds_write2_b32 v54, v2, v3 offset0:2 offset1:3
	v_add_u32_e32 v0, 0x420, v54
	ds_write2_b32 v0, v4, v5 offset1:1
	v_add_u32_e32 v0, 0x428, v54
	ds_write2_b32 v0, v6, v7 offset1:1
	v_add_u32_e32 v0, 0x840, v54
	ds_write2_b32 v0, v8, v9 offset1:1
	v_add_u32_e32 v0, 0x848, v54
	ds_write2_b32 v0, v10, v11 offset1:1
	v_add_u32_e32 v0, 0xc60, v54
	ds_write2_b32 v0, v12, v13 offset1:1
	v_add_u32_e32 v0, 0xc68, v54
	ds_write2_b32 v0, v14, v15 offset1:1
	v_add_u32_e32 v0, 0x1080, v54
	ds_write2_b32 v0, v16, v17 offset1:1
	v_add_u32_e32 v0, 0x1088, v54
	ds_write2_b32 v0, v18, v19 offset1:1
	v_add_u32_e32 v0, 0x14a0, v54
	ds_write2_b32 v0, v20, v21 offset1:1
	v_add_u32_e32 v0, 0x14a8, v54
	ds_write2_b32 v0, v22, v23 offset1:1
	v_add_u32_e32 v0, 0x18c0, v54
	ds_write2_b32 v0, v24, v25 offset1:1
	v_add_u32_e32 v0, 0x18c8, v54
	ds_write2_b32 v0, v26, v27 offset1:1
	v_add_u32_e32 v0, 0x1ce0, v54
	ds_write2_b32 v0, v28, v29 offset1:1
	v_add_u32_e32 v0, 0x1ce8, v54
	ds_write2_b32 v0, v30, v31 offset1:1
	s_waitcnt lgkmcnt(0)
	v_lshl_add_u64 v[0:1], s[4:5], 0, v[160:161]
	s_mov_b64 s[4:5], 0x3400000
	v_lshl_add_u64 v[4:5], v[0:1], 0, s[4:5]
	ds_read_b32 v0, v63
	ds_read_b32 v1, v63 offset:132
	s_waitcnt lgkmcnt(0)
	v_cvt_pk_bf16_f32 v0, v0, v1
	ds_read_b32 v1, v63 offset:264
	ds_read_b32 v2, v63 offset:396
	s_waitcnt lgkmcnt(0)
	v_cvt_pk_bf16_f32 v1, v1, v2
	ds_read_b32 v2, v63 offset:528
	ds_read_b32 v3, v63 offset:660
	s_waitcnt lgkmcnt(0)
	v_cvt_pk_bf16_f32 v2, v2, v3
	ds_read_b32 v3, v63 offset:792
	ds_read_b32 v6, v63 offset:924
	s_waitcnt lgkmcnt(0)
	v_cvt_pk_bf16_f32 v3, v3, v6
	v_or_b32_e32 v6, s0, v32
	v_mul_u32_u24_e32 v6, 0xb00, v6
	v_lshlrev_b32_e32 v160, 1, v6
	v_lshl_add_u64 v[6:7], v[4:5], 0, v[160:161]
	flat_store_dwordx4 v[6:7], v[0:3] nt
	ds_read_b32 v0, v63 offset:32
	ds_read_b32 v1, v63 offset:164
	s_waitcnt lgkmcnt(0)
	v_cvt_pk_bf16_f32 v0, v0, v1
	ds_read_b32 v1, v63 offset:296
	ds_read_b32 v2, v63 offset:428
	s_waitcnt lgkmcnt(0)
	v_cvt_pk_bf16_f32 v1, v1, v2
	ds_read_b32 v2, v63 offset:560
	ds_read_b32 v3, v63 offset:692
	s_waitcnt lgkmcnt(0)
	v_cvt_pk_bf16_f32 v2, v2, v3
	ds_read_b32 v3, v63 offset:824
	ds_read_b32 v6, v63 offset:956
	s_waitcnt lgkmcnt(0)
	v_cvt_pk_bf16_f32 v3, v3, v6
	v_or_b32_e32 v6, s0, v60
	v_mul_u32_u24_e32 v6, 0xb00, v6
	v_lshlrev_b32_e32 v160, 1, v6
	v_lshl_add_u64 v[6:7], v[4:5], 0, v[160:161]
	flat_store_dwordx4 v[6:7], v[0:3] nt
	ds_read_b32 v0, v63 offset:64
	ds_read_b32 v1, v63 offset:196
	s_waitcnt lgkmcnt(0)
	v_cvt_pk_bf16_f32 v0, v0, v1
	ds_read_b32 v1, v63 offset:328
	ds_read_b32 v2, v63 offset:460
	s_waitcnt lgkmcnt(0)
	v_cvt_pk_bf16_f32 v1, v1, v2
	ds_read_b32 v2, v63 offset:592
	ds_read_b32 v3, v63 offset:724
	s_waitcnt lgkmcnt(0)
	v_cvt_pk_bf16_f32 v2, v2, v3
	ds_read_b32 v3, v63 offset:856
	ds_read_b32 v6, v63 offset:988
	s_waitcnt lgkmcnt(0)
	v_cvt_pk_bf16_f32 v3, v3, v6
	v_or_b32_e32 v6, s0, v61
	v_mul_u32_u24_e32 v6, 0xb00, v6
	v_lshlrev_b32_e32 v160, 1, v6
	v_lshl_add_u64 v[6:7], v[4:5], 0, v[160:161]
	flat_store_dwordx4 v[6:7], v[0:3] nt
	ds_read_b32 v0, v63 offset:96
	ds_read_b32 v1, v63 offset:228
	s_waitcnt lgkmcnt(0)
	v_cvt_pk_bf16_f32 v0, v0, v1
	ds_read_b32 v1, v63 offset:360
	ds_read_b32 v2, v63 offset:492
	s_waitcnt lgkmcnt(0)
	v_cvt_pk_bf16_f32 v1, v1, v2
	ds_read_b32 v2, v63 offset:624
	ds_read_b32 v3, v63 offset:756
	s_waitcnt lgkmcnt(0)
	v_cvt_pk_bf16_f32 v2, v2, v3
	ds_read_b32 v3, v63 offset:888
	ds_read_b32 v6, v63 offset:1020
	s_waitcnt lgkmcnt(0)
	v_cvt_pk_bf16_f32 v3, v3, v6
	v_or_b32_e32 v6, s0, v62
	v_mul_u32_u24_e32 v6, 0xb00, v6
	v_lshlrev_b32_e32 v160, 1, v6
	v_lshl_add_u64 v[4:5], v[4:5], 0, v[160:161]
	flat_store_dwordx4 v[4:5], v[0:3] nt
	s_waitcnt lgkmcnt(0)

.LBB0_552:
	s_or_b64 exec, exec, s[10:11]
	s_add_u32 s8, s8, 0x2000
	s_addc_u32 s9, s9, 0
	s_add_i32 s10, s2, s8
	s_addk_i32 s10, 0xe000
	s_add_u32 s12, s12, 0x10000
	s_addc_u32 s13, s13, 0
	s_add_u32 s14, s14, 0x10000
	s_addc_u32 s15, s15, 0
	s_add_u32 s19, s19, 0x10000
	s_addc_u32 s20, s20, 0
	v_cvt_pk_bf16_f32 v12, v12, v13
	v_cvt_pk_bf16_f32 v13, v14, v15
	v_cvt_pk_bf16_f32 v14, v8, v9
	v_lshl_add_u64 v[8:9], s[94:95], 0, v[64:65]
	s_add_u32 s21, s21, 0x10000
	v_add_co_u32_e32 v8, vcc, 0x5a00000, v8
	s_mov_b64 s[24:25], 0x1000000
	s_addc_u32 s22, s22, 0
	v_cvt_pk_bf16_f32 v15, v10, v11
	v_addc_co_u32_e32 v9, vcc, 0, v9, vcc
	v_cvt_pk_bf16_f32 v4, v4, v5
	v_cvt_pk_bf16_f32 v5, v6, v7
	v_cvt_pk_bf16_f32 v6, v0, v1
	v_cvt_pk_bf16_f32 v7, v2, v3
	v_lshl_add_u64 v[64:65], v[64:65], 0, s[24:25]
	v_lshl_add_u64 v[66:67], v[66:67], 0, s[24:25]
	v_lshl_add_u64 v[68:69], v[68:69], 0, s[24:25]
	s_cmpk_gt_i32 s10, 0x5fff
	v_lshl_add_u64 v[70:71], v[70:71], 0, s[24:25]
	flat_store_dwordx4 v[8:9], v[12:15] nt
	flat_store_dwordx4 v[8:9], v[4:7] offset:1024 nt
	s_cbranch_scc1 .LBB0_561

.LBB0_555:
	s_or_b64 exec, exec, s[10:11]
	v_mul_f32_e32 v79, v45, v45
	s_waitcnt lgkmcnt(0)
	v_mul_f32_e32 v80, v47, v47
	v_fmac_f32_e32 v79, v44, v44
	v_fmac_f32_e32 v80, v46, v46
	v_add_f32_e32 v79, v79, v80
	v_mul_f32_e32 v80, v41, v41
	v_mul_f32_e32 v81, v43, v43
	v_fmac_f32_e32 v80, v40, v40
	v_fmac_f32_e32 v81, v42, v42
	v_add_f32_e32 v80, v80, v81
	v_add_f32_e32 v79, v79, v80
	v_mul_f32_e32 v80, v37, v37
	v_mul_f32_e32 v81, v39, v39
	v_fmac_f32_e32 v80, v36, v36
	v_fmac_f32_e32 v81, v38, v38
	v_add_f32_e32 v80, v80, v81
	v_add_f32_e32 v79, v79, v80
	v_mul_f32_e32 v80, v33, v33
	v_mul_f32_e32 v81, v35, v35
	v_fmac_f32_e32 v80, v32, v32
	v_fmac_f32_e32 v81, v34, v34
	v_add_f32_e32 v80, v80, v81
	v_add_f32_e32 v79, v79, v80
	ds_bpermute_b32 v80, v72, v79
	v_cvt_pk_bf16_f32 v60, v60, v61
	v_cvt_pk_bf16_f32 v61, v62, v63
	v_cvt_pk_bf16_f32 v63, v58, v59
	v_cvt_pk_bf16_f32 v62, v56, v57
	s_waitcnt lgkmcnt(0)
	v_add_f32_e32 v79, v79, v80
	ds_bpermute_b32 v80, v73, v79
	v_lshl_add_u64 v[56:57], s[94:95], 0, v[70:71]
	s_waitcnt lgkmcnt(0)
	v_add_f32_e32 v79, v79, v80
	ds_bpermute_b32 v80, v74, v79
	s_waitcnt lgkmcnt(0)
	v_add_f32_e32 v79, v79, v80
	ds_bpermute_b32 v81, v75, v79
	v_add_co_u32_e32 v80, vcc, s27, v56
	v_cvt_pk_bf16_f32 v56, v52, v53
	s_waitcnt lgkmcnt(0)
	v_add_f32_e32 v58, v79, v81
	ds_bpermute_b32 v59, v76, v58
	v_addc_co_u32_e32 v81, vcc, 0, v57, vcc
	v_cvt_pk_bf16_f32 v57, v54, v55
	flat_store_dwordx4 v[80:81], v[60:63] nt
	s_waitcnt lgkmcnt(0)
	v_add_f32_e32 v52, v58, v59
	ds_bpermute_b32 v53, v77, v52
	v_cvt_pk_bf16_f32 v58, v48, v49
	v_cvt_pk_bf16_f32 v59, v50, v51
	flat_store_dwordx4 v[80:81], v[56:59] offset:1024 nt
	s_and_saveexec_b64 s[10:11], s[38:39]
	s_cbranch_execz .LBB0_557
	s_waitcnt lgkmcnt(0)
	v_add_f32_e32 v48, v52, v53
	v_fma_f32 v48, v48, s17, 0.5
	v_trunc_f32_e32 v48, v48
	v_mul_f32_e32 v49, 0x2f800000, v48
	v_floor_f32_e32 v49, v49
	v_fmac_f32_e32 v48, 0xcf800000, v49
	v_cvt_u32_f32_e32 v48, v48
	v_cvt_u32_f32_e32 v49, v49
	s_add_u32 s24, s94, s19
	s_addc_u32 s25, s95, s20
	v_mov_b64_e32 v[50:51], s[24:25]
	flat_store_dwordx2 v[50:51], v[48:49]
.LBB0_557:
	s_or_b64 exec, exec, s[10:11]
	v_mul_f32_e32 v48, v29, v29
	v_mul_f32_e32 v49, v31, v31
	v_fmac_f32_e32 v48, v28, v28
	v_fmac_f32_e32 v49, v30, v30
	v_add_f32_e32 v48, v48, v49
	v_mul_f32_e32 v49, v25, v25
	v_mul_f32_e32 v50, v27, v27
	v_fmac_f32_e32 v49, v24, v24
	v_fmac_f32_e32 v50, v26, v26
	v_add_f32_e32 v49, v49, v50
	v_add_f32_e32 v48, v48, v49
	v_mul_f32_e32 v49, v21, v21
	v_mul_f32_e32 v50, v23, v23
	v_fmac_f32_e32 v49, v20, v20
	v_fmac_f32_e32 v50, v22, v22
	v_add_f32_e32 v49, v49, v50
	v_add_f32_e32 v48, v48, v49
	v_mul_f32_e32 v49, v17, v17
	v_mul_f32_e32 v50, v19, v19
	v_fmac_f32_e32 v49, v16, v16
	v_fmac_f32_e32 v50, v18, v18
	v_add_f32_e32 v49, v49, v50
	v_add_f32_e32 v48, v48, v49
	ds_bpermute_b32 v49, v72, v48
	v_cvt_pk_bf16_f32 v44, v44, v45
	v_cvt_pk_bf16_f32 v45, v46, v47
	v_cvt_pk_bf16_f32 v47, v42, v43
	v_cvt_pk_bf16_f32 v46, v40, v41
	s_waitcnt lgkmcnt(0)
	v_add_f32_e32 v48, v48, v49
	ds_bpermute_b32 v49, v73, v48
	v_lshl_add_u64 v[40:41], s[94:95], 0, v[68:69]
	s_waitcnt lgkmcnt(0)
	v_add_f32_e32 v48, v48, v49
	ds_bpermute_b32 v49, v74, v48
	s_waitcnt lgkmcnt(0)
	v_add_f32_e32 v49, v48, v49
	ds_bpermute_b32 v50, v75, v49
	v_add_co_u32_e32 v48, vcc, s27, v40
	v_cvt_pk_bf16_f32 v40, v36, v37
	s_waitcnt lgkmcnt(0)
	v_add_f32_e32 v42, v49, v50
	ds_bpermute_b32 v43, v76, v42
	v_addc_co_u32_e32 v49, vcc, 0, v41, vcc
	v_cvt_pk_bf16_f32 v41, v38, v39
	flat_store_dwordx4 v[48:49], v[44:47] nt
	s_waitcnt lgkmcnt(0)
	v_add_f32_e32 v36, v42, v43
	ds_bpermute_b32 v37, v77, v36
	v_cvt_pk_bf16_f32 v42, v32, v33
	v_cvt_pk_bf16_f32 v43, v34, v35
	flat_store_dwordx4 v[48:49], v[40:43] offset:1024 nt
	s_and_saveexec_b64 s[10:11], s[38:39]
	s_cbranch_execz .LBB0_559
	s_waitcnt lgkmcnt(0)
	v_add_f32_e32 v32, v36, v37
	v_fma_f32 v32, v32, s17, 0.5
	v_trunc_f32_e32 v32, v32
	v_mul_f32_e32 v33, 0x2f800000, v32
	v_floor_f32_e32 v33, v33
	v_fmac_f32_e32 v32, 0xcf800000, v33
	v_cvt_u32_f32_e32 v32, v32
	v_cvt_u32_f32_e32 v33, v33
	s_add_u32 s24, s94, s14
	s_addc_u32 s25, s95, s15
	v_mov_b64_e32 v[34:35], s[24:25]
	flat_store_dwordx2 v[34:35], v[32:33]
.LBB0_559:
	s_or_b64 exec, exec, s[10:11]
	v_mul_f32_e32 v32, v13, v13
	v_mul_f32_e32 v33, v15, v15
	v_fmac_f32_e32 v32, v12, v12
	v_fmac_f32_e32 v33, v14, v14
	v_add_f32_e32 v32, v32, v33
	v_mul_f32_e32 v33, v9, v9
	v_mul_f32_e32 v34, v11, v11
	v_fmac_f32_e32 v33, v8, v8
	v_fmac_f32_e32 v34, v10, v10
	v_add_f32_e32 v33, v33, v34
	v_add_f32_e32 v32, v32, v33
	v_mul_f32_e32 v33, v5, v5
	v_mul_f32_e32 v34, v7, v7
	v_fmac_f32_e32 v33, v4, v4
	v_fmac_f32_e32 v34, v6, v6
	v_add_f32_e32 v33, v33, v34
	v_add_f32_e32 v32, v32, v33
	v_mul_f32_e32 v33, v1, v1
	v_mul_f32_e32 v34, v3, v3
	v_fmac_f32_e32 v33, v0, v0
	v_fmac_f32_e32 v34, v2, v2
	v_add_f32_e32 v33, v33, v34
	v_add_f32_e32 v32, v32, v33
	ds_bpermute_b32 v33, v72, v32
	v_cvt_pk_bf16_f32 v28, v28, v29
	v_cvt_pk_bf16_f32 v29, v30, v31
	v_cvt_pk_bf16_f32 v31, v26, v27
	v_cvt_pk_bf16_f32 v30, v24, v25
	s_waitcnt lgkmcnt(0)
	v_add_f32_e32 v32, v32, v33
	ds_bpermute_b32 v33, v73, v32
	v_lshl_add_u64 v[24:25], s[94:95], 0, v[66:67]
	s_waitcnt lgkmcnt(0)
	v_add_f32_e32 v32, v32, v33
	ds_bpermute_b32 v33, v74, v32
	s_waitcnt lgkmcnt(0)
	v_add_f32_e32 v33, v32, v33
	ds_bpermute_b32 v34, v75, v33
	v_add_co_u32_e32 v32, vcc, s27, v24
	v_cvt_pk_bf16_f32 v24, v20, v21
	s_waitcnt lgkmcnt(0)
	v_add_f32_e32 v26, v33, v34
	ds_bpermute_b32 v27, v76, v26
	v_addc_co_u32_e32 v33, vcc, 0, v25, vcc
	v_cvt_pk_bf16_f32 v25, v22, v23
	flat_store_dwordx4 v[32:33], v[28:31] nt
	s_waitcnt lgkmcnt(0)
	v_add_f32_e32 v20, v26, v27
	ds_bpermute_b32 v21, v77, v20
	v_cvt_pk_bf16_f32 v26, v16, v17
	v_cvt_pk_bf16_f32 v27, v18, v19
	flat_store_dwordx4 v[32:33], v[24:27] offset:1024 nt
	s_and_saveexec_b64 s[10:11], s[38:39]
	s_cbranch_execz .LBB0_552
	s_waitcnt lgkmcnt(0)
	v_add_f32_e32 v16, v20, v21
	v_fma_f32 v16, v16, s17, 0.5
	v_trunc_f32_e32 v16, v16
	v_mul_f32_e32 v17, 0x2f800000, v16
	v_floor_f32_e32 v17, v17
	v_fmac_f32_e32 v16, 0xcf800000, v17
	v_cvt_u32_f32_e32 v16, v16
	v_cvt_u32_f32_e32 v17, v17
	s_add_u32 s24, s94, s12
	s_addc_u32 s25, s95, s13
	v_mov_b64_e32 v[18:19], s[24:25]
	flat_store_dwordx2 v[18:19], v[16:17]
	s_branch .LBB0_552
